# merge epilogues: packed sigmoid divisions issued two row pairs at a time (loaded gate dword registers reused as temporaries)
# baseline (speedup 1.0000x reference)
; #define PG8_STAGE(bufoff, gbase, voff) do { _Pragma("unroll") for (int _i = 0; _i < 2; ++_i) \
;         __builtin_amdgcn_global_load_lds((const unsigned*)((const char*)(gbase) + (voff)[_i]), (LAS unsigned*)(lds + (bufoff) + ldsw + _i * 8192), 16, 0, 0); } while (0)
; #define PG8_LDA(dst, b, h) do { _Pragma("unroll") for (int m = 0; m < 4; ++m) _Pragma("unroll") for (int k = 0; k < 2; ++k) dst[m][k] = *(const LAS bf16x8*)(lds + PG8_SA(b, h) + aoff + m * 2048 + k * 1024); } while (0)
; #define PG8_LDB(dst, b, h) do { _Pragma("unroll") for (int n = 0; n < 2; ++n) _Pragma("unroll") for (int k = 0; k < 2; ++k) dst[n][k] = *(const LAS bf16x8*)(lds + PG8_SB(b, h) + boff + n * 2048 + k * 1024); } while (0)
; #define PG8_MMA(ai, bj, At, Bt) do { __builtin_amdgcn_s_setprio(1); _Pragma("unroll") for (int m = 0; m < 4; ++m) _Pragma("unroll") for (int n = 0; n < 2; ++n) _Pragma("unroll") for (int k = 0; k < 2; ++k) \
;         acc[ai][bj][m][n] = __builtin_amdgcn_mfma_f32_16x16x32_bf16(Bt[n][k], At[m][k], acc[ai][bj][m][n], 0, 0, 0); __builtin_amdgcn_s_setprio(0); } while (0)
; #define PG8_WAIT_L(n) asm volatile("s_waitcnt lgkmcnt(" #n ")" ::: "memory")
; #define PG8_BAR __builtin_amdgcn_s_barrier()
; #define PG8_SCHED __builtin_amdgcn_sched_barrier(0)
;     ...
;         for (int t = 0; t < nt; t += 2) {
;             const bool last = (t == nt - 2);
;             const char* a1 = cA + (size_t)(t + 1) * kstep;
;             const char* a2 = last ? nA : cA + (size_t)(t + 2) * kstep; const char* b2 = last ? nB : cB + (size_t)(t + 2) * kstep;
;             const char* a3 = a2 + kstep; const char* b3 = b2 + kstep;
;             if (last && has_next) PG8_A_READY(nxt);
;             PG8_LDB(B0, 0, 0); PG8_SCHED; PG8_LDA(At, 0, 0); PG8_STAGE(PG8_SA(1, 1), a1 + hA, voffA);
;             PG8_WAIT_L(8); PG8_BAR; PG8_WAIT_L(0); PG8_MMA(0, 0, At, B0); PG8_BAR; PG8_SCHED;
;             PG8_LDB(B1, 0, 1); PG8_STAGE(PG8_SB(0, 0), b2, voffB);
;             PG8_BAR; PG8_WAIT_L(0); PG8_MMA(0, 1, At, B1); PG8_BAR;
;             PG8_LDA(At, 0, 1); PG8_STAGE(PG8_SA(0, 0), a2, voffA);
;             PG8_BAR; PG8_WAIT_L(0); PG8_MMA(1, 0, At, B0); PG8_BAR; PG8_SCHED;
.LBB0_700:
	ds_read_b128 v[146:149], v159
	ds_read_b128 v[150:153], v159 offset:1024
	ds_read_b128 v[162:165], v159 offset:2048
	ds_read_b128 v[170:173], v159 offset:3072
	s_add_u32 s16, s14, 0xfffe0080
	s_addc_u32 s17, s15, -1
	s_cmp_eq_u32 s41, 4
	s_cselect_b32 s19, s7, s17
	s_cselect_b32 s18, s8, s16
	s_cselect_b32 s17, s9, s33
	s_cselect_b32 s16, s20, s21
	v_lshl_add_u64 v[154:155], s[14:15], 0, v[138:139]
	s_add_i32 m0, s67, 0xc000
	ds_read_b128 v[174:177], v160
	ds_read_b128 v[178:181], v160 offset:1024
	ds_read_b128 v[182:185], v160 offset:2048
	ds_read_b128 v[186:189], v160 offset:3072
	ds_read_b128 v[190:193], v160 offset:4096
	ds_read_b128 v[194:197], v160 offset:5120
	ds_read_b128 v[198:201], v160 offset:6144
	ds_read_b128 v[202:205], v160 offset:7168
	global_load_lds_dwordx4 v[154:155], off
	v_lshl_add_u64 v[154:155], s[14:15], 0, v[136:137]
	s_add_i32 m0, s67, 0xe000
	s_nop 0
	global_load_lds_dwordx4 v[154:155], off
	s_waitcnt lgkmcnt(8)
	s_barrier
	s_waitcnt lgkmcnt(0)
	s_setprio 1
	s_waitcnt lgkmcnt(0)
	v_mfma_f32_16x16x32_bf16 v[124:127], v[146:149], v[174:177], v[124:127]
	v_mfma_f32_16x16x32_bf16 v[120:123], v[162:165], v[174:177], v[120:123]
	v_mfma_f32_16x16x32_bf16 v[108:111], v[146:149], v[182:185], v[108:111]
	v_mfma_f32_16x16x32_bf16 v[104:107], v[162:165], v[182:185], v[104:107]
	v_mfma_f32_16x16x32_bf16 v[92:95], v[146:149], v[190:193], v[92:95]
	v_mfma_f32_16x16x32_bf16 v[88:91], v[162:165], v[190:193], v[88:91]
	v_mfma_f32_16x16x32_bf16 v[76:79], v[146:149], v[198:201], v[76:79]
	v_mfma_f32_16x16x32_bf16 v[72:75], v[162:165], v[198:201], v[72:75]
	v_mfma_f32_16x16x32_bf16 v[124:127], v[150:153], v[178:181], v[124:127]
	v_mfma_f32_16x16x32_bf16 v[120:123], v[170:173], v[178:181], v[120:123]
	v_mfma_f32_16x16x32_bf16 v[108:111], v[150:153], v[186:189], v[108:111]
	v_mfma_f32_16x16x32_bf16 v[104:107], v[170:173], v[186:189], v[104:107]
	v_mfma_f32_16x16x32_bf16 v[92:95], v[150:153], v[194:197], v[92:95]
	v_mfma_f32_16x16x32_bf16 v[88:91], v[170:173], v[194:197], v[88:91]
	v_mfma_f32_16x16x32_bf16 v[76:79], v[150:153], v[202:205], v[76:79]
	v_mfma_f32_16x16x32_bf16 v[72:75], v[170:173], v[202:205], v[72:75]
	s_setprio 0
	s_barrier
	s_add_i32 s42, s75, s66
	v_lshl_add_u64 v[154:155], s[16:17], 0, v[130:131]
	s_mov_b32 m0, s42
	ds_read_b128 v[206:209], v161
	ds_read_b128 v[210:213], v161 offset:1024
	ds_read_b128 v[214:217], v161 offset:2048
	ds_read_b128 v[218:221], v161 offset:3072
	global_load_lds_dwordx4 v[154:155], off
	v_lshl_add_u64 v[222:223], s[16:17], 0, v[134:135]
	s_add_i32 m0, s42, 0x2000
	s_nop 0
	global_load_lds_dwordx4 v[222:223], off
	s_barrier
	s_waitcnt lgkmcnt(0)
	s_setprio 1
	s_waitcnt lgkmcnt(0)
	v_mfma_f32_16x16x32_bf16 v[116:119], v[206:209], v[174:177], v[116:119]
	v_mfma_f32_16x16x32_bf16 v[112:115], v[214:217], v[174:177], v[112:115]
	v_mfma_f32_16x16x32_bf16 v[100:103], v[206:209], v[182:185], v[100:103]
	v_mfma_f32_16x16x32_bf16 v[96:99], v[214:217], v[182:185], v[96:99]
	v_mfma_f32_16x16x32_bf16 v[84:87], v[206:209], v[190:193], v[84:87]
	v_mfma_f32_16x16x32_bf16 v[80:83], v[214:217], v[190:193], v[80:83]
	v_mfma_f32_16x16x32_bf16 v[68:71], v[206:209], v[198:201], v[68:71]
	v_mfma_f32_16x16x32_bf16 v[64:67], v[214:217], v[198:201], v[64:67]
	v_mfma_f32_16x16x32_bf16 v[116:119], v[210:213], v[178:181], v[116:119]
	v_mfma_f32_16x16x32_bf16 v[112:115], v[218:221], v[178:181], v[112:115]
	v_mfma_f32_16x16x32_bf16 v[100:103], v[210:213], v[186:189], v[100:103]
	v_mfma_f32_16x16x32_bf16 v[96:99], v[218:221], v[186:189], v[96:99]
	v_mfma_f32_16x16x32_bf16 v[84:87], v[210:213], v[194:197], v[84:87]
	v_mfma_f32_16x16x32_bf16 v[80:83], v[218:221], v[194:197], v[80:83]
	v_mfma_f32_16x16x32_bf16 v[68:71], v[210:213], v[202:205], v[68:71]
	v_mfma_f32_16x16x32_bf16 v[64:67], v[218:221], v[202:205], v[64:67]
	s_setprio 0
	s_mov_b32 m0, s67
	v_lshl_add_u64 v[224:225], s[18:19], 0, v[128:129]
	s_barrier
	ds_read_b128 v[174:177], v160 offset:16384
	ds_read_b128 v[178:181], v160 offset:17408
	ds_read_b128 v[182:185], v160 offset:18432
	ds_read_b128 v[186:189], v160 offset:19456
	ds_read_b128 v[190:193], v160 offset:20480
	ds_read_b128 v[194:197], v160 offset:21504
	ds_read_b128 v[198:201], v160 offset:22528
	ds_read_b128 v[202:205], v160 offset:23552
	global_load_lds_dwordx4 v[224:225], off
	v_lshl_add_u64 v[226:227], s[18:19], 0, v[132:133]
	s_mov_b32 m0, s68
	s_nop 0
	global_load_lds_dwordx4 v[226:227], off
	s_barrier
	s_waitcnt lgkmcnt(0)
	s_setprio 1
	s_waitcnt lgkmcnt(0)
	v_mfma_f32_16x16x32_bf16 v[60:63], v[146:149], v[174:177], v[60:63]
	v_mfma_f32_16x16x32_bf16 v[56:59], v[162:165], v[174:177], v[56:59]
	v_mfma_f32_16x16x32_bf16 v[44:47], v[146:149], v[182:185], v[44:47]
	v_mfma_f32_16x16x32_bf16 v[40:43], v[162:165], v[182:185], v[40:43]
	v_mfma_f32_16x16x32_bf16 v[28:31], v[146:149], v[190:193], v[28:31]
	v_mfma_f32_16x16x32_bf16 v[24:27], v[162:165], v[190:193], v[24:27]
	v_mfma_f32_16x16x32_bf16 v[12:15], v[146:149], v[198:201], v[12:15]
	v_mfma_f32_16x16x32_bf16 v[8:11], v[162:165], v[198:201], v[8:11]
	v_mfma_f32_16x16x32_bf16 v[60:63], v[150:153], v[178:181], v[60:63]
	v_mfma_f32_16x16x32_bf16 v[56:59], v[170:173], v[178:181], v[56:59]
	v_mfma_f32_16x16x32_bf16 v[44:47], v[150:153], v[186:189], v[44:47]
	v_mfma_f32_16x16x32_bf16 v[40:43], v[170:173], v[186:189], v[40:43]
	v_mfma_f32_16x16x32_bf16 v[28:31], v[150:153], v[194:197], v[28:31]
	v_mfma_f32_16x16x32_bf16 v[24:27], v[170:173], v[194:197], v[24:27]
	v_mfma_f32_16x16x32_bf16 v[12:15], v[150:153], v[202:205], v[12:15]
	v_mfma_f32_16x16x32_bf16 v[8:11], v[170:173], v[202:205], v[8:11]
	s_setprio 0
	s_barrier
; #define PG8_STAGE(bufoff, gbase, voff) do { _Pragma("unroll") for (int _i = 0; _i < 2; ++_i) \
;         __builtin_amdgcn_global_load_lds((const unsigned*)((const char*)(gbase) + (voff)[_i]), (LAS unsigned*)(lds + (bufoff) + ldsw + _i * 8192), 16, 0, 0); } while (0)
; #define PG8_LDA(dst, b, h) do { _Pragma("unroll") for (int m = 0; m < 4; ++m) _Pragma("unroll") for (int k = 0; k < 2; ++k) dst[m][k] = *(const LAS bf16x8*)(lds + PG8_SA(b, h) + aoff + m * 2048 + k * 1024); } while (0)
; #define PG8_LDB(dst, b, h) do { _Pragma("unroll") for (int n = 0; n < 2; ++n) _Pragma("unroll") for (int k = 0; k < 2; ++k) dst[n][k] = *(const LAS bf16x8*)(lds + PG8_SB(b, h) + boff + n * 2048 + k * 1024); } while (0)
; #define PG8_MMA(ai, bj, At, Bt) do { __builtin_amdgcn_s_setprio(1); _Pragma("unroll") for (int m = 0; m < 4; ++m) _Pragma("unroll") for (int n = 0; n < 2; ++n) _Pragma("unroll") for (int k = 0; k < 2; ++k) \
;         acc[ai][bj][m][n] = __builtin_amdgcn_mfma_f32_16x16x32_bf16(Bt[n][k], At[m][k], acc[ai][bj][m][n], 0, 0, 0); __builtin_amdgcn_s_setprio(0); } while (0)
; #define PG8_WAIT_V(n) asm volatile("s_waitcnt vmcnt(" #n ")" ::: "memory")
;     ...
;             PG8_LDB(B0, 0, 0); PG8_SCHED; PG8_LDA(At, 0, 0); PG8_STAGE(PG8_SA(1, 1), a1 + hA, voffA);
;             PG8_WAIT_L(8); PG8_BAR; PG8_WAIT_L(0); PG8_MMA(0, 0, At, B0); PG8_BAR; PG8_SCHED;
;             PG8_LDB(B1, 0, 1); PG8_STAGE(PG8_SB(0, 0), b2, voffB);
;             PG8_BAR; PG8_WAIT_L(0); PG8_MMA(0, 1, At, B1); PG8_BAR;
;             PG8_LDA(At, 0, 1); PG8_STAGE(PG8_SA(0, 0), a2, voffA);
;             PG8_BAR; PG8_WAIT_L(0); PG8_MMA(1, 0, At, B0); PG8_BAR; PG8_SCHED;
;             PG8_STAGE(PG8_SB(0, 1), b2 + hB, voffB);
;             PG8_WAIT_V(6); PG8_BAR; PG8_MMA(1, 1, At, B1); PG8_BAR;
;             PG8_LDB(B0, 1, 0); PG8_SCHED; PG8_LDA(At, 1, 0); PG8_STAGE(PG8_SA(0, 1), a2 + hA, voffA);
;             PG8_WAIT_L(8); PG8_BAR; PG8_WAIT_L(0); PG8_MMA(0, 0, At, B0); PG8_BAR; PG8_SCHED;
;             PG8_LDB(B1, 1, 1); PG8_STAGE(PG8_SB(1, 0), b3, voffB);
;             PG8_BAR; PG8_WAIT_L(0); PG8_MMA(0, 1, At, B1); PG8_BAR;
;             PG8_LDA(At, 1, 1); PG8_STAGE(PG8_SA(1, 0), a3, voffA);
;             PG8_BAR; PG8_WAIT_L(0); PG8_MMA(1, 0, At, B0); PG8_BAR; PG8_SCHED;
;             PG8_STAGE(PG8_SB(1, 1), b3 + hB, voffB);
;             PG8_WAIT_V(6); PG8_BAR; PG8_MMA(1, 1, At, B1); PG8_BAR;
	s_add_u32 s42, s16, 0x20000
	s_addc_u32 s43, s17, 0
	s_add_i32 s44, s76, s66
	v_lshl_add_u64 v[146:147], s[42:43], 0, v[130:131]
	s_mov_b32 m0, s44
	s_nop 0
	global_load_lds_dwordx4 v[146:147], off
	v_lshl_add_u64 v[146:147], s[42:43], 0, v[134:135]
	s_add_i32 m0, s44, 0x2000
	s_nop 0
	global_load_lds_dwordx4 v[146:147], off
	s_waitcnt vmcnt(6)
	s_barrier
	s_setprio 1
	v_mfma_f32_16x16x32_bf16 v[52:55], v[206:209], v[174:177], v[52:55]
	v_mfma_f32_16x16x32_bf16 v[48:51], v[214:217], v[174:177], v[48:51]
	v_mfma_f32_16x16x32_bf16 v[36:39], v[206:209], v[182:185], v[36:39]
	v_mfma_f32_16x16x32_bf16 v[32:35], v[214:217], v[182:185], v[32:35]
	v_mfma_f32_16x16x32_bf16 v[20:23], v[206:209], v[190:193], v[20:23]
	v_mfma_f32_16x16x32_bf16 v[16:19], v[214:217], v[190:193], v[16:19]
	v_mfma_f32_16x16x32_bf16 v[4:7], v[206:209], v[198:201], v[4:7]
	v_mfma_f32_16x16x32_bf16 v[0:3], v[214:217], v[198:201], v[0:3]
	v_mfma_f32_16x16x32_bf16 v[52:55], v[210:213], v[178:181], v[52:55]
	v_mfma_f32_16x16x32_bf16 v[48:51], v[218:221], v[178:181], v[48:51]
	v_mfma_f32_16x16x32_bf16 v[36:39], v[210:213], v[186:189], v[36:39]
	v_mfma_f32_16x16x32_bf16 v[32:35], v[218:221], v[186:189], v[32:35]
	v_mfma_f32_16x16x32_bf16 v[20:23], v[210:213], v[194:197], v[20:23]
	v_mfma_f32_16x16x32_bf16 v[16:19], v[218:221], v[194:197], v[16:19]
	v_mfma_f32_16x16x32_bf16 v[4:7], v[210:213], v[202:205], v[4:7]
	v_mfma_f32_16x16x32_bf16 v[0:3], v[218:221], v[202:205], v[0:3]
	s_setprio 0
	s_add_i32 s42, 0, 0x18000
	v_add_u32_e32 v170, s42, v157
	s_barrier
	ds_read_b128 v[146:149], v170
	ds_read_b128 v[150:153], v170 offset:1024
	ds_read_b128 v[162:165], v170 offset:2048
	ds_read_b128 v[170:173], v170 offset:3072
	s_add_u32 s18, s18, 0x20000
	s_addc_u32 s19, s19, 0
	s_mov_b32 m0, s69
	v_lshl_add_u64 v[206:207], s[18:19], 0, v[128:129]
	ds_read_b128 v[174:177], v160 offset:32768
	ds_read_b128 v[178:181], v160 offset:33792
	ds_read_b128 v[182:185], v160 offset:34816
	ds_read_b128 v[186:189], v160 offset:35840
	ds_read_b128 v[190:193], v160 offset:36864
	ds_read_b128 v[194:197], v160 offset:37888
	ds_read_b128 v[198:201], v160 offset:38912
	ds_read_b128 v[202:205], v160 offset:39936
	global_load_lds_dwordx4 v[206:207], off
	v_lshl_add_u64 v[206:207], s[18:19], 0, v[132:133]
	s_mov_b32 m0, s70
	s_nop 0
	global_load_lds_dwordx4 v[206:207], off
	s_waitcnt lgkmcnt(8)
	s_barrier
	s_waitcnt lgkmcnt(0)
	s_setprio 1
	s_waitcnt lgkmcnt(0)
	v_mfma_f32_16x16x32_bf16 v[124:127], v[146:149], v[174:177], v[124:127]
	v_mfma_f32_16x16x32_bf16 v[120:123], v[162:165], v[174:177], v[120:123]
	v_mfma_f32_16x16x32_bf16 v[108:111], v[146:149], v[182:185], v[108:111]
	v_mfma_f32_16x16x32_bf16 v[104:107], v[162:165], v[182:185], v[104:107]
	v_mfma_f32_16x16x32_bf16 v[92:95], v[146:149], v[190:193], v[92:95]
	v_mfma_f32_16x16x32_bf16 v[88:91], v[162:165], v[190:193], v[88:91]
	v_mfma_f32_16x16x32_bf16 v[76:79], v[146:149], v[198:201], v[76:79]
	v_mfma_f32_16x16x32_bf16 v[72:75], v[162:165], v[198:201], v[72:75]
	v_mfma_f32_16x16x32_bf16 v[124:127], v[150:153], v[178:181], v[124:127]
	v_mfma_f32_16x16x32_bf16 v[120:123], v[170:173], v[178:181], v[120:123]
	v_mfma_f32_16x16x32_bf16 v[108:111], v[150:153], v[186:189], v[108:111]
	v_mfma_f32_16x16x32_bf16 v[104:107], v[170:173], v[186:189], v[104:107]
	v_mfma_f32_16x16x32_bf16 v[92:95], v[150:153], v[194:197], v[92:95]
	v_mfma_f32_16x16x32_bf16 v[88:91], v[170:173], v[194:197], v[88:91]
	v_mfma_f32_16x16x32_bf16 v[76:79], v[150:153], v[202:205], v[76:79]
	v_mfma_f32_16x16x32_bf16 v[72:75], v[170:173], v[202:205], v[72:75]
	s_setprio 0
	s_barrier
	s_add_i32 s18, 0, 0x1c000
	s_add_i32 s19, s42, s66
	v_add_u32_e32 v218, s18, v157
	v_lshl_add_u64 v[154:155], v[154:155], 0, s[54:55]
	s_mov_b32 m0, s19
	ds_read_b128 v[206:209], v218
	ds_read_b128 v[210:213], v218 offset:1024
	ds_read_b128 v[214:217], v218 offset:2048
	ds_read_b128 v[218:221], v218 offset:3072
	global_load_lds_dwordx4 v[154:155], off
	v_lshl_add_u64 v[154:155], v[222:223], 0, s[54:55]
	s_add_i32 m0, s19, 0x2000
	s_nop 0
	global_load_lds_dwordx4 v[154:155], off
	s_barrier
	s_waitcnt lgkmcnt(0)
	s_setprio 1
	s_waitcnt lgkmcnt(0)
	v_mfma_f32_16x16x32_bf16 v[116:119], v[206:209], v[174:177], v[116:119]
	v_mfma_f32_16x16x32_bf16 v[112:115], v[214:217], v[174:177], v[112:115]
	v_mfma_f32_16x16x32_bf16 v[100:103], v[206:209], v[182:185], v[100:103]
	v_mfma_f32_16x16x32_bf16 v[96:99], v[214:217], v[182:185], v[96:99]
	v_mfma_f32_16x16x32_bf16 v[84:87], v[206:209], v[190:193], v[84:87]
	v_mfma_f32_16x16x32_bf16 v[80:83], v[214:217], v[190:193], v[80:83]
	v_mfma_f32_16x16x32_bf16 v[68:71], v[206:209], v[198:201], v[68:71]
	v_mfma_f32_16x16x32_bf16 v[64:67], v[214:217], v[198:201], v[64:67]
	v_mfma_f32_16x16x32_bf16 v[116:119], v[210:213], v[178:181], v[116:119]
	v_mfma_f32_16x16x32_bf16 v[112:115], v[218:221], v[178:181], v[112:115]
	v_mfma_f32_16x16x32_bf16 v[100:103], v[210:213], v[186:189], v[100:103]
	v_mfma_f32_16x16x32_bf16 v[96:99], v[218:221], v[186:189], v[96:99]
	v_mfma_f32_16x16x32_bf16 v[84:87], v[210:213], v[194:197], v[84:87]
	v_mfma_f32_16x16x32_bf16 v[80:83], v[218:221], v[194:197], v[80:83]
	v_mfma_f32_16x16x32_bf16 v[68:71], v[210:213], v[202:205], v[68:71]
	v_mfma_f32_16x16x32_bf16 v[64:67], v[218:221], v[202:205], v[64:67]
	s_setprio 0
	s_mov_b32 m0, s72
	v_lshl_add_u64 v[154:155], v[224:225], 0, s[54:55]
	s_barrier
	ds_read_b128 v[174:177], v160 offset:49152
	ds_read_b128 v[178:181], v160 offset:50176
	ds_read_b128 v[182:185], v160 offset:51200
	ds_read_b128 v[186:189], v160 offset:52224
	ds_read_b128 v[190:193], v160 offset:53248
	ds_read_b128 v[194:197], v160 offset:54272
	ds_read_b128 v[198:201], v160 offset:55296
	ds_read_b128 v[202:205], v160 offset:56320
	global_load_lds_dwordx4 v[154:155], off
	v_lshl_add_u64 v[154:155], v[226:227], 0, s[54:55]
	s_mov_b32 m0, s73
	s_nop 0
	global_load_lds_dwordx4 v[154:155], off
	s_barrier
; __device__ __forceinline__ float sigmoidf_(float x) { return 1.0f / (1.0f + __expf(-x)); }
; #define PG8_STAGE(bufoff, gbase, voff) do { _Pragma("unroll") for (int _i = 0; _i < 2; ++_i) \
;         __builtin_amdgcn_global_load_lds((const unsigned*)((const char*)(gbase) + (voff)[_i]), (LAS unsigned*)(lds + (bufoff) + ldsw + _i * 8192), 16, 0, 0); } while (0)
; #define PG8_LDA(dst, b, h) do { _Pragma("unroll") for (int m = 0; m < 4; ++m) _Pragma("unroll") for (int k = 0; k < 2; ++k) dst[m][k] = *(const LAS bf16x8*)(lds + PG8_SA(b, h) + aoff + m * 2048 + k * 1024); } while (0)
; #define PG8_WAIT_V(n) asm volatile("s_waitcnt vmcnt(" #n ")" ::: "memory")
;     ...
;             PG8_WAIT_V(6); PG8_BAR; PG8_MMA(1, 1, At, B1); PG8_BAR;
;             PG8_LDB(B0, 1, 0); PG8_SCHED; PG8_LDA(At, 1, 0); PG8_STAGE(PG8_SA(0, 1), a2 + hA, voffA);
;             PG8_WAIT_L(8); PG8_BAR; PG8_WAIT_L(0); PG8_MMA(0, 0, At, B0); PG8_BAR; PG8_SCHED;
;             PG8_LDB(B1, 1, 1); PG8_STAGE(PG8_SB(1, 0), b3, voffB);
;             PG8_BAR; PG8_WAIT_L(0); PG8_MMA(0, 1, At, B1); PG8_BAR;
;             PG8_LDA(At, 1, 1); PG8_STAGE(PG8_SA(1, 0), a3, voffA);
;             PG8_BAR; PG8_WAIT_L(0); PG8_MMA(1, 0, At, B0); PG8_BAR; PG8_SCHED;
;             PG8_STAGE(PG8_SB(1, 1), b3 + hB, voffB);
;             PG8_WAIT_V(6); PG8_BAR; PG8_MMA(1, 1, At, B1); PG8_BAR;
;         }
;     __device__ __forceinline__ void operator()(const f32x4 (&acc)[2][2][4][2], const Unit& u, int wr, int wc, int fr, int fq) const {
;         const __amdgpu_buffer_rsrc_t rsrc = __builtin_amdgcn_make_buffer_rsrc((void*)z, 0, T_ALL * DIN * 2, 0x00020000);
;         const int row0 = row_off + u.pm * 256 + wr * 64 + fr, col0 = u.pn * 256 + wc * 32 + 8 * fq;
; #pragma unroll
;         for (int ai = 0; ai < 2; ++ai)
; #pragma unroll
;             for (int m = 0; m < 4; ++m) {
;                 const int row = row0 + ai * 128 + m * 16;
;                 const bf16_t* rowp = z + (size_t)row * DIN + col0;
; #pragma unroll
;                 for (int bj = 0; bj < 2; ++bj) {
;                     const u32x4 gw = *(const u32x4*)(rowp + O_GA + bj * 128);
;                     f32x4 g0, g1; unpack8(gw, g0, g1);
;                     f32x4 v0, v1;
; #pragma unroll
;                     for (int j = 0; j < 4; ++j) { v0[j] = sigmoidf_(g0[j]) * acc[ai][bj][m][0][j]; v1[j] = sigmoidf_(g1[j]) * acc[ai][bj][m][1][j]; }
	s_waitcnt lgkmcnt(0)
	s_setprio 1
	s_waitcnt lgkmcnt(0)
	v_mfma_f32_16x16x32_bf16 v[60:63], v[146:149], v[174:177], v[60:63]
	v_mfma_f32_16x16x32_bf16 v[56:59], v[162:165], v[174:177], v[56:59]
	v_mfma_f32_16x16x32_bf16 v[44:47], v[146:149], v[182:185], v[44:47]
	v_mfma_f32_16x16x32_bf16 v[40:43], v[162:165], v[182:185], v[40:43]
	v_mfma_f32_16x16x32_bf16 v[28:31], v[146:149], v[190:193], v[28:31]
	v_mfma_f32_16x16x32_bf16 v[24:27], v[162:165], v[190:193], v[24:27]
	v_mfma_f32_16x16x32_bf16 v[12:15], v[146:149], v[198:201], v[12:15]
	v_mfma_f32_16x16x32_bf16 v[8:11], v[162:165], v[198:201], v[8:11]
	v_mfma_f32_16x16x32_bf16 v[60:63], v[150:153], v[178:181], v[60:63]
	v_mfma_f32_16x16x32_bf16 v[56:59], v[170:173], v[178:181], v[56:59]
	v_mfma_f32_16x16x32_bf16 v[44:47], v[150:153], v[186:189], v[44:47]
	v_mfma_f32_16x16x32_bf16 v[40:43], v[170:173], v[186:189], v[40:43]
	v_mfma_f32_16x16x32_bf16 v[28:31], v[150:153], v[194:197], v[28:31]
	v_mfma_f32_16x16x32_bf16 v[24:27], v[170:173], v[194:197], v[24:27]
	v_mfma_f32_16x16x32_bf16 v[12:15], v[150:153], v[202:205], v[12:15]
	v_mfma_f32_16x16x32_bf16 v[8:11], v[170:173], v[202:205], v[8:11]
	s_setprio 0
	s_barrier
	s_add_u32 s16, s16, 0x20080
	s_addc_u32 s17, s17, 0
	s_add_i32 s18, s18, s66
	v_lshl_add_u64 v[146:147], s[16:17], 0, v[130:131]
	s_mov_b32 m0, s18
	s_nop 0
	global_load_lds_dwordx4 v[146:147], off
	v_lshl_add_u64 v[146:147], s[16:17], 0, v[134:135]
	s_add_i32 m0, s18, 0x2000
	s_nop 0
	global_load_lds_dwordx4 v[146:147], off
	s_waitcnt vmcnt(6)
	s_barrier
	s_setprio 1
	v_mfma_f32_16x16x32_bf16 v[52:55], v[206:209], v[174:177], v[52:55]
	v_mfma_f32_16x16x32_bf16 v[48:51], v[214:217], v[174:177], v[48:51]
	v_mfma_f32_16x16x32_bf16 v[36:39], v[206:209], v[182:185], v[36:39]
	v_mfma_f32_16x16x32_bf16 v[32:35], v[214:217], v[182:185], v[32:35]
	v_mfma_f32_16x16x32_bf16 v[20:23], v[206:209], v[190:193], v[20:23]
	v_mfma_f32_16x16x32_bf16 v[16:19], v[214:217], v[190:193], v[16:19]
	v_mfma_f32_16x16x32_bf16 v[4:7], v[206:209], v[198:201], v[4:7]
	v_mfma_f32_16x16x32_bf16 v[0:3], v[214:217], v[198:201], v[0:3]
	v_mfma_f32_16x16x32_bf16 v[52:55], v[210:213], v[178:181], v[52:55]
	v_mfma_f32_16x16x32_bf16 v[48:51], v[218:221], v[178:181], v[48:51]
	v_mfma_f32_16x16x32_bf16 v[36:39], v[210:213], v[186:189], v[36:39]
	v_mfma_f32_16x16x32_bf16 v[32:35], v[218:221], v[186:189], v[32:35]
	v_mfma_f32_16x16x32_bf16 v[20:23], v[210:213], v[194:197], v[20:23]
	v_mfma_f32_16x16x32_bf16 v[16:19], v[218:221], v[194:197], v[16:19]
	v_mfma_f32_16x16x32_bf16 v[4:7], v[210:213], v[202:205], v[4:7]
	v_mfma_f32_16x16x32_bf16 v[0:3], v[218:221], v[202:205], v[0:3]
	s_setprio 0
	s_add_i32 s41, s41, 2
	s_add_u32 s21, s21, 0x100
	s_addc_u32 s33, s33, 0
	s_add_u32 s14, s14, 0x100
	s_addc_u32 s15, s15, 0
	s_cmp_gt_u32 s41, 5
	s_barrier
	s_cbranch_scc0 .LBB0_700
	v_lshl_or_b32 v146, s6, 8, v158
	v_lshl_add_u32 v162, s79, 8, v156
	v_ashrrev_i32_e32 v147, 31, v146
	v_mad_i64_i32 v[154:155], s[6:7], v162, s77, 0
	v_lshl_add_u64 v[150:151], v[154:155], 1, s[38:39]
	v_lshlrev_b64 v[148:149], 1, v[146:147]
	v_lshl_add_u64 v[150:151], v[150:151], 0, v[148:149]
	v_add_co_u32_e32 v152, vcc, 0x1000, v150
	s_nop 1
	v_addc_co_u32_e32 v153, vcc, 0, v151, vcc
	v_subrev_u32_e32 v202, s38, v150
	v_add_u32_e32 v203, 0x1200, v202
	global_load_dwordx4 v[204:207], v203, s[38:39]
	v_add_u32_e32 v203, 0x0, v202
	global_load_dwordx4 v[208:211], v203, s[38:39]
	v_add_u32_e32 v203, 0x1300, v202
	global_load_dwordx4 v[212:215], v203, s[38:39]
	v_add_u32_e32 v203, 0x100, v202
	global_load_dwordx4 v[216:219], v203, s[38:39]
	v_add_u32_e32 v203, 0x23200, v202
	global_load_dwordx4 v[232:235], v203, s[38:39]
	v_add_u32_e32 v203, 0x22000, v202
	global_load_dwordx4 v[236:239], v203, s[38:39]
	s_waitcnt vmcnt(4)
	v_mov_b32_e32 v170, v204
	v_mov_b32_e32 v171, v205
	v_mov_b32_e32 v172, v206
	v_mov_b32_e32 v173, v207
	v_mov_b32_e32 v174, v208
	v_mov_b32_e32 v175, v209
	v_mov_b32_e32 v176, v210
	v_mov_b32_e32 v177, v211
	v_add_u32_e32 v203, 0x23300, v202
	global_load_dwordx4 v[204:207], v203, s[38:39]
	v_add_u32_e32 v203, 0x22100, v202
	global_load_dwordx4 v[208:211], v203, s[38:39]
	s_mov_b32 s100, 0xbfb8aa3b
	v_lshlrev_b32_e32 v240, 16, v170
	v_and_b32_e32 v241, 0xffff0000, v170
	v_lshlrev_b32_e32 v242, 16, v172
	v_and_b32_e32 v243, 0xffff0000, v172
	v_lshlrev_b32_e32 v244, 16, v171
	v_and_b32_e32 v245, 0xffff0000, v171
	v_lshlrev_b32_e32 v246, 16, v173
	v_and_b32_e32 v247, 0xffff0000, v173
	v_pk_mul_f32 v[240:241], v[240:241], s[100:101] op_sel_hi:[1,0]
	v_pk_mul_f32 v[242:243], v[242:243], s[100:101] op_sel_hi:[1,0]
	v_pk_mul_f32 v[244:245], v[244:245], s[100:101] op_sel_hi:[1,0]
	v_pk_mul_f32 v[246:247], v[246:247], s[100:101] op_sel_hi:[1,0]
	v_exp_f32_e32 v240, v240
	v_exp_f32_e32 v241, v241
	v_exp_f32_e32 v242, v242
	v_exp_f32_e32 v243, v243
	v_exp_f32_e32 v244, v244
	v_exp_f32_e32 v245, v245
	v_exp_f32_e32 v246, v246
	v_exp_f32_e32 v247, v247
	s_nop 0
	v_pk_add_f32 v[240:241], v[240:241], 1.0 op_sel_hi:[1,0]
	v_pk_add_f32 v[242:243], v[242:243], 1.0 op_sel_hi:[1,0]
	v_pk_add_f32 v[244:245], v[244:245], 1.0 op_sel_hi:[1,0]
	v_pk_add_f32 v[246:247], v[246:247], 1.0 op_sel_hi:[1,0]
	v_rcp_f32_e32 v248, v240
	v_rcp_f32_e32 v249, v241
	v_rcp_f32_e32 v254, v242
	v_rcp_f32_e32 v255, v243
	v_pk_fma_f32 v[250:251], v[240:241], v[248:249], 1.0 op_sel_hi:[1,1,0] neg_lo:[1,0,0] neg_hi:[1,0,0]
	v_pk_fma_f32 v[170:171], v[242:243], v[254:255], 1.0 op_sel_hi:[1,1,0] neg_lo:[1,0,0] neg_hi:[1,0,0]
	v_pk_fma_f32 v[248:249], v[250:251], v[248:249], v[248:249]
	v_pk_fma_f32 v[254:255], v[170:171], v[254:255], v[254:255]
; __device__ __forceinline__ float sigmoidf_(float x) { return 1.0f / (1.0f + __expf(-x)); }
; __device__ __forceinline__ u32x4 pack8(const f32x4 v0, const f32x4 v1) { u32x4 w; w.x = pk2(v0[0], v0[1]); w.y = pk2(v0[2], v0[3]); w.z = pk2(v1[0], v1[1]); w.w = pk2(v1[2], v1[3]); return w; }
; __device__ __forceinline__ void unpack8(const u32x4 w, f32x4& v0, f32x4& v1) { v0 = (f32x4){bflo(w.x), bfhi(w.x), bflo(w.y), bfhi(w.y)}; v1 = (f32x4){bflo(w.z), bfhi(w.z), bflo(w.w), bfhi(w.w)}; }
;     __device__ __forceinline__ void operator()(const f32x4 (&acc)[2][2][4][2], const Unit& u, int wr, int wc, int fr, int fq) const {
;     ...
;                     const u32x4 gw = *(const u32x4*)(rowp + O_GA + bj * 128);
;                     f32x4 g0, g1; unpack8(gw, g0, g1);
;                     f32x4 v0, v1;
; #pragma unroll
;                     for (int j = 0; j < 4; ++j) { v0[j] = sigmoidf_(g0[j]) * acc[ai][bj][m][0][j]; v1[j] = sigmoidf_(g1[j]) * acc[ai][bj][m][1][j]; }
;                     const u32x4 mw = *(const u32x4*)(rowp + bj * 128); f32x4 m0, m1; unpack8(mw, m0, m1); v0 += m0; v1 += m1;
;                     __builtin_amdgcn_raw_buffer_store_b128(pack8(v0, v1), rsrc, (unsigned)(((size_t)row * DIN + col0 + bj * 128) * 2), 0, 16  ); }
	v_pk_fma_f32 v[250:251], v[240:241], v[248:249], 1.0 op_sel_hi:[1,1,0] neg_lo:[1,0,0] neg_hi:[1,0,0]
	v_pk_fma_f32 v[170:171], v[242:243], v[254:255], 1.0 op_sel_hi:[1,1,0] neg_lo:[1,0,0] neg_hi:[1,0,0]
	v_pk_fma_f32 v[252:253], v[250:251], v[248:249], v[248:249]
	v_pk_fma_f32 v[172:173], v[170:171], v[254:255], v[254:255]
	v_pk_fma_f32 v[250:251], v[240:241], v[252:253], 1.0 op_sel_hi:[1,1,0] neg_lo:[1,0,0] neg_hi:[1,0,0]
	v_pk_fma_f32 v[170:171], v[242:243], v[172:173], 1.0 op_sel_hi:[1,1,0] neg_lo:[1,0,0] neg_hi:[1,0,0]
	v_pk_fma_f32 v[252:253], v[250:251], v[248:249], v[252:253]
	v_pk_fma_f32 v[172:173], v[170:171], v[254:255], v[172:173]
	v_div_fixup_f32 v240, v252, v240, 1.0
	v_div_fixup_f32 v241, v253, v241, 1.0
	v_div_fixup_f32 v242, v172, v242, 1.0
	v_div_fixup_f32 v243, v173, v243, 1.0
	v_rcp_f32_e32 v248, v244
	v_rcp_f32_e32 v249, v245
	v_rcp_f32_e32 v254, v246
	v_rcp_f32_e32 v255, v247
	v_pk_fma_f32 v[250:251], v[244:245], v[248:249], 1.0 op_sel_hi:[1,1,0] neg_lo:[1,0,0] neg_hi:[1,0,0]
	v_pk_fma_f32 v[170:171], v[246:247], v[254:255], 1.0 op_sel_hi:[1,1,0] neg_lo:[1,0,0] neg_hi:[1,0,0]
	v_pk_fma_f32 v[248:249], v[250:251], v[248:249], v[248:249]
	v_pk_fma_f32 v[254:255], v[170:171], v[254:255], v[254:255]
	v_pk_fma_f32 v[250:251], v[244:245], v[248:249], 1.0 op_sel_hi:[1,1,0] neg_lo:[1,0,0] neg_hi:[1,0,0]
	v_pk_fma_f32 v[170:171], v[246:247], v[254:255], 1.0 op_sel_hi:[1,1,0] neg_lo:[1,0,0] neg_hi:[1,0,0]
	v_pk_fma_f32 v[252:253], v[250:251], v[248:249], v[248:249]
	v_pk_fma_f32 v[172:173], v[170:171], v[254:255], v[254:255]
	v_pk_fma_f32 v[250:251], v[244:245], v[252:253], 1.0 op_sel_hi:[1,1,0] neg_lo:[1,0,0] neg_hi:[1,0,0]
	v_pk_fma_f32 v[170:171], v[246:247], v[172:173], 1.0 op_sel_hi:[1,1,0] neg_lo:[1,0,0] neg_hi:[1,0,0]
	v_pk_fma_f32 v[252:253], v[250:251], v[248:249], v[252:253]
	v_pk_fma_f32 v[172:173], v[170:171], v[254:255], v[172:173]
	v_div_fixup_f32 v244, v252, v244, 1.0
	v_div_fixup_f32 v245, v253, v245, 1.0
	v_div_fixup_f32 v246, v172, v246, 1.0
	v_div_fixup_f32 v247, v173, v247, 1.0
	s_mov_b64 vcc, s[14:15]
	s_mov_b64 vcc, s[16:17]
	s_mov_b64 vcc, s[18:19]
	s_mov_b64 vcc, s[20:21]
	v_lshlrev_b32_e32 v182, 16, v176
	v_and_b32_e32 v183, 0xffff0000, v176
	v_lshlrev_b32_e32 v180, 16, v174
	v_and_b32_e32 v181, 0xffff0000, v174
	v_lshlrev_b32_e32 v176, 16, v177
	v_and_b32_e32 v177, 0xffff0000, v177
	v_lshlrev_b32_e32 v174, 16, v175
	v_and_b32_e32 v175, 0xffff0000, v175
	v_pk_fma_f32 v[124:125], v[124:125], v[240:241], v[180:181]
	v_pk_fma_f32 v[164:165], v[122:123], v[246:247], v[176:177]
	v_pk_fma_f32 v[122:123], v[120:121], v[242:243], v[182:183]
	v_add_lshl_u32 v147, v146, v154, 1
	v_pk_fma_f32 v[126:127], v[126:127], v[244:245], v[174:175]
	v_cvt_pk_bf16_f32 v120, v124, v125
	s_nop 0
	v_cvt_pk_bf16_f32 v121, v126, v127
	v_cvt_pk_bf16_f32 v122, v122, v123
	v_cvt_pk_bf16_f32 v123, v164, v165
	buffer_store_dwordx4 v[120:123], v147, s[24:27], 0 offen sc1
	s_nop 0
	s_waitcnt vmcnt(5)
	v_mov_b32_e32 v120, v212
	v_mov_b32_e32 v121, v213
	v_mov_b32_e32 v122, v214
	v_mov_b32_e32 v123, v215
	v_mov_b32_e32 v124, v216
	v_mov_b32_e32 v125, v217
	v_mov_b32_e32 v126, v218
	v_mov_b32_e32 v127, v219
	v_add_u32_e32 v203, 0x45200, v202
	global_load_dwordx4 v[212:215], v203, s[38:39]
	v_add_u32_e32 v203, 0x44000, v202
	global_load_dwordx4 v[216:219], v203, s[38:39]
	s_mov_b32 s100, 0xbfb8aa3b
	v_lshlrev_b32_e32 v240, 16, v120
	v_and_b32_e32 v241, 0xffff0000, v120
	v_lshlrev_b32_e32 v242, 16, v122
	v_and_b32_e32 v243, 0xffff0000, v122
	v_lshlrev_b32_e32 v244, 16, v121
	v_and_b32_e32 v245, 0xffff0000, v121
	v_lshlrev_b32_e32 v246, 16, v123
	v_and_b32_e32 v247, 0xffff0000, v123
	v_pk_mul_f32 v[240:241], v[240:241], s[100:101] op_sel_hi:[1,0]
	v_pk_mul_f32 v[242:243], v[242:243], s[100:101] op_sel_hi:[1,0]
	v_pk_mul_f32 v[244:245], v[244:245], s[100:101] op_sel_hi:[1,0]
	v_pk_mul_f32 v[246:247], v[246:247], s[100:101] op_sel_hi:[1,0]
	v_exp_f32_e32 v240, v240
	v_exp_f32_e32 v241, v241
	v_exp_f32_e32 v242, v242
	v_exp_f32_e32 v243, v243
	v_exp_f32_e32 v244, v244
	v_exp_f32_e32 v245, v245
	v_exp_f32_e32 v246, v246
	v_exp_f32_e32 v247, v247
	s_nop 0
	v_pk_add_f32 v[240:241], v[240:241], 1.0 op_sel_hi:[1,0]
	v_pk_add_f32 v[242:243], v[242:243], 1.0 op_sel_hi:[1,0]
	v_pk_add_f32 v[244:245], v[244:245], 1.0 op_sel_hi:[1,0]
	v_pk_add_f32 v[246:247], v[246:247], 1.0 op_sel_hi:[1,0]
	v_rcp_f32_e32 v248, v240
	v_rcp_f32_e32 v249, v241
	v_rcp_f32_e32 v254, v242
	v_rcp_f32_e32 v255, v243
	v_pk_fma_f32 v[250:251], v[240:241], v[248:249], 1.0 op_sel_hi:[1,1,0] neg_lo:[1,0,0] neg_hi:[1,0,0]
	v_pk_fma_f32 v[120:121], v[242:243], v[254:255], 1.0 op_sel_hi:[1,1,0] neg_lo:[1,0,0] neg_hi:[1,0,0]
	v_pk_fma_f32 v[248:249], v[250:251], v[248:249], v[248:249]
	v_pk_fma_f32 v[254:255], v[120:121], v[254:255], v[254:255]
	v_pk_fma_f32 v[250:251], v[240:241], v[248:249], 1.0 op_sel_hi:[1,1,0] neg_lo:[1,0,0] neg_hi:[1,0,0]
	v_pk_fma_f32 v[120:121], v[242:243], v[254:255], 1.0 op_sel_hi:[1,1,0] neg_lo:[1,0,0] neg_hi:[1,0,0]
	v_pk_fma_f32 v[252:253], v[250:251], v[248:249], v[248:249]
	v_pk_fma_f32 v[122:123], v[120:121], v[254:255], v[254:255]
	v_pk_fma_f32 v[250:251], v[240:241], v[252:253], 1.0 op_sel_hi:[1,1,0] neg_lo:[1,0,0] neg_hi:[1,0,0]
	v_pk_fma_f32 v[120:121], v[242:243], v[122:123], 1.0 op_sel_hi:[1,1,0] neg_lo:[1,0,0] neg_hi:[1,0,0]
	v_pk_fma_f32 v[252:253], v[250:251], v[248:249], v[252:253]
	v_pk_fma_f32 v[122:123], v[120:121], v[254:255], v[122:123]
	v_div_fixup_f32 v240, v252, v240, 1.0
	v_div_fixup_f32 v241, v253, v241, 1.0
	v_div_fixup_f32 v242, v122, v242, 1.0
	v_div_fixup_f32 v243, v123, v243, 1.0
	v_rcp_f32_e32 v248, v244
	v_rcp_f32_e32 v249, v245
; __device__ __forceinline__ float sigmoidf_(float x) { return 1.0f / (1.0f + __expf(-x)); }
; __device__ __forceinline__ u32x4 pack8(const f32x4 v0, const f32x4 v1) { u32x4 w; w.x = pk2(v0[0], v0[1]); w.y = pk2(v0[2], v0[3]); w.z = pk2(v1[0], v1[1]); w.w = pk2(v1[2], v1[3]); return w; }
; __device__ __forceinline__ void unpack8(const u32x4 w, f32x4& v0, f32x4& v1) { v0 = (f32x4){bflo(w.x), bfhi(w.x), bflo(w.y), bfhi(w.y)}; v1 = (f32x4){bflo(w.z), bfhi(w.z), bflo(w.w), bfhi(w.w)}; }
;     __device__ __forceinline__ void operator()(const f32x4 (&acc)[2][2][4][2], const Unit& u, int wr, int wc, int fr, int fq) const {
;     ...
;                     const u32x4 gw = *(const u32x4*)(rowp + O_GA + bj * 128);
;                     f32x4 g0, g1; unpack8(gw, g0, g1);
;                     f32x4 v0, v1;
; #pragma unroll
;                     for (int j = 0; j < 4; ++j) { v0[j] = sigmoidf_(g0[j]) * acc[ai][bj][m][0][j]; v1[j] = sigmoidf_(g1[j]) * acc[ai][bj][m][1][j]; }
;                     const u32x4 mw = *(const u32x4*)(rowp + bj * 128); f32x4 m0, m1; unpack8(mw, m0, m1); v0 += m0; v1 += m1;
;                     __builtin_amdgcn_raw_buffer_store_b128(pack8(v0, v1), rsrc, (unsigned)(((size_t)row * DIN + col0 + bj * 128) * 2), 0, 16  ); }
	v_rcp_f32_e32 v254, v246
	v_rcp_f32_e32 v255, v247
	v_pk_fma_f32 v[250:251], v[244:245], v[248:249], 1.0 op_sel_hi:[1,1,0] neg_lo:[1,0,0] neg_hi:[1,0,0]
	v_pk_fma_f32 v[120:121], v[246:247], v[254:255], 1.0 op_sel_hi:[1,1,0] neg_lo:[1,0,0] neg_hi:[1,0,0]
	v_pk_fma_f32 v[248:249], v[250:251], v[248:249], v[248:249]
	v_pk_fma_f32 v[254:255], v[120:121], v[254:255], v[254:255]
	v_pk_fma_f32 v[250:251], v[244:245], v[248:249], 1.0 op_sel_hi:[1,1,0] neg_lo:[1,0,0] neg_hi:[1,0,0]
	v_pk_fma_f32 v[120:121], v[246:247], v[254:255], 1.0 op_sel_hi:[1,1,0] neg_lo:[1,0,0] neg_hi:[1,0,0]
	v_pk_fma_f32 v[252:253], v[250:251], v[248:249], v[248:249]
	v_pk_fma_f32 v[122:123], v[120:121], v[254:255], v[254:255]
	v_pk_fma_f32 v[250:251], v[244:245], v[252:253], 1.0 op_sel_hi:[1,1,0] neg_lo:[1,0,0] neg_hi:[1,0,0]
	v_pk_fma_f32 v[120:121], v[246:247], v[122:123], 1.0 op_sel_hi:[1,1,0] neg_lo:[1,0,0] neg_hi:[1,0,0]
	v_pk_fma_f32 v[252:253], v[250:251], v[248:249], v[252:253]
	v_pk_fma_f32 v[122:123], v[120:121], v[254:255], v[122:123]
	v_div_fixup_f32 v244, v252, v244, 1.0
	v_div_fixup_f32 v245, v253, v245, 1.0
	v_div_fixup_f32 v246, v122, v246, 1.0
	v_div_fixup_f32 v247, v123, v247, 1.0
	v_lshlrev_b32_e32 v154, 16, v124
	v_and_b32_e32 v155, 0xffff0000, v124
	v_lshlrev_b32_e32 v164, 16, v126
	v_and_b32_e32 v165, 0xffff0000, v126
	v_lshlrev_b32_e32 v126, 16, v127
	v_and_b32_e32 v127, 0xffff0000, v127
	v_lshlrev_b32_e32 v124, 16, v125
	v_and_b32_e32 v125, 0xffff0000, v125
	v_pk_fma_f32 v[116:117], v[116:117], v[240:241], v[154:155]
	v_pk_fma_f32 v[120:121], v[114:115], v[246:247], v[126:127]
	v_pk_fma_f32 v[114:115], v[112:113], v[242:243], v[164:165]
	v_cvt_pk_bf16_f32 v112, v116, v117
	v_pk_fma_f32 v[118:119], v[118:119], v[244:245], v[124:125]
	s_nop 0
	v_cvt_pk_bf16_f32 v113, v118, v119
	v_cvt_pk_bf16_f32 v114, v114, v115
	v_cvt_pk_bf16_f32 v115, v120, v121
	buffer_store_dwordx4 v[112:115], v147, s[24:27], 0 offen offset:256 sc1
	s_nop 1
	v_or_b32_e32 v112, 16, v162
	v_mad_i64_i32 v[114:115], s[6:7], v112, s77, 0
	v_lshl_add_u64 v[112:113], v[114:115], 1, s[38:39]
	v_lshl_add_u64 v[112:113], v[112:113], 0, v[148:149]
	v_add_co_u32_e32 v116, vcc, s78, v112
	s_nop 1
	v_addc_co_u32_e32 v117, vcc, 0, v113, vcc
	s_waitcnt vmcnt(6)
	v_mov_b32_e32 v118, v232
	v_mov_b32_e32 v119, v233
	v_mov_b32_e32 v120, v234
	v_mov_b32_e32 v121, v235
	v_mov_b32_e32 v122, v236
	v_mov_b32_e32 v123, v237
	v_mov_b32_e32 v124, v238
	v_mov_b32_e32 v125, v239
	v_add_u32_e32 v203, 0x45300, v202
	global_load_dwordx4 v[232:235], v203, s[38:39]
	v_add_u32_e32 v203, 0x44100, v202
	global_load_dwordx4 v[236:239], v203, s[38:39]
	s_mov_b32 s100, 0xbfb8aa3b
	v_lshlrev_b32_e32 v240, 16, v118
	v_and_b32_e32 v241, 0xffff0000, v118
	v_lshlrev_b32_e32 v242, 16, v120
	v_and_b32_e32 v243, 0xffff0000, v120
	v_lshlrev_b32_e32 v244, 16, v119
	v_and_b32_e32 v245, 0xffff0000, v119
	v_lshlrev_b32_e32 v246, 16, v121
	v_and_b32_e32 v247, 0xffff0000, v121
	v_pk_mul_f32 v[240:241], v[240:241], s[100:101] op_sel_hi:[1,0]
	v_pk_mul_f32 v[242:243], v[242:243], s[100:101] op_sel_hi:[1,0]
	v_pk_mul_f32 v[244:245], v[244:245], s[100:101] op_sel_hi:[1,0]
	v_pk_mul_f32 v[246:247], v[246:247], s[100:101] op_sel_hi:[1,0]
	v_exp_f32_e32 v240, v240
	v_exp_f32_e32 v241, v241
	v_exp_f32_e32 v242, v242
	v_exp_f32_e32 v243, v243
	v_exp_f32_e32 v244, v244
	v_exp_f32_e32 v245, v245
	v_exp_f32_e32 v246, v246
	v_exp_f32_e32 v247, v247
	s_nop 0
	v_pk_add_f32 v[240:241], v[240:241], 1.0 op_sel_hi:[1,0]
	v_pk_add_f32 v[242:243], v[242:243], 1.0 op_sel_hi:[1,0]
	v_pk_add_f32 v[244:245], v[244:245], 1.0 op_sel_hi:[1,0]
	v_pk_add_f32 v[246:247], v[246:247], 1.0 op_sel_hi:[1,0]
	v_rcp_f32_e32 v248, v240
	v_rcp_f32_e32 v249, v241
	v_rcp_f32_e32 v254, v242
	v_rcp_f32_e32 v255, v243
	v_pk_fma_f32 v[250:251], v[240:241], v[248:249], 1.0 op_sel_hi:[1,1,0] neg_lo:[1,0,0] neg_hi:[1,0,0]
	v_pk_fma_f32 v[118:119], v[242:243], v[254:255], 1.0 op_sel_hi:[1,1,0] neg_lo:[1,0,0] neg_hi:[1,0,0]
	v_pk_fma_f32 v[248:249], v[250:251], v[248:249], v[248:249]
	v_pk_fma_f32 v[254:255], v[118:119], v[254:255], v[254:255]
	v_pk_fma_f32 v[250:251], v[240:241], v[248:249], 1.0 op_sel_hi:[1,1,0] neg_lo:[1,0,0] neg_hi:[1,0,0]
	v_pk_fma_f32 v[118:119], v[242:243], v[254:255], 1.0 op_sel_hi:[1,1,0] neg_lo:[1,0,0] neg_hi:[1,0,0]
	v_pk_fma_f32 v[252:253], v[250:251], v[248:249], v[248:249]
	v_pk_fma_f32 v[120:121], v[118:119], v[254:255], v[254:255]
	v_pk_fma_f32 v[250:251], v[240:241], v[252:253], 1.0 op_sel_hi:[1,1,0] neg_lo:[1,0,0] neg_hi:[1,0,0]
	v_pk_fma_f32 v[118:119], v[242:243], v[120:121], 1.0 op_sel_hi:[1,1,0] neg_lo:[1,0,0] neg_hi:[1,0,0]
	v_pk_fma_f32 v[252:253], v[250:251], v[248:249], v[252:253]
	v_pk_fma_f32 v[120:121], v[118:119], v[254:255], v[120:121]
	v_div_fixup_f32 v240, v252, v240, 1.0
	v_div_fixup_f32 v241, v253, v241, 1.0
	v_div_fixup_f32 v242, v120, v242, 1.0
	v_div_fixup_f32 v243, v121, v243, 1.0
	v_rcp_f32_e32 v248, v244
	v_rcp_f32_e32 v249, v245
	v_rcp_f32_e32 v254, v246
	v_rcp_f32_e32 v255, v247
	v_pk_fma_f32 v[250:251], v[244:245], v[248:249], 1.0 op_sel_hi:[1,1,0] neg_lo:[1,0,0] neg_hi:[1,0,0]
	v_pk_fma_f32 v[118:119], v[246:247], v[254:255], 1.0 op_sel_hi:[1,1,0] neg_lo:[1,0,0] neg_hi:[1,0,0]
	v_pk_fma_f32 v[248:249], v[250:251], v[248:249], v[248:249]
	v_pk_fma_f32 v[254:255], v[118:119], v[254:255], v[254:255]
	v_pk_fma_f32 v[250:251], v[244:245], v[248:249], 1.0 op_sel_hi:[1,1,0] neg_lo:[1,0,0] neg_hi:[1,0,0]
	v_pk_fma_f32 v[118:119], v[246:247], v[254:255], 1.0 op_sel_hi:[1,1,0] neg_lo:[1,0,0] neg_hi:[1,0,0]
	v_pk_fma_f32 v[252:253], v[250:251], v[248:249], v[248:249]
	v_pk_fma_f32 v[120:121], v[118:119], v[254:255], v[254:255]
	v_pk_fma_f32 v[250:251], v[244:245], v[252:253], 1.0 op_sel_hi:[1,1,0] neg_lo:[1,0,0] neg_hi:[1,0,0]
	v_pk_fma_f32 v[118:119], v[246:247], v[120:121], 1.0 op_sel_hi:[1,1,0] neg_lo:[1,0,0] neg_hi:[1,0,0]
	v_pk_fma_f32 v[252:253], v[250:251], v[248:249], v[252:253]
	v_pk_fma_f32 v[120:121], v[118:119], v[254:255], v[120:121]
	v_div_fixup_f32 v244, v252, v244, 1.0
	v_div_fixup_f32 v245, v253, v245, 1.0
	v_div_fixup_f32 v246, v120, v246, 1.0
	v_div_fixup_f32 v247, v121, v247, 1.0
	v_and_b32_e32 v155, 0xffff0000, v124
	v_lshlrev_b32_e32 v152, 16, v122
	v_and_b32_e32 v153, 0xffff0000, v122
	v_lshlrev_b32_e32 v154, 16, v124
	v_lshlrev_b32_e32 v124, 16, v125
	v_and_b32_e32 v125, 0xffff0000, v125
	v_lshlrev_b32_e32 v122, 16, v123
	v_and_b32_e32 v123, 0xffff0000, v123
	v_pk_fma_f32 v[108:109], v[108:109], v[240:241], v[152:153]
	v_pk_fma_f32 v[118:119], v[106:107], v[246:247], v[124:125]
	v_pk_fma_f32 v[106:107], v[104:105], v[242:243], v[154:155]
	v_add_lshl_u32 v120, v146, v114, 1
	v_pk_fma_f32 v[110:111], v[110:111], v[244:245], v[122:123]
	v_cvt_pk_bf16_f32 v104, v108, v109
	s_nop 0
	v_cvt_pk_bf16_f32 v105, v110, v111
	v_cvt_pk_bf16_f32 v106, v106, v107
	v_cvt_pk_bf16_f32 v107, v118, v119
	buffer_store_dwordx4 v[104:107], v120, s[24:27], 0 offen sc1
	s_nop 0
	s_waitcnt vmcnt(7)
; __device__ __forceinline__ float sigmoidf_(float x) { return 1.0f / (1.0f + __expf(-x)); }
; __device__ __forceinline__ u32x4 pack8(const f32x4 v0, const f32x4 v1) { u32x4 w; w.x = pk2(v0[0], v0[1]); w.y = pk2(v0[2], v0[3]); w.z = pk2(v1[0], v1[1]); w.w = pk2(v1[2], v1[3]); return w; }
; __device__ __forceinline__ void unpack8(const u32x4 w, f32x4& v0, f32x4& v1) { v0 = (f32x4){bflo(w.x), bfhi(w.x), bflo(w.y), bfhi(w.y)}; v1 = (f32x4){bflo(w.z), bfhi(w.z), bflo(w.w), bfhi(w.w)}; }
;     __device__ __forceinline__ void operator()(const f32x4 (&acc)[2][2][4][2], const Unit& u, int wr, int wc, int fr, int fq) const {
;     ...
;                     const u32x4 gw = *(const u32x4*)(rowp + O_GA + bj * 128);
;                     f32x4 g0, g1; unpack8(gw, g0, g1);
;                     f32x4 v0, v1;
; #pragma unroll
;                     for (int j = 0; j < 4; ++j) { v0[j] = sigmoidf_(g0[j]) * acc[ai][bj][m][0][j]; v1[j] = sigmoidf_(g1[j]) * acc[ai][bj][m][1][j]; }
;                     const u32x4 mw = *(const u32x4*)(rowp + bj * 128); f32x4 m0, m1; unpack8(mw, m0, m1); v0 += m0; v1 += m1;
;                     __builtin_amdgcn_raw_buffer_store_b128(pack8(v0, v1), rsrc, (unsigned)(((size_t)row * DIN + col0 + bj * 128) * 2), 0, 16  ); }
	v_mov_b32_e32 v104, v204
	v_mov_b32_e32 v105, v205
	v_mov_b32_e32 v106, v206
	v_mov_b32_e32 v107, v207
	v_mov_b32_e32 v108, v208
	v_mov_b32_e32 v109, v209
	v_mov_b32_e32 v110, v210
	v_mov_b32_e32 v111, v211
	v_add_u32_e32 v203, 0x67200, v202
	global_load_dwordx4 v[204:207], v203, s[38:39]
	v_add_u32_e32 v203, 0x66000, v202
	global_load_dwordx4 v[208:211], v203, s[38:39]
	s_mov_b32 s100, 0xbfb8aa3b
	v_lshlrev_b32_e32 v240, 16, v106
	v_and_b32_e32 v241, 0xffff0000, v106
	v_lshlrev_b32_e32 v242, 16, v104
	v_and_b32_e32 v243, 0xffff0000, v104
	v_lshlrev_b32_e32 v244, 16, v105
	v_and_b32_e32 v245, 0xffff0000, v105
	v_lshlrev_b32_e32 v246, 16, v107
	v_and_b32_e32 v247, 0xffff0000, v107
	v_pk_mul_f32 v[240:241], v[240:241], s[100:101] op_sel_hi:[1,0]
	v_pk_mul_f32 v[242:243], v[242:243], s[100:101] op_sel_hi:[1,0]
	v_pk_mul_f32 v[244:245], v[244:245], s[100:101] op_sel_hi:[1,0]
	v_pk_mul_f32 v[246:247], v[246:247], s[100:101] op_sel_hi:[1,0]
	v_exp_f32_e32 v240, v240
	v_exp_f32_e32 v241, v241
	v_exp_f32_e32 v242, v242
	v_exp_f32_e32 v243, v243
	v_exp_f32_e32 v244, v244
	v_exp_f32_e32 v245, v245
	v_exp_f32_e32 v246, v246
	v_exp_f32_e32 v247, v247
	s_nop 0
	v_pk_add_f32 v[240:241], v[240:241], 1.0 op_sel_hi:[1,0]
	v_pk_add_f32 v[242:243], v[242:243], 1.0 op_sel_hi:[1,0]
	v_pk_add_f32 v[244:245], v[244:245], 1.0 op_sel_hi:[1,0]
	v_pk_add_f32 v[246:247], v[246:247], 1.0 op_sel_hi:[1,0]
	v_rcp_f32_e32 v248, v240
	v_rcp_f32_e32 v249, v241
	v_rcp_f32_e32 v254, v242
	v_rcp_f32_e32 v255, v243
	v_pk_fma_f32 v[250:251], v[240:241], v[248:249], 1.0 op_sel_hi:[1,1,0] neg_lo:[1,0,0] neg_hi:[1,0,0]
	v_pk_fma_f32 v[104:105], v[242:243], v[254:255], 1.0 op_sel_hi:[1,1,0] neg_lo:[1,0,0] neg_hi:[1,0,0]
	v_pk_fma_f32 v[248:249], v[250:251], v[248:249], v[248:249]
	v_pk_fma_f32 v[254:255], v[104:105], v[254:255], v[254:255]
	v_pk_fma_f32 v[250:251], v[240:241], v[248:249], 1.0 op_sel_hi:[1,1,0] neg_lo:[1,0,0] neg_hi:[1,0,0]
	v_pk_fma_f32 v[104:105], v[242:243], v[254:255], 1.0 op_sel_hi:[1,1,0] neg_lo:[1,0,0] neg_hi:[1,0,0]
	v_pk_fma_f32 v[252:253], v[250:251], v[248:249], v[248:249]
	v_pk_fma_f32 v[106:107], v[104:105], v[254:255], v[254:255]
	v_pk_fma_f32 v[250:251], v[240:241], v[252:253], 1.0 op_sel_hi:[1,1,0] neg_lo:[1,0,0] neg_hi:[1,0,0]
	v_pk_fma_f32 v[104:105], v[242:243], v[106:107], 1.0 op_sel_hi:[1,1,0] neg_lo:[1,0,0] neg_hi:[1,0,0]
	v_pk_fma_f32 v[252:253], v[250:251], v[248:249], v[252:253]
	v_pk_fma_f32 v[106:107], v[104:105], v[254:255], v[106:107]
	v_div_fixup_f32 v240, v252, v240, 1.0
	v_div_fixup_f32 v241, v253, v241, 1.0
	v_div_fixup_f32 v242, v106, v242, 1.0
	v_div_fixup_f32 v243, v107, v243, 1.0
	v_rcp_f32_e32 v248, v244
	v_rcp_f32_e32 v249, v245
	v_rcp_f32_e32 v254, v246
	v_rcp_f32_e32 v255, v247
	v_pk_fma_f32 v[250:251], v[244:245], v[248:249], 1.0 op_sel_hi:[1,1,0] neg_lo:[1,0,0] neg_hi:[1,0,0]
	v_pk_fma_f32 v[104:105], v[246:247], v[254:255], 1.0 op_sel_hi:[1,1,0] neg_lo:[1,0,0] neg_hi:[1,0,0]
	v_pk_fma_f32 v[248:249], v[250:251], v[248:249], v[248:249]
	v_pk_fma_f32 v[254:255], v[104:105], v[254:255], v[254:255]
	v_pk_fma_f32 v[250:251], v[244:245], v[248:249], 1.0 op_sel_hi:[1,1,0] neg_lo:[1,0,0] neg_hi:[1,0,0]
	v_pk_fma_f32 v[104:105], v[246:247], v[254:255], 1.0 op_sel_hi:[1,1,0] neg_lo:[1,0,0] neg_hi:[1,0,0]
	v_pk_fma_f32 v[252:253], v[250:251], v[248:249], v[248:249]
	v_pk_fma_f32 v[106:107], v[104:105], v[254:255], v[254:255]
	v_pk_fma_f32 v[250:251], v[244:245], v[252:253], 1.0 op_sel_hi:[1,1,0] neg_lo:[1,0,0] neg_hi:[1,0,0]
	v_pk_fma_f32 v[104:105], v[246:247], v[106:107], 1.0 op_sel_hi:[1,1,0] neg_lo:[1,0,0] neg_hi:[1,0,0]
	v_pk_fma_f32 v[252:253], v[250:251], v[248:249], v[252:253]
	v_pk_fma_f32 v[106:107], v[104:105], v[254:255], v[106:107]
	v_div_fixup_f32 v244, v252, v244, 1.0
	v_div_fixup_f32 v245, v253, v245, 1.0
	v_div_fixup_f32 v246, v106, v246, 1.0
	v_div_fixup_f32 v247, v107, v247, 1.0
	v_lshlrev_b32_e32 v116, 16, v108
	v_and_b32_e32 v117, 0xffff0000, v108
	v_lshlrev_b32_e32 v118, 16, v110
	v_and_b32_e32 v119, 0xffff0000, v110
	v_lshlrev_b32_e32 v110, 16, v111
	v_and_b32_e32 v111, 0xffff0000, v111
	v_lshlrev_b32_e32 v108, 16, v109
	v_and_b32_e32 v109, 0xffff0000, v109
	v_pk_fma_f32 v[100:101], v[100:101], v[242:243], v[116:117]
	v_pk_fma_f32 v[104:105], v[98:99], v[246:247], v[110:111]
	v_pk_fma_f32 v[98:99], v[96:97], v[240:241], v[118:119]
	v_cvt_pk_bf16_f32 v96, v100, v101
	v_pk_fma_f32 v[102:103], v[102:103], v[244:245], v[108:109]
	s_nop 0
	v_cvt_pk_bf16_f32 v97, v102, v103
	v_cvt_pk_bf16_f32 v98, v98, v99
	v_cvt_pk_bf16_f32 v99, v104, v105
	buffer_store_dwordx4 v[96:99], v120, s[24:27], 0 offen offset:256 sc1
	s_nop 1
	v_or_b32_e32 v96, 32, v162
	v_mad_i64_i32 v[98:99], s[6:7], v96, s77, 0
	v_lshl_add_u64 v[96:97], v[98:99], 1, s[38:39]
	v_lshl_add_u64 v[96:97], v[96:97], 0, v[148:149]
	v_add_co_u32_e32 v100, vcc, s78, v96
	s_nop 1
	v_addc_co_u32_e32 v101, vcc, 0, v97, vcc
	s_waitcnt vmcnt(7)
; __device__ __forceinline__ float sigmoidf_(float x) { return 1.0f / (1.0f + __expf(-x)); }
; __device__ __forceinline__ u32x4 pack8(const f32x4 v0, const f32x4 v1) { u32x4 w; w.x = pk2(v0[0], v0[1]); w.y = pk2(v0[2], v0[3]); w.z = pk2(v1[0], v1[1]); w.w = pk2(v1[2], v1[3]); return w; }
; __device__ __forceinline__ void unpack8(const u32x4 w, f32x4& v0, f32x4& v1) { v0 = (f32x4){bflo(w.x), bfhi(w.x), bflo(w.y), bfhi(w.y)}; v1 = (f32x4){bflo(w.z), bfhi(w.z), bflo(w.w), bfhi(w.w)}; }
;     __device__ __forceinline__ void operator()(const f32x4 (&acc)[2][2][4][2], const Unit& u, int wr, int wc, int fr, int fq) const {
;     ...
;                     const u32x4 gw = *(const u32x4*)(rowp + O_GA + bj * 128);
;                     f32x4 g0, g1; unpack8(gw, g0, g1);
;                     f32x4 v0, v1;
; #pragma unroll
;                     for (int j = 0; j < 4; ++j) { v0[j] = sigmoidf_(g0[j]) * acc[ai][bj][m][0][j]; v1[j] = sigmoidf_(g1[j]) * acc[ai][bj][m][1][j]; }
;                     const u32x4 mw = *(const u32x4*)(rowp + bj * 128); f32x4 m0, m1; unpack8(mw, m0, m1); v0 += m0; v1 += m1;
;                     __builtin_amdgcn_raw_buffer_store_b128(pack8(v0, v1), rsrc, (unsigned)(((size_t)row * DIN + col0 + bj * 128) * 2), 0, 16  ); }
	v_mov_b32_e32 v102, v212
	v_mov_b32_e32 v103, v213
	v_mov_b32_e32 v104, v214
	v_mov_b32_e32 v105, v215
	v_mov_b32_e32 v106, v216
	v_mov_b32_e32 v107, v217
	v_mov_b32_e32 v108, v218
	v_mov_b32_e32 v109, v219
	v_add_u32_e32 v203, 0x67300, v202
	global_load_dwordx4 v[212:215], v203, s[38:39]
	v_add_u32_e32 v203, 0x66100, v202
	global_load_dwordx4 v[216:219], v203, s[38:39]
	s_mov_b32 s100, 0xbfb8aa3b
	v_lshlrev_b32_e32 v240, 16, v102
	v_and_b32_e32 v241, 0xffff0000, v102
	v_lshlrev_b32_e32 v242, 16, v104
	v_and_b32_e32 v243, 0xffff0000, v104
	v_lshlrev_b32_e32 v244, 16, v103
	v_and_b32_e32 v245, 0xffff0000, v103
	v_lshlrev_b32_e32 v246, 16, v105
	v_and_b32_e32 v247, 0xffff0000, v105
	v_pk_mul_f32 v[240:241], v[240:241], s[100:101] op_sel_hi:[1,0]
	v_pk_mul_f32 v[242:243], v[242:243], s[100:101] op_sel_hi:[1,0]
	v_pk_mul_f32 v[244:245], v[244:245], s[100:101] op_sel_hi:[1,0]
	v_pk_mul_f32 v[246:247], v[246:247], s[100:101] op_sel_hi:[1,0]
	v_exp_f32_e32 v240, v240
	v_exp_f32_e32 v241, v241
	v_exp_f32_e32 v242, v242
	v_exp_f32_e32 v243, v243
	v_exp_f32_e32 v244, v244
	v_exp_f32_e32 v245, v245
	v_exp_f32_e32 v246, v246
	v_exp_f32_e32 v247, v247
	s_nop 0
	v_pk_add_f32 v[240:241], v[240:241], 1.0 op_sel_hi:[1,0]
	v_pk_add_f32 v[242:243], v[242:243], 1.0 op_sel_hi:[1,0]
	v_pk_add_f32 v[244:245], v[244:245], 1.0 op_sel_hi:[1,0]
	v_pk_add_f32 v[246:247], v[246:247], 1.0 op_sel_hi:[1,0]
	v_rcp_f32_e32 v248, v240
	v_rcp_f32_e32 v249, v241
	v_rcp_f32_e32 v254, v242
	v_rcp_f32_e32 v255, v243
	v_pk_fma_f32 v[250:251], v[240:241], v[248:249], 1.0 op_sel_hi:[1,1,0] neg_lo:[1,0,0] neg_hi:[1,0,0]
	v_pk_fma_f32 v[102:103], v[242:243], v[254:255], 1.0 op_sel_hi:[1,1,0] neg_lo:[1,0,0] neg_hi:[1,0,0]
	v_pk_fma_f32 v[248:249], v[250:251], v[248:249], v[248:249]
	v_pk_fma_f32 v[254:255], v[102:103], v[254:255], v[254:255]
	v_pk_fma_f32 v[250:251], v[240:241], v[248:249], 1.0 op_sel_hi:[1,1,0] neg_lo:[1,0,0] neg_hi:[1,0,0]
	v_pk_fma_f32 v[102:103], v[242:243], v[254:255], 1.0 op_sel_hi:[1,1,0] neg_lo:[1,0,0] neg_hi:[1,0,0]
	v_pk_fma_f32 v[252:253], v[250:251], v[248:249], v[248:249]
	v_pk_fma_f32 v[104:105], v[102:103], v[254:255], v[254:255]
	v_pk_fma_f32 v[250:251], v[240:241], v[252:253], 1.0 op_sel_hi:[1,1,0] neg_lo:[1,0,0] neg_hi:[1,0,0]
	v_pk_fma_f32 v[102:103], v[242:243], v[104:105], 1.0 op_sel_hi:[1,1,0] neg_lo:[1,0,0] neg_hi:[1,0,0]
	v_pk_fma_f32 v[252:253], v[250:251], v[248:249], v[252:253]
	v_pk_fma_f32 v[104:105], v[102:103], v[254:255], v[104:105]
	v_div_fixup_f32 v240, v252, v240, 1.0
	v_div_fixup_f32 v241, v253, v241, 1.0
	v_div_fixup_f32 v242, v104, v242, 1.0
	v_div_fixup_f32 v243, v105, v243, 1.0
	v_rcp_f32_e32 v248, v244
	v_rcp_f32_e32 v249, v245
	v_rcp_f32_e32 v254, v246
	v_rcp_f32_e32 v255, v247
	v_pk_fma_f32 v[250:251], v[244:245], v[248:249], 1.0 op_sel_hi:[1,1,0] neg_lo:[1,0,0] neg_hi:[1,0,0]
	v_pk_fma_f32 v[102:103], v[246:247], v[254:255], 1.0 op_sel_hi:[1,1,0] neg_lo:[1,0,0] neg_hi:[1,0,0]
	v_pk_fma_f32 v[248:249], v[250:251], v[248:249], v[248:249]
	v_pk_fma_f32 v[254:255], v[102:103], v[254:255], v[254:255]
	v_pk_fma_f32 v[250:251], v[244:245], v[248:249], 1.0 op_sel_hi:[1,1,0] neg_lo:[1,0,0] neg_hi:[1,0,0]
	v_pk_fma_f32 v[102:103], v[246:247], v[254:255], 1.0 op_sel_hi:[1,1,0] neg_lo:[1,0,0] neg_hi:[1,0,0]
	v_pk_fma_f32 v[252:253], v[250:251], v[248:249], v[248:249]
	v_pk_fma_f32 v[104:105], v[102:103], v[254:255], v[254:255]
	v_pk_fma_f32 v[250:251], v[244:245], v[252:253], 1.0 op_sel_hi:[1,1,0] neg_lo:[1,0,0] neg_hi:[1,0,0]
	v_pk_fma_f32 v[102:103], v[246:247], v[104:105], 1.0 op_sel_hi:[1,1,0] neg_lo:[1,0,0] neg_hi:[1,0,0]
	v_pk_fma_f32 v[252:253], v[250:251], v[248:249], v[252:253]
	v_pk_fma_f32 v[104:105], v[102:103], v[254:255], v[104:105]
	v_div_fixup_f32 v244, v252, v244, 1.0
	v_div_fixup_f32 v245, v253, v245, 1.0
	v_div_fixup_f32 v246, v104, v246, 1.0
	v_div_fixup_f32 v247, v105, v247, 1.0
	v_lshlrev_b32_e32 v114, 16, v106
	v_and_b32_e32 v115, 0xffff0000, v106
	v_lshlrev_b32_e32 v116, 16, v108
	v_and_b32_e32 v117, 0xffff0000, v108
	v_lshlrev_b32_e32 v108, 16, v109
	v_and_b32_e32 v109, 0xffff0000, v109
	v_lshlrev_b32_e32 v106, 16, v107
	v_and_b32_e32 v107, 0xffff0000, v107
	v_pk_fma_f32 v[92:93], v[92:93], v[240:241], v[114:115]
	v_pk_fma_f32 v[102:103], v[90:91], v[246:247], v[108:109]
	v_pk_fma_f32 v[90:91], v[88:89], v[242:243], v[116:117]
	v_add_lshl_u32 v104, v146, v98, 1
	v_pk_fma_f32 v[94:95], v[94:95], v[244:245], v[106:107]
	v_cvt_pk_bf16_f32 v88, v92, v93
	s_nop 0
	v_cvt_pk_bf16_f32 v89, v94, v95
	v_cvt_pk_bf16_f32 v90, v90, v91
	v_cvt_pk_bf16_f32 v91, v102, v103
	buffer_store_dwordx4 v[88:91], v104, s[24:27], 0 offen sc1
	s_nop 0
	s_waitcnt vmcnt(7)
; __device__ __forceinline__ float sigmoidf_(float x) { return 1.0f / (1.0f + __expf(-x)); }
; __device__ __forceinline__ u32x4 pack8(const f32x4 v0, const f32x4 v1) { u32x4 w; w.x = pk2(v0[0], v0[1]); w.y = pk2(v0[2], v0[3]); w.z = pk2(v1[0], v1[1]); w.w = pk2(v1[2], v1[3]); return w; }
; __device__ __forceinline__ void unpack8(const u32x4 w, f32x4& v0, f32x4& v1) { v0 = (f32x4){bflo(w.x), bfhi(w.x), bflo(w.y), bfhi(w.y)}; v1 = (f32x4){bflo(w.z), bfhi(w.z), bflo(w.w), bfhi(w.w)}; }
;     __device__ __forceinline__ void operator()(const f32x4 (&acc)[2][2][4][2], const Unit& u, int wr, int wc, int fr, int fq) const {
;     ...
;                     const u32x4 gw = *(const u32x4*)(rowp + O_GA + bj * 128);
;                     f32x4 g0, g1; unpack8(gw, g0, g1);
;                     f32x4 v0, v1;
; #pragma unroll
;                     for (int j = 0; j < 4; ++j) { v0[j] = sigmoidf_(g0[j]) * acc[ai][bj][m][0][j]; v1[j] = sigmoidf_(g1[j]) * acc[ai][bj][m][1][j]; }
;                     const u32x4 mw = *(const u32x4*)(rowp + bj * 128); f32x4 m0, m1; unpack8(mw, m0, m1); v0 += m0; v1 += m1;
;                     __builtin_amdgcn_raw_buffer_store_b128(pack8(v0, v1), rsrc, (unsigned)(((size_t)row * DIN + col0 + bj * 128) * 2), 0, 16  ); }
	v_mov_b32_e32 v88, v232
	v_mov_b32_e32 v89, v233
	v_mov_b32_e32 v90, v234
	v_mov_b32_e32 v91, v235
	v_mov_b32_e32 v92, v236
	v_mov_b32_e32 v93, v237
	v_mov_b32_e32 v94, v238
	v_mov_b32_e32 v95, v239
	v_add_u32_e32 v203, 0x111200, v202
	global_load_dwordx4 v[232:235], v203, s[38:39]
	v_add_u32_e32 v203, 0x110000, v202
	global_load_dwordx4 v[236:239], v203, s[38:39]
	s_mov_b32 s100, 0xbfb8aa3b
	v_lshlrev_b32_e32 v240, 16, v90
	v_and_b32_e32 v241, 0xffff0000, v90
	v_lshlrev_b32_e32 v242, 16, v88
	v_and_b32_e32 v243, 0xffff0000, v88
	v_lshlrev_b32_e32 v244, 16, v89
	v_and_b32_e32 v245, 0xffff0000, v89
	v_lshlrev_b32_e32 v246, 16, v91
	v_and_b32_e32 v247, 0xffff0000, v91
	v_pk_mul_f32 v[240:241], v[240:241], s[100:101] op_sel_hi:[1,0]
	v_pk_mul_f32 v[242:243], v[242:243], s[100:101] op_sel_hi:[1,0]
	v_pk_mul_f32 v[244:245], v[244:245], s[100:101] op_sel_hi:[1,0]
	v_pk_mul_f32 v[246:247], v[246:247], s[100:101] op_sel_hi:[1,0]
	v_exp_f32_e32 v240, v240
	v_exp_f32_e32 v241, v241
	v_exp_f32_e32 v242, v242
	v_exp_f32_e32 v243, v243
	v_exp_f32_e32 v244, v244
	v_exp_f32_e32 v245, v245
	v_exp_f32_e32 v246, v246
	v_exp_f32_e32 v247, v247
	s_nop 0
	v_pk_add_f32 v[240:241], v[240:241], 1.0 op_sel_hi:[1,0]
	v_pk_add_f32 v[242:243], v[242:243], 1.0 op_sel_hi:[1,0]
	v_pk_add_f32 v[244:245], v[244:245], 1.0 op_sel_hi:[1,0]
	v_pk_add_f32 v[246:247], v[246:247], 1.0 op_sel_hi:[1,0]
	v_rcp_f32_e32 v248, v240
	v_rcp_f32_e32 v249, v241
	v_rcp_f32_e32 v254, v242
	v_rcp_f32_e32 v255, v243
	v_pk_fma_f32 v[250:251], v[240:241], v[248:249], 1.0 op_sel_hi:[1,1,0] neg_lo:[1,0,0] neg_hi:[1,0,0]
	v_pk_fma_f32 v[88:89], v[242:243], v[254:255], 1.0 op_sel_hi:[1,1,0] neg_lo:[1,0,0] neg_hi:[1,0,0]
	v_pk_fma_f32 v[248:249], v[250:251], v[248:249], v[248:249]
	v_pk_fma_f32 v[254:255], v[88:89], v[254:255], v[254:255]
	v_pk_fma_f32 v[250:251], v[240:241], v[248:249], 1.0 op_sel_hi:[1,1,0] neg_lo:[1,0,0] neg_hi:[1,0,0]
	v_pk_fma_f32 v[88:89], v[242:243], v[254:255], 1.0 op_sel_hi:[1,1,0] neg_lo:[1,0,0] neg_hi:[1,0,0]
	v_pk_fma_f32 v[252:253], v[250:251], v[248:249], v[248:249]
	v_pk_fma_f32 v[90:91], v[88:89], v[254:255], v[254:255]
	v_pk_fma_f32 v[250:251], v[240:241], v[252:253], 1.0 op_sel_hi:[1,1,0] neg_lo:[1,0,0] neg_hi:[1,0,0]
	v_pk_fma_f32 v[88:89], v[242:243], v[90:91], 1.0 op_sel_hi:[1,1,0] neg_lo:[1,0,0] neg_hi:[1,0,0]
	v_pk_fma_f32 v[252:253], v[250:251], v[248:249], v[252:253]
	v_pk_fma_f32 v[90:91], v[88:89], v[254:255], v[90:91]
	v_div_fixup_f32 v240, v252, v240, 1.0
	v_div_fixup_f32 v241, v253, v241, 1.0
	v_div_fixup_f32 v242, v90, v242, 1.0
	v_div_fixup_f32 v243, v91, v243, 1.0
	v_rcp_f32_e32 v248, v244
	v_rcp_f32_e32 v249, v245
	v_rcp_f32_e32 v254, v246
	v_rcp_f32_e32 v255, v247
	v_pk_fma_f32 v[250:251], v[244:245], v[248:249], 1.0 op_sel_hi:[1,1,0] neg_lo:[1,0,0] neg_hi:[1,0,0]
	v_pk_fma_f32 v[88:89], v[246:247], v[254:255], 1.0 op_sel_hi:[1,1,0] neg_lo:[1,0,0] neg_hi:[1,0,0]
	v_pk_fma_f32 v[248:249], v[250:251], v[248:249], v[248:249]
	v_pk_fma_f32 v[254:255], v[88:89], v[254:255], v[254:255]
	v_pk_fma_f32 v[250:251], v[244:245], v[248:249], 1.0 op_sel_hi:[1,1,0] neg_lo:[1,0,0] neg_hi:[1,0,0]
	v_pk_fma_f32 v[88:89], v[246:247], v[254:255], 1.0 op_sel_hi:[1,1,0] neg_lo:[1,0,0] neg_hi:[1,0,0]
	v_pk_fma_f32 v[252:253], v[250:251], v[248:249], v[248:249]
	v_pk_fma_f32 v[90:91], v[88:89], v[254:255], v[254:255]
	v_pk_fma_f32 v[250:251], v[244:245], v[252:253], 1.0 op_sel_hi:[1,1,0] neg_lo:[1,0,0] neg_hi:[1,0,0]
	v_pk_fma_f32 v[88:89], v[246:247], v[90:91], 1.0 op_sel_hi:[1,1,0] neg_lo:[1,0,0] neg_hi:[1,0,0]
	v_pk_fma_f32 v[252:253], v[250:251], v[248:249], v[252:253]
	v_pk_fma_f32 v[90:91], v[88:89], v[254:255], v[90:91]
	v_div_fixup_f32 v244, v252, v244, 1.0
	v_div_fixup_f32 v245, v253, v245, 1.0
	v_div_fixup_f32 v246, v90, v246, 1.0
	v_div_fixup_f32 v247, v91, v247, 1.0
	v_lshlrev_b32_e32 v100, 16, v92
	v_and_b32_e32 v101, 0xffff0000, v92
	v_lshlrev_b32_e32 v102, 16, v94
	v_and_b32_e32 v103, 0xffff0000, v94
	v_lshlrev_b32_e32 v94, 16, v95
	v_and_b32_e32 v95, 0xffff0000, v95
	v_lshlrev_b32_e32 v92, 16, v93
	v_and_b32_e32 v93, 0xffff0000, v93
	v_pk_fma_f32 v[84:85], v[84:85], v[242:243], v[100:101]
	v_pk_fma_f32 v[88:89], v[82:83], v[246:247], v[94:95]
	v_pk_fma_f32 v[82:83], v[80:81], v[240:241], v[102:103]
	v_cvt_pk_bf16_f32 v80, v84, v85
	v_pk_fma_f32 v[86:87], v[86:87], v[244:245], v[92:93]
	s_nop 0
	v_cvt_pk_bf16_f32 v81, v86, v87
	v_cvt_pk_bf16_f32 v82, v82, v83
	v_cvt_pk_bf16_f32 v83, v88, v89
	buffer_store_dwordx4 v[80:83], v104, s[24:27], 0 offen offset:256 sc1
	s_nop 1
	v_or_b32_e32 v80, 48, v162
	v_mad_i64_i32 v[82:83], s[6:7], v80, s77, 0
	v_lshl_add_u64 v[80:81], v[82:83], 1, s[38:39]
	v_lshl_add_u64 v[80:81], v[80:81], 0, v[148:149]
	v_add_co_u32_e32 v84, vcc, s78, v80
	s_nop 1
	v_addc_co_u32_e32 v85, vcc, 0, v81, vcc
	s_waitcnt vmcnt(7)
; __device__ __forceinline__ float sigmoidf_(float x) { return 1.0f / (1.0f + __expf(-x)); }
; __device__ __forceinline__ u32x4 pack8(const f32x4 v0, const f32x4 v1) { u32x4 w; w.x = pk2(v0[0], v0[1]); w.y = pk2(v0[2], v0[3]); w.z = pk2(v1[0], v1[1]); w.w = pk2(v1[2], v1[3]); return w; }
; __device__ __forceinline__ void unpack8(const u32x4 w, f32x4& v0, f32x4& v1) { v0 = (f32x4){bflo(w.x), bfhi(w.x), bflo(w.y), bfhi(w.y)}; v1 = (f32x4){bflo(w.z), bfhi(w.z), bflo(w.w), bfhi(w.w)}; }
;     __device__ __forceinline__ void operator()(const f32x4 (&acc)[2][2][4][2], const Unit& u, int wr, int wc, int fr, int fq) const {
;     ...
;                     const u32x4 gw = *(const u32x4*)(rowp + O_GA + bj * 128);
;                     f32x4 g0, g1; unpack8(gw, g0, g1);
;                     f32x4 v0, v1;
; #pragma unroll
;                     for (int j = 0; j < 4; ++j) { v0[j] = sigmoidf_(g0[j]) * acc[ai][bj][m][0][j]; v1[j] = sigmoidf_(g1[j]) * acc[ai][bj][m][1][j]; }
;                     const u32x4 mw = *(const u32x4*)(rowp + bj * 128); f32x4 m0, m1; unpack8(mw, m0, m1); v0 += m0; v1 += m1;
;                     __builtin_amdgcn_raw_buffer_store_b128(pack8(v0, v1), rsrc, (unsigned)(((size_t)row * DIN + col0 + bj * 128) * 2), 0, 16  ); }
	v_mov_b32_e32 v86, v204
	v_mov_b32_e32 v87, v205
	v_mov_b32_e32 v88, v206
	v_mov_b32_e32 v89, v207
	v_mov_b32_e32 v90, v208
	v_mov_b32_e32 v91, v209
	v_mov_b32_e32 v92, v210
	v_mov_b32_e32 v93, v211
	v_add_u32_e32 v203, 0x111300, v202
	global_load_dwordx4 v[204:207], v203, s[38:39]
	v_add_u32_e32 v203, 0x110100, v202
	global_load_dwordx4 v[208:211], v203, s[38:39]
	s_mov_b32 s100, 0xbfb8aa3b
	v_lshlrev_b32_e32 v240, 16, v86
	v_and_b32_e32 v241, 0xffff0000, v86
	v_lshlrev_b32_e32 v242, 16, v88
	v_and_b32_e32 v243, 0xffff0000, v88
	v_lshlrev_b32_e32 v244, 16, v87
	v_and_b32_e32 v245, 0xffff0000, v87
	v_lshlrev_b32_e32 v246, 16, v89
	v_and_b32_e32 v247, 0xffff0000, v89
	v_pk_mul_f32 v[240:241], v[240:241], s[100:101] op_sel_hi:[1,0]
	v_pk_mul_f32 v[242:243], v[242:243], s[100:101] op_sel_hi:[1,0]
	v_pk_mul_f32 v[244:245], v[244:245], s[100:101] op_sel_hi:[1,0]
	v_pk_mul_f32 v[246:247], v[246:247], s[100:101] op_sel_hi:[1,0]
	v_exp_f32_e32 v240, v240
	v_exp_f32_e32 v241, v241
	v_exp_f32_e32 v242, v242
	v_exp_f32_e32 v243, v243
	v_exp_f32_e32 v244, v244
	v_exp_f32_e32 v245, v245
	v_exp_f32_e32 v246, v246
	v_exp_f32_e32 v247, v247
	s_nop 0
	v_pk_add_f32 v[240:241], v[240:241], 1.0 op_sel_hi:[1,0]
	v_pk_add_f32 v[242:243], v[242:243], 1.0 op_sel_hi:[1,0]
	v_pk_add_f32 v[244:245], v[244:245], 1.0 op_sel_hi:[1,0]
	v_pk_add_f32 v[246:247], v[246:247], 1.0 op_sel_hi:[1,0]
	v_rcp_f32_e32 v248, v240
	v_rcp_f32_e32 v249, v241
	v_rcp_f32_e32 v254, v242
	v_rcp_f32_e32 v255, v243
	v_pk_fma_f32 v[250:251], v[240:241], v[248:249], 1.0 op_sel_hi:[1,1,0] neg_lo:[1,0,0] neg_hi:[1,0,0]
	v_pk_fma_f32 v[86:87], v[242:243], v[254:255], 1.0 op_sel_hi:[1,1,0] neg_lo:[1,0,0] neg_hi:[1,0,0]
	v_pk_fma_f32 v[248:249], v[250:251], v[248:249], v[248:249]
	v_pk_fma_f32 v[254:255], v[86:87], v[254:255], v[254:255]
	v_pk_fma_f32 v[250:251], v[240:241], v[248:249], 1.0 op_sel_hi:[1,1,0] neg_lo:[1,0,0] neg_hi:[1,0,0]
	v_pk_fma_f32 v[86:87], v[242:243], v[254:255], 1.0 op_sel_hi:[1,1,0] neg_lo:[1,0,0] neg_hi:[1,0,0]
	v_pk_fma_f32 v[252:253], v[250:251], v[248:249], v[248:249]
	v_pk_fma_f32 v[88:89], v[86:87], v[254:255], v[254:255]
	v_pk_fma_f32 v[250:251], v[240:241], v[252:253], 1.0 op_sel_hi:[1,1,0] neg_lo:[1,0,0] neg_hi:[1,0,0]
	v_pk_fma_f32 v[86:87], v[242:243], v[88:89], 1.0 op_sel_hi:[1,1,0] neg_lo:[1,0,0] neg_hi:[1,0,0]
	v_pk_fma_f32 v[252:253], v[250:251], v[248:249], v[252:253]
	v_pk_fma_f32 v[88:89], v[86:87], v[254:255], v[88:89]
	v_div_fixup_f32 v240, v252, v240, 1.0
	v_div_fixup_f32 v241, v253, v241, 1.0
	v_div_fixup_f32 v242, v88, v242, 1.0
	v_div_fixup_f32 v243, v89, v243, 1.0
	v_rcp_f32_e32 v248, v244
	v_rcp_f32_e32 v249, v245
	v_rcp_f32_e32 v254, v246
	v_rcp_f32_e32 v255, v247
	v_pk_fma_f32 v[250:251], v[244:245], v[248:249], 1.0 op_sel_hi:[1,1,0] neg_lo:[1,0,0] neg_hi:[1,0,0]
	v_pk_fma_f32 v[86:87], v[246:247], v[254:255], 1.0 op_sel_hi:[1,1,0] neg_lo:[1,0,0] neg_hi:[1,0,0]
	v_pk_fma_f32 v[248:249], v[250:251], v[248:249], v[248:249]
	v_pk_fma_f32 v[254:255], v[86:87], v[254:255], v[254:255]
	v_pk_fma_f32 v[250:251], v[244:245], v[248:249], 1.0 op_sel_hi:[1,1,0] neg_lo:[1,0,0] neg_hi:[1,0,0]
	v_pk_fma_f32 v[86:87], v[246:247], v[254:255], 1.0 op_sel_hi:[1,1,0] neg_lo:[1,0,0] neg_hi:[1,0,0]
	v_pk_fma_f32 v[252:253], v[250:251], v[248:249], v[248:249]
	v_pk_fma_f32 v[88:89], v[86:87], v[254:255], v[254:255]
	v_pk_fma_f32 v[250:251], v[244:245], v[252:253], 1.0 op_sel_hi:[1,1,0] neg_lo:[1,0,0] neg_hi:[1,0,0]
	v_pk_fma_f32 v[86:87], v[246:247], v[88:89], 1.0 op_sel_hi:[1,1,0] neg_lo:[1,0,0] neg_hi:[1,0,0]
	v_pk_fma_f32 v[252:253], v[250:251], v[248:249], v[252:253]
	v_pk_fma_f32 v[88:89], v[86:87], v[254:255], v[88:89]
	v_div_fixup_f32 v244, v252, v244, 1.0
	v_div_fixup_f32 v245, v253, v245, 1.0
	v_div_fixup_f32 v246, v88, v246, 1.0
	v_div_fixup_f32 v247, v89, v247, 1.0
	v_lshlrev_b32_e32 v98, 16, v90
	v_and_b32_e32 v99, 0xffff0000, v90
	v_lshlrev_b32_e32 v100, 16, v92
	v_and_b32_e32 v101, 0xffff0000, v92
	v_lshlrev_b32_e32 v92, 16, v93
	v_and_b32_e32 v93, 0xffff0000, v93
	v_lshlrev_b32_e32 v90, 16, v91
	v_and_b32_e32 v91, 0xffff0000, v91
	v_pk_fma_f32 v[76:77], v[76:77], v[240:241], v[98:99]
	v_pk_fma_f32 v[86:87], v[74:75], v[246:247], v[92:93]
	v_pk_fma_f32 v[74:75], v[72:73], v[242:243], v[100:101]
	v_add_lshl_u32 v88, v146, v82, 1
	v_pk_fma_f32 v[78:79], v[78:79], v[244:245], v[90:91]
	v_cvt_pk_bf16_f32 v72, v76, v77
	s_nop 0
	v_cvt_pk_bf16_f32 v73, v78, v79
	v_cvt_pk_bf16_f32 v74, v74, v75
	v_cvt_pk_bf16_f32 v75, v86, v87
	buffer_store_dwordx4 v[72:75], v88, s[24:27], 0 offen sc1
	s_nop 0
	s_waitcnt vmcnt(7)
; __device__ __forceinline__ float sigmoidf_(float x) { return 1.0f / (1.0f + __expf(-x)); }
; __device__ __forceinline__ u32x4 pack8(const f32x4 v0, const f32x4 v1) { u32x4 w; w.x = pk2(v0[0], v0[1]); w.y = pk2(v0[2], v0[3]); w.z = pk2(v1[0], v1[1]); w.w = pk2(v1[2], v1[3]); return w; }
; __device__ __forceinline__ void unpack8(const u32x4 w, f32x4& v0, f32x4& v1) { v0 = (f32x4){bflo(w.x), bfhi(w.x), bflo(w.y), bfhi(w.y)}; v1 = (f32x4){bflo(w.z), bfhi(w.z), bflo(w.w), bfhi(w.w)}; }
;     __device__ __forceinline__ void operator()(const f32x4 (&acc)[2][2][4][2], const Unit& u, int wr, int wc, int fr, int fq) const {
;     ...
;                     const u32x4 gw = *(const u32x4*)(rowp + O_GA + bj * 128);
;                     f32x4 g0, g1; unpack8(gw, g0, g1);
;                     f32x4 v0, v1;
; #pragma unroll
;                     for (int j = 0; j < 4; ++j) { v0[j] = sigmoidf_(g0[j]) * acc[ai][bj][m][0][j]; v1[j] = sigmoidf_(g1[j]) * acc[ai][bj][m][1][j]; }
;                     const u32x4 mw = *(const u32x4*)(rowp + bj * 128); f32x4 m0, m1; unpack8(mw, m0, m1); v0 += m0; v1 += m1;
;                     __builtin_amdgcn_raw_buffer_store_b128(pack8(v0, v1), rsrc, (unsigned)(((size_t)row * DIN + col0 + bj * 128) * 2), 0, 16  ); }
	v_mov_b32_e32 v72, v212
	v_mov_b32_e32 v73, v213
	v_mov_b32_e32 v74, v214
	v_mov_b32_e32 v75, v215
	v_mov_b32_e32 v76, v216
	v_mov_b32_e32 v77, v217
	v_mov_b32_e32 v78, v218
	v_mov_b32_e32 v79, v219
	v_add_u32_e32 v203, 0x133200, v202
	global_load_dwordx4 v[212:215], v203, s[38:39]
	v_add_u32_e32 v203, 0x132000, v202
	global_load_dwordx4 v[216:219], v203, s[38:39]
	s_mov_b32 s100, 0xbfb8aa3b
	v_lshlrev_b32_e32 v240, 16, v74
	v_and_b32_e32 v241, 0xffff0000, v74
	v_lshlrev_b32_e32 v242, 16, v72
	v_and_b32_e32 v243, 0xffff0000, v72
	v_lshlrev_b32_e32 v244, 16, v73
	v_and_b32_e32 v245, 0xffff0000, v73
	v_lshlrev_b32_e32 v246, 16, v75
	v_and_b32_e32 v247, 0xffff0000, v75
	v_pk_mul_f32 v[240:241], v[240:241], s[100:101] op_sel_hi:[1,0]
	v_pk_mul_f32 v[242:243], v[242:243], s[100:101] op_sel_hi:[1,0]
	v_pk_mul_f32 v[244:245], v[244:245], s[100:101] op_sel_hi:[1,0]
	v_pk_mul_f32 v[246:247], v[246:247], s[100:101] op_sel_hi:[1,0]
	v_exp_f32_e32 v240, v240
	v_exp_f32_e32 v241, v241
	v_exp_f32_e32 v242, v242
	v_exp_f32_e32 v243, v243
	v_exp_f32_e32 v244, v244
	v_exp_f32_e32 v245, v245
	v_exp_f32_e32 v246, v246
	v_exp_f32_e32 v247, v247
	s_nop 0
	v_pk_add_f32 v[240:241], v[240:241], 1.0 op_sel_hi:[1,0]
	v_pk_add_f32 v[242:243], v[242:243], 1.0 op_sel_hi:[1,0]
	v_pk_add_f32 v[244:245], v[244:245], 1.0 op_sel_hi:[1,0]
	v_pk_add_f32 v[246:247], v[246:247], 1.0 op_sel_hi:[1,0]
	v_rcp_f32_e32 v248, v240
	v_rcp_f32_e32 v249, v241
	v_rcp_f32_e32 v254, v242
	v_rcp_f32_e32 v255, v243
	v_pk_fma_f32 v[250:251], v[240:241], v[248:249], 1.0 op_sel_hi:[1,1,0] neg_lo:[1,0,0] neg_hi:[1,0,0]
	v_pk_fma_f32 v[72:73], v[242:243], v[254:255], 1.0 op_sel_hi:[1,1,0] neg_lo:[1,0,0] neg_hi:[1,0,0]
	v_pk_fma_f32 v[248:249], v[250:251], v[248:249], v[248:249]
	v_pk_fma_f32 v[254:255], v[72:73], v[254:255], v[254:255]
	v_pk_fma_f32 v[250:251], v[240:241], v[248:249], 1.0 op_sel_hi:[1,1,0] neg_lo:[1,0,0] neg_hi:[1,0,0]
	v_pk_fma_f32 v[72:73], v[242:243], v[254:255], 1.0 op_sel_hi:[1,1,0] neg_lo:[1,0,0] neg_hi:[1,0,0]
	v_pk_fma_f32 v[252:253], v[250:251], v[248:249], v[248:249]
	v_pk_fma_f32 v[74:75], v[72:73], v[254:255], v[254:255]
	v_pk_fma_f32 v[250:251], v[240:241], v[252:253], 1.0 op_sel_hi:[1,1,0] neg_lo:[1,0,0] neg_hi:[1,0,0]
	v_pk_fma_f32 v[72:73], v[242:243], v[74:75], 1.0 op_sel_hi:[1,1,0] neg_lo:[1,0,0] neg_hi:[1,0,0]
	v_pk_fma_f32 v[252:253], v[250:251], v[248:249], v[252:253]
	v_pk_fma_f32 v[74:75], v[72:73], v[254:255], v[74:75]
	v_div_fixup_f32 v240, v252, v240, 1.0
	v_div_fixup_f32 v241, v253, v241, 1.0
	v_div_fixup_f32 v242, v74, v242, 1.0
	v_div_fixup_f32 v243, v75, v243, 1.0
	v_rcp_f32_e32 v248, v244
	v_rcp_f32_e32 v249, v245
	v_rcp_f32_e32 v254, v246
	v_rcp_f32_e32 v255, v247
	v_pk_fma_f32 v[250:251], v[244:245], v[248:249], 1.0 op_sel_hi:[1,1,0] neg_lo:[1,0,0] neg_hi:[1,0,0]
	v_pk_fma_f32 v[72:73], v[246:247], v[254:255], 1.0 op_sel_hi:[1,1,0] neg_lo:[1,0,0] neg_hi:[1,0,0]
	v_pk_fma_f32 v[248:249], v[250:251], v[248:249], v[248:249]
	v_pk_fma_f32 v[254:255], v[72:73], v[254:255], v[254:255]
	v_pk_fma_f32 v[250:251], v[244:245], v[248:249], 1.0 op_sel_hi:[1,1,0] neg_lo:[1,0,0] neg_hi:[1,0,0]
	v_pk_fma_f32 v[72:73], v[246:247], v[254:255], 1.0 op_sel_hi:[1,1,0] neg_lo:[1,0,0] neg_hi:[1,0,0]
	v_pk_fma_f32 v[252:253], v[250:251], v[248:249], v[248:249]
	v_pk_fma_f32 v[74:75], v[72:73], v[254:255], v[254:255]
	v_pk_fma_f32 v[250:251], v[244:245], v[252:253], 1.0 op_sel_hi:[1,1,0] neg_lo:[1,0,0] neg_hi:[1,0,0]
	v_pk_fma_f32 v[72:73], v[246:247], v[74:75], 1.0 op_sel_hi:[1,1,0] neg_lo:[1,0,0] neg_hi:[1,0,0]
	v_pk_fma_f32 v[252:253], v[250:251], v[248:249], v[252:253]
	v_pk_fma_f32 v[74:75], v[72:73], v[254:255], v[74:75]
	v_div_fixup_f32 v244, v252, v244, 1.0
	v_div_fixup_f32 v245, v253, v245, 1.0
	v_div_fixup_f32 v246, v74, v246, 1.0
	v_div_fixup_f32 v247, v75, v247, 1.0
	v_lshlrev_b32_e32 v84, 16, v76
	v_and_b32_e32 v85, 0xffff0000, v76
	v_lshlrev_b32_e32 v86, 16, v78
	v_and_b32_e32 v87, 0xffff0000, v78
	v_lshlrev_b32_e32 v78, 16, v79
	v_and_b32_e32 v79, 0xffff0000, v79
	v_lshlrev_b32_e32 v76, 16, v77
	v_and_b32_e32 v77, 0xffff0000, v77
	v_pk_fma_f32 v[68:69], v[68:69], v[242:243], v[84:85]
	v_pk_fma_f32 v[72:73], v[66:67], v[246:247], v[78:79]
	v_pk_fma_f32 v[66:67], v[64:65], v[240:241], v[86:87]
	v_cvt_pk_bf16_f32 v64, v68, v69
	v_pk_fma_f32 v[70:71], v[70:71], v[244:245], v[76:77]
	s_nop 0
	v_cvt_pk_bf16_f32 v65, v70, v71
	v_cvt_pk_bf16_f32 v66, v66, v67
	v_cvt_pk_bf16_f32 v67, v72, v73
	buffer_store_dwordx4 v[64:67], v88, s[24:27], 0 offen offset:256 sc1
	s_nop 1
	v_add_u32_e32 v64, 0x80, v162
	v_mad_i64_i32 v[66:67], s[6:7], v64, s77, 0
	v_lshl_add_u64 v[64:65], v[66:67], 1, s[38:39]
	v_lshl_add_u64 v[64:65], v[64:65], 0, v[148:149]
	v_add_co_u32_e32 v68, vcc, s78, v64
	s_nop 1
	v_addc_co_u32_e32 v69, vcc, 0, v65, vcc
	s_waitcnt vmcnt(7)
; __device__ __forceinline__ float sigmoidf_(float x) { return 1.0f / (1.0f + __expf(-x)); }
; __device__ __forceinline__ u32x4 pack8(const f32x4 v0, const f32x4 v1) { u32x4 w; w.x = pk2(v0[0], v0[1]); w.y = pk2(v0[2], v0[3]); w.z = pk2(v1[0], v1[1]); w.w = pk2(v1[2], v1[3]); return w; }
; __device__ __forceinline__ void unpack8(const u32x4 w, f32x4& v0, f32x4& v1) { v0 = (f32x4){bflo(w.x), bfhi(w.x), bflo(w.y), bfhi(w.y)}; v1 = (f32x4){bflo(w.z), bfhi(w.z), bflo(w.w), bfhi(w.w)}; }
;     __device__ __forceinline__ void operator()(const f32x4 (&acc)[2][2][4][2], const Unit& u, int wr, int wc, int fr, int fq) const {
;     ...
;                     const u32x4 gw = *(const u32x4*)(rowp + O_GA + bj * 128);
;                     f32x4 g0, g1; unpack8(gw, g0, g1);
;                     f32x4 v0, v1;
; #pragma unroll
;                     for (int j = 0; j < 4; ++j) { v0[j] = sigmoidf_(g0[j]) * acc[ai][bj][m][0][j]; v1[j] = sigmoidf_(g1[j]) * acc[ai][bj][m][1][j]; }
;                     const u32x4 mw = *(const u32x4*)(rowp + bj * 128); f32x4 m0, m1; unpack8(mw, m0, m1); v0 += m0; v1 += m1;
;                     __builtin_amdgcn_raw_buffer_store_b128(pack8(v0, v1), rsrc, (unsigned)(((size_t)row * DIN + col0 + bj * 128) * 2), 0, 16  ); }
	v_mov_b32_e32 v70, v232
	v_mov_b32_e32 v71, v233
	v_mov_b32_e32 v72, v234
	v_mov_b32_e32 v73, v235
	v_mov_b32_e32 v74, v236
	v_mov_b32_e32 v75, v237
	v_mov_b32_e32 v76, v238
	v_mov_b32_e32 v77, v239
	v_add_u32_e32 v203, 0x133300, v202
	global_load_dwordx4 v[232:235], v203, s[38:39]
	v_add_u32_e32 v203, 0x132100, v202
	global_load_dwordx4 v[236:239], v203, s[38:39]
	s_mov_b32 s100, 0xbfb8aa3b
	v_lshlrev_b32_e32 v240, 16, v70
	v_and_b32_e32 v241, 0xffff0000, v70
	v_lshlrev_b32_e32 v242, 16, v72
	v_and_b32_e32 v243, 0xffff0000, v72
	v_lshlrev_b32_e32 v244, 16, v71
	v_and_b32_e32 v245, 0xffff0000, v71
	v_lshlrev_b32_e32 v246, 16, v73
	v_and_b32_e32 v247, 0xffff0000, v73
	v_pk_mul_f32 v[240:241], v[240:241], s[100:101] op_sel_hi:[1,0]
	v_pk_mul_f32 v[242:243], v[242:243], s[100:101] op_sel_hi:[1,0]
	v_pk_mul_f32 v[244:245], v[244:245], s[100:101] op_sel_hi:[1,0]
	v_pk_mul_f32 v[246:247], v[246:247], s[100:101] op_sel_hi:[1,0]
	v_exp_f32_e32 v240, v240
	v_exp_f32_e32 v241, v241
	v_exp_f32_e32 v242, v242
	v_exp_f32_e32 v243, v243
	v_exp_f32_e32 v244, v244
	v_exp_f32_e32 v245, v245
	v_exp_f32_e32 v246, v246
	v_exp_f32_e32 v247, v247
	s_nop 0
	v_pk_add_f32 v[240:241], v[240:241], 1.0 op_sel_hi:[1,0]
	v_pk_add_f32 v[242:243], v[242:243], 1.0 op_sel_hi:[1,0]
	v_pk_add_f32 v[244:245], v[244:245], 1.0 op_sel_hi:[1,0]
	v_pk_add_f32 v[246:247], v[246:247], 1.0 op_sel_hi:[1,0]
	v_rcp_f32_e32 v248, v240
	v_rcp_f32_e32 v249, v241
	v_rcp_f32_e32 v254, v242
	v_rcp_f32_e32 v255, v243
	v_pk_fma_f32 v[250:251], v[240:241], v[248:249], 1.0 op_sel_hi:[1,1,0] neg_lo:[1,0,0] neg_hi:[1,0,0]
	v_pk_fma_f32 v[70:71], v[242:243], v[254:255], 1.0 op_sel_hi:[1,1,0] neg_lo:[1,0,0] neg_hi:[1,0,0]
	v_pk_fma_f32 v[248:249], v[250:251], v[248:249], v[248:249]
	v_pk_fma_f32 v[254:255], v[70:71], v[254:255], v[254:255]
	v_pk_fma_f32 v[250:251], v[240:241], v[248:249], 1.0 op_sel_hi:[1,1,0] neg_lo:[1,0,0] neg_hi:[1,0,0]
	v_pk_fma_f32 v[70:71], v[242:243], v[254:255], 1.0 op_sel_hi:[1,1,0] neg_lo:[1,0,0] neg_hi:[1,0,0]
	v_pk_fma_f32 v[252:253], v[250:251], v[248:249], v[248:249]
	v_pk_fma_f32 v[72:73], v[70:71], v[254:255], v[254:255]
	v_pk_fma_f32 v[250:251], v[240:241], v[252:253], 1.0 op_sel_hi:[1,1,0] neg_lo:[1,0,0] neg_hi:[1,0,0]
	v_pk_fma_f32 v[70:71], v[242:243], v[72:73], 1.0 op_sel_hi:[1,1,0] neg_lo:[1,0,0] neg_hi:[1,0,0]
	v_pk_fma_f32 v[252:253], v[250:251], v[248:249], v[252:253]
	v_pk_fma_f32 v[72:73], v[70:71], v[254:255], v[72:73]
	v_div_fixup_f32 v240, v252, v240, 1.0
	v_div_fixup_f32 v241, v253, v241, 1.0
	v_div_fixup_f32 v242, v72, v242, 1.0
	v_div_fixup_f32 v243, v73, v243, 1.0
	v_rcp_f32_e32 v248, v244
	v_rcp_f32_e32 v249, v245
	v_rcp_f32_e32 v254, v246
	v_rcp_f32_e32 v255, v247
	v_pk_fma_f32 v[250:251], v[244:245], v[248:249], 1.0 op_sel_hi:[1,1,0] neg_lo:[1,0,0] neg_hi:[1,0,0]
	v_pk_fma_f32 v[70:71], v[246:247], v[254:255], 1.0 op_sel_hi:[1,1,0] neg_lo:[1,0,0] neg_hi:[1,0,0]
	v_pk_fma_f32 v[248:249], v[250:251], v[248:249], v[248:249]
	v_pk_fma_f32 v[254:255], v[70:71], v[254:255], v[254:255]
	v_pk_fma_f32 v[250:251], v[244:245], v[248:249], 1.0 op_sel_hi:[1,1,0] neg_lo:[1,0,0] neg_hi:[1,0,0]
	v_pk_fma_f32 v[70:71], v[246:247], v[254:255], 1.0 op_sel_hi:[1,1,0] neg_lo:[1,0,0] neg_hi:[1,0,0]
	v_pk_fma_f32 v[252:253], v[250:251], v[248:249], v[248:249]
	v_pk_fma_f32 v[72:73], v[70:71], v[254:255], v[254:255]
	v_pk_fma_f32 v[250:251], v[244:245], v[252:253], 1.0 op_sel_hi:[1,1,0] neg_lo:[1,0,0] neg_hi:[1,0,0]
	v_pk_fma_f32 v[70:71], v[246:247], v[72:73], 1.0 op_sel_hi:[1,1,0] neg_lo:[1,0,0] neg_hi:[1,0,0]
	v_pk_fma_f32 v[252:253], v[250:251], v[248:249], v[252:253]
	v_pk_fma_f32 v[72:73], v[70:71], v[254:255], v[72:73]
	v_div_fixup_f32 v244, v252, v244, 1.0
	v_div_fixup_f32 v245, v253, v245, 1.0
	v_div_fixup_f32 v246, v72, v246, 1.0
	v_div_fixup_f32 v247, v73, v247, 1.0
	v_lshlrev_b32_e32 v82, 16, v74
	v_and_b32_e32 v83, 0xffff0000, v74
	v_lshlrev_b32_e32 v84, 16, v76
	v_and_b32_e32 v85, 0xffff0000, v76
	v_lshlrev_b32_e32 v76, 16, v77
	v_and_b32_e32 v77, 0xffff0000, v77
	v_lshlrev_b32_e32 v74, 16, v75
	v_and_b32_e32 v75, 0xffff0000, v75
	v_pk_fma_f32 v[60:61], v[60:61], v[240:241], v[82:83]
	v_pk_fma_f32 v[70:71], v[58:59], v[246:247], v[76:77]
	v_pk_fma_f32 v[58:59], v[56:57], v[242:243], v[84:85]
	v_add_lshl_u32 v72, v146, v66, 1
	v_pk_fma_f32 v[62:63], v[62:63], v[244:245], v[74:75]
	v_cvt_pk_bf16_f32 v56, v60, v61
	s_nop 0
	v_cvt_pk_bf16_f32 v57, v62, v63
	v_cvt_pk_bf16_f32 v58, v58, v59
	v_cvt_pk_bf16_f32 v59, v70, v71
	buffer_store_dwordx4 v[56:59], v72, s[24:27], 0 offen sc1
	s_nop 0
	s_waitcnt vmcnt(7)
; __device__ __forceinline__ float sigmoidf_(float x) { return 1.0f / (1.0f + __expf(-x)); }
; __device__ __forceinline__ u32x4 pack8(const f32x4 v0, const f32x4 v1) { u32x4 w; w.x = pk2(v0[0], v0[1]); w.y = pk2(v0[2], v0[3]); w.z = pk2(v1[0], v1[1]); w.w = pk2(v1[2], v1[3]); return w; }
; __device__ __forceinline__ void unpack8(const u32x4 w, f32x4& v0, f32x4& v1) { v0 = (f32x4){bflo(w.x), bfhi(w.x), bflo(w.y), bfhi(w.y)}; v1 = (f32x4){bflo(w.z), bfhi(w.z), bflo(w.w), bfhi(w.w)}; }
;     __device__ __forceinline__ void operator()(const f32x4 (&acc)[2][2][4][2], const Unit& u, int wr, int wc, int fr, int fq) const {
;     ...
;                     const u32x4 gw = *(const u32x4*)(rowp + O_GA + bj * 128);
;                     f32x4 g0, g1; unpack8(gw, g0, g1);
;                     f32x4 v0, v1;
; #pragma unroll
;                     for (int j = 0; j < 4; ++j) { v0[j] = sigmoidf_(g0[j]) * acc[ai][bj][m][0][j]; v1[j] = sigmoidf_(g1[j]) * acc[ai][bj][m][1][j]; }
;                     const u32x4 mw = *(const u32x4*)(rowp + bj * 128); f32x4 m0, m1; unpack8(mw, m0, m1); v0 += m0; v1 += m1;
;                     __builtin_amdgcn_raw_buffer_store_b128(pack8(v0, v1), rsrc, (unsigned)(((size_t)row * DIN + col0 + bj * 128) * 2), 0, 16  ); }
	v_mov_b32_e32 v56, v204
	v_mov_b32_e32 v57, v205
	v_mov_b32_e32 v58, v206
	v_mov_b32_e32 v59, v207
	v_mov_b32_e32 v60, v208
	v_mov_b32_e32 v61, v209
	v_mov_b32_e32 v62, v210
	v_mov_b32_e32 v63, v211
	v_add_u32_e32 v203, 0x155200, v202
	global_load_dwordx4 v[204:207], v203, s[38:39]
	v_add_u32_e32 v203, 0x154000, v202
	global_load_dwordx4 v[208:211], v203, s[38:39]
	s_mov_b32 s100, 0xbfb8aa3b
	v_lshlrev_b32_e32 v240, 16, v58
	v_and_b32_e32 v241, 0xffff0000, v58
	v_lshlrev_b32_e32 v242, 16, v56
	v_and_b32_e32 v243, 0xffff0000, v56
	v_lshlrev_b32_e32 v244, 16, v57
	v_and_b32_e32 v245, 0xffff0000, v57
	v_lshlrev_b32_e32 v246, 16, v59
	v_and_b32_e32 v247, 0xffff0000, v59
	v_pk_mul_f32 v[240:241], v[240:241], s[100:101] op_sel_hi:[1,0]
	v_pk_mul_f32 v[242:243], v[242:243], s[100:101] op_sel_hi:[1,0]
	v_pk_mul_f32 v[244:245], v[244:245], s[100:101] op_sel_hi:[1,0]
	v_pk_mul_f32 v[246:247], v[246:247], s[100:101] op_sel_hi:[1,0]
	v_exp_f32_e32 v240, v240
	v_exp_f32_e32 v241, v241
	v_exp_f32_e32 v242, v242
	v_exp_f32_e32 v243, v243
	v_exp_f32_e32 v244, v244
	v_exp_f32_e32 v245, v245
	v_exp_f32_e32 v246, v246
	v_exp_f32_e32 v247, v247
	s_nop 0
	v_pk_add_f32 v[240:241], v[240:241], 1.0 op_sel_hi:[1,0]
	v_pk_add_f32 v[242:243], v[242:243], 1.0 op_sel_hi:[1,0]
	v_pk_add_f32 v[244:245], v[244:245], 1.0 op_sel_hi:[1,0]
	v_pk_add_f32 v[246:247], v[246:247], 1.0 op_sel_hi:[1,0]
	v_rcp_f32_e32 v248, v240
	v_rcp_f32_e32 v249, v241
	v_rcp_f32_e32 v254, v242
	v_rcp_f32_e32 v255, v243
	v_pk_fma_f32 v[250:251], v[240:241], v[248:249], 1.0 op_sel_hi:[1,1,0] neg_lo:[1,0,0] neg_hi:[1,0,0]
	v_pk_fma_f32 v[56:57], v[242:243], v[254:255], 1.0 op_sel_hi:[1,1,0] neg_lo:[1,0,0] neg_hi:[1,0,0]
	v_pk_fma_f32 v[248:249], v[250:251], v[248:249], v[248:249]
	v_pk_fma_f32 v[254:255], v[56:57], v[254:255], v[254:255]
	v_pk_fma_f32 v[250:251], v[240:241], v[248:249], 1.0 op_sel_hi:[1,1,0] neg_lo:[1,0,0] neg_hi:[1,0,0]
	v_pk_fma_f32 v[56:57], v[242:243], v[254:255], 1.0 op_sel_hi:[1,1,0] neg_lo:[1,0,0] neg_hi:[1,0,0]
	v_pk_fma_f32 v[252:253], v[250:251], v[248:249], v[248:249]
	v_pk_fma_f32 v[58:59], v[56:57], v[254:255], v[254:255]
	v_pk_fma_f32 v[250:251], v[240:241], v[252:253], 1.0 op_sel_hi:[1,1,0] neg_lo:[1,0,0] neg_hi:[1,0,0]
	v_pk_fma_f32 v[56:57], v[242:243], v[58:59], 1.0 op_sel_hi:[1,1,0] neg_lo:[1,0,0] neg_hi:[1,0,0]
	v_pk_fma_f32 v[252:253], v[250:251], v[248:249], v[252:253]
	v_pk_fma_f32 v[58:59], v[56:57], v[254:255], v[58:59]
	v_div_fixup_f32 v240, v252, v240, 1.0
	v_div_fixup_f32 v241, v253, v241, 1.0
	v_div_fixup_f32 v242, v58, v242, 1.0
	v_div_fixup_f32 v243, v59, v243, 1.0
	v_rcp_f32_e32 v248, v244
	v_rcp_f32_e32 v249, v245
	v_rcp_f32_e32 v254, v246
	v_rcp_f32_e32 v255, v247
	v_pk_fma_f32 v[250:251], v[244:245], v[248:249], 1.0 op_sel_hi:[1,1,0] neg_lo:[1,0,0] neg_hi:[1,0,0]
	v_pk_fma_f32 v[56:57], v[246:247], v[254:255], 1.0 op_sel_hi:[1,1,0] neg_lo:[1,0,0] neg_hi:[1,0,0]
	v_pk_fma_f32 v[248:249], v[250:251], v[248:249], v[248:249]
	v_pk_fma_f32 v[254:255], v[56:57], v[254:255], v[254:255]
	v_pk_fma_f32 v[250:251], v[244:245], v[248:249], 1.0 op_sel_hi:[1,1,0] neg_lo:[1,0,0] neg_hi:[1,0,0]
	v_pk_fma_f32 v[56:57], v[246:247], v[254:255], 1.0 op_sel_hi:[1,1,0] neg_lo:[1,0,0] neg_hi:[1,0,0]
	v_pk_fma_f32 v[252:253], v[250:251], v[248:249], v[248:249]
	v_pk_fma_f32 v[58:59], v[56:57], v[254:255], v[254:255]
	v_pk_fma_f32 v[250:251], v[244:245], v[252:253], 1.0 op_sel_hi:[1,1,0] neg_lo:[1,0,0] neg_hi:[1,0,0]
	v_pk_fma_f32 v[56:57], v[246:247], v[58:59], 1.0 op_sel_hi:[1,1,0] neg_lo:[1,0,0] neg_hi:[1,0,0]
	v_pk_fma_f32 v[252:253], v[250:251], v[248:249], v[252:253]
	v_pk_fma_f32 v[58:59], v[56:57], v[254:255], v[58:59]
	v_div_fixup_f32 v244, v252, v244, 1.0
	v_div_fixup_f32 v245, v253, v245, 1.0
	v_div_fixup_f32 v246, v58, v246, 1.0
	v_div_fixup_f32 v247, v59, v247, 1.0
	v_lshlrev_b32_e32 v68, 16, v60
	v_and_b32_e32 v69, 0xffff0000, v60
	v_lshlrev_b32_e32 v70, 16, v62
	v_and_b32_e32 v71, 0xffff0000, v62
	v_lshlrev_b32_e32 v62, 16, v63
	v_and_b32_e32 v63, 0xffff0000, v63
	v_lshlrev_b32_e32 v60, 16, v61
	v_and_b32_e32 v61, 0xffff0000, v61
	v_pk_fma_f32 v[52:53], v[52:53], v[242:243], v[68:69]
	v_pk_fma_f32 v[56:57], v[50:51], v[246:247], v[62:63]
	v_pk_fma_f32 v[50:51], v[48:49], v[240:241], v[70:71]
	v_cvt_pk_bf16_f32 v48, v52, v53
	v_pk_fma_f32 v[54:55], v[54:55], v[244:245], v[60:61]
	s_nop 0
	v_cvt_pk_bf16_f32 v49, v54, v55
	v_cvt_pk_bf16_f32 v50, v50, v51
	v_cvt_pk_bf16_f32 v51, v56, v57
	buffer_store_dwordx4 v[48:51], v72, s[24:27], 0 offen offset:256 sc1
	s_nop 1
	v_add_u32_e32 v48, 0x90, v162
	v_mad_i64_i32 v[50:51], s[6:7], v48, s77, 0
	v_lshl_add_u64 v[48:49], v[50:51], 1, s[38:39]
	v_lshl_add_u64 v[48:49], v[48:49], 0, v[148:149]
	v_add_co_u32_e32 v52, vcc, s78, v48
	s_nop 1
	v_addc_co_u32_e32 v53, vcc, 0, v49, vcc
	s_waitcnt vmcnt(7)
; __device__ __forceinline__ float sigmoidf_(float x) { return 1.0f / (1.0f + __expf(-x)); }
; __device__ __forceinline__ u32x4 pack8(const f32x4 v0, const f32x4 v1) { u32x4 w; w.x = pk2(v0[0], v0[1]); w.y = pk2(v0[2], v0[3]); w.z = pk2(v1[0], v1[1]); w.w = pk2(v1[2], v1[3]); return w; }
; __device__ __forceinline__ void unpack8(const u32x4 w, f32x4& v0, f32x4& v1) { v0 = (f32x4){bflo(w.x), bfhi(w.x), bflo(w.y), bfhi(w.y)}; v1 = (f32x4){bflo(w.z), bfhi(w.z), bflo(w.w), bfhi(w.w)}; }
;     __device__ __forceinline__ void operator()(const f32x4 (&acc)[2][2][4][2], const Unit& u, int wr, int wc, int fr, int fq) const {
;     ...
;                     const u32x4 gw = *(const u32x4*)(rowp + O_GA + bj * 128);
;                     f32x4 g0, g1; unpack8(gw, g0, g1);
;                     f32x4 v0, v1;
; #pragma unroll
;                     for (int j = 0; j < 4; ++j) { v0[j] = sigmoidf_(g0[j]) * acc[ai][bj][m][0][j]; v1[j] = sigmoidf_(g1[j]) * acc[ai][bj][m][1][j]; }
;                     const u32x4 mw = *(const u32x4*)(rowp + bj * 128); f32x4 m0, m1; unpack8(mw, m0, m1); v0 += m0; v1 += m1;
;                     __builtin_amdgcn_raw_buffer_store_b128(pack8(v0, v1), rsrc, (unsigned)(((size_t)row * DIN + col0 + bj * 128) * 2), 0, 16  ); }
	v_mov_b32_e32 v54, v212
	v_mov_b32_e32 v55, v213
	v_mov_b32_e32 v56, v214
	v_mov_b32_e32 v57, v215
	v_mov_b32_e32 v58, v216
	v_mov_b32_e32 v59, v217
	v_mov_b32_e32 v60, v218
	v_mov_b32_e32 v61, v219
	v_add_u32_e32 v203, 0x155300, v202
	global_load_dwordx4 v[212:215], v203, s[38:39]
	v_add_u32_e32 v203, 0x154100, v202
	global_load_dwordx4 v[216:219], v203, s[38:39]
	s_mov_b32 s100, 0xbfb8aa3b
	v_lshlrev_b32_e32 v240, 16, v54
	v_and_b32_e32 v241, 0xffff0000, v54
	v_lshlrev_b32_e32 v242, 16, v56
	v_and_b32_e32 v243, 0xffff0000, v56
	v_lshlrev_b32_e32 v244, 16, v55
	v_and_b32_e32 v245, 0xffff0000, v55
	v_lshlrev_b32_e32 v246, 16, v57
	v_and_b32_e32 v247, 0xffff0000, v57
	v_pk_mul_f32 v[240:241], v[240:241], s[100:101] op_sel_hi:[1,0]
	v_pk_mul_f32 v[242:243], v[242:243], s[100:101] op_sel_hi:[1,0]
	v_pk_mul_f32 v[244:245], v[244:245], s[100:101] op_sel_hi:[1,0]
	v_pk_mul_f32 v[246:247], v[246:247], s[100:101] op_sel_hi:[1,0]
	v_exp_f32_e32 v240, v240
	v_exp_f32_e32 v241, v241
	v_exp_f32_e32 v242, v242
	v_exp_f32_e32 v243, v243
	v_exp_f32_e32 v244, v244
	v_exp_f32_e32 v245, v245
	v_exp_f32_e32 v246, v246
	v_exp_f32_e32 v247, v247
	s_nop 0
	v_pk_add_f32 v[240:241], v[240:241], 1.0 op_sel_hi:[1,0]
	v_pk_add_f32 v[242:243], v[242:243], 1.0 op_sel_hi:[1,0]
	v_pk_add_f32 v[244:245], v[244:245], 1.0 op_sel_hi:[1,0]
	v_pk_add_f32 v[246:247], v[246:247], 1.0 op_sel_hi:[1,0]
	v_rcp_f32_e32 v248, v240
	v_rcp_f32_e32 v249, v241
	v_rcp_f32_e32 v254, v242
	v_rcp_f32_e32 v255, v243
	v_pk_fma_f32 v[250:251], v[240:241], v[248:249], 1.0 op_sel_hi:[1,1,0] neg_lo:[1,0,0] neg_hi:[1,0,0]
	v_pk_fma_f32 v[54:55], v[242:243], v[254:255], 1.0 op_sel_hi:[1,1,0] neg_lo:[1,0,0] neg_hi:[1,0,0]
	v_pk_fma_f32 v[248:249], v[250:251], v[248:249], v[248:249]
	v_pk_fma_f32 v[254:255], v[54:55], v[254:255], v[254:255]
	v_pk_fma_f32 v[250:251], v[240:241], v[248:249], 1.0 op_sel_hi:[1,1,0] neg_lo:[1,0,0] neg_hi:[1,0,0]
	v_pk_fma_f32 v[54:55], v[242:243], v[254:255], 1.0 op_sel_hi:[1,1,0] neg_lo:[1,0,0] neg_hi:[1,0,0]
	v_pk_fma_f32 v[252:253], v[250:251], v[248:249], v[248:249]
	v_pk_fma_f32 v[56:57], v[54:55], v[254:255], v[254:255]
	v_pk_fma_f32 v[250:251], v[240:241], v[252:253], 1.0 op_sel_hi:[1,1,0] neg_lo:[1,0,0] neg_hi:[1,0,0]
	v_pk_fma_f32 v[54:55], v[242:243], v[56:57], 1.0 op_sel_hi:[1,1,0] neg_lo:[1,0,0] neg_hi:[1,0,0]
	v_pk_fma_f32 v[252:253], v[250:251], v[248:249], v[252:253]
	v_pk_fma_f32 v[56:57], v[54:55], v[254:255], v[56:57]
	v_div_fixup_f32 v240, v252, v240, 1.0
	v_div_fixup_f32 v241, v253, v241, 1.0
	v_div_fixup_f32 v242, v56, v242, 1.0
	v_div_fixup_f32 v243, v57, v243, 1.0
	v_rcp_f32_e32 v248, v244
	v_rcp_f32_e32 v249, v245
	v_rcp_f32_e32 v254, v246
	v_rcp_f32_e32 v255, v247
	v_pk_fma_f32 v[250:251], v[244:245], v[248:249], 1.0 op_sel_hi:[1,1,0] neg_lo:[1,0,0] neg_hi:[1,0,0]
	v_pk_fma_f32 v[54:55], v[246:247], v[254:255], 1.0 op_sel_hi:[1,1,0] neg_lo:[1,0,0] neg_hi:[1,0,0]
	v_pk_fma_f32 v[248:249], v[250:251], v[248:249], v[248:249]
	v_pk_fma_f32 v[254:255], v[54:55], v[254:255], v[254:255]
	v_pk_fma_f32 v[250:251], v[244:245], v[248:249], 1.0 op_sel_hi:[1,1,0] neg_lo:[1,0,0] neg_hi:[1,0,0]
	v_pk_fma_f32 v[54:55], v[246:247], v[254:255], 1.0 op_sel_hi:[1,1,0] neg_lo:[1,0,0] neg_hi:[1,0,0]
	v_pk_fma_f32 v[252:253], v[250:251], v[248:249], v[248:249]
	v_pk_fma_f32 v[56:57], v[54:55], v[254:255], v[254:255]
	v_pk_fma_f32 v[250:251], v[244:245], v[252:253], 1.0 op_sel_hi:[1,1,0] neg_lo:[1,0,0] neg_hi:[1,0,0]
	v_pk_fma_f32 v[54:55], v[246:247], v[56:57], 1.0 op_sel_hi:[1,1,0] neg_lo:[1,0,0] neg_hi:[1,0,0]
	v_pk_fma_f32 v[252:253], v[250:251], v[248:249], v[252:253]
	v_pk_fma_f32 v[56:57], v[54:55], v[254:255], v[56:57]
	v_div_fixup_f32 v244, v252, v244, 1.0
	v_div_fixup_f32 v245, v253, v245, 1.0
	v_div_fixup_f32 v246, v56, v246, 1.0
	v_div_fixup_f32 v247, v57, v247, 1.0
	v_lshlrev_b32_e32 v66, 16, v58
	v_and_b32_e32 v67, 0xffff0000, v58
	v_lshlrev_b32_e32 v68, 16, v60
	v_and_b32_e32 v69, 0xffff0000, v60
	v_lshlrev_b32_e32 v60, 16, v61
	v_and_b32_e32 v61, 0xffff0000, v61
	v_lshlrev_b32_e32 v58, 16, v59
	v_and_b32_e32 v59, 0xffff0000, v59
	v_pk_fma_f32 v[44:45], v[44:45], v[240:241], v[66:67]
	v_pk_fma_f32 v[54:55], v[42:43], v[246:247], v[60:61]
	v_pk_fma_f32 v[42:43], v[40:41], v[242:243], v[68:69]
	v_add_lshl_u32 v56, v146, v50, 1
	v_pk_fma_f32 v[46:47], v[46:47], v[244:245], v[58:59]
	v_cvt_pk_bf16_f32 v40, v44, v45
	s_nop 0
	v_cvt_pk_bf16_f32 v41, v46, v47
	v_cvt_pk_bf16_f32 v42, v42, v43
	v_cvt_pk_bf16_f32 v43, v54, v55
	buffer_store_dwordx4 v[40:43], v56, s[24:27], 0 offen sc1
	s_nop 0
	s_waitcnt vmcnt(7)
; __device__ __forceinline__ float sigmoidf_(float x) { return 1.0f / (1.0f + __expf(-x)); }
; __device__ __forceinline__ u32x4 pack8(const f32x4 v0, const f32x4 v1) { u32x4 w; w.x = pk2(v0[0], v0[1]); w.y = pk2(v0[2], v0[3]); w.z = pk2(v1[0], v1[1]); w.w = pk2(v1[2], v1[3]); return w; }
; __device__ __forceinline__ void unpack8(const u32x4 w, f32x4& v0, f32x4& v1) { v0 = (f32x4){bflo(w.x), bfhi(w.x), bflo(w.y), bfhi(w.y)}; v1 = (f32x4){bflo(w.z), bfhi(w.z), bflo(w.w), bfhi(w.w)}; }
;     __device__ __forceinline__ void operator()(const f32x4 (&acc)[2][2][4][2], const Unit& u, int wr, int wc, int fr, int fq) const {
;     ...
;                     const u32x4 gw = *(const u32x4*)(rowp + O_GA + bj * 128);
;                     f32x4 g0, g1; unpack8(gw, g0, g1);
;                     f32x4 v0, v1;
; #pragma unroll
;                     for (int j = 0; j < 4; ++j) { v0[j] = sigmoidf_(g0[j]) * acc[ai][bj][m][0][j]; v1[j] = sigmoidf_(g1[j]) * acc[ai][bj][m][1][j]; }
;                     const u32x4 mw = *(const u32x4*)(rowp + bj * 128); f32x4 m0, m1; unpack8(mw, m0, m1); v0 += m0; v1 += m1;
;                     __builtin_amdgcn_raw_buffer_store_b128(pack8(v0, v1), rsrc, (unsigned)(((size_t)row * DIN + col0 + bj * 128) * 2), 0, 16  ); }
	v_mov_b32_e32 v40, v232
	v_mov_b32_e32 v41, v233
	v_mov_b32_e32 v42, v234
	v_mov_b32_e32 v43, v235
	v_mov_b32_e32 v44, v236
	v_mov_b32_e32 v45, v237
	v_mov_b32_e32 v46, v238
	v_mov_b32_e32 v47, v239
	v_add_u32_e32 v203, 0x177200, v202
	global_load_dwordx4 v[232:235], v203, s[38:39]
	v_add_u32_e32 v203, 0x176000, v202
	global_load_dwordx4 v[236:239], v203, s[38:39]
	s_mov_b32 s100, 0xbfb8aa3b
	v_lshlrev_b32_e32 v240, 16, v42
	v_and_b32_e32 v241, 0xffff0000, v42
	v_lshlrev_b32_e32 v242, 16, v40
	v_and_b32_e32 v243, 0xffff0000, v40
	v_lshlrev_b32_e32 v244, 16, v41
	v_and_b32_e32 v245, 0xffff0000, v41
	v_lshlrev_b32_e32 v246, 16, v43
	v_and_b32_e32 v247, 0xffff0000, v43
	v_pk_mul_f32 v[240:241], v[240:241], s[100:101] op_sel_hi:[1,0]
	v_pk_mul_f32 v[242:243], v[242:243], s[100:101] op_sel_hi:[1,0]
	v_pk_mul_f32 v[244:245], v[244:245], s[100:101] op_sel_hi:[1,0]
	v_pk_mul_f32 v[246:247], v[246:247], s[100:101] op_sel_hi:[1,0]
	v_exp_f32_e32 v240, v240
	v_exp_f32_e32 v241, v241
	v_exp_f32_e32 v242, v242
	v_exp_f32_e32 v243, v243
	v_exp_f32_e32 v244, v244
	v_exp_f32_e32 v245, v245
	v_exp_f32_e32 v246, v246
	v_exp_f32_e32 v247, v247
	s_nop 0
	v_pk_add_f32 v[240:241], v[240:241], 1.0 op_sel_hi:[1,0]
	v_pk_add_f32 v[242:243], v[242:243], 1.0 op_sel_hi:[1,0]
	v_pk_add_f32 v[244:245], v[244:245], 1.0 op_sel_hi:[1,0]
	v_pk_add_f32 v[246:247], v[246:247], 1.0 op_sel_hi:[1,0]
	v_rcp_f32_e32 v248, v240
	v_rcp_f32_e32 v249, v241
	v_rcp_f32_e32 v254, v242
	v_rcp_f32_e32 v255, v243
	v_pk_fma_f32 v[250:251], v[240:241], v[248:249], 1.0 op_sel_hi:[1,1,0] neg_lo:[1,0,0] neg_hi:[1,0,0]
	v_pk_fma_f32 v[40:41], v[242:243], v[254:255], 1.0 op_sel_hi:[1,1,0] neg_lo:[1,0,0] neg_hi:[1,0,0]
	v_pk_fma_f32 v[248:249], v[250:251], v[248:249], v[248:249]
	v_pk_fma_f32 v[254:255], v[40:41], v[254:255], v[254:255]
	v_pk_fma_f32 v[250:251], v[240:241], v[248:249], 1.0 op_sel_hi:[1,1,0] neg_lo:[1,0,0] neg_hi:[1,0,0]
	v_pk_fma_f32 v[40:41], v[242:243], v[254:255], 1.0 op_sel_hi:[1,1,0] neg_lo:[1,0,0] neg_hi:[1,0,0]
	v_pk_fma_f32 v[252:253], v[250:251], v[248:249], v[248:249]
	v_pk_fma_f32 v[42:43], v[40:41], v[254:255], v[254:255]
	v_pk_fma_f32 v[250:251], v[240:241], v[252:253], 1.0 op_sel_hi:[1,1,0] neg_lo:[1,0,0] neg_hi:[1,0,0]
	v_pk_fma_f32 v[40:41], v[242:243], v[42:43], 1.0 op_sel_hi:[1,1,0] neg_lo:[1,0,0] neg_hi:[1,0,0]
	v_pk_fma_f32 v[252:253], v[250:251], v[248:249], v[252:253]
	v_pk_fma_f32 v[42:43], v[40:41], v[254:255], v[42:43]
	v_div_fixup_f32 v240, v252, v240, 1.0
	v_div_fixup_f32 v241, v253, v241, 1.0
	v_div_fixup_f32 v242, v42, v242, 1.0
	v_div_fixup_f32 v243, v43, v243, 1.0
	v_rcp_f32_e32 v248, v244
	v_rcp_f32_e32 v249, v245
	v_rcp_f32_e32 v254, v246
	v_rcp_f32_e32 v255, v247
	v_pk_fma_f32 v[250:251], v[244:245], v[248:249], 1.0 op_sel_hi:[1,1,0] neg_lo:[1,0,0] neg_hi:[1,0,0]
	v_pk_fma_f32 v[40:41], v[246:247], v[254:255], 1.0 op_sel_hi:[1,1,0] neg_lo:[1,0,0] neg_hi:[1,0,0]
	v_pk_fma_f32 v[248:249], v[250:251], v[248:249], v[248:249]
	v_pk_fma_f32 v[254:255], v[40:41], v[254:255], v[254:255]
	v_pk_fma_f32 v[250:251], v[244:245], v[248:249], 1.0 op_sel_hi:[1,1,0] neg_lo:[1,0,0] neg_hi:[1,0,0]
	v_pk_fma_f32 v[40:41], v[246:247], v[254:255], 1.0 op_sel_hi:[1,1,0] neg_lo:[1,0,0] neg_hi:[1,0,0]
	v_pk_fma_f32 v[252:253], v[250:251], v[248:249], v[248:249]
	v_pk_fma_f32 v[42:43], v[40:41], v[254:255], v[254:255]
	v_pk_fma_f32 v[250:251], v[244:245], v[252:253], 1.0 op_sel_hi:[1,1,0] neg_lo:[1,0,0] neg_hi:[1,0,0]
	v_pk_fma_f32 v[40:41], v[246:247], v[42:43], 1.0 op_sel_hi:[1,1,0] neg_lo:[1,0,0] neg_hi:[1,0,0]
	v_pk_fma_f32 v[252:253], v[250:251], v[248:249], v[252:253]
	v_pk_fma_f32 v[42:43], v[40:41], v[254:255], v[42:43]
	v_div_fixup_f32 v244, v252, v244, 1.0
	v_div_fixup_f32 v245, v253, v245, 1.0
	v_div_fixup_f32 v246, v42, v246, 1.0
	v_div_fixup_f32 v247, v43, v247, 1.0
	v_lshlrev_b32_e32 v52, 16, v44
	v_and_b32_e32 v53, 0xffff0000, v44
	v_lshlrev_b32_e32 v54, 16, v46
	v_and_b32_e32 v55, 0xffff0000, v46
	v_lshlrev_b32_e32 v46, 16, v47
	v_and_b32_e32 v47, 0xffff0000, v47
	v_lshlrev_b32_e32 v44, 16, v45
	v_and_b32_e32 v45, 0xffff0000, v45
	v_pk_fma_f32 v[36:37], v[36:37], v[242:243], v[52:53]
	v_pk_fma_f32 v[40:41], v[34:35], v[246:247], v[46:47]
	v_pk_fma_f32 v[34:35], v[32:33], v[240:241], v[54:55]
	v_cvt_pk_bf16_f32 v32, v36, v37
	v_pk_fma_f32 v[38:39], v[38:39], v[244:245], v[44:45]
	s_nop 0
	v_cvt_pk_bf16_f32 v33, v38, v39
	v_cvt_pk_bf16_f32 v34, v34, v35
	v_cvt_pk_bf16_f32 v35, v40, v41
	buffer_store_dwordx4 v[32:35], v56, s[24:27], 0 offen offset:256 sc1
	s_nop 1
	v_add_u32_e32 v32, 0xa0, v162
	v_mad_i64_i32 v[34:35], s[6:7], v32, s77, 0
	v_lshl_add_u64 v[32:33], v[34:35], 1, s[38:39]
	v_lshl_add_u64 v[32:33], v[32:33], 0, v[148:149]
	v_add_co_u32_e32 v36, vcc, s78, v32
	s_nop 1
	v_addc_co_u32_e32 v37, vcc, 0, v33, vcc
	s_waitcnt vmcnt(7)
; __device__ __forceinline__ float sigmoidf_(float x) { return 1.0f / (1.0f + __expf(-x)); }
; __device__ __forceinline__ u32x4 pack8(const f32x4 v0, const f32x4 v1) { u32x4 w; w.x = pk2(v0[0], v0[1]); w.y = pk2(v0[2], v0[3]); w.z = pk2(v1[0], v1[1]); w.w = pk2(v1[2], v1[3]); return w; }
; __device__ __forceinline__ void unpack8(const u32x4 w, f32x4& v0, f32x4& v1) { v0 = (f32x4){bflo(w.x), bfhi(w.x), bflo(w.y), bfhi(w.y)}; v1 = (f32x4){bflo(w.z), bfhi(w.z), bflo(w.w), bfhi(w.w)}; }
;     __device__ __forceinline__ void operator()(const f32x4 (&acc)[2][2][4][2], const Unit& u, int wr, int wc, int fr, int fq) const {
;     ...
;                     const u32x4 gw = *(const u32x4*)(rowp + O_GA + bj * 128);
;                     f32x4 g0, g1; unpack8(gw, g0, g1);
;                     f32x4 v0, v1;
; #pragma unroll
;                     for (int j = 0; j < 4; ++j) { v0[j] = sigmoidf_(g0[j]) * acc[ai][bj][m][0][j]; v1[j] = sigmoidf_(g1[j]) * acc[ai][bj][m][1][j]; }
;                     const u32x4 mw = *(const u32x4*)(rowp + bj * 128); f32x4 m0, m1; unpack8(mw, m0, m1); v0 += m0; v1 += m1;
;                     __builtin_amdgcn_raw_buffer_store_b128(pack8(v0, v1), rsrc, (unsigned)(((size_t)row * DIN + col0 + bj * 128) * 2), 0, 16  ); }
	v_mov_b32_e32 v38, v204
	v_mov_b32_e32 v39, v205
	v_mov_b32_e32 v40, v206
	v_mov_b32_e32 v41, v207
	v_mov_b32_e32 v42, v208
	v_mov_b32_e32 v43, v209
	v_mov_b32_e32 v44, v210
	v_mov_b32_e32 v45, v211
	v_add_u32_e32 v203, 0x177300, v202
	global_load_dwordx4 v[204:207], v203, s[38:39]
	v_add_u32_e32 v203, 0x176100, v202
	global_load_dwordx4 v[208:211], v203, s[38:39]
	s_mov_b32 s100, 0xbfb8aa3b
	v_lshlrev_b32_e32 v240, 16, v38
	v_and_b32_e32 v241, 0xffff0000, v38
	v_lshlrev_b32_e32 v242, 16, v40
	v_and_b32_e32 v243, 0xffff0000, v40
	v_lshlrev_b32_e32 v244, 16, v39
	v_and_b32_e32 v245, 0xffff0000, v39
	v_lshlrev_b32_e32 v246, 16, v41
	v_and_b32_e32 v247, 0xffff0000, v41
	v_pk_mul_f32 v[240:241], v[240:241], s[100:101] op_sel_hi:[1,0]
	v_pk_mul_f32 v[242:243], v[242:243], s[100:101] op_sel_hi:[1,0]
	v_pk_mul_f32 v[244:245], v[244:245], s[100:101] op_sel_hi:[1,0]
	v_pk_mul_f32 v[246:247], v[246:247], s[100:101] op_sel_hi:[1,0]
	v_exp_f32_e32 v240, v240
	v_exp_f32_e32 v241, v241
	v_exp_f32_e32 v242, v242
	v_exp_f32_e32 v243, v243
	v_exp_f32_e32 v244, v244
	v_exp_f32_e32 v245, v245
	v_exp_f32_e32 v246, v246
	v_exp_f32_e32 v247, v247
	s_nop 0
	v_pk_add_f32 v[240:241], v[240:241], 1.0 op_sel_hi:[1,0]
	v_pk_add_f32 v[242:243], v[242:243], 1.0 op_sel_hi:[1,0]
	v_pk_add_f32 v[244:245], v[244:245], 1.0 op_sel_hi:[1,0]
	v_pk_add_f32 v[246:247], v[246:247], 1.0 op_sel_hi:[1,0]
	v_rcp_f32_e32 v248, v240
	v_rcp_f32_e32 v249, v241
	v_rcp_f32_e32 v254, v242
	v_rcp_f32_e32 v255, v243
	v_pk_fma_f32 v[250:251], v[240:241], v[248:249], 1.0 op_sel_hi:[1,1,0] neg_lo:[1,0,0] neg_hi:[1,0,0]
	v_pk_fma_f32 v[38:39], v[242:243], v[254:255], 1.0 op_sel_hi:[1,1,0] neg_lo:[1,0,0] neg_hi:[1,0,0]
	v_pk_fma_f32 v[248:249], v[250:251], v[248:249], v[248:249]
	v_pk_fma_f32 v[254:255], v[38:39], v[254:255], v[254:255]
	v_pk_fma_f32 v[250:251], v[240:241], v[248:249], 1.0 op_sel_hi:[1,1,0] neg_lo:[1,0,0] neg_hi:[1,0,0]
	v_pk_fma_f32 v[38:39], v[242:243], v[254:255], 1.0 op_sel_hi:[1,1,0] neg_lo:[1,0,0] neg_hi:[1,0,0]
	v_pk_fma_f32 v[252:253], v[250:251], v[248:249], v[248:249]
	v_pk_fma_f32 v[40:41], v[38:39], v[254:255], v[254:255]
	v_pk_fma_f32 v[250:251], v[240:241], v[252:253], 1.0 op_sel_hi:[1,1,0] neg_lo:[1,0,0] neg_hi:[1,0,0]
	v_pk_fma_f32 v[38:39], v[242:243], v[40:41], 1.0 op_sel_hi:[1,1,0] neg_lo:[1,0,0] neg_hi:[1,0,0]
	v_pk_fma_f32 v[252:253], v[250:251], v[248:249], v[252:253]
	v_pk_fma_f32 v[40:41], v[38:39], v[254:255], v[40:41]
	v_div_fixup_f32 v240, v252, v240, 1.0
	v_div_fixup_f32 v241, v253, v241, 1.0
	v_div_fixup_f32 v242, v40, v242, 1.0
	v_div_fixup_f32 v243, v41, v243, 1.0
	v_rcp_f32_e32 v248, v244
	v_rcp_f32_e32 v249, v245
	v_rcp_f32_e32 v254, v246
	v_rcp_f32_e32 v255, v247
	v_pk_fma_f32 v[250:251], v[244:245], v[248:249], 1.0 op_sel_hi:[1,1,0] neg_lo:[1,0,0] neg_hi:[1,0,0]
	v_pk_fma_f32 v[38:39], v[246:247], v[254:255], 1.0 op_sel_hi:[1,1,0] neg_lo:[1,0,0] neg_hi:[1,0,0]
	v_pk_fma_f32 v[248:249], v[250:251], v[248:249], v[248:249]
	v_pk_fma_f32 v[254:255], v[38:39], v[254:255], v[254:255]
	v_pk_fma_f32 v[250:251], v[244:245], v[248:249], 1.0 op_sel_hi:[1,1,0] neg_lo:[1,0,0] neg_hi:[1,0,0]
	v_pk_fma_f32 v[38:39], v[246:247], v[254:255], 1.0 op_sel_hi:[1,1,0] neg_lo:[1,0,0] neg_hi:[1,0,0]
	v_pk_fma_f32 v[252:253], v[250:251], v[248:249], v[248:249]
	v_pk_fma_f32 v[40:41], v[38:39], v[254:255], v[254:255]
	v_pk_fma_f32 v[250:251], v[244:245], v[252:253], 1.0 op_sel_hi:[1,1,0] neg_lo:[1,0,0] neg_hi:[1,0,0]
	v_pk_fma_f32 v[38:39], v[246:247], v[40:41], 1.0 op_sel_hi:[1,1,0] neg_lo:[1,0,0] neg_hi:[1,0,0]
	v_pk_fma_f32 v[252:253], v[250:251], v[248:249], v[252:253]
	v_pk_fma_f32 v[40:41], v[38:39], v[254:255], v[40:41]
	v_div_fixup_f32 v244, v252, v244, 1.0
	v_div_fixup_f32 v245, v253, v245, 1.0
	v_div_fixup_f32 v246, v40, v246, 1.0
	v_div_fixup_f32 v247, v41, v247, 1.0
	v_lshlrev_b32_e32 v50, 16, v42
	v_and_b32_e32 v51, 0xffff0000, v42
	v_lshlrev_b32_e32 v52, 16, v44
	v_and_b32_e32 v53, 0xffff0000, v44
	v_lshlrev_b32_e32 v44, 16, v45
	v_and_b32_e32 v45, 0xffff0000, v45
	v_lshlrev_b32_e32 v42, 16, v43
	v_and_b32_e32 v43, 0xffff0000, v43
	v_pk_fma_f32 v[28:29], v[28:29], v[240:241], v[50:51]
	v_pk_fma_f32 v[38:39], v[26:27], v[246:247], v[44:45]
	v_pk_fma_f32 v[26:27], v[24:25], v[242:243], v[52:53]
	v_add_lshl_u32 v40, v146, v34, 1
	v_pk_fma_f32 v[30:31], v[30:31], v[244:245], v[42:43]
	v_cvt_pk_bf16_f32 v24, v28, v29
	s_nop 0
	v_cvt_pk_bf16_f32 v25, v30, v31
	v_cvt_pk_bf16_f32 v26, v26, v27
	v_cvt_pk_bf16_f32 v27, v38, v39
	buffer_store_dwordx4 v[24:27], v40, s[24:27], 0 offen sc1
	s_nop 0
	s_waitcnt vmcnt(7)
; __device__ __forceinline__ float sigmoidf_(float x) { return 1.0f / (1.0f + __expf(-x)); }
; __device__ __forceinline__ u32x4 pack8(const f32x4 v0, const f32x4 v1) { u32x4 w; w.x = pk2(v0[0], v0[1]); w.y = pk2(v0[2], v0[3]); w.z = pk2(v1[0], v1[1]); w.w = pk2(v1[2], v1[3]); return w; }
; __device__ __forceinline__ void unpack8(const u32x4 w, f32x4& v0, f32x4& v1) { v0 = (f32x4){bflo(w.x), bfhi(w.x), bflo(w.y), bfhi(w.y)}; v1 = (f32x4){bflo(w.z), bfhi(w.z), bflo(w.w), bfhi(w.w)}; }
;     __device__ __forceinline__ void operator()(const f32x4 (&acc)[2][2][4][2], const Unit& u, int wr, int wc, int fr, int fq) const {
;     ...
;                     const u32x4 gw = *(const u32x4*)(rowp + O_GA + bj * 128);
;                     f32x4 g0, g1; unpack8(gw, g0, g1);
;                     f32x4 v0, v1;
; #pragma unroll
;                     for (int j = 0; j < 4; ++j) { v0[j] = sigmoidf_(g0[j]) * acc[ai][bj][m][0][j]; v1[j] = sigmoidf_(g1[j]) * acc[ai][bj][m][1][j]; }
;                     const u32x4 mw = *(const u32x4*)(rowp + bj * 128); f32x4 m0, m1; unpack8(mw, m0, m1); v0 += m0; v1 += m1;
;                     __builtin_amdgcn_raw_buffer_store_b128(pack8(v0, v1), rsrc, (unsigned)(((size_t)row * DIN + col0 + bj * 128) * 2), 0, 16  ); }
	v_mov_b32_e32 v24, v212
	v_mov_b32_e32 v25, v213
	v_mov_b32_e32 v26, v214
	v_mov_b32_e32 v27, v215
	v_mov_b32_e32 v28, v216
	v_mov_b32_e32 v29, v217
	v_mov_b32_e32 v30, v218
	v_mov_b32_e32 v31, v219
	s_mov_b32 s100, 0xbfb8aa3b
	v_lshlrev_b32_e32 v240, 16, v26
	v_and_b32_e32 v241, 0xffff0000, v26
	v_lshlrev_b32_e32 v242, 16, v24
	v_and_b32_e32 v243, 0xffff0000, v24
	v_lshlrev_b32_e32 v244, 16, v25
	v_and_b32_e32 v245, 0xffff0000, v25
	v_lshlrev_b32_e32 v246, 16, v27
	v_and_b32_e32 v247, 0xffff0000, v27
	v_pk_mul_f32 v[240:241], v[240:241], s[100:101] op_sel_hi:[1,0]
	v_pk_mul_f32 v[242:243], v[242:243], s[100:101] op_sel_hi:[1,0]
	v_pk_mul_f32 v[244:245], v[244:245], s[100:101] op_sel_hi:[1,0]
	v_pk_mul_f32 v[246:247], v[246:247], s[100:101] op_sel_hi:[1,0]
	v_exp_f32_e32 v240, v240
	v_exp_f32_e32 v241, v241
	v_exp_f32_e32 v242, v242
	v_exp_f32_e32 v243, v243
	v_exp_f32_e32 v244, v244
	v_exp_f32_e32 v245, v245
	v_exp_f32_e32 v246, v246
	v_exp_f32_e32 v247, v247
	s_nop 0
	v_pk_add_f32 v[240:241], v[240:241], 1.0 op_sel_hi:[1,0]
	v_pk_add_f32 v[242:243], v[242:243], 1.0 op_sel_hi:[1,0]
	v_pk_add_f32 v[244:245], v[244:245], 1.0 op_sel_hi:[1,0]
	v_pk_add_f32 v[246:247], v[246:247], 1.0 op_sel_hi:[1,0]
	v_rcp_f32_e32 v248, v240
	v_rcp_f32_e32 v249, v241
	v_rcp_f32_e32 v254, v242
	v_rcp_f32_e32 v255, v243
	v_pk_fma_f32 v[250:251], v[240:241], v[248:249], 1.0 op_sel_hi:[1,1,0] neg_lo:[1,0,0] neg_hi:[1,0,0]
	v_pk_fma_f32 v[24:25], v[242:243], v[254:255], 1.0 op_sel_hi:[1,1,0] neg_lo:[1,0,0] neg_hi:[1,0,0]
	v_pk_fma_f32 v[248:249], v[250:251], v[248:249], v[248:249]
	v_pk_fma_f32 v[254:255], v[24:25], v[254:255], v[254:255]
	v_pk_fma_f32 v[250:251], v[240:241], v[248:249], 1.0 op_sel_hi:[1,1,0] neg_lo:[1,0,0] neg_hi:[1,0,0]
	v_pk_fma_f32 v[24:25], v[242:243], v[254:255], 1.0 op_sel_hi:[1,1,0] neg_lo:[1,0,0] neg_hi:[1,0,0]
	v_pk_fma_f32 v[252:253], v[250:251], v[248:249], v[248:249]
	v_pk_fma_f32 v[26:27], v[24:25], v[254:255], v[254:255]
	v_pk_fma_f32 v[250:251], v[240:241], v[252:253], 1.0 op_sel_hi:[1,1,0] neg_lo:[1,0,0] neg_hi:[1,0,0]
	v_pk_fma_f32 v[24:25], v[242:243], v[26:27], 1.0 op_sel_hi:[1,1,0] neg_lo:[1,0,0] neg_hi:[1,0,0]
	v_pk_fma_f32 v[252:253], v[250:251], v[248:249], v[252:253]
	v_pk_fma_f32 v[26:27], v[24:25], v[254:255], v[26:27]
	v_div_fixup_f32 v240, v252, v240, 1.0
	v_div_fixup_f32 v241, v253, v241, 1.0
	v_div_fixup_f32 v242, v26, v242, 1.0
	v_div_fixup_f32 v243, v27, v243, 1.0
	v_rcp_f32_e32 v248, v244
	v_rcp_f32_e32 v249, v245
	v_rcp_f32_e32 v254, v246
	v_rcp_f32_e32 v255, v247
	v_pk_fma_f32 v[250:251], v[244:245], v[248:249], 1.0 op_sel_hi:[1,1,0] neg_lo:[1,0,0] neg_hi:[1,0,0]
	v_pk_fma_f32 v[24:25], v[246:247], v[254:255], 1.0 op_sel_hi:[1,1,0] neg_lo:[1,0,0] neg_hi:[1,0,0]
	v_pk_fma_f32 v[248:249], v[250:251], v[248:249], v[248:249]
	v_pk_fma_f32 v[254:255], v[24:25], v[254:255], v[254:255]
	v_pk_fma_f32 v[250:251], v[244:245], v[248:249], 1.0 op_sel_hi:[1,1,0] neg_lo:[1,0,0] neg_hi:[1,0,0]
	v_pk_fma_f32 v[24:25], v[246:247], v[254:255], 1.0 op_sel_hi:[1,1,0] neg_lo:[1,0,0] neg_hi:[1,0,0]
	v_pk_fma_f32 v[252:253], v[250:251], v[248:249], v[248:249]
	v_pk_fma_f32 v[26:27], v[24:25], v[254:255], v[254:255]
	v_pk_fma_f32 v[250:251], v[244:245], v[252:253], 1.0 op_sel_hi:[1,1,0] neg_lo:[1,0,0] neg_hi:[1,0,0]
	v_pk_fma_f32 v[24:25], v[246:247], v[26:27], 1.0 op_sel_hi:[1,1,0] neg_lo:[1,0,0] neg_hi:[1,0,0]
	v_pk_fma_f32 v[252:253], v[250:251], v[248:249], v[252:253]
	v_pk_fma_f32 v[26:27], v[24:25], v[254:255], v[26:27]
	v_div_fixup_f32 v244, v252, v244, 1.0
	v_div_fixup_f32 v245, v253, v245, 1.0
	v_div_fixup_f32 v246, v26, v246, 1.0
	v_div_fixup_f32 v247, v27, v247, 1.0
	v_lshlrev_b32_e32 v36, 16, v28
	v_and_b32_e32 v37, 0xffff0000, v28
	v_lshlrev_b32_e32 v38, 16, v30
	v_and_b32_e32 v39, 0xffff0000, v30
	v_lshlrev_b32_e32 v30, 16, v31
	v_and_b32_e32 v31, 0xffff0000, v31
	v_lshlrev_b32_e32 v28, 16, v29
	v_and_b32_e32 v29, 0xffff0000, v29
	v_pk_fma_f32 v[20:21], v[20:21], v[242:243], v[36:37]
	v_pk_fma_f32 v[24:25], v[18:19], v[246:247], v[30:31]
	v_pk_fma_f32 v[18:19], v[16:17], v[240:241], v[38:39]
	v_cvt_pk_bf16_f32 v16, v20, v21
	v_pk_fma_f32 v[22:23], v[22:23], v[244:245], v[28:29]
	s_nop 0
	v_cvt_pk_bf16_f32 v17, v22, v23
	v_cvt_pk_bf16_f32 v18, v18, v19
	v_cvt_pk_bf16_f32 v19, v24, v25
	buffer_store_dwordx4 v[16:19], v40, s[24:27], 0 offen offset:256 sc1
	s_nop 1
	v_add_u32_e32 v16, 0xb0, v162
	v_mad_i64_i32 v[18:19], s[6:7], v16, s77, 0
	v_lshl_add_u64 v[16:17], v[18:19], 1, s[38:39]
	v_lshl_add_u64 v[16:17], v[16:17], 0, v[148:149]
	v_add_co_u32_e32 v20, vcc, s78, v16
	s_nop 1
	v_addc_co_u32_e32 v21, vcc, 0, v17, vcc
	s_waitcnt vmcnt(5)
; __device__ __forceinline__ float sigmoidf_(float x) { return 1.0f / (1.0f + __expf(-x)); }
; __device__ __forceinline__ u32x4 pack8(const f32x4 v0, const f32x4 v1) { u32x4 w; w.x = pk2(v0[0], v0[1]); w.y = pk2(v0[2], v0[3]); w.z = pk2(v1[0], v1[1]); w.w = pk2(v1[2], v1[3]); return w; }
; __device__ __forceinline__ void unpack8(const u32x4 w, f32x4& v0, f32x4& v1) { v0 = (f32x4){bflo(w.x), bfhi(w.x), bflo(w.y), bfhi(w.y)}; v1 = (f32x4){bflo(w.z), bfhi(w.z), bflo(w.w), bfhi(w.w)}; }
;     __device__ __forceinline__ void operator()(const f32x4 (&acc)[2][2][4][2], const Unit& u, int wr, int wc, int fr, int fq) const {
;     ...
;                     const u32x4 gw = *(const u32x4*)(rowp + O_GA + bj * 128);
;                     f32x4 g0, g1; unpack8(gw, g0, g1);
;                     f32x4 v0, v1;
; #pragma unroll
;                     for (int j = 0; j < 4; ++j) { v0[j] = sigmoidf_(g0[j]) * acc[ai][bj][m][0][j]; v1[j] = sigmoidf_(g1[j]) * acc[ai][bj][m][1][j]; }
;                     const u32x4 mw = *(const u32x4*)(rowp + bj * 128); f32x4 m0, m1; unpack8(mw, m0, m1); v0 += m0; v1 += m1;
;                     __builtin_amdgcn_raw_buffer_store_b128(pack8(v0, v1), rsrc, (unsigned)(((size_t)row * DIN + col0 + bj * 128) * 2), 0, 16  ); }
	v_mov_b32_e32 v22, v232
	v_mov_b32_e32 v23, v233
	v_mov_b32_e32 v24, v234
	v_mov_b32_e32 v25, v235
	v_mov_b32_e32 v26, v236
	v_mov_b32_e32 v27, v237
	v_mov_b32_e32 v28, v238
	v_mov_b32_e32 v29, v239
	s_mov_b32 s100, 0xbfb8aa3b
	v_lshlrev_b32_e32 v240, 16, v22
	v_and_b32_e32 v241, 0xffff0000, v22
	v_lshlrev_b32_e32 v242, 16, v24
	v_and_b32_e32 v243, 0xffff0000, v24
	v_lshlrev_b32_e32 v244, 16, v23
	v_and_b32_e32 v245, 0xffff0000, v23
	v_lshlrev_b32_e32 v246, 16, v25
	v_and_b32_e32 v247, 0xffff0000, v25
	v_pk_mul_f32 v[240:241], v[240:241], s[100:101] op_sel_hi:[1,0]
	v_pk_mul_f32 v[242:243], v[242:243], s[100:101] op_sel_hi:[1,0]
	v_pk_mul_f32 v[244:245], v[244:245], s[100:101] op_sel_hi:[1,0]
	v_pk_mul_f32 v[246:247], v[246:247], s[100:101] op_sel_hi:[1,0]
	v_exp_f32_e32 v240, v240
	v_exp_f32_e32 v241, v241
	v_exp_f32_e32 v242, v242
	v_exp_f32_e32 v243, v243
	v_exp_f32_e32 v244, v244
	v_exp_f32_e32 v245, v245
	v_exp_f32_e32 v246, v246
	v_exp_f32_e32 v247, v247
	s_nop 0
	v_pk_add_f32 v[240:241], v[240:241], 1.0 op_sel_hi:[1,0]
	v_pk_add_f32 v[242:243], v[242:243], 1.0 op_sel_hi:[1,0]
	v_pk_add_f32 v[244:245], v[244:245], 1.0 op_sel_hi:[1,0]
	v_pk_add_f32 v[246:247], v[246:247], 1.0 op_sel_hi:[1,0]
	v_rcp_f32_e32 v248, v240
	v_rcp_f32_e32 v249, v241
	v_rcp_f32_e32 v254, v242
	v_rcp_f32_e32 v255, v243
	v_pk_fma_f32 v[250:251], v[240:241], v[248:249], 1.0 op_sel_hi:[1,1,0] neg_lo:[1,0,0] neg_hi:[1,0,0]
	v_pk_fma_f32 v[22:23], v[242:243], v[254:255], 1.0 op_sel_hi:[1,1,0] neg_lo:[1,0,0] neg_hi:[1,0,0]
	v_pk_fma_f32 v[248:249], v[250:251], v[248:249], v[248:249]
	v_pk_fma_f32 v[254:255], v[22:23], v[254:255], v[254:255]
	v_pk_fma_f32 v[250:251], v[240:241], v[248:249], 1.0 op_sel_hi:[1,1,0] neg_lo:[1,0,0] neg_hi:[1,0,0]
	v_pk_fma_f32 v[22:23], v[242:243], v[254:255], 1.0 op_sel_hi:[1,1,0] neg_lo:[1,0,0] neg_hi:[1,0,0]
	v_pk_fma_f32 v[252:253], v[250:251], v[248:249], v[248:249]
	v_pk_fma_f32 v[24:25], v[22:23], v[254:255], v[254:255]
	v_pk_fma_f32 v[250:251], v[240:241], v[252:253], 1.0 op_sel_hi:[1,1,0] neg_lo:[1,0,0] neg_hi:[1,0,0]
	v_pk_fma_f32 v[22:23], v[242:243], v[24:25], 1.0 op_sel_hi:[1,1,0] neg_lo:[1,0,0] neg_hi:[1,0,0]
	v_pk_fma_f32 v[252:253], v[250:251], v[248:249], v[252:253]
	v_pk_fma_f32 v[24:25], v[22:23], v[254:255], v[24:25]
	v_div_fixup_f32 v240, v252, v240, 1.0
	v_div_fixup_f32 v241, v253, v241, 1.0
	v_div_fixup_f32 v242, v24, v242, 1.0
	v_div_fixup_f32 v243, v25, v243, 1.0
	v_rcp_f32_e32 v248, v244
	v_rcp_f32_e32 v249, v245
	v_rcp_f32_e32 v254, v246
	v_rcp_f32_e32 v255, v247
	v_pk_fma_f32 v[250:251], v[244:245], v[248:249], 1.0 op_sel_hi:[1,1,0] neg_lo:[1,0,0] neg_hi:[1,0,0]
	v_pk_fma_f32 v[22:23], v[246:247], v[254:255], 1.0 op_sel_hi:[1,1,0] neg_lo:[1,0,0] neg_hi:[1,0,0]
	v_pk_fma_f32 v[248:249], v[250:251], v[248:249], v[248:249]
	v_pk_fma_f32 v[254:255], v[22:23], v[254:255], v[254:255]
	v_pk_fma_f32 v[250:251], v[244:245], v[248:249], 1.0 op_sel_hi:[1,1,0] neg_lo:[1,0,0] neg_hi:[1,0,0]
	v_pk_fma_f32 v[22:23], v[246:247], v[254:255], 1.0 op_sel_hi:[1,1,0] neg_lo:[1,0,0] neg_hi:[1,0,0]
	v_pk_fma_f32 v[252:253], v[250:251], v[248:249], v[248:249]
	v_pk_fma_f32 v[24:25], v[22:23], v[254:255], v[254:255]
	v_pk_fma_f32 v[250:251], v[244:245], v[252:253], 1.0 op_sel_hi:[1,1,0] neg_lo:[1,0,0] neg_hi:[1,0,0]
	v_pk_fma_f32 v[22:23], v[246:247], v[24:25], 1.0 op_sel_hi:[1,1,0] neg_lo:[1,0,0] neg_hi:[1,0,0]
	v_pk_fma_f32 v[252:253], v[250:251], v[248:249], v[252:253]
	v_pk_fma_f32 v[24:25], v[22:23], v[254:255], v[24:25]
	v_div_fixup_f32 v244, v252, v244, 1.0
	v_div_fixup_f32 v245, v253, v245, 1.0
	v_div_fixup_f32 v246, v24, v246, 1.0
	v_div_fixup_f32 v247, v25, v247, 1.0
	v_lshlrev_b32_e32 v34, 16, v26
	v_and_b32_e32 v35, 0xffff0000, v26
	v_lshlrev_b32_e32 v36, 16, v28
	v_and_b32_e32 v37, 0xffff0000, v28
	v_lshlrev_b32_e32 v28, 16, v29
	v_and_b32_e32 v29, 0xffff0000, v29
	v_lshlrev_b32_e32 v26, 16, v27
	v_and_b32_e32 v27, 0xffff0000, v27
	v_pk_fma_f32 v[12:13], v[12:13], v[240:241], v[34:35]
	v_pk_fma_f32 v[22:23], v[10:11], v[246:247], v[28:29]
	v_pk_fma_f32 v[10:11], v[8:9], v[242:243], v[36:37]
	v_add_lshl_u32 v24, v146, v18, 1
	v_pk_fma_f32 v[14:15], v[14:15], v[244:245], v[26:27]
	v_cvt_pk_bf16_f32 v8, v12, v13
	s_nop 0
	v_cvt_pk_bf16_f32 v9, v14, v15
	v_cvt_pk_bf16_f32 v10, v10, v11
	v_cvt_pk_bf16_f32 v11, v22, v23
	buffer_store_dwordx4 v[8:11], v24, s[24:27], 0 offen sc1
	s_nop 0
	s_waitcnt vmcnt(3)
; __device__ __forceinline__ float sigmoidf_(float x) { return 1.0f / (1.0f + __expf(-x)); }
; __device__ __forceinline__ u32x4 pack8(const f32x4 v0, const f32x4 v1) { u32x4 w; w.x = pk2(v0[0], v0[1]); w.y = pk2(v0[2], v0[3]); w.z = pk2(v1[0], v1[1]); w.w = pk2(v1[2], v1[3]); return w; }
; __device__ __forceinline__ void unpack8(const u32x4 w, f32x4& v0, f32x4& v1) { v0 = (f32x4){bflo(w.x), bfhi(w.x), bflo(w.y), bfhi(w.y)}; v1 = (f32x4){bflo(w.z), bfhi(w.z), bflo(w.w), bfhi(w.w)}; }
;     __device__ __forceinline__ void operator()(const f32x4 (&acc)[2][2][4][2], const Unit& u, int wr, int wc, int fr, int fq) const {
;     ...
;                     const u32x4 gw = *(const u32x4*)(rowp + O_GA + bj * 128);
;                     f32x4 g0, g1; unpack8(gw, g0, g1);
;                     f32x4 v0, v1;
; #pragma unroll
;                     for (int j = 0; j < 4; ++j) { v0[j] = sigmoidf_(g0[j]) * acc[ai][bj][m][0][j]; v1[j] = sigmoidf_(g1[j]) * acc[ai][bj][m][1][j]; }
;                     const u32x4 mw = *(const u32x4*)(rowp + bj * 128); f32x4 m0, m1; unpack8(mw, m0, m1); v0 += m0; v1 += m1;
;                     __builtin_amdgcn_raw_buffer_store_b128(pack8(v0, v1), rsrc, (unsigned)(((size_t)row * DIN + col0 + bj * 128) * 2), 0, 16  ); }
;             }
;         asm volatile("s_waitcnt vmcnt(0)" ::: "memory");
;         if (fr == 0 && fq == 0) (void)__hip_atomic_fetch_add(ready + 64 * (pm_off + u.pm), 1u, __ATOMIC_RELAXED, __HIP_MEMORY_SCOPE_AGENT);
	v_mov_b32_e32 v8, v204
	v_mov_b32_e32 v9, v205
	v_mov_b32_e32 v10, v206
	v_mov_b32_e32 v11, v207
	v_mov_b32_e32 v12, v208
	v_mov_b32_e32 v13, v209
	v_mov_b32_e32 v14, v210
	v_mov_b32_e32 v15, v211
	s_mov_b32 s100, 0xbfb8aa3b
	v_lshlrev_b32_e32 v240, 16, v10
	v_and_b32_e32 v241, 0xffff0000, v10
	v_lshlrev_b32_e32 v242, 16, v8
	v_and_b32_e32 v243, 0xffff0000, v8
	v_lshlrev_b32_e32 v244, 16, v9
	v_and_b32_e32 v245, 0xffff0000, v9
	v_lshlrev_b32_e32 v246, 16, v11
	v_and_b32_e32 v247, 0xffff0000, v11
	v_pk_mul_f32 v[240:241], v[240:241], s[100:101] op_sel_hi:[1,0]
	v_pk_mul_f32 v[242:243], v[242:243], s[100:101] op_sel_hi:[1,0]
	v_pk_mul_f32 v[244:245], v[244:245], s[100:101] op_sel_hi:[1,0]
	v_pk_mul_f32 v[246:247], v[246:247], s[100:101] op_sel_hi:[1,0]
	v_exp_f32_e32 v240, v240
	v_exp_f32_e32 v241, v241
	v_exp_f32_e32 v242, v242
	v_exp_f32_e32 v243, v243
	v_exp_f32_e32 v244, v244
	v_exp_f32_e32 v245, v245
	v_exp_f32_e32 v246, v246
	v_exp_f32_e32 v247, v247
	s_nop 0
	v_pk_add_f32 v[240:241], v[240:241], 1.0 op_sel_hi:[1,0]
	v_pk_add_f32 v[242:243], v[242:243], 1.0 op_sel_hi:[1,0]
	v_pk_add_f32 v[244:245], v[244:245], 1.0 op_sel_hi:[1,0]
	v_pk_add_f32 v[246:247], v[246:247], 1.0 op_sel_hi:[1,0]
	v_rcp_f32_e32 v248, v240
	v_rcp_f32_e32 v249, v241
	v_rcp_f32_e32 v254, v242
	v_rcp_f32_e32 v255, v243
	v_pk_fma_f32 v[250:251], v[240:241], v[248:249], 1.0 op_sel_hi:[1,1,0] neg_lo:[1,0,0] neg_hi:[1,0,0]
	v_pk_fma_f32 v[8:9], v[242:243], v[254:255], 1.0 op_sel_hi:[1,1,0] neg_lo:[1,0,0] neg_hi:[1,0,0]
	v_pk_fma_f32 v[248:249], v[250:251], v[248:249], v[248:249]
	v_pk_fma_f32 v[254:255], v[8:9], v[254:255], v[254:255]
	v_pk_fma_f32 v[250:251], v[240:241], v[248:249], 1.0 op_sel_hi:[1,1,0] neg_lo:[1,0,0] neg_hi:[1,0,0]
	v_pk_fma_f32 v[8:9], v[242:243], v[254:255], 1.0 op_sel_hi:[1,1,0] neg_lo:[1,0,0] neg_hi:[1,0,0]
	v_pk_fma_f32 v[252:253], v[250:251], v[248:249], v[248:249]
	v_pk_fma_f32 v[10:11], v[8:9], v[254:255], v[254:255]
	v_pk_fma_f32 v[250:251], v[240:241], v[252:253], 1.0 op_sel_hi:[1,1,0] neg_lo:[1,0,0] neg_hi:[1,0,0]
	v_pk_fma_f32 v[8:9], v[242:243], v[10:11], 1.0 op_sel_hi:[1,1,0] neg_lo:[1,0,0] neg_hi:[1,0,0]
	v_pk_fma_f32 v[252:253], v[250:251], v[248:249], v[252:253]
	v_pk_fma_f32 v[10:11], v[8:9], v[254:255], v[10:11]
	v_div_fixup_f32 v240, v252, v240, 1.0
	v_div_fixup_f32 v241, v253, v241, 1.0
	v_div_fixup_f32 v242, v10, v242, 1.0
	v_div_fixup_f32 v243, v11, v243, 1.0
	v_rcp_f32_e32 v248, v244
	v_rcp_f32_e32 v249, v245
	v_rcp_f32_e32 v254, v246
	v_rcp_f32_e32 v255, v247
	v_pk_fma_f32 v[250:251], v[244:245], v[248:249], 1.0 op_sel_hi:[1,1,0] neg_lo:[1,0,0] neg_hi:[1,0,0]
	v_pk_fma_f32 v[8:9], v[246:247], v[254:255], 1.0 op_sel_hi:[1,1,0] neg_lo:[1,0,0] neg_hi:[1,0,0]
	v_pk_fma_f32 v[248:249], v[250:251], v[248:249], v[248:249]
	v_pk_fma_f32 v[254:255], v[8:9], v[254:255], v[254:255]
	v_pk_fma_f32 v[250:251], v[244:245], v[248:249], 1.0 op_sel_hi:[1,1,0] neg_lo:[1,0,0] neg_hi:[1,0,0]
	v_pk_fma_f32 v[8:9], v[246:247], v[254:255], 1.0 op_sel_hi:[1,1,0] neg_lo:[1,0,0] neg_hi:[1,0,0]
	v_pk_fma_f32 v[252:253], v[250:251], v[248:249], v[248:249]
	v_pk_fma_f32 v[10:11], v[8:9], v[254:255], v[254:255]
	v_pk_fma_f32 v[250:251], v[244:245], v[252:253], 1.0 op_sel_hi:[1,1,0] neg_lo:[1,0,0] neg_hi:[1,0,0]
	v_pk_fma_f32 v[8:9], v[246:247], v[10:11], 1.0 op_sel_hi:[1,1,0] neg_lo:[1,0,0] neg_hi:[1,0,0]
	v_pk_fma_f32 v[252:253], v[250:251], v[248:249], v[252:253]
	v_pk_fma_f32 v[10:11], v[8:9], v[254:255], v[10:11]
	v_div_fixup_f32 v244, v252, v244, 1.0
	v_div_fixup_f32 v245, v253, v245, 1.0
	v_div_fixup_f32 v246, v10, v246, 1.0
	v_div_fixup_f32 v247, v11, v247, 1.0
	v_lshlrev_b32_e32 v20, 16, v12
	v_and_b32_e32 v21, 0xffff0000, v12
	v_lshlrev_b32_e32 v22, 16, v14
	v_and_b32_e32 v23, 0xffff0000, v14
	v_lshlrev_b32_e32 v14, 16, v15
	v_and_b32_e32 v15, 0xffff0000, v15
	v_lshlrev_b32_e32 v12, 16, v13
	v_and_b32_e32 v13, 0xffff0000, v13
	v_pk_fma_f32 v[4:5], v[4:5], v[242:243], v[20:21]
	v_pk_fma_f32 v[8:9], v[2:3], v[246:247], v[14:15]
	v_pk_fma_f32 v[2:3], v[0:1], v[240:241], v[22:23]
	v_pk_fma_f32 v[6:7], v[6:7], v[244:245], v[12:13]
	v_cvt_pk_bf16_f32 v0, v4, v5
	s_nop 0
	v_cvt_pk_bf16_f32 v1, v6, v7
	v_cvt_pk_bf16_f32 v2, v2, v3
	v_cvt_pk_bf16_f32 v3, v8, v9
	buffer_store_dwordx4 v[0:3], v24, s[24:27], 0 offen offset:256 sc1
	s_waitcnt vmcnt(0)
	s_and_saveexec_b64 s[14:15], s[10:11]
	s_cbranch_execz .LBB0_692
	s_mov_b64 s[16:17], exec
	v_mbcnt_lo_u32_b32 v0, s16, 0
	v_mbcnt_hi_u32_b32 v0, s17, v0
	v_cmp_eq_u32_e32 vcc, 0, v0
	s_and_b64 s[6:7], exec, vcc
	s_mov_b64 exec, s[6:7]
	s_cbranch_execz .LBB0_692
	s_lshl_b32 s6, s79, 6
	s_ashr_i32 s7, s6, 31
	s_lshl_b64 s[6:7], s[6:7], 2
	s_add_u32 s6, s34, s6
	s_addc_u32 s7, s35, s7
	s_bcnt1_i32_b64 s8, s[16:17]
	v_mov_b32_e32 v0, s8
	global_atomic_add v131, v0, s[6:7]
	s_branch .LBB0_692

; #define PG8_STAGE(bufoff, gbase, voff) do { _Pragma("unroll") for (int _i = 0; _i < 2; ++_i) \
;         __builtin_amdgcn_global_load_lds((const unsigned*)((const char*)(gbase) + (voff)[_i]), (LAS unsigned*)(lds + (bufoff) + ldsw + _i * 8192), 16, 0, 0); } while (0)
; #define PG8_LDA(dst, b, h) do { _Pragma("unroll") for (int m = 0; m < 4; ++m) _Pragma("unroll") for (int k = 0; k < 2; ++k) dst[m][k] = *(const LAS bf16x8*)(lds + PG8_SA(b, h) + aoff + m * 2048 + k * 1024); } while (0)
; #define PG8_LDB(dst, b, h) do { _Pragma("unroll") for (int n = 0; n < 2; ++n) _Pragma("unroll") for (int k = 0; k < 2; ++k) dst[n][k] = *(const LAS bf16x8*)(lds + PG8_SB(b, h) + boff + n * 2048 + k * 1024); } while (0)
; #define PG8_MMA(ai, bj, At, Bt) do { __builtin_amdgcn_s_setprio(1); _Pragma("unroll") for (int m = 0; m < 4; ++m) _Pragma("unroll") for (int n = 0; n < 2; ++n) _Pragma("unroll") for (int k = 0; k < 2; ++k) \
;         acc[ai][bj][m][n] = __builtin_amdgcn_mfma_f32_16x16x32_bf16(Bt[n][k], At[m][k], acc[ai][bj][m][n], 0, 0, 0); __builtin_amdgcn_s_setprio(0); } while (0)
; #define PG8_WAIT_L(n) asm volatile("s_waitcnt lgkmcnt(" #n ")" ::: "memory")
; #define PG8_BAR __builtin_amdgcn_s_barrier()
; #define PG8_SCHED __builtin_amdgcn_sched_barrier(0)
;     ...
;         for (int t = 0; t < nt; t += 2) {
;             const bool last = (t == nt - 2);
;             const char* a1 = cA + (size_t)(t + 1) * kstep;
;             const char* a2 = last ? nA : cA + (size_t)(t + 2) * kstep; const char* b2 = last ? nB : cB + (size_t)(t + 2) * kstep;
;             const char* a3 = a2 + kstep; const char* b3 = b2 + kstep;
;             if (last && has_next) PG8_A_READY(nxt);
;             PG8_LDB(B0, 0, 0); PG8_SCHED; PG8_LDA(At, 0, 0); PG8_STAGE(PG8_SA(1, 1), a1 + hA, voffA);
;             PG8_WAIT_L(8); PG8_BAR; PG8_WAIT_L(0); PG8_MMA(0, 0, At, B0); PG8_BAR; PG8_SCHED;
;             PG8_LDB(B1, 0, 1); PG8_STAGE(PG8_SB(0, 0), b2, voffB);
;             PG8_BAR; PG8_WAIT_L(0); PG8_MMA(0, 1, At, B1); PG8_BAR;
;             PG8_LDA(At, 0, 1); PG8_STAGE(PG8_SA(0, 0), a2, voffA);
;             PG8_BAR; PG8_WAIT_L(0); PG8_MMA(1, 0, At, B0); PG8_BAR; PG8_SCHED;
.LBB0_723:
	ds_read_b128 v[140:143], v155
	ds_read_b128 v[146:149], v155 offset:1024
	ds_read_b128 v[158:161], v155 offset:2048
	ds_read_b128 v[162:165], v155 offset:3072
	s_add_u32 s14, s12, 0xfffe0080
	s_addc_u32 s15, s13, -1
	s_cmp_eq_u32 s39, 4
	s_cselect_b32 s17, s7, s15
	s_cselect_b32 s16, s8, s14
	s_cselect_b32 s15, s9, s33
	s_cselect_b32 s14, s18, s19
	v_lshl_add_u64 v[150:151], s[12:13], 0, v[138:139]
	s_add_i32 m0, s67, 0xc000
	ds_read_b128 v[170:173], v156
	ds_read_b128 v[174:177], v156 offset:1024
	ds_read_b128 v[178:181], v156 offset:2048
	ds_read_b128 v[182:185], v156 offset:3072
	ds_read_b128 v[186:189], v156 offset:4096
	ds_read_b128 v[190:193], v156 offset:5120
	ds_read_b128 v[194:197], v156 offset:6144
	ds_read_b128 v[198:201], v156 offset:7168
	global_load_lds_dwordx4 v[150:151], off
	v_lshl_add_u64 v[150:151], s[12:13], 0, v[136:137]
	s_add_i32 m0, s67, 0xe000
	s_nop 0
	global_load_lds_dwordx4 v[150:151], off
	s_waitcnt lgkmcnt(8)
	s_barrier
	s_waitcnt lgkmcnt(0)
	s_setprio 1
	s_waitcnt lgkmcnt(0)
	v_mfma_f32_16x16x32_bf16 v[124:127], v[140:143], v[170:173], v[124:127]
	v_mfma_f32_16x16x32_bf16 v[120:123], v[158:161], v[170:173], v[120:123]
	v_mfma_f32_16x16x32_bf16 v[108:111], v[140:143], v[178:181], v[108:111]
	v_mfma_f32_16x16x32_bf16 v[104:107], v[158:161], v[178:181], v[104:107]
	v_mfma_f32_16x16x32_bf16 v[92:95], v[140:143], v[186:189], v[92:95]
	v_mfma_f32_16x16x32_bf16 v[88:91], v[158:161], v[186:189], v[88:91]
	v_mfma_f32_16x16x32_bf16 v[76:79], v[140:143], v[194:197], v[76:79]
	v_mfma_f32_16x16x32_bf16 v[72:75], v[158:161], v[194:197], v[72:75]
	v_mfma_f32_16x16x32_bf16 v[124:127], v[146:149], v[174:177], v[124:127]
	v_mfma_f32_16x16x32_bf16 v[120:123], v[162:165], v[174:177], v[120:123]
	v_mfma_f32_16x16x32_bf16 v[108:111], v[146:149], v[182:185], v[108:111]
	v_mfma_f32_16x16x32_bf16 v[104:107], v[162:165], v[182:185], v[104:107]
	v_mfma_f32_16x16x32_bf16 v[92:95], v[146:149], v[190:193], v[92:95]
	v_mfma_f32_16x16x32_bf16 v[88:91], v[162:165], v[190:193], v[88:91]
	v_mfma_f32_16x16x32_bf16 v[76:79], v[146:149], v[198:201], v[76:79]
	v_mfma_f32_16x16x32_bf16 v[72:75], v[162:165], v[198:201], v[72:75]
	s_setprio 0
	s_barrier
	s_add_i32 s42, s75, s66
	v_lshl_add_u64 v[150:151], s[14:15], 0, v[130:131]
	s_mov_b32 m0, s42
	ds_read_b128 v[202:205], v157
	ds_read_b128 v[206:209], v157 offset:1024
	ds_read_b128 v[210:213], v157 offset:2048
	ds_read_b128 v[214:217], v157 offset:3072
	global_load_lds_dwordx4 v[150:151], off
	v_lshl_add_u64 v[218:219], s[14:15], 0, v[134:135]
	s_add_i32 m0, s42, 0x2000
	s_nop 0
	global_load_lds_dwordx4 v[218:219], off
	s_barrier
	s_waitcnt lgkmcnt(0)
	s_setprio 1
	s_waitcnt lgkmcnt(0)
	v_mfma_f32_16x16x32_bf16 v[116:119], v[202:205], v[170:173], v[116:119]
	v_mfma_f32_16x16x32_bf16 v[112:115], v[210:213], v[170:173], v[112:115]
	v_mfma_f32_16x16x32_bf16 v[100:103], v[202:205], v[178:181], v[100:103]
	v_mfma_f32_16x16x32_bf16 v[96:99], v[210:213], v[178:181], v[96:99]
	v_mfma_f32_16x16x32_bf16 v[84:87], v[202:205], v[186:189], v[84:87]
	v_mfma_f32_16x16x32_bf16 v[80:83], v[210:213], v[186:189], v[80:83]
	v_mfma_f32_16x16x32_bf16 v[68:71], v[202:205], v[194:197], v[68:71]
	v_mfma_f32_16x16x32_bf16 v[64:67], v[210:213], v[194:197], v[64:67]
	v_mfma_f32_16x16x32_bf16 v[116:119], v[206:209], v[174:177], v[116:119]
	v_mfma_f32_16x16x32_bf16 v[112:115], v[214:217], v[174:177], v[112:115]
	v_mfma_f32_16x16x32_bf16 v[100:103], v[206:209], v[182:185], v[100:103]
	v_mfma_f32_16x16x32_bf16 v[96:99], v[214:217], v[182:185], v[96:99]
	v_mfma_f32_16x16x32_bf16 v[84:87], v[206:209], v[190:193], v[84:87]
	v_mfma_f32_16x16x32_bf16 v[80:83], v[214:217], v[190:193], v[80:83]
	v_mfma_f32_16x16x32_bf16 v[68:71], v[206:209], v[198:201], v[68:71]
	v_mfma_f32_16x16x32_bf16 v[64:67], v[214:217], v[198:201], v[64:67]
	s_setprio 0
	s_mov_b32 m0, s67
	v_lshl_add_u64 v[220:221], s[16:17], 0, v[128:129]
	s_barrier
	ds_read_b128 v[170:173], v156 offset:16384
	ds_read_b128 v[174:177], v156 offset:17408
	ds_read_b128 v[178:181], v156 offset:18432
	ds_read_b128 v[182:185], v156 offset:19456
	ds_read_b128 v[186:189], v156 offset:20480
	ds_read_b128 v[190:193], v156 offset:21504
	ds_read_b128 v[194:197], v156 offset:22528
	ds_read_b128 v[198:201], v156 offset:23552
	global_load_lds_dwordx4 v[220:221], off
	v_lshl_add_u64 v[222:223], s[16:17], 0, v[132:133]
	s_mov_b32 m0, s68
	s_nop 0
	global_load_lds_dwordx4 v[222:223], off
	s_barrier
	s_waitcnt lgkmcnt(0)
	s_setprio 1
	s_waitcnt lgkmcnt(0)
	v_mfma_f32_16x16x32_bf16 v[60:63], v[140:143], v[170:173], v[60:63]
	v_mfma_f32_16x16x32_bf16 v[56:59], v[158:161], v[170:173], v[56:59]
	v_mfma_f32_16x16x32_bf16 v[44:47], v[140:143], v[178:181], v[44:47]
	v_mfma_f32_16x16x32_bf16 v[40:43], v[158:161], v[178:181], v[40:43]
	v_mfma_f32_16x16x32_bf16 v[28:31], v[140:143], v[186:189], v[28:31]
	v_mfma_f32_16x16x32_bf16 v[24:27], v[158:161], v[186:189], v[24:27]
	v_mfma_f32_16x16x32_bf16 v[12:15], v[140:143], v[194:197], v[12:15]
	v_mfma_f32_16x16x32_bf16 v[8:11], v[158:161], v[194:197], v[8:11]
	v_mfma_f32_16x16x32_bf16 v[60:63], v[146:149], v[174:177], v[60:63]
	v_mfma_f32_16x16x32_bf16 v[56:59], v[162:165], v[174:177], v[56:59]
	v_mfma_f32_16x16x32_bf16 v[44:47], v[146:149], v[182:185], v[44:47]
	v_mfma_f32_16x16x32_bf16 v[40:43], v[162:165], v[182:185], v[40:43]
	v_mfma_f32_16x16x32_bf16 v[28:31], v[146:149], v[190:193], v[28:31]
	v_mfma_f32_16x16x32_bf16 v[24:27], v[162:165], v[190:193], v[24:27]
	v_mfma_f32_16x16x32_bf16 v[12:15], v[146:149], v[198:201], v[12:15]
	v_mfma_f32_16x16x32_bf16 v[8:11], v[162:165], v[198:201], v[8:11]
	s_setprio 0
	s_barrier
; #define PG8_STAGE(bufoff, gbase, voff) do { _Pragma("unroll") for (int _i = 0; _i < 2; ++_i) \
;         __builtin_amdgcn_global_load_lds((const unsigned*)((const char*)(gbase) + (voff)[_i]), (LAS unsigned*)(lds + (bufoff) + ldsw + _i * 8192), 16, 0, 0); } while (0)
; #define PG8_LDA(dst, b, h) do { _Pragma("unroll") for (int m = 0; m < 4; ++m) _Pragma("unroll") for (int k = 0; k < 2; ++k) dst[m][k] = *(const LAS bf16x8*)(lds + PG8_SA(b, h) + aoff + m * 2048 + k * 1024); } while (0)
; #define PG8_LDB(dst, b, h) do { _Pragma("unroll") for (int n = 0; n < 2; ++n) _Pragma("unroll") for (int k = 0; k < 2; ++k) dst[n][k] = *(const LAS bf16x8*)(lds + PG8_SB(b, h) + boff + n * 2048 + k * 1024); } while (0)
; #define PG8_MMA(ai, bj, At, Bt) do { __builtin_amdgcn_s_setprio(1); _Pragma("unroll") for (int m = 0; m < 4; ++m) _Pragma("unroll") for (int n = 0; n < 2; ++n) _Pragma("unroll") for (int k = 0; k < 2; ++k) \
;         acc[ai][bj][m][n] = __builtin_amdgcn_mfma_f32_16x16x32_bf16(Bt[n][k], At[m][k], acc[ai][bj][m][n], 0, 0, 0); __builtin_amdgcn_s_setprio(0); } while (0)
; #define PG8_WAIT_V(n) asm volatile("s_waitcnt vmcnt(" #n ")" ::: "memory")
; #define PG8_WAIT_L(n) asm volatile("s_waitcnt lgkmcnt(" #n ")" ::: "memory")
; #define PG8_BAR __builtin_amdgcn_s_barrier()
; #define PG8_SCHED __builtin_amdgcn_sched_barrier(0)
;     ...
;             PG8_STAGE(PG8_SB(0, 1), b2 + hB, voffB);
;             PG8_WAIT_V(6); PG8_BAR; PG8_MMA(1, 1, At, B1); PG8_BAR;
;             PG8_LDB(B0, 1, 0); PG8_SCHED; PG8_LDA(At, 1, 0); PG8_STAGE(PG8_SA(0, 1), a2 + hA, voffA);
;             PG8_WAIT_L(8); PG8_BAR; PG8_WAIT_L(0); PG8_MMA(0, 0, At, B0); PG8_BAR; PG8_SCHED;
;             PG8_LDB(B1, 1, 1); PG8_STAGE(PG8_SB(1, 0), b3, voffB);
;             PG8_BAR; PG8_WAIT_L(0); PG8_MMA(0, 1, At, B1); PG8_BAR;
;             PG8_LDA(At, 1, 1); PG8_STAGE(PG8_SA(1, 0), a3, voffA);
;             PG8_BAR; PG8_WAIT_L(0); PG8_MMA(1, 0, At, B0); PG8_BAR; PG8_SCHED;
	s_add_u32 s42, s14, 0x20000
	s_addc_u32 s43, s15, 0
	s_add_i32 s44, s76, s66
	v_lshl_add_u64 v[140:141], s[42:43], 0, v[130:131]
	s_mov_b32 m0, s44
	s_nop 0
	global_load_lds_dwordx4 v[140:141], off
	v_lshl_add_u64 v[140:141], s[42:43], 0, v[134:135]
	s_add_i32 m0, s44, 0x2000
	s_nop 0
	global_load_lds_dwordx4 v[140:141], off
	s_waitcnt vmcnt(6)
	s_barrier
	s_setprio 1
	v_mfma_f32_16x16x32_bf16 v[52:55], v[202:205], v[170:173], v[52:55]
	v_mfma_f32_16x16x32_bf16 v[48:51], v[210:213], v[170:173], v[48:51]
	v_mfma_f32_16x16x32_bf16 v[36:39], v[202:205], v[178:181], v[36:39]
	v_mfma_f32_16x16x32_bf16 v[32:35], v[210:213], v[178:181], v[32:35]
	v_mfma_f32_16x16x32_bf16 v[20:23], v[202:205], v[186:189], v[20:23]
	v_mfma_f32_16x16x32_bf16 v[16:19], v[210:213], v[186:189], v[16:19]
	v_mfma_f32_16x16x32_bf16 v[4:7], v[202:205], v[194:197], v[4:7]
	v_mfma_f32_16x16x32_bf16 v[0:3], v[210:213], v[194:197], v[0:3]
	v_mfma_f32_16x16x32_bf16 v[52:55], v[206:209], v[174:177], v[52:55]
	v_mfma_f32_16x16x32_bf16 v[48:51], v[214:217], v[174:177], v[48:51]
	v_mfma_f32_16x16x32_bf16 v[36:39], v[206:209], v[182:185], v[36:39]
	v_mfma_f32_16x16x32_bf16 v[32:35], v[214:217], v[182:185], v[32:35]
	v_mfma_f32_16x16x32_bf16 v[20:23], v[206:209], v[190:193], v[20:23]
	v_mfma_f32_16x16x32_bf16 v[16:19], v[214:217], v[190:193], v[16:19]
	v_mfma_f32_16x16x32_bf16 v[4:7], v[206:209], v[198:201], v[4:7]
	v_mfma_f32_16x16x32_bf16 v[0:3], v[214:217], v[198:201], v[0:3]
	s_setprio 0
	s_add_i32 s42, 0, 0x18000
	v_add_u32_e32 v162, s42, v153
	s_barrier
	ds_read_b128 v[140:143], v162
	ds_read_b128 v[146:149], v162 offset:1024
	ds_read_b128 v[158:161], v162 offset:2048
	ds_read_b128 v[162:165], v162 offset:3072
	s_add_u32 s16, s16, 0x20000
	s_addc_u32 s17, s17, 0
	s_mov_b32 m0, s69
	v_lshl_add_u64 v[202:203], s[16:17], 0, v[128:129]
	ds_read_b128 v[170:173], v156 offset:32768
	ds_read_b128 v[174:177], v156 offset:33792
	ds_read_b128 v[178:181], v156 offset:34816
	ds_read_b128 v[182:185], v156 offset:35840
	ds_read_b128 v[186:189], v156 offset:36864
	ds_read_b128 v[190:193], v156 offset:37888
	ds_read_b128 v[194:197], v156 offset:38912
	ds_read_b128 v[198:201], v156 offset:39936
	global_load_lds_dwordx4 v[202:203], off
	v_lshl_add_u64 v[202:203], s[16:17], 0, v[132:133]
	s_mov_b32 m0, s70
	s_nop 0
	global_load_lds_dwordx4 v[202:203], off
	s_waitcnt lgkmcnt(8)
	s_barrier
	s_waitcnt lgkmcnt(0)
	s_setprio 1
	s_waitcnt lgkmcnt(0)
	v_mfma_f32_16x16x32_bf16 v[124:127], v[140:143], v[170:173], v[124:127]
	v_mfma_f32_16x16x32_bf16 v[120:123], v[158:161], v[170:173], v[120:123]
	v_mfma_f32_16x16x32_bf16 v[108:111], v[140:143], v[178:181], v[108:111]
	v_mfma_f32_16x16x32_bf16 v[104:107], v[158:161], v[178:181], v[104:107]
	v_mfma_f32_16x16x32_bf16 v[92:95], v[140:143], v[186:189], v[92:95]
	v_mfma_f32_16x16x32_bf16 v[88:91], v[158:161], v[186:189], v[88:91]
	v_mfma_f32_16x16x32_bf16 v[76:79], v[140:143], v[194:197], v[76:79]
	v_mfma_f32_16x16x32_bf16 v[72:75], v[158:161], v[194:197], v[72:75]
	v_mfma_f32_16x16x32_bf16 v[124:127], v[146:149], v[174:177], v[124:127]
	v_mfma_f32_16x16x32_bf16 v[120:123], v[162:165], v[174:177], v[120:123]
	v_mfma_f32_16x16x32_bf16 v[108:111], v[146:149], v[182:185], v[108:111]
	v_mfma_f32_16x16x32_bf16 v[104:107], v[162:165], v[182:185], v[104:107]
	v_mfma_f32_16x16x32_bf16 v[92:95], v[146:149], v[190:193], v[92:95]
	v_mfma_f32_16x16x32_bf16 v[88:91], v[162:165], v[190:193], v[88:91]
	v_mfma_f32_16x16x32_bf16 v[76:79], v[146:149], v[198:201], v[76:79]
	v_mfma_f32_16x16x32_bf16 v[72:75], v[162:165], v[198:201], v[72:75]
	s_setprio 0
	s_barrier
	s_add_i32 s16, 0, 0x1c000
	s_add_i32 s17, s42, s66
	v_add_u32_e32 v214, s16, v153
	v_lshl_add_u64 v[150:151], v[150:151], 0, s[40:41]
	s_mov_b32 m0, s17
	ds_read_b128 v[202:205], v214
	ds_read_b128 v[206:209], v214 offset:1024
	ds_read_b128 v[210:213], v214 offset:2048
	ds_read_b128 v[214:217], v214 offset:3072
	global_load_lds_dwordx4 v[150:151], off
	v_lshl_add_u64 v[150:151], v[218:219], 0, s[40:41]
	s_add_i32 m0, s17, 0x2000
	s_nop 0
	global_load_lds_dwordx4 v[150:151], off
	s_barrier
	s_waitcnt lgkmcnt(0)
	s_setprio 1
	s_waitcnt lgkmcnt(0)
	v_mfma_f32_16x16x32_bf16 v[116:119], v[202:205], v[170:173], v[116:119]
	v_mfma_f32_16x16x32_bf16 v[112:115], v[210:213], v[170:173], v[112:115]
	v_mfma_f32_16x16x32_bf16 v[100:103], v[202:205], v[178:181], v[100:103]
	v_mfma_f32_16x16x32_bf16 v[96:99], v[210:213], v[178:181], v[96:99]
	v_mfma_f32_16x16x32_bf16 v[84:87], v[202:205], v[186:189], v[84:87]
	v_mfma_f32_16x16x32_bf16 v[80:83], v[210:213], v[186:189], v[80:83]
	v_mfma_f32_16x16x32_bf16 v[68:71], v[202:205], v[194:197], v[68:71]
	v_mfma_f32_16x16x32_bf16 v[64:67], v[210:213], v[194:197], v[64:67]
	v_mfma_f32_16x16x32_bf16 v[116:119], v[206:209], v[174:177], v[116:119]
	v_mfma_f32_16x16x32_bf16 v[112:115], v[214:217], v[174:177], v[112:115]
	v_mfma_f32_16x16x32_bf16 v[100:103], v[206:209], v[182:185], v[100:103]
	v_mfma_f32_16x16x32_bf16 v[96:99], v[214:217], v[182:185], v[96:99]
	v_mfma_f32_16x16x32_bf16 v[84:87], v[206:209], v[190:193], v[84:87]
	v_mfma_f32_16x16x32_bf16 v[80:83], v[214:217], v[190:193], v[80:83]
	v_mfma_f32_16x16x32_bf16 v[68:71], v[206:209], v[198:201], v[68:71]
	v_mfma_f32_16x16x32_bf16 v[64:67], v[214:217], v[198:201], v[64:67]
	s_setprio 0
	s_mov_b32 m0, s72
	v_lshl_add_u64 v[150:151], v[220:221], 0, s[40:41]
	s_barrier
	ds_read_b128 v[170:173], v156 offset:49152
	ds_read_b128 v[174:177], v156 offset:50176
	ds_read_b128 v[178:181], v156 offset:51200
	ds_read_b128 v[182:185], v156 offset:52224
	ds_read_b128 v[186:189], v156 offset:53248
	ds_read_b128 v[190:193], v156 offset:54272
	ds_read_b128 v[194:197], v156 offset:55296
	ds_read_b128 v[198:201], v156 offset:56320
	global_load_lds_dwordx4 v[150:151], off
	v_lshl_add_u64 v[150:151], v[222:223], 0, s[40:41]
	s_mov_b32 m0, s73
	s_nop 0
	global_load_lds_dwordx4 v[150:151], off
	s_barrier
; __device__ __forceinline__ float sigmoidf_(float x) { return 1.0f / (1.0f + __expf(-x)); }
; #define PG8_STAGE(bufoff, gbase, voff) do { _Pragma("unroll") for (int _i = 0; _i < 2; ++_i) \
;         __builtin_amdgcn_global_load_lds((const unsigned*)((const char*)(gbase) + (voff)[_i]), (LAS unsigned*)(lds + (bufoff) + ldsw + _i * 8192), 16, 0, 0); } while (0)
; #define PG8_MMA(ai, bj, At, Bt) do { __builtin_amdgcn_s_setprio(1); _Pragma("unroll") for (int m = 0; m < 4; ++m) _Pragma("unroll") for (int n = 0; n < 2; ++n) _Pragma("unroll") for (int k = 0; k < 2; ++k) \
;         acc[ai][bj][m][n] = __builtin_amdgcn_mfma_f32_16x16x32_bf16(Bt[n][k], At[m][k], acc[ai][bj][m][n], 0, 0, 0); __builtin_amdgcn_s_setprio(0); } while (0)
; #define PG8_WAIT_V(n) asm volatile("s_waitcnt vmcnt(" #n ")" ::: "memory")
; #define PG8_WAIT_L(n) asm volatile("s_waitcnt lgkmcnt(" #n ")" ::: "memory")
; #define PG8_BAR __builtin_amdgcn_s_barrier()
; #define PG8_SCHED __builtin_amdgcn_sched_barrier(0)
; __device__ __forceinline__ void unpack8(const u32x4 w, f32x4& v0, f32x4& v1) { v0 = (f32x4){bflo(w.x), bfhi(w.x), bflo(w.y), bfhi(w.y)}; v1 = (f32x4){bflo(w.z), bfhi(w.z), bflo(w.w), bfhi(w.w)}; }
;     ...
;             PG8_BAR; PG8_WAIT_L(0); PG8_MMA(1, 0, At, B0); PG8_BAR; PG8_SCHED;
;             PG8_STAGE(PG8_SB(1, 1), b3 + hB, voffB);
;             PG8_WAIT_V(6); PG8_BAR; PG8_MMA(1, 1, At, B1); PG8_BAR;
;         }
;         E(acc, cur, wr, wc, fr, fq);
;     __device__ __forceinline__ void operator()(const f32x4 (&acc)[2][2][4][2], const Unit& u, int wr, int wc, int fr, int fq) const {
;     ...
;                 const int row = row0 + ai * 128 + m * 16;
;                 const bf16_t* rowp = z + (size_t)row * DIN + col0;
; #pragma unroll
;                 for (int bj = 0; bj < 2; ++bj) {
;                     const u32x4 gw = *(const u32x4*)(rowp + O_GA + bj * 128);
;                     f32x4 g0, g1; unpack8(gw, g0, g1);
;                     f32x4 v0, v1;
; #pragma unroll
;                     for (int j = 0; j < 4; ++j) { v0[j] = sigmoidf_(g0[j]) * acc[ai][bj][m][0][j]; v1[j] = sigmoidf_(g1[j]) * acc[ai][bj][m][1][j]; }
	s_waitcnt lgkmcnt(0)
	s_setprio 1
	s_waitcnt lgkmcnt(0)
	v_mfma_f32_16x16x32_bf16 v[60:63], v[140:143], v[170:173], v[60:63]
	v_mfma_f32_16x16x32_bf16 v[56:59], v[158:161], v[170:173], v[56:59]
	v_mfma_f32_16x16x32_bf16 v[44:47], v[140:143], v[178:181], v[44:47]
	v_mfma_f32_16x16x32_bf16 v[40:43], v[158:161], v[178:181], v[40:43]
	v_mfma_f32_16x16x32_bf16 v[28:31], v[140:143], v[186:189], v[28:31]
	v_mfma_f32_16x16x32_bf16 v[24:27], v[158:161], v[186:189], v[24:27]
	v_mfma_f32_16x16x32_bf16 v[12:15], v[140:143], v[194:197], v[12:15]
	v_mfma_f32_16x16x32_bf16 v[8:11], v[158:161], v[194:197], v[8:11]
	v_mfma_f32_16x16x32_bf16 v[60:63], v[146:149], v[174:177], v[60:63]
	v_mfma_f32_16x16x32_bf16 v[56:59], v[162:165], v[174:177], v[56:59]
	v_mfma_f32_16x16x32_bf16 v[44:47], v[146:149], v[182:185], v[44:47]
	v_mfma_f32_16x16x32_bf16 v[40:43], v[162:165], v[182:185], v[40:43]
	v_mfma_f32_16x16x32_bf16 v[28:31], v[146:149], v[190:193], v[28:31]
	v_mfma_f32_16x16x32_bf16 v[24:27], v[162:165], v[190:193], v[24:27]
	v_mfma_f32_16x16x32_bf16 v[12:15], v[146:149], v[198:201], v[12:15]
	v_mfma_f32_16x16x32_bf16 v[8:11], v[162:165], v[198:201], v[8:11]
	s_setprio 0
	s_barrier
	s_add_u32 s14, s14, 0x20080
	s_addc_u32 s15, s15, 0
	s_add_i32 s16, s16, s66
	v_lshl_add_u64 v[140:141], s[14:15], 0, v[130:131]
	s_mov_b32 m0, s16
	s_nop 0
	global_load_lds_dwordx4 v[140:141], off
	v_lshl_add_u64 v[140:141], s[14:15], 0, v[134:135]
	s_add_i32 m0, s16, 0x2000
	s_nop 0
	global_load_lds_dwordx4 v[140:141], off
	s_waitcnt vmcnt(6)
	s_barrier
	s_setprio 1
	v_mfma_f32_16x16x32_bf16 v[52:55], v[202:205], v[170:173], v[52:55]
	v_mfma_f32_16x16x32_bf16 v[48:51], v[210:213], v[170:173], v[48:51]
	v_mfma_f32_16x16x32_bf16 v[36:39], v[202:205], v[178:181], v[36:39]
	v_mfma_f32_16x16x32_bf16 v[32:35], v[210:213], v[178:181], v[32:35]
	v_mfma_f32_16x16x32_bf16 v[20:23], v[202:205], v[186:189], v[20:23]
	v_mfma_f32_16x16x32_bf16 v[16:19], v[210:213], v[186:189], v[16:19]
	v_mfma_f32_16x16x32_bf16 v[4:7], v[202:205], v[194:197], v[4:7]
	v_mfma_f32_16x16x32_bf16 v[0:3], v[210:213], v[194:197], v[0:3]
	v_mfma_f32_16x16x32_bf16 v[52:55], v[206:209], v[174:177], v[52:55]
	v_mfma_f32_16x16x32_bf16 v[48:51], v[214:217], v[174:177], v[48:51]
	v_mfma_f32_16x16x32_bf16 v[36:39], v[206:209], v[182:185], v[36:39]
	v_mfma_f32_16x16x32_bf16 v[32:35], v[214:217], v[182:185], v[32:35]
	v_mfma_f32_16x16x32_bf16 v[20:23], v[206:209], v[190:193], v[20:23]
	v_mfma_f32_16x16x32_bf16 v[16:19], v[214:217], v[190:193], v[16:19]
	v_mfma_f32_16x16x32_bf16 v[4:7], v[206:209], v[198:201], v[4:7]
	v_mfma_f32_16x16x32_bf16 v[0:3], v[214:217], v[198:201], v[0:3]
	s_setprio 0
	s_add_i32 s39, s39, 2
	s_add_u32 s19, s19, 0x100
	s_addc_u32 s33, s33, 0
	s_add_u32 s12, s12, 0x100
	s_addc_u32 s13, s13, 0
	s_cmp_gt_u32 s39, 5
	s_barrier
	s_cbranch_scc0 .LBB0_723
	v_lshl_add_u32 v158, s79, 8, v152
	v_lshl_or_b32 v140, s6, 8, v154
	v_add_u32_e32 v142, 0x4000, v158
	v_ashrrev_i32_e32 v141, 31, v140
	v_mad_i64_i32 v[150:151], s[6:7], v142, s77, 0
	v_lshl_add_u64 v[146:147], v[150:151], 1, s[26:27]
	v_lshlrev_b64 v[142:143], 1, v[140:141]
	v_lshl_add_u64 v[146:147], v[146:147], 0, v[142:143]
	v_add_co_u32_e32 v148, vcc, 0x1000, v146
	s_nop 1
	v_addc_co_u32_e32 v149, vcc, 0, v147, vcc
	v_subrev_u32_e32 v198, s26, v146
	v_add_u32_e32 v199, 0x1200, v198
	global_load_dwordx4 v[200:203], v199, s[26:27]
	v_add_u32_e32 v199, 0x0, v198
	global_load_dwordx4 v[204:207], v199, s[26:27]
	v_add_u32_e32 v199, 0x1300, v198
	global_load_dwordx4 v[208:211], v199, s[26:27]
	v_add_u32_e32 v199, 0x100, v198
	global_load_dwordx4 v[212:215], v199, s[26:27]
	v_add_u32_e32 v199, 0x23200, v198
	global_load_dwordx4 v[232:235], v199, s[26:27]
	v_add_u32_e32 v199, 0x22000, v198
	global_load_dwordx4 v[236:239], v199, s[26:27]
	s_waitcnt vmcnt(4)
	v_mov_b32_e32 v160, v200
	v_mov_b32_e32 v161, v201
	v_mov_b32_e32 v162, v202
	v_mov_b32_e32 v163, v203
	v_mov_b32_e32 v170, v204
	v_mov_b32_e32 v171, v205
	v_mov_b32_e32 v172, v206
	v_mov_b32_e32 v173, v207
	v_add_u32_e32 v199, 0x23300, v198
	global_load_dwordx4 v[200:203], v199, s[26:27]
	v_add_u32_e32 v199, 0x22100, v198
	global_load_dwordx4 v[204:207], v199, s[26:27]
	s_mov_b32 s100, 0xbfb8aa3b
	v_lshlrev_b32_e32 v240, 16, v160
	v_and_b32_e32 v241, 0xffff0000, v160
	v_lshlrev_b32_e32 v242, 16, v162
	v_and_b32_e32 v243, 0xffff0000, v162
	v_lshlrev_b32_e32 v244, 16, v161
	v_and_b32_e32 v245, 0xffff0000, v161
	v_lshlrev_b32_e32 v246, 16, v163
	v_and_b32_e32 v247, 0xffff0000, v163
	v_pk_mul_f32 v[240:241], v[240:241], s[100:101] op_sel_hi:[1,0]
	v_pk_mul_f32 v[242:243], v[242:243], s[100:101] op_sel_hi:[1,0]
	v_pk_mul_f32 v[244:245], v[244:245], s[100:101] op_sel_hi:[1,0]
	v_pk_mul_f32 v[246:247], v[246:247], s[100:101] op_sel_hi:[1,0]
	v_exp_f32_e32 v240, v240
	v_exp_f32_e32 v241, v241
	v_exp_f32_e32 v242, v242
	v_exp_f32_e32 v243, v243
	v_exp_f32_e32 v244, v244
	v_exp_f32_e32 v245, v245
	v_exp_f32_e32 v246, v246
	v_exp_f32_e32 v247, v247
	s_nop 0
	v_pk_add_f32 v[240:241], v[240:241], 1.0 op_sel_hi:[1,0]
	v_pk_add_f32 v[242:243], v[242:243], 1.0 op_sel_hi:[1,0]
	v_pk_add_f32 v[244:245], v[244:245], 1.0 op_sel_hi:[1,0]
	v_pk_add_f32 v[246:247], v[246:247], 1.0 op_sel_hi:[1,0]
	v_rcp_f32_e32 v248, v240
	v_rcp_f32_e32 v249, v241
	v_rcp_f32_e32 v254, v242
	v_rcp_f32_e32 v255, v243
	v_pk_fma_f32 v[250:251], v[240:241], v[248:249], 1.0 op_sel_hi:[1,1,0] neg_lo:[1,0,0] neg_hi:[1,0,0]
	v_pk_fma_f32 v[160:161], v[242:243], v[254:255], 1.0 op_sel_hi:[1,1,0] neg_lo:[1,0,0] neg_hi:[1,0,0]
	v_pk_fma_f32 v[248:249], v[250:251], v[248:249], v[248:249]
	v_pk_fma_f32 v[254:255], v[160:161], v[254:255], v[254:255]
; __device__ __forceinline__ float sigmoidf_(float x) { return 1.0f / (1.0f + __expf(-x)); }
; __device__ __forceinline__ u32x4 pack8(const f32x4 v0, const f32x4 v1) { u32x4 w; w.x = pk2(v0[0], v0[1]); w.y = pk2(v0[2], v0[3]); w.z = pk2(v1[0], v1[1]); w.w = pk2(v1[2], v1[3]); return w; }
; __device__ __forceinline__ void unpack8(const u32x4 w, f32x4& v0, f32x4& v1) { v0 = (f32x4){bflo(w.x), bfhi(w.x), bflo(w.y), bfhi(w.y)}; v1 = (f32x4){bflo(w.z), bfhi(w.z), bflo(w.w), bfhi(w.w)}; }
;     __device__ __forceinline__ void operator()(const f32x4 (&acc)[2][2][4][2], const Unit& u, int wr, int wc, int fr, int fq) const {
;     ...
;                 const int row = row0 + ai * 128 + m * 16;
;                 const bf16_t* rowp = z + (size_t)row * DIN + col0;
; #pragma unroll
;                 for (int bj = 0; bj < 2; ++bj) {
;                     const u32x4 gw = *(const u32x4*)(rowp + O_GA + bj * 128);
;                     f32x4 g0, g1; unpack8(gw, g0, g1);
;                     f32x4 v0, v1;
; #pragma unroll
;                     for (int j = 0; j < 4; ++j) { v0[j] = sigmoidf_(g0[j]) * acc[ai][bj][m][0][j]; v1[j] = sigmoidf_(g1[j]) * acc[ai][bj][m][1][j]; }
;                     const u32x4 mw = *(const u32x4*)(rowp + bj * 128); f32x4 m0, m1; unpack8(mw, m0, m1); v0 += m0; v1 += m1;
;                     __builtin_amdgcn_raw_buffer_store_b128(pack8(v0, v1), rsrc, (unsigned)(((size_t)row * DIN + col0 + bj * 128) * 2), 0, 16  ); }
	v_pk_fma_f32 v[250:251], v[240:241], v[248:249], 1.0 op_sel_hi:[1,1,0] neg_lo:[1,0,0] neg_hi:[1,0,0]
	v_pk_fma_f32 v[160:161], v[242:243], v[254:255], 1.0 op_sel_hi:[1,1,0] neg_lo:[1,0,0] neg_hi:[1,0,0]
	v_pk_fma_f32 v[252:253], v[250:251], v[248:249], v[248:249]
	v_pk_fma_f32 v[162:163], v[160:161], v[254:255], v[254:255]
	v_pk_fma_f32 v[250:251], v[240:241], v[252:253], 1.0 op_sel_hi:[1,1,0] neg_lo:[1,0,0] neg_hi:[1,0,0]
	v_pk_fma_f32 v[160:161], v[242:243], v[162:163], 1.0 op_sel_hi:[1,1,0] neg_lo:[1,0,0] neg_hi:[1,0,0]
	v_pk_fma_f32 v[252:253], v[250:251], v[248:249], v[252:253]
	v_pk_fma_f32 v[162:163], v[160:161], v[254:255], v[162:163]
	v_div_fixup_f32 v240, v252, v240, 1.0
	v_div_fixup_f32 v241, v253, v241, 1.0
	v_div_fixup_f32 v242, v162, v242, 1.0
	v_div_fixup_f32 v243, v163, v243, 1.0
	v_rcp_f32_e32 v248, v244
	v_rcp_f32_e32 v249, v245
	v_rcp_f32_e32 v254, v246
	v_rcp_f32_e32 v255, v247
	v_pk_fma_f32 v[250:251], v[244:245], v[248:249], 1.0 op_sel_hi:[1,1,0] neg_lo:[1,0,0] neg_hi:[1,0,0]
	v_pk_fma_f32 v[160:161], v[246:247], v[254:255], 1.0 op_sel_hi:[1,1,0] neg_lo:[1,0,0] neg_hi:[1,0,0]
	v_pk_fma_f32 v[248:249], v[250:251], v[248:249], v[248:249]
	v_pk_fma_f32 v[254:255], v[160:161], v[254:255], v[254:255]
	v_pk_fma_f32 v[250:251], v[244:245], v[248:249], 1.0 op_sel_hi:[1,1,0] neg_lo:[1,0,0] neg_hi:[1,0,0]
	v_pk_fma_f32 v[160:161], v[246:247], v[254:255], 1.0 op_sel_hi:[1,1,0] neg_lo:[1,0,0] neg_hi:[1,0,0]
	v_pk_fma_f32 v[252:253], v[250:251], v[248:249], v[248:249]
	v_pk_fma_f32 v[162:163], v[160:161], v[254:255], v[254:255]
	v_pk_fma_f32 v[250:251], v[244:245], v[252:253], 1.0 op_sel_hi:[1,1,0] neg_lo:[1,0,0] neg_hi:[1,0,0]
	v_pk_fma_f32 v[160:161], v[246:247], v[162:163], 1.0 op_sel_hi:[1,1,0] neg_lo:[1,0,0] neg_hi:[1,0,0]
	v_pk_fma_f32 v[252:253], v[250:251], v[248:249], v[252:253]
	v_pk_fma_f32 v[162:163], v[160:161], v[254:255], v[162:163]
	v_div_fixup_f32 v244, v252, v244, 1.0
	v_div_fixup_f32 v245, v253, v245, 1.0
	v_div_fixup_f32 v246, v162, v246, 1.0
	v_div_fixup_f32 v247, v163, v247, 1.0
	s_mov_b64 vcc, s[12:13]
	s_mov_b64 vcc, s[14:15]
	s_mov_b64 vcc, s[16:17]
	s_mov_b64 vcc, s[18:19]
	v_lshlrev_b32_e32 v178, 16, v172
	v_and_b32_e32 v179, 0xffff0000, v172
	v_lshlrev_b32_e32 v176, 16, v170
	v_and_b32_e32 v177, 0xffff0000, v170
	v_lshlrev_b32_e32 v172, 16, v173
	v_and_b32_e32 v173, 0xffff0000, v173
	v_lshlrev_b32_e32 v170, 16, v171
	v_and_b32_e32 v171, 0xffff0000, v171
	v_pk_fma_f32 v[124:125], v[124:125], v[240:241], v[176:177]
	v_pk_fma_f32 v[160:161], v[122:123], v[246:247], v[172:173]
	v_pk_fma_f32 v[122:123], v[120:121], v[242:243], v[178:179]
	v_add_lshl_u32 v141, v140, v150, 1
	v_pk_fma_f32 v[126:127], v[126:127], v[244:245], v[170:171]
	v_cvt_pk_bf16_f32 v120, v124, v125
	s_nop 0
	v_cvt_pk_bf16_f32 v121, v126, v127
	v_cvt_pk_bf16_f32 v122, v122, v123
	v_cvt_pk_bf16_f32 v123, v160, v161
	buffer_store_dwordx4 v[120:123], v141, s[20:23], 0 offen sc1
	s_nop 0
	s_waitcnt vmcnt(5)
	v_mov_b32_e32 v120, v208
	v_mov_b32_e32 v121, v209
	v_mov_b32_e32 v122, v210
	v_mov_b32_e32 v123, v211
	v_mov_b32_e32 v124, v212
	v_mov_b32_e32 v125, v213
	v_mov_b32_e32 v126, v214
	v_mov_b32_e32 v127, v215
	v_add_u32_e32 v199, 0x45200, v198
	global_load_dwordx4 v[208:211], v199, s[26:27]
	v_add_u32_e32 v199, 0x44000, v198
	global_load_dwordx4 v[212:215], v199, s[26:27]
	s_mov_b32 s100, 0xbfb8aa3b
	v_lshlrev_b32_e32 v240, 16, v120
	v_and_b32_e32 v241, 0xffff0000, v120
	v_lshlrev_b32_e32 v242, 16, v122
	v_and_b32_e32 v243, 0xffff0000, v122
	v_lshlrev_b32_e32 v244, 16, v121
	v_and_b32_e32 v245, 0xffff0000, v121
	v_lshlrev_b32_e32 v246, 16, v123
	v_and_b32_e32 v247, 0xffff0000, v123
	v_pk_mul_f32 v[240:241], v[240:241], s[100:101] op_sel_hi:[1,0]
	v_pk_mul_f32 v[242:243], v[242:243], s[100:101] op_sel_hi:[1,0]
	v_pk_mul_f32 v[244:245], v[244:245], s[100:101] op_sel_hi:[1,0]
	v_pk_mul_f32 v[246:247], v[246:247], s[100:101] op_sel_hi:[1,0]
	v_exp_f32_e32 v240, v240
	v_exp_f32_e32 v241, v241
	v_exp_f32_e32 v242, v242
	v_exp_f32_e32 v243, v243
	v_exp_f32_e32 v244, v244
	v_exp_f32_e32 v245, v245
	v_exp_f32_e32 v246, v246
	v_exp_f32_e32 v247, v247
	s_nop 0
	v_pk_add_f32 v[240:241], v[240:241], 1.0 op_sel_hi:[1,0]
	v_pk_add_f32 v[242:243], v[242:243], 1.0 op_sel_hi:[1,0]
	v_pk_add_f32 v[244:245], v[244:245], 1.0 op_sel_hi:[1,0]
	v_pk_add_f32 v[246:247], v[246:247], 1.0 op_sel_hi:[1,0]
	v_rcp_f32_e32 v248, v240
	v_rcp_f32_e32 v249, v241
	v_rcp_f32_e32 v254, v242
	v_rcp_f32_e32 v255, v243
	v_pk_fma_f32 v[250:251], v[240:241], v[248:249], 1.0 op_sel_hi:[1,1,0] neg_lo:[1,0,0] neg_hi:[1,0,0]
	v_pk_fma_f32 v[120:121], v[242:243], v[254:255], 1.0 op_sel_hi:[1,1,0] neg_lo:[1,0,0] neg_hi:[1,0,0]
	v_pk_fma_f32 v[248:249], v[250:251], v[248:249], v[248:249]
	v_pk_fma_f32 v[254:255], v[120:121], v[254:255], v[254:255]
	v_pk_fma_f32 v[250:251], v[240:241], v[248:249], 1.0 op_sel_hi:[1,1,0] neg_lo:[1,0,0] neg_hi:[1,0,0]
	v_pk_fma_f32 v[120:121], v[242:243], v[254:255], 1.0 op_sel_hi:[1,1,0] neg_lo:[1,0,0] neg_hi:[1,0,0]
	v_pk_fma_f32 v[252:253], v[250:251], v[248:249], v[248:249]
	v_pk_fma_f32 v[122:123], v[120:121], v[254:255], v[254:255]
	v_pk_fma_f32 v[250:251], v[240:241], v[252:253], 1.0 op_sel_hi:[1,1,0] neg_lo:[1,0,0] neg_hi:[1,0,0]
	v_pk_fma_f32 v[120:121], v[242:243], v[122:123], 1.0 op_sel_hi:[1,1,0] neg_lo:[1,0,0] neg_hi:[1,0,0]
	v_pk_fma_f32 v[252:253], v[250:251], v[248:249], v[252:253]
	v_pk_fma_f32 v[122:123], v[120:121], v[254:255], v[122:123]
	v_div_fixup_f32 v240, v252, v240, 1.0
	v_div_fixup_f32 v241, v253, v241, 1.0
	v_div_fixup_f32 v242, v122, v242, 1.0
	v_div_fixup_f32 v243, v123, v243, 1.0
	v_rcp_f32_e32 v248, v244
	v_rcp_f32_e32 v249, v245
; __device__ __forceinline__ float sigmoidf_(float x) { return 1.0f / (1.0f + __expf(-x)); }
; __device__ __forceinline__ u32x4 pack8(const f32x4 v0, const f32x4 v1) { u32x4 w; w.x = pk2(v0[0], v0[1]); w.y = pk2(v0[2], v0[3]); w.z = pk2(v1[0], v1[1]); w.w = pk2(v1[2], v1[3]); return w; }
; __device__ __forceinline__ void unpack8(const u32x4 w, f32x4& v0, f32x4& v1) { v0 = (f32x4){bflo(w.x), bfhi(w.x), bflo(w.y), bfhi(w.y)}; v1 = (f32x4){bflo(w.z), bfhi(w.z), bflo(w.w), bfhi(w.w)}; }
;     __device__ __forceinline__ void operator()(const f32x4 (&acc)[2][2][4][2], const Unit& u, int wr, int wc, int fr, int fq) const {
;     ...
;                 const int row = row0 + ai * 128 + m * 16;
;                 const bf16_t* rowp = z + (size_t)row * DIN + col0;
; #pragma unroll
;                 for (int bj = 0; bj < 2; ++bj) {
;                     const u32x4 gw = *(const u32x4*)(rowp + O_GA + bj * 128);
;                     f32x4 g0, g1; unpack8(gw, g0, g1);
;                     f32x4 v0, v1;
; #pragma unroll
;                     for (int j = 0; j < 4; ++j) { v0[j] = sigmoidf_(g0[j]) * acc[ai][bj][m][0][j]; v1[j] = sigmoidf_(g1[j]) * acc[ai][bj][m][1][j]; }
;                     const u32x4 mw = *(const u32x4*)(rowp + bj * 128); f32x4 m0, m1; unpack8(mw, m0, m1); v0 += m0; v1 += m1;
;                     __builtin_amdgcn_raw_buffer_store_b128(pack8(v0, v1), rsrc, (unsigned)(((size_t)row * DIN + col0 + bj * 128) * 2), 0, 16  ); }
	v_rcp_f32_e32 v254, v246
	v_rcp_f32_e32 v255, v247
	v_pk_fma_f32 v[250:251], v[244:245], v[248:249], 1.0 op_sel_hi:[1,1,0] neg_lo:[1,0,0] neg_hi:[1,0,0]
	v_pk_fma_f32 v[120:121], v[246:247], v[254:255], 1.0 op_sel_hi:[1,1,0] neg_lo:[1,0,0] neg_hi:[1,0,0]
	v_pk_fma_f32 v[248:249], v[250:251], v[248:249], v[248:249]
	v_pk_fma_f32 v[254:255], v[120:121], v[254:255], v[254:255]
	v_pk_fma_f32 v[250:251], v[244:245], v[248:249], 1.0 op_sel_hi:[1,1,0] neg_lo:[1,0,0] neg_hi:[1,0,0]
	v_pk_fma_f32 v[120:121], v[246:247], v[254:255], 1.0 op_sel_hi:[1,1,0] neg_lo:[1,0,0] neg_hi:[1,0,0]
	v_pk_fma_f32 v[252:253], v[250:251], v[248:249], v[248:249]
	v_pk_fma_f32 v[122:123], v[120:121], v[254:255], v[254:255]
	v_pk_fma_f32 v[250:251], v[244:245], v[252:253], 1.0 op_sel_hi:[1,1,0] neg_lo:[1,0,0] neg_hi:[1,0,0]
	v_pk_fma_f32 v[120:121], v[246:247], v[122:123], 1.0 op_sel_hi:[1,1,0] neg_lo:[1,0,0] neg_hi:[1,0,0]
	v_pk_fma_f32 v[252:253], v[250:251], v[248:249], v[252:253]
	v_pk_fma_f32 v[122:123], v[120:121], v[254:255], v[122:123]
	v_div_fixup_f32 v244, v252, v244, 1.0
	v_div_fixup_f32 v245, v253, v245, 1.0
	v_div_fixup_f32 v246, v122, v246, 1.0
	v_div_fixup_f32 v247, v123, v247, 1.0
	v_lshlrev_b32_e32 v150, 16, v124
	v_and_b32_e32 v151, 0xffff0000, v124
	v_lshlrev_b32_e32 v160, 16, v126
	v_and_b32_e32 v161, 0xffff0000, v126
	v_lshlrev_b32_e32 v126, 16, v127
	v_and_b32_e32 v127, 0xffff0000, v127
	v_lshlrev_b32_e32 v124, 16, v125
	v_and_b32_e32 v125, 0xffff0000, v125
	v_pk_fma_f32 v[116:117], v[116:117], v[240:241], v[150:151]
	v_pk_fma_f32 v[120:121], v[114:115], v[246:247], v[126:127]
	v_pk_fma_f32 v[114:115], v[112:113], v[242:243], v[160:161]
	v_cvt_pk_bf16_f32 v112, v116, v117
	v_pk_fma_f32 v[118:119], v[118:119], v[244:245], v[124:125]
	s_nop 0
	v_cvt_pk_bf16_f32 v113, v118, v119
	v_cvt_pk_bf16_f32 v114, v114, v115
	v_cvt_pk_bf16_f32 v115, v120, v121
	buffer_store_dwordx4 v[112:115], v141, s[20:23], 0 offen offset:256 sc1
	s_nop 1
	v_add_u32_e32 v112, 0x4010, v158
	v_mad_i64_i32 v[114:115], s[6:7], v112, s77, 0
	v_lshl_add_u64 v[112:113], v[114:115], 1, s[26:27]
	v_lshl_add_u64 v[112:113], v[112:113], 0, v[142:143]
	v_add_co_u32_e32 v116, vcc, s78, v112
	s_nop 1
	v_addc_co_u32_e32 v117, vcc, 0, v113, vcc
	s_waitcnt vmcnt(6)
	v_mov_b32_e32 v118, v232
	v_mov_b32_e32 v119, v233
	v_mov_b32_e32 v120, v234
	v_mov_b32_e32 v121, v235
	v_mov_b32_e32 v122, v236
	v_mov_b32_e32 v123, v237
	v_mov_b32_e32 v124, v238
	v_mov_b32_e32 v125, v239
	v_add_u32_e32 v199, 0x45300, v198
	global_load_dwordx4 v[232:235], v199, s[26:27]
	v_add_u32_e32 v199, 0x44100, v198
	global_load_dwordx4 v[236:239], v199, s[26:27]
	s_mov_b32 s100, 0xbfb8aa3b
	v_lshlrev_b32_e32 v240, 16, v118
	v_and_b32_e32 v241, 0xffff0000, v118
	v_lshlrev_b32_e32 v242, 16, v120
	v_and_b32_e32 v243, 0xffff0000, v120
	v_lshlrev_b32_e32 v244, 16, v119
	v_and_b32_e32 v245, 0xffff0000, v119
	v_lshlrev_b32_e32 v246, 16, v121
	v_and_b32_e32 v247, 0xffff0000, v121
	v_pk_mul_f32 v[240:241], v[240:241], s[100:101] op_sel_hi:[1,0]
	v_pk_mul_f32 v[242:243], v[242:243], s[100:101] op_sel_hi:[1,0]
	v_pk_mul_f32 v[244:245], v[244:245], s[100:101] op_sel_hi:[1,0]
	v_pk_mul_f32 v[246:247], v[246:247], s[100:101] op_sel_hi:[1,0]
	v_exp_f32_e32 v240, v240
	v_exp_f32_e32 v241, v241
	v_exp_f32_e32 v242, v242
	v_exp_f32_e32 v243, v243
	v_exp_f32_e32 v244, v244
	v_exp_f32_e32 v245, v245
	v_exp_f32_e32 v246, v246
	v_exp_f32_e32 v247, v247
	s_nop 0
	v_pk_add_f32 v[240:241], v[240:241], 1.0 op_sel_hi:[1,0]
	v_pk_add_f32 v[242:243], v[242:243], 1.0 op_sel_hi:[1,0]
	v_pk_add_f32 v[244:245], v[244:245], 1.0 op_sel_hi:[1,0]
	v_pk_add_f32 v[246:247], v[246:247], 1.0 op_sel_hi:[1,0]
	v_rcp_f32_e32 v248, v240
	v_rcp_f32_e32 v249, v241
	v_rcp_f32_e32 v254, v242
	v_rcp_f32_e32 v255, v243
	v_pk_fma_f32 v[250:251], v[240:241], v[248:249], 1.0 op_sel_hi:[1,1,0] neg_lo:[1,0,0] neg_hi:[1,0,0]
	v_pk_fma_f32 v[118:119], v[242:243], v[254:255], 1.0 op_sel_hi:[1,1,0] neg_lo:[1,0,0] neg_hi:[1,0,0]
	v_pk_fma_f32 v[248:249], v[250:251], v[248:249], v[248:249]
	v_pk_fma_f32 v[254:255], v[118:119], v[254:255], v[254:255]
	v_pk_fma_f32 v[250:251], v[240:241], v[248:249], 1.0 op_sel_hi:[1,1,0] neg_lo:[1,0,0] neg_hi:[1,0,0]
	v_pk_fma_f32 v[118:119], v[242:243], v[254:255], 1.0 op_sel_hi:[1,1,0] neg_lo:[1,0,0] neg_hi:[1,0,0]
	v_pk_fma_f32 v[252:253], v[250:251], v[248:249], v[248:249]
	v_pk_fma_f32 v[120:121], v[118:119], v[254:255], v[254:255]
	v_pk_fma_f32 v[250:251], v[240:241], v[252:253], 1.0 op_sel_hi:[1,1,0] neg_lo:[1,0,0] neg_hi:[1,0,0]
	v_pk_fma_f32 v[118:119], v[242:243], v[120:121], 1.0 op_sel_hi:[1,1,0] neg_lo:[1,0,0] neg_hi:[1,0,0]
	v_pk_fma_f32 v[252:253], v[250:251], v[248:249], v[252:253]
	v_pk_fma_f32 v[120:121], v[118:119], v[254:255], v[120:121]
	v_div_fixup_f32 v240, v252, v240, 1.0
	v_div_fixup_f32 v241, v253, v241, 1.0
	v_div_fixup_f32 v242, v120, v242, 1.0
	v_div_fixup_f32 v243, v121, v243, 1.0
	v_rcp_f32_e32 v248, v244
	v_rcp_f32_e32 v249, v245
	v_rcp_f32_e32 v254, v246
	v_rcp_f32_e32 v255, v247
	v_pk_fma_f32 v[250:251], v[244:245], v[248:249], 1.0 op_sel_hi:[1,1,0] neg_lo:[1,0,0] neg_hi:[1,0,0]
	v_pk_fma_f32 v[118:119], v[246:247], v[254:255], 1.0 op_sel_hi:[1,1,0] neg_lo:[1,0,0] neg_hi:[1,0,0]
	v_pk_fma_f32 v[248:249], v[250:251], v[248:249], v[248:249]
	v_pk_fma_f32 v[254:255], v[118:119], v[254:255], v[254:255]
	v_pk_fma_f32 v[250:251], v[244:245], v[248:249], 1.0 op_sel_hi:[1,1,0] neg_lo:[1,0,0] neg_hi:[1,0,0]
	v_pk_fma_f32 v[118:119], v[246:247], v[254:255], 1.0 op_sel_hi:[1,1,0] neg_lo:[1,0,0] neg_hi:[1,0,0]
	v_pk_fma_f32 v[252:253], v[250:251], v[248:249], v[248:249]
	v_pk_fma_f32 v[120:121], v[118:119], v[254:255], v[254:255]
	v_pk_fma_f32 v[250:251], v[244:245], v[252:253], 1.0 op_sel_hi:[1,1,0] neg_lo:[1,0,0] neg_hi:[1,0,0]
	v_pk_fma_f32 v[118:119], v[246:247], v[120:121], 1.0 op_sel_hi:[1,1,0] neg_lo:[1,0,0] neg_hi:[1,0,0]
	v_pk_fma_f32 v[252:253], v[250:251], v[248:249], v[252:253]
	v_pk_fma_f32 v[120:121], v[118:119], v[254:255], v[120:121]
	v_div_fixup_f32 v244, v252, v244, 1.0
	v_div_fixup_f32 v245, v253, v245, 1.0
	v_div_fixup_f32 v246, v120, v246, 1.0
	v_div_fixup_f32 v247, v121, v247, 1.0
	v_and_b32_e32 v151, 0xffff0000, v124
	v_lshlrev_b32_e32 v148, 16, v122
	v_and_b32_e32 v149, 0xffff0000, v122
	v_lshlrev_b32_e32 v150, 16, v124
	v_lshlrev_b32_e32 v124, 16, v125
	v_and_b32_e32 v125, 0xffff0000, v125
	v_lshlrev_b32_e32 v122, 16, v123
	v_and_b32_e32 v123, 0xffff0000, v123
	v_pk_fma_f32 v[108:109], v[108:109], v[240:241], v[148:149]
	v_pk_fma_f32 v[118:119], v[106:107], v[246:247], v[124:125]
	v_pk_fma_f32 v[106:107], v[104:105], v[242:243], v[150:151]
	v_add_lshl_u32 v120, v140, v114, 1
	v_pk_fma_f32 v[110:111], v[110:111], v[244:245], v[122:123]
	v_cvt_pk_bf16_f32 v104, v108, v109
	s_nop 0
	v_cvt_pk_bf16_f32 v105, v110, v111
	v_cvt_pk_bf16_f32 v106, v106, v107
	v_cvt_pk_bf16_f32 v107, v118, v119
	buffer_store_dwordx4 v[104:107], v120, s[20:23], 0 offen sc1
	s_nop 0
	s_waitcnt vmcnt(7)
; __device__ __forceinline__ float sigmoidf_(float x) { return 1.0f / (1.0f + __expf(-x)); }
; __device__ __forceinline__ u32x4 pack8(const f32x4 v0, const f32x4 v1) { u32x4 w; w.x = pk2(v0[0], v0[1]); w.y = pk2(v0[2], v0[3]); w.z = pk2(v1[0], v1[1]); w.w = pk2(v1[2], v1[3]); return w; }
; __device__ __forceinline__ void unpack8(const u32x4 w, f32x4& v0, f32x4& v1) { v0 = (f32x4){bflo(w.x), bfhi(w.x), bflo(w.y), bfhi(w.y)}; v1 = (f32x4){bflo(w.z), bfhi(w.z), bflo(w.w), bfhi(w.w)}; }
;     __device__ __forceinline__ void operator()(const f32x4 (&acc)[2][2][4][2], const Unit& u, int wr, int wc, int fr, int fq) const {
;     ...
;                 const int row = row0 + ai * 128 + m * 16;
;                 const bf16_t* rowp = z + (size_t)row * DIN + col0;
; #pragma unroll
;                 for (int bj = 0; bj < 2; ++bj) {
;                     const u32x4 gw = *(const u32x4*)(rowp + O_GA + bj * 128);
;                     f32x4 g0, g1; unpack8(gw, g0, g1);
;                     f32x4 v0, v1;
; #pragma unroll
;                     for (int j = 0; j < 4; ++j) { v0[j] = sigmoidf_(g0[j]) * acc[ai][bj][m][0][j]; v1[j] = sigmoidf_(g1[j]) * acc[ai][bj][m][1][j]; }
;                     const u32x4 mw = *(const u32x4*)(rowp + bj * 128); f32x4 m0, m1; unpack8(mw, m0, m1); v0 += m0; v1 += m1;
;                     __builtin_amdgcn_raw_buffer_store_b128(pack8(v0, v1), rsrc, (unsigned)(((size_t)row * DIN + col0 + bj * 128) * 2), 0, 16  ); }
	v_mov_b32_e32 v104, v200
	v_mov_b32_e32 v105, v201
	v_mov_b32_e32 v106, v202
	v_mov_b32_e32 v107, v203
	v_mov_b32_e32 v108, v204
	v_mov_b32_e32 v109, v205
	v_mov_b32_e32 v110, v206
	v_mov_b32_e32 v111, v207
	v_add_u32_e32 v199, 0x67200, v198
	global_load_dwordx4 v[200:203], v199, s[26:27]
	v_add_u32_e32 v199, 0x66000, v198
	global_load_dwordx4 v[204:207], v199, s[26:27]
	s_mov_b32 s100, 0xbfb8aa3b
	v_lshlrev_b32_e32 v240, 16, v106
	v_and_b32_e32 v241, 0xffff0000, v106
	v_lshlrev_b32_e32 v242, 16, v104
	v_and_b32_e32 v243, 0xffff0000, v104
	v_lshlrev_b32_e32 v244, 16, v105
	v_and_b32_e32 v245, 0xffff0000, v105
	v_lshlrev_b32_e32 v246, 16, v107
	v_and_b32_e32 v247, 0xffff0000, v107
	v_pk_mul_f32 v[240:241], v[240:241], s[100:101] op_sel_hi:[1,0]
	v_pk_mul_f32 v[242:243], v[242:243], s[100:101] op_sel_hi:[1,0]
	v_pk_mul_f32 v[244:245], v[244:245], s[100:101] op_sel_hi:[1,0]
	v_pk_mul_f32 v[246:247], v[246:247], s[100:101] op_sel_hi:[1,0]
	v_exp_f32_e32 v240, v240
	v_exp_f32_e32 v241, v241
	v_exp_f32_e32 v242, v242
	v_exp_f32_e32 v243, v243
	v_exp_f32_e32 v244, v244
	v_exp_f32_e32 v245, v245
	v_exp_f32_e32 v246, v246
	v_exp_f32_e32 v247, v247
	s_nop 0
	v_pk_add_f32 v[240:241], v[240:241], 1.0 op_sel_hi:[1,0]
	v_pk_add_f32 v[242:243], v[242:243], 1.0 op_sel_hi:[1,0]
	v_pk_add_f32 v[244:245], v[244:245], 1.0 op_sel_hi:[1,0]
	v_pk_add_f32 v[246:247], v[246:247], 1.0 op_sel_hi:[1,0]
	v_rcp_f32_e32 v248, v240
	v_rcp_f32_e32 v249, v241
	v_rcp_f32_e32 v254, v242
	v_rcp_f32_e32 v255, v243
	v_pk_fma_f32 v[250:251], v[240:241], v[248:249], 1.0 op_sel_hi:[1,1,0] neg_lo:[1,0,0] neg_hi:[1,0,0]
	v_pk_fma_f32 v[104:105], v[242:243], v[254:255], 1.0 op_sel_hi:[1,1,0] neg_lo:[1,0,0] neg_hi:[1,0,0]
	v_pk_fma_f32 v[248:249], v[250:251], v[248:249], v[248:249]
	v_pk_fma_f32 v[254:255], v[104:105], v[254:255], v[254:255]
	v_pk_fma_f32 v[250:251], v[240:241], v[248:249], 1.0 op_sel_hi:[1,1,0] neg_lo:[1,0,0] neg_hi:[1,0,0]
	v_pk_fma_f32 v[104:105], v[242:243], v[254:255], 1.0 op_sel_hi:[1,1,0] neg_lo:[1,0,0] neg_hi:[1,0,0]
	v_pk_fma_f32 v[252:253], v[250:251], v[248:249], v[248:249]
	v_pk_fma_f32 v[106:107], v[104:105], v[254:255], v[254:255]
	v_pk_fma_f32 v[250:251], v[240:241], v[252:253], 1.0 op_sel_hi:[1,1,0] neg_lo:[1,0,0] neg_hi:[1,0,0]
	v_pk_fma_f32 v[104:105], v[242:243], v[106:107], 1.0 op_sel_hi:[1,1,0] neg_lo:[1,0,0] neg_hi:[1,0,0]
	v_pk_fma_f32 v[252:253], v[250:251], v[248:249], v[252:253]
	v_pk_fma_f32 v[106:107], v[104:105], v[254:255], v[106:107]
	v_div_fixup_f32 v240, v252, v240, 1.0
	v_div_fixup_f32 v241, v253, v241, 1.0
	v_div_fixup_f32 v242, v106, v242, 1.0
	v_div_fixup_f32 v243, v107, v243, 1.0
	v_rcp_f32_e32 v248, v244
	v_rcp_f32_e32 v249, v245
	v_rcp_f32_e32 v254, v246
	v_rcp_f32_e32 v255, v247
	v_pk_fma_f32 v[250:251], v[244:245], v[248:249], 1.0 op_sel_hi:[1,1,0] neg_lo:[1,0,0] neg_hi:[1,0,0]
	v_pk_fma_f32 v[104:105], v[246:247], v[254:255], 1.0 op_sel_hi:[1,1,0] neg_lo:[1,0,0] neg_hi:[1,0,0]
	v_pk_fma_f32 v[248:249], v[250:251], v[248:249], v[248:249]
	v_pk_fma_f32 v[254:255], v[104:105], v[254:255], v[254:255]
	v_pk_fma_f32 v[250:251], v[244:245], v[248:249], 1.0 op_sel_hi:[1,1,0] neg_lo:[1,0,0] neg_hi:[1,0,0]
	v_pk_fma_f32 v[104:105], v[246:247], v[254:255], 1.0 op_sel_hi:[1,1,0] neg_lo:[1,0,0] neg_hi:[1,0,0]
	v_pk_fma_f32 v[252:253], v[250:251], v[248:249], v[248:249]
	v_pk_fma_f32 v[106:107], v[104:105], v[254:255], v[254:255]
	v_pk_fma_f32 v[250:251], v[244:245], v[252:253], 1.0 op_sel_hi:[1,1,0] neg_lo:[1,0,0] neg_hi:[1,0,0]
	v_pk_fma_f32 v[104:105], v[246:247], v[106:107], 1.0 op_sel_hi:[1,1,0] neg_lo:[1,0,0] neg_hi:[1,0,0]
	v_pk_fma_f32 v[252:253], v[250:251], v[248:249], v[252:253]
	v_pk_fma_f32 v[106:107], v[104:105], v[254:255], v[106:107]
	v_div_fixup_f32 v244, v252, v244, 1.0
	v_div_fixup_f32 v245, v253, v245, 1.0
	v_div_fixup_f32 v246, v106, v246, 1.0
	v_div_fixup_f32 v247, v107, v247, 1.0
	v_lshlrev_b32_e32 v116, 16, v108
	v_and_b32_e32 v117, 0xffff0000, v108
	v_lshlrev_b32_e32 v118, 16, v110
	v_and_b32_e32 v119, 0xffff0000, v110
	v_lshlrev_b32_e32 v110, 16, v111
	v_and_b32_e32 v111, 0xffff0000, v111
	v_lshlrev_b32_e32 v108, 16, v109
	v_and_b32_e32 v109, 0xffff0000, v109
	v_pk_fma_f32 v[100:101], v[100:101], v[242:243], v[116:117]
	v_pk_fma_f32 v[104:105], v[98:99], v[246:247], v[110:111]
	v_pk_fma_f32 v[98:99], v[96:97], v[240:241], v[118:119]
	v_cvt_pk_bf16_f32 v96, v100, v101
	v_pk_fma_f32 v[102:103], v[102:103], v[244:245], v[108:109]
	s_nop 0
	v_cvt_pk_bf16_f32 v97, v102, v103
	v_cvt_pk_bf16_f32 v98, v98, v99
	v_cvt_pk_bf16_f32 v99, v104, v105
	buffer_store_dwordx4 v[96:99], v120, s[20:23], 0 offen offset:256 sc1
	s_nop 1
	v_add_u32_e32 v96, 0x4020, v158
	v_mad_i64_i32 v[98:99], s[6:7], v96, s77, 0
	v_lshl_add_u64 v[96:97], v[98:99], 1, s[26:27]
	v_lshl_add_u64 v[96:97], v[96:97], 0, v[142:143]
	v_add_co_u32_e32 v100, vcc, s78, v96
	s_nop 1
	v_addc_co_u32_e32 v101, vcc, 0, v97, vcc
	s_waitcnt vmcnt(7)
; __device__ __forceinline__ float sigmoidf_(float x) { return 1.0f / (1.0f + __expf(-x)); }
; __device__ __forceinline__ u32x4 pack8(const f32x4 v0, const f32x4 v1) { u32x4 w; w.x = pk2(v0[0], v0[1]); w.y = pk2(v0[2], v0[3]); w.z = pk2(v1[0], v1[1]); w.w = pk2(v1[2], v1[3]); return w; }
; __device__ __forceinline__ void unpack8(const u32x4 w, f32x4& v0, f32x4& v1) { v0 = (f32x4){bflo(w.x), bfhi(w.x), bflo(w.y), bfhi(w.y)}; v1 = (f32x4){bflo(w.z), bfhi(w.z), bflo(w.w), bfhi(w.w)}; }
;     __device__ __forceinline__ void operator()(const f32x4 (&acc)[2][2][4][2], const Unit& u, int wr, int wc, int fr, int fq) const {
;     ...
;                 const int row = row0 + ai * 128 + m * 16;
;                 const bf16_t* rowp = z + (size_t)row * DIN + col0;
; #pragma unroll
;                 for (int bj = 0; bj < 2; ++bj) {
;                     const u32x4 gw = *(const u32x4*)(rowp + O_GA + bj * 128);
;                     f32x4 g0, g1; unpack8(gw, g0, g1);
;                     f32x4 v0, v1;
; #pragma unroll
;                     for (int j = 0; j < 4; ++j) { v0[j] = sigmoidf_(g0[j]) * acc[ai][bj][m][0][j]; v1[j] = sigmoidf_(g1[j]) * acc[ai][bj][m][1][j]; }
;                     const u32x4 mw = *(const u32x4*)(rowp + bj * 128); f32x4 m0, m1; unpack8(mw, m0, m1); v0 += m0; v1 += m1;
;                     __builtin_amdgcn_raw_buffer_store_b128(pack8(v0, v1), rsrc, (unsigned)(((size_t)row * DIN + col0 + bj * 128) * 2), 0, 16  ); }
	v_mov_b32_e32 v102, v208
	v_mov_b32_e32 v103, v209
	v_mov_b32_e32 v104, v210
	v_mov_b32_e32 v105, v211
	v_mov_b32_e32 v106, v212
	v_mov_b32_e32 v107, v213
	v_mov_b32_e32 v108, v214
	v_mov_b32_e32 v109, v215
	v_add_u32_e32 v199, 0x67300, v198
	global_load_dwordx4 v[208:211], v199, s[26:27]
	v_add_u32_e32 v199, 0x66100, v198
	global_load_dwordx4 v[212:215], v199, s[26:27]
	s_mov_b32 s100, 0xbfb8aa3b
	v_lshlrev_b32_e32 v240, 16, v102
	v_and_b32_e32 v241, 0xffff0000, v102
	v_lshlrev_b32_e32 v242, 16, v104
	v_and_b32_e32 v243, 0xffff0000, v104
	v_lshlrev_b32_e32 v244, 16, v103
	v_and_b32_e32 v245, 0xffff0000, v103
	v_lshlrev_b32_e32 v246, 16, v105
	v_and_b32_e32 v247, 0xffff0000, v105
	v_pk_mul_f32 v[240:241], v[240:241], s[100:101] op_sel_hi:[1,0]
	v_pk_mul_f32 v[242:243], v[242:243], s[100:101] op_sel_hi:[1,0]
	v_pk_mul_f32 v[244:245], v[244:245], s[100:101] op_sel_hi:[1,0]
	v_pk_mul_f32 v[246:247], v[246:247], s[100:101] op_sel_hi:[1,0]
	v_exp_f32_e32 v240, v240
	v_exp_f32_e32 v241, v241
	v_exp_f32_e32 v242, v242
	v_exp_f32_e32 v243, v243
	v_exp_f32_e32 v244, v244
	v_exp_f32_e32 v245, v245
	v_exp_f32_e32 v246, v246
	v_exp_f32_e32 v247, v247
	s_nop 0
	v_pk_add_f32 v[240:241], v[240:241], 1.0 op_sel_hi:[1,0]
	v_pk_add_f32 v[242:243], v[242:243], 1.0 op_sel_hi:[1,0]
	v_pk_add_f32 v[244:245], v[244:245], 1.0 op_sel_hi:[1,0]
	v_pk_add_f32 v[246:247], v[246:247], 1.0 op_sel_hi:[1,0]
	v_rcp_f32_e32 v248, v240
	v_rcp_f32_e32 v249, v241
	v_rcp_f32_e32 v254, v242
	v_rcp_f32_e32 v255, v243
	v_pk_fma_f32 v[250:251], v[240:241], v[248:249], 1.0 op_sel_hi:[1,1,0] neg_lo:[1,0,0] neg_hi:[1,0,0]
	v_pk_fma_f32 v[102:103], v[242:243], v[254:255], 1.0 op_sel_hi:[1,1,0] neg_lo:[1,0,0] neg_hi:[1,0,0]
	v_pk_fma_f32 v[248:249], v[250:251], v[248:249], v[248:249]
	v_pk_fma_f32 v[254:255], v[102:103], v[254:255], v[254:255]
	v_pk_fma_f32 v[250:251], v[240:241], v[248:249], 1.0 op_sel_hi:[1,1,0] neg_lo:[1,0,0] neg_hi:[1,0,0]
	v_pk_fma_f32 v[102:103], v[242:243], v[254:255], 1.0 op_sel_hi:[1,1,0] neg_lo:[1,0,0] neg_hi:[1,0,0]
	v_pk_fma_f32 v[252:253], v[250:251], v[248:249], v[248:249]
	v_pk_fma_f32 v[104:105], v[102:103], v[254:255], v[254:255]
	v_pk_fma_f32 v[250:251], v[240:241], v[252:253], 1.0 op_sel_hi:[1,1,0] neg_lo:[1,0,0] neg_hi:[1,0,0]
	v_pk_fma_f32 v[102:103], v[242:243], v[104:105], 1.0 op_sel_hi:[1,1,0] neg_lo:[1,0,0] neg_hi:[1,0,0]
	v_pk_fma_f32 v[252:253], v[250:251], v[248:249], v[252:253]
	v_pk_fma_f32 v[104:105], v[102:103], v[254:255], v[104:105]
	v_div_fixup_f32 v240, v252, v240, 1.0
	v_div_fixup_f32 v241, v253, v241, 1.0
	v_div_fixup_f32 v242, v104, v242, 1.0
	v_div_fixup_f32 v243, v105, v243, 1.0
	v_rcp_f32_e32 v248, v244
	v_rcp_f32_e32 v249, v245
	v_rcp_f32_e32 v254, v246
	v_rcp_f32_e32 v255, v247
	v_pk_fma_f32 v[250:251], v[244:245], v[248:249], 1.0 op_sel_hi:[1,1,0] neg_lo:[1,0,0] neg_hi:[1,0,0]
	v_pk_fma_f32 v[102:103], v[246:247], v[254:255], 1.0 op_sel_hi:[1,1,0] neg_lo:[1,0,0] neg_hi:[1,0,0]
	v_pk_fma_f32 v[248:249], v[250:251], v[248:249], v[248:249]
	v_pk_fma_f32 v[254:255], v[102:103], v[254:255], v[254:255]
	v_pk_fma_f32 v[250:251], v[244:245], v[248:249], 1.0 op_sel_hi:[1,1,0] neg_lo:[1,0,0] neg_hi:[1,0,0]
	v_pk_fma_f32 v[102:103], v[246:247], v[254:255], 1.0 op_sel_hi:[1,1,0] neg_lo:[1,0,0] neg_hi:[1,0,0]
	v_pk_fma_f32 v[252:253], v[250:251], v[248:249], v[248:249]
	v_pk_fma_f32 v[104:105], v[102:103], v[254:255], v[254:255]
	v_pk_fma_f32 v[250:251], v[244:245], v[252:253], 1.0 op_sel_hi:[1,1,0] neg_lo:[1,0,0] neg_hi:[1,0,0]
	v_pk_fma_f32 v[102:103], v[246:247], v[104:105], 1.0 op_sel_hi:[1,1,0] neg_lo:[1,0,0] neg_hi:[1,0,0]
	v_pk_fma_f32 v[252:253], v[250:251], v[248:249], v[252:253]
	v_pk_fma_f32 v[104:105], v[102:103], v[254:255], v[104:105]
	v_div_fixup_f32 v244, v252, v244, 1.0
	v_div_fixup_f32 v245, v253, v245, 1.0
	v_div_fixup_f32 v246, v104, v246, 1.0
	v_div_fixup_f32 v247, v105, v247, 1.0
	v_lshlrev_b32_e32 v114, 16, v106
	v_and_b32_e32 v115, 0xffff0000, v106
	v_lshlrev_b32_e32 v116, 16, v108
	v_and_b32_e32 v117, 0xffff0000, v108
	v_lshlrev_b32_e32 v108, 16, v109
	v_and_b32_e32 v109, 0xffff0000, v109
	v_lshlrev_b32_e32 v106, 16, v107
	v_and_b32_e32 v107, 0xffff0000, v107
	v_pk_fma_f32 v[92:93], v[92:93], v[240:241], v[114:115]
	v_pk_fma_f32 v[102:103], v[90:91], v[246:247], v[108:109]
	v_pk_fma_f32 v[90:91], v[88:89], v[242:243], v[116:117]
	v_add_lshl_u32 v104, v140, v98, 1
	v_pk_fma_f32 v[94:95], v[94:95], v[244:245], v[106:107]
	v_cvt_pk_bf16_f32 v88, v92, v93
	s_nop 0
	v_cvt_pk_bf16_f32 v89, v94, v95
	v_cvt_pk_bf16_f32 v90, v90, v91
	v_cvt_pk_bf16_f32 v91, v102, v103
	buffer_store_dwordx4 v[88:91], v104, s[20:23], 0 offen sc1
	s_nop 0
	s_waitcnt vmcnt(7)
; __device__ __forceinline__ float sigmoidf_(float x) { return 1.0f / (1.0f + __expf(-x)); }
; __device__ __forceinline__ u32x4 pack8(const f32x4 v0, const f32x4 v1) { u32x4 w; w.x = pk2(v0[0], v0[1]); w.y = pk2(v0[2], v0[3]); w.z = pk2(v1[0], v1[1]); w.w = pk2(v1[2], v1[3]); return w; }
; __device__ __forceinline__ void unpack8(const u32x4 w, f32x4& v0, f32x4& v1) { v0 = (f32x4){bflo(w.x), bfhi(w.x), bflo(w.y), bfhi(w.y)}; v1 = (f32x4){bflo(w.z), bfhi(w.z), bflo(w.w), bfhi(w.w)}; }
;     __device__ __forceinline__ void operator()(const f32x4 (&acc)[2][2][4][2], const Unit& u, int wr, int wc, int fr, int fq) const {
;     ...
;                 const int row = row0 + ai * 128 + m * 16;
;                 const bf16_t* rowp = z + (size_t)row * DIN + col0;
; #pragma unroll
;                 for (int bj = 0; bj < 2; ++bj) {
;                     const u32x4 gw = *(const u32x4*)(rowp + O_GA + bj * 128);
;                     f32x4 g0, g1; unpack8(gw, g0, g1);
;                     f32x4 v0, v1;
; #pragma unroll
;                     for (int j = 0; j < 4; ++j) { v0[j] = sigmoidf_(g0[j]) * acc[ai][bj][m][0][j]; v1[j] = sigmoidf_(g1[j]) * acc[ai][bj][m][1][j]; }
;                     const u32x4 mw = *(const u32x4*)(rowp + bj * 128); f32x4 m0, m1; unpack8(mw, m0, m1); v0 += m0; v1 += m1;
;                     __builtin_amdgcn_raw_buffer_store_b128(pack8(v0, v1), rsrc, (unsigned)(((size_t)row * DIN + col0 + bj * 128) * 2), 0, 16  ); }
	v_mov_b32_e32 v88, v232
	v_mov_b32_e32 v89, v233
	v_mov_b32_e32 v90, v234
	v_mov_b32_e32 v91, v235
	v_mov_b32_e32 v92, v236
	v_mov_b32_e32 v93, v237
	v_mov_b32_e32 v94, v238
	v_mov_b32_e32 v95, v239
	v_add_u32_e32 v199, 0x111200, v198
	global_load_dwordx4 v[232:235], v199, s[26:27]
	v_add_u32_e32 v199, 0x110000, v198
	global_load_dwordx4 v[236:239], v199, s[26:27]
	s_mov_b32 s100, 0xbfb8aa3b
	v_lshlrev_b32_e32 v240, 16, v90
	v_and_b32_e32 v241, 0xffff0000, v90
	v_lshlrev_b32_e32 v242, 16, v88
	v_and_b32_e32 v243, 0xffff0000, v88
	v_lshlrev_b32_e32 v244, 16, v89
	v_and_b32_e32 v245, 0xffff0000, v89
	v_lshlrev_b32_e32 v246, 16, v91
	v_and_b32_e32 v247, 0xffff0000, v91
	v_pk_mul_f32 v[240:241], v[240:241], s[100:101] op_sel_hi:[1,0]
	v_pk_mul_f32 v[242:243], v[242:243], s[100:101] op_sel_hi:[1,0]
	v_pk_mul_f32 v[244:245], v[244:245], s[100:101] op_sel_hi:[1,0]
	v_pk_mul_f32 v[246:247], v[246:247], s[100:101] op_sel_hi:[1,0]
	v_exp_f32_e32 v240, v240
	v_exp_f32_e32 v241, v241
	v_exp_f32_e32 v242, v242
	v_exp_f32_e32 v243, v243
	v_exp_f32_e32 v244, v244
	v_exp_f32_e32 v245, v245
	v_exp_f32_e32 v246, v246
	v_exp_f32_e32 v247, v247
	s_nop 0
	v_pk_add_f32 v[240:241], v[240:241], 1.0 op_sel_hi:[1,0]
	v_pk_add_f32 v[242:243], v[242:243], 1.0 op_sel_hi:[1,0]
	v_pk_add_f32 v[244:245], v[244:245], 1.0 op_sel_hi:[1,0]
	v_pk_add_f32 v[246:247], v[246:247], 1.0 op_sel_hi:[1,0]
	v_rcp_f32_e32 v248, v240
	v_rcp_f32_e32 v249, v241
	v_rcp_f32_e32 v254, v242
	v_rcp_f32_e32 v255, v243
	v_pk_fma_f32 v[250:251], v[240:241], v[248:249], 1.0 op_sel_hi:[1,1,0] neg_lo:[1,0,0] neg_hi:[1,0,0]
	v_pk_fma_f32 v[88:89], v[242:243], v[254:255], 1.0 op_sel_hi:[1,1,0] neg_lo:[1,0,0] neg_hi:[1,0,0]
	v_pk_fma_f32 v[248:249], v[250:251], v[248:249], v[248:249]
	v_pk_fma_f32 v[254:255], v[88:89], v[254:255], v[254:255]
	v_pk_fma_f32 v[250:251], v[240:241], v[248:249], 1.0 op_sel_hi:[1,1,0] neg_lo:[1,0,0] neg_hi:[1,0,0]
	v_pk_fma_f32 v[88:89], v[242:243], v[254:255], 1.0 op_sel_hi:[1,1,0] neg_lo:[1,0,0] neg_hi:[1,0,0]
	v_pk_fma_f32 v[252:253], v[250:251], v[248:249], v[248:249]
	v_pk_fma_f32 v[90:91], v[88:89], v[254:255], v[254:255]
	v_pk_fma_f32 v[250:251], v[240:241], v[252:253], 1.0 op_sel_hi:[1,1,0] neg_lo:[1,0,0] neg_hi:[1,0,0]
	v_pk_fma_f32 v[88:89], v[242:243], v[90:91], 1.0 op_sel_hi:[1,1,0] neg_lo:[1,0,0] neg_hi:[1,0,0]
	v_pk_fma_f32 v[252:253], v[250:251], v[248:249], v[252:253]
	v_pk_fma_f32 v[90:91], v[88:89], v[254:255], v[90:91]
	v_div_fixup_f32 v240, v252, v240, 1.0
	v_div_fixup_f32 v241, v253, v241, 1.0
	v_div_fixup_f32 v242, v90, v242, 1.0
	v_div_fixup_f32 v243, v91, v243, 1.0
	v_rcp_f32_e32 v248, v244
	v_rcp_f32_e32 v249, v245
	v_rcp_f32_e32 v254, v246
	v_rcp_f32_e32 v255, v247
	v_pk_fma_f32 v[250:251], v[244:245], v[248:249], 1.0 op_sel_hi:[1,1,0] neg_lo:[1,0,0] neg_hi:[1,0,0]
	v_pk_fma_f32 v[88:89], v[246:247], v[254:255], 1.0 op_sel_hi:[1,1,0] neg_lo:[1,0,0] neg_hi:[1,0,0]
	v_pk_fma_f32 v[248:249], v[250:251], v[248:249], v[248:249]
	v_pk_fma_f32 v[254:255], v[88:89], v[254:255], v[254:255]
	v_pk_fma_f32 v[250:251], v[244:245], v[248:249], 1.0 op_sel_hi:[1,1,0] neg_lo:[1,0,0] neg_hi:[1,0,0]
	v_pk_fma_f32 v[88:89], v[246:247], v[254:255], 1.0 op_sel_hi:[1,1,0] neg_lo:[1,0,0] neg_hi:[1,0,0]
	v_pk_fma_f32 v[252:253], v[250:251], v[248:249], v[248:249]
	v_pk_fma_f32 v[90:91], v[88:89], v[254:255], v[254:255]
	v_pk_fma_f32 v[250:251], v[244:245], v[252:253], 1.0 op_sel_hi:[1,1,0] neg_lo:[1,0,0] neg_hi:[1,0,0]
	v_pk_fma_f32 v[88:89], v[246:247], v[90:91], 1.0 op_sel_hi:[1,1,0] neg_lo:[1,0,0] neg_hi:[1,0,0]
	v_pk_fma_f32 v[252:253], v[250:251], v[248:249], v[252:253]
	v_pk_fma_f32 v[90:91], v[88:89], v[254:255], v[90:91]
	v_div_fixup_f32 v244, v252, v244, 1.0
	v_div_fixup_f32 v245, v253, v245, 1.0
	v_div_fixup_f32 v246, v90, v246, 1.0
	v_div_fixup_f32 v247, v91, v247, 1.0
	v_lshlrev_b32_e32 v100, 16, v92
	v_and_b32_e32 v101, 0xffff0000, v92
	v_lshlrev_b32_e32 v102, 16, v94
	v_and_b32_e32 v103, 0xffff0000, v94
	v_lshlrev_b32_e32 v94, 16, v95
	v_and_b32_e32 v95, 0xffff0000, v95
	v_lshlrev_b32_e32 v92, 16, v93
	v_and_b32_e32 v93, 0xffff0000, v93
	v_pk_fma_f32 v[84:85], v[84:85], v[242:243], v[100:101]
	v_pk_fma_f32 v[88:89], v[82:83], v[246:247], v[94:95]
	v_pk_fma_f32 v[82:83], v[80:81], v[240:241], v[102:103]
	v_cvt_pk_bf16_f32 v80, v84, v85
	v_pk_fma_f32 v[86:87], v[86:87], v[244:245], v[92:93]
	s_nop 0
	v_cvt_pk_bf16_f32 v81, v86, v87
	v_cvt_pk_bf16_f32 v82, v82, v83
	v_cvt_pk_bf16_f32 v83, v88, v89
	buffer_store_dwordx4 v[80:83], v104, s[20:23], 0 offen offset:256 sc1
	s_nop 1
	v_add_u32_e32 v80, 0x4030, v158
	v_mad_i64_i32 v[82:83], s[6:7], v80, s77, 0
	v_lshl_add_u64 v[80:81], v[82:83], 1, s[26:27]
	v_lshl_add_u64 v[80:81], v[80:81], 0, v[142:143]
	v_add_co_u32_e32 v84, vcc, s78, v80
	s_nop 1
	v_addc_co_u32_e32 v85, vcc, 0, v81, vcc
	s_waitcnt vmcnt(7)
; __device__ __forceinline__ float sigmoidf_(float x) { return 1.0f / (1.0f + __expf(-x)); }
; __device__ __forceinline__ u32x4 pack8(const f32x4 v0, const f32x4 v1) { u32x4 w; w.x = pk2(v0[0], v0[1]); w.y = pk2(v0[2], v0[3]); w.z = pk2(v1[0], v1[1]); w.w = pk2(v1[2], v1[3]); return w; }
; __device__ __forceinline__ void unpack8(const u32x4 w, f32x4& v0, f32x4& v1) { v0 = (f32x4){bflo(w.x), bfhi(w.x), bflo(w.y), bfhi(w.y)}; v1 = (f32x4){bflo(w.z), bfhi(w.z), bflo(w.w), bfhi(w.w)}; }
;     __device__ __forceinline__ void operator()(const f32x4 (&acc)[2][2][4][2], const Unit& u, int wr, int wc, int fr, int fq) const {
;     ...
;                 const int row = row0 + ai * 128 + m * 16;
;                 const bf16_t* rowp = z + (size_t)row * DIN + col0;
; #pragma unroll
;                 for (int bj = 0; bj < 2; ++bj) {
;                     const u32x4 gw = *(const u32x4*)(rowp + O_GA + bj * 128);
;                     f32x4 g0, g1; unpack8(gw, g0, g1);
;                     f32x4 v0, v1;
; #pragma unroll
;                     for (int j = 0; j < 4; ++j) { v0[j] = sigmoidf_(g0[j]) * acc[ai][bj][m][0][j]; v1[j] = sigmoidf_(g1[j]) * acc[ai][bj][m][1][j]; }
;                     const u32x4 mw = *(const u32x4*)(rowp + bj * 128); f32x4 m0, m1; unpack8(mw, m0, m1); v0 += m0; v1 += m1;
;                     __builtin_amdgcn_raw_buffer_store_b128(pack8(v0, v1), rsrc, (unsigned)(((size_t)row * DIN + col0 + bj * 128) * 2), 0, 16  ); }
	v_mov_b32_e32 v86, v200
	v_mov_b32_e32 v87, v201
	v_mov_b32_e32 v88, v202
	v_mov_b32_e32 v89, v203
	v_mov_b32_e32 v90, v204
	v_mov_b32_e32 v91, v205
	v_mov_b32_e32 v92, v206
	v_mov_b32_e32 v93, v207
	v_add_u32_e32 v199, 0x111300, v198
	global_load_dwordx4 v[200:203], v199, s[26:27]
	v_add_u32_e32 v199, 0x110100, v198
	global_load_dwordx4 v[204:207], v199, s[26:27]
	s_mov_b32 s100, 0xbfb8aa3b
	v_lshlrev_b32_e32 v240, 16, v86
	v_and_b32_e32 v241, 0xffff0000, v86
	v_lshlrev_b32_e32 v242, 16, v88
	v_and_b32_e32 v243, 0xffff0000, v88
	v_lshlrev_b32_e32 v244, 16, v87
	v_and_b32_e32 v245, 0xffff0000, v87
	v_lshlrev_b32_e32 v246, 16, v89
	v_and_b32_e32 v247, 0xffff0000, v89
	v_pk_mul_f32 v[240:241], v[240:241], s[100:101] op_sel_hi:[1,0]
	v_pk_mul_f32 v[242:243], v[242:243], s[100:101] op_sel_hi:[1,0]
	v_pk_mul_f32 v[244:245], v[244:245], s[100:101] op_sel_hi:[1,0]
	v_pk_mul_f32 v[246:247], v[246:247], s[100:101] op_sel_hi:[1,0]
	v_exp_f32_e32 v240, v240
	v_exp_f32_e32 v241, v241
	v_exp_f32_e32 v242, v242
	v_exp_f32_e32 v243, v243
	v_exp_f32_e32 v244, v244
	v_exp_f32_e32 v245, v245
	v_exp_f32_e32 v246, v246
	v_exp_f32_e32 v247, v247
	s_nop 0
	v_pk_add_f32 v[240:241], v[240:241], 1.0 op_sel_hi:[1,0]
	v_pk_add_f32 v[242:243], v[242:243], 1.0 op_sel_hi:[1,0]
	v_pk_add_f32 v[244:245], v[244:245], 1.0 op_sel_hi:[1,0]
	v_pk_add_f32 v[246:247], v[246:247], 1.0 op_sel_hi:[1,0]
	v_rcp_f32_e32 v248, v240
	v_rcp_f32_e32 v249, v241
	v_rcp_f32_e32 v254, v242
	v_rcp_f32_e32 v255, v243
	v_pk_fma_f32 v[250:251], v[240:241], v[248:249], 1.0 op_sel_hi:[1,1,0] neg_lo:[1,0,0] neg_hi:[1,0,0]
	v_pk_fma_f32 v[86:87], v[242:243], v[254:255], 1.0 op_sel_hi:[1,1,0] neg_lo:[1,0,0] neg_hi:[1,0,0]
	v_pk_fma_f32 v[248:249], v[250:251], v[248:249], v[248:249]
	v_pk_fma_f32 v[254:255], v[86:87], v[254:255], v[254:255]
	v_pk_fma_f32 v[250:251], v[240:241], v[248:249], 1.0 op_sel_hi:[1,1,0] neg_lo:[1,0,0] neg_hi:[1,0,0]
	v_pk_fma_f32 v[86:87], v[242:243], v[254:255], 1.0 op_sel_hi:[1,1,0] neg_lo:[1,0,0] neg_hi:[1,0,0]
	v_pk_fma_f32 v[252:253], v[250:251], v[248:249], v[248:249]
	v_pk_fma_f32 v[88:89], v[86:87], v[254:255], v[254:255]
	v_pk_fma_f32 v[250:251], v[240:241], v[252:253], 1.0 op_sel_hi:[1,1,0] neg_lo:[1,0,0] neg_hi:[1,0,0]
	v_pk_fma_f32 v[86:87], v[242:243], v[88:89], 1.0 op_sel_hi:[1,1,0] neg_lo:[1,0,0] neg_hi:[1,0,0]
	v_pk_fma_f32 v[252:253], v[250:251], v[248:249], v[252:253]
	v_pk_fma_f32 v[88:89], v[86:87], v[254:255], v[88:89]
	v_div_fixup_f32 v240, v252, v240, 1.0
	v_div_fixup_f32 v241, v253, v241, 1.0
	v_div_fixup_f32 v242, v88, v242, 1.0
	v_div_fixup_f32 v243, v89, v243, 1.0
	v_rcp_f32_e32 v248, v244
	v_rcp_f32_e32 v249, v245
	v_rcp_f32_e32 v254, v246
	v_rcp_f32_e32 v255, v247
	v_pk_fma_f32 v[250:251], v[244:245], v[248:249], 1.0 op_sel_hi:[1,1,0] neg_lo:[1,0,0] neg_hi:[1,0,0]
	v_pk_fma_f32 v[86:87], v[246:247], v[254:255], 1.0 op_sel_hi:[1,1,0] neg_lo:[1,0,0] neg_hi:[1,0,0]
	v_pk_fma_f32 v[248:249], v[250:251], v[248:249], v[248:249]
	v_pk_fma_f32 v[254:255], v[86:87], v[254:255], v[254:255]
	v_pk_fma_f32 v[250:251], v[244:245], v[248:249], 1.0 op_sel_hi:[1,1,0] neg_lo:[1,0,0] neg_hi:[1,0,0]
	v_pk_fma_f32 v[86:87], v[246:247], v[254:255], 1.0 op_sel_hi:[1,1,0] neg_lo:[1,0,0] neg_hi:[1,0,0]
	v_pk_fma_f32 v[252:253], v[250:251], v[248:249], v[248:249]
	v_pk_fma_f32 v[88:89], v[86:87], v[254:255], v[254:255]
	v_pk_fma_f32 v[250:251], v[244:245], v[252:253], 1.0 op_sel_hi:[1,1,0] neg_lo:[1,0,0] neg_hi:[1,0,0]
	v_pk_fma_f32 v[86:87], v[246:247], v[88:89], 1.0 op_sel_hi:[1,1,0] neg_lo:[1,0,0] neg_hi:[1,0,0]
	v_pk_fma_f32 v[252:253], v[250:251], v[248:249], v[252:253]
	v_pk_fma_f32 v[88:89], v[86:87], v[254:255], v[88:89]
	v_div_fixup_f32 v244, v252, v244, 1.0
	v_div_fixup_f32 v245, v253, v245, 1.0
	v_div_fixup_f32 v246, v88, v246, 1.0
	v_div_fixup_f32 v247, v89, v247, 1.0
	v_lshlrev_b32_e32 v98, 16, v90
	v_and_b32_e32 v99, 0xffff0000, v90
	v_lshlrev_b32_e32 v100, 16, v92
	v_and_b32_e32 v101, 0xffff0000, v92
	v_lshlrev_b32_e32 v92, 16, v93
	v_and_b32_e32 v93, 0xffff0000, v93
	v_lshlrev_b32_e32 v90, 16, v91
	v_and_b32_e32 v91, 0xffff0000, v91
	v_pk_fma_f32 v[76:77], v[76:77], v[240:241], v[98:99]
	v_pk_fma_f32 v[86:87], v[74:75], v[246:247], v[92:93]
	v_pk_fma_f32 v[74:75], v[72:73], v[242:243], v[100:101]
	v_add_lshl_u32 v88, v140, v82, 1
	v_pk_fma_f32 v[78:79], v[78:79], v[244:245], v[90:91]
	v_cvt_pk_bf16_f32 v72, v76, v77
	s_nop 0
	v_cvt_pk_bf16_f32 v73, v78, v79
	v_cvt_pk_bf16_f32 v74, v74, v75
	v_cvt_pk_bf16_f32 v75, v86, v87
	buffer_store_dwordx4 v[72:75], v88, s[20:23], 0 offen sc1
	s_nop 0
	s_waitcnt vmcnt(7)
; __device__ __forceinline__ float sigmoidf_(float x) { return 1.0f / (1.0f + __expf(-x)); }
; __device__ __forceinline__ u32x4 pack8(const f32x4 v0, const f32x4 v1) { u32x4 w; w.x = pk2(v0[0], v0[1]); w.y = pk2(v0[2], v0[3]); w.z = pk2(v1[0], v1[1]); w.w = pk2(v1[2], v1[3]); return w; }
; __device__ __forceinline__ void unpack8(const u32x4 w, f32x4& v0, f32x4& v1) { v0 = (f32x4){bflo(w.x), bfhi(w.x), bflo(w.y), bfhi(w.y)}; v1 = (f32x4){bflo(w.z), bfhi(w.z), bflo(w.w), bfhi(w.w)}; }
;     __device__ __forceinline__ void operator()(const f32x4 (&acc)[2][2][4][2], const Unit& u, int wr, int wc, int fr, int fq) const {
;     ...
;                 const int row = row0 + ai * 128 + m * 16;
;                 const bf16_t* rowp = z + (size_t)row * DIN + col0;
; #pragma unroll
;                 for (int bj = 0; bj < 2; ++bj) {
;                     const u32x4 gw = *(const u32x4*)(rowp + O_GA + bj * 128);
;                     f32x4 g0, g1; unpack8(gw, g0, g1);
;                     f32x4 v0, v1;
; #pragma unroll
;                     for (int j = 0; j < 4; ++j) { v0[j] = sigmoidf_(g0[j]) * acc[ai][bj][m][0][j]; v1[j] = sigmoidf_(g1[j]) * acc[ai][bj][m][1][j]; }
;                     const u32x4 mw = *(const u32x4*)(rowp + bj * 128); f32x4 m0, m1; unpack8(mw, m0, m1); v0 += m0; v1 += m1;
;                     __builtin_amdgcn_raw_buffer_store_b128(pack8(v0, v1), rsrc, (unsigned)(((size_t)row * DIN + col0 + bj * 128) * 2), 0, 16  ); }
	v_mov_b32_e32 v72, v208
	v_mov_b32_e32 v73, v209
	v_mov_b32_e32 v74, v210
	v_mov_b32_e32 v75, v211
	v_mov_b32_e32 v76, v212
	v_mov_b32_e32 v77, v213
	v_mov_b32_e32 v78, v214
	v_mov_b32_e32 v79, v215
	v_add_u32_e32 v199, 0x133200, v198
	global_load_dwordx4 v[208:211], v199, s[26:27]
	v_add_u32_e32 v199, 0x132000, v198
	global_load_dwordx4 v[212:215], v199, s[26:27]
	s_mov_b32 s100, 0xbfb8aa3b
	v_lshlrev_b32_e32 v240, 16, v74
	v_and_b32_e32 v241, 0xffff0000, v74
	v_lshlrev_b32_e32 v242, 16, v72
	v_and_b32_e32 v243, 0xffff0000, v72
	v_lshlrev_b32_e32 v244, 16, v73
	v_and_b32_e32 v245, 0xffff0000, v73
	v_lshlrev_b32_e32 v246, 16, v75
	v_and_b32_e32 v247, 0xffff0000, v75
	v_pk_mul_f32 v[240:241], v[240:241], s[100:101] op_sel_hi:[1,0]
	v_pk_mul_f32 v[242:243], v[242:243], s[100:101] op_sel_hi:[1,0]
	v_pk_mul_f32 v[244:245], v[244:245], s[100:101] op_sel_hi:[1,0]
	v_pk_mul_f32 v[246:247], v[246:247], s[100:101] op_sel_hi:[1,0]
	v_exp_f32_e32 v240, v240
	v_exp_f32_e32 v241, v241
	v_exp_f32_e32 v242, v242
	v_exp_f32_e32 v243, v243
	v_exp_f32_e32 v244, v244
	v_exp_f32_e32 v245, v245
	v_exp_f32_e32 v246, v246
	v_exp_f32_e32 v247, v247
	s_nop 0
	v_pk_add_f32 v[240:241], v[240:241], 1.0 op_sel_hi:[1,0]
	v_pk_add_f32 v[242:243], v[242:243], 1.0 op_sel_hi:[1,0]
	v_pk_add_f32 v[244:245], v[244:245], 1.0 op_sel_hi:[1,0]
	v_pk_add_f32 v[246:247], v[246:247], 1.0 op_sel_hi:[1,0]
	v_rcp_f32_e32 v248, v240
	v_rcp_f32_e32 v249, v241
	v_rcp_f32_e32 v254, v242
	v_rcp_f32_e32 v255, v243
	v_pk_fma_f32 v[250:251], v[240:241], v[248:249], 1.0 op_sel_hi:[1,1,0] neg_lo:[1,0,0] neg_hi:[1,0,0]
	v_pk_fma_f32 v[72:73], v[242:243], v[254:255], 1.0 op_sel_hi:[1,1,0] neg_lo:[1,0,0] neg_hi:[1,0,0]
	v_pk_fma_f32 v[248:249], v[250:251], v[248:249], v[248:249]
	v_pk_fma_f32 v[254:255], v[72:73], v[254:255], v[254:255]
	v_pk_fma_f32 v[250:251], v[240:241], v[248:249], 1.0 op_sel_hi:[1,1,0] neg_lo:[1,0,0] neg_hi:[1,0,0]
	v_pk_fma_f32 v[72:73], v[242:243], v[254:255], 1.0 op_sel_hi:[1,1,0] neg_lo:[1,0,0] neg_hi:[1,0,0]
	v_pk_fma_f32 v[252:253], v[250:251], v[248:249], v[248:249]
	v_pk_fma_f32 v[74:75], v[72:73], v[254:255], v[254:255]
	v_pk_fma_f32 v[250:251], v[240:241], v[252:253], 1.0 op_sel_hi:[1,1,0] neg_lo:[1,0,0] neg_hi:[1,0,0]
	v_pk_fma_f32 v[72:73], v[242:243], v[74:75], 1.0 op_sel_hi:[1,1,0] neg_lo:[1,0,0] neg_hi:[1,0,0]
	v_pk_fma_f32 v[252:253], v[250:251], v[248:249], v[252:253]
	v_pk_fma_f32 v[74:75], v[72:73], v[254:255], v[74:75]
	v_div_fixup_f32 v240, v252, v240, 1.0
	v_div_fixup_f32 v241, v253, v241, 1.0
	v_div_fixup_f32 v242, v74, v242, 1.0
	v_div_fixup_f32 v243, v75, v243, 1.0
	v_rcp_f32_e32 v248, v244
	v_rcp_f32_e32 v249, v245
	v_rcp_f32_e32 v254, v246
	v_rcp_f32_e32 v255, v247
	v_pk_fma_f32 v[250:251], v[244:245], v[248:249], 1.0 op_sel_hi:[1,1,0] neg_lo:[1,0,0] neg_hi:[1,0,0]
	v_pk_fma_f32 v[72:73], v[246:247], v[254:255], 1.0 op_sel_hi:[1,1,0] neg_lo:[1,0,0] neg_hi:[1,0,0]
	v_pk_fma_f32 v[248:249], v[250:251], v[248:249], v[248:249]
	v_pk_fma_f32 v[254:255], v[72:73], v[254:255], v[254:255]
	v_pk_fma_f32 v[250:251], v[244:245], v[248:249], 1.0 op_sel_hi:[1,1,0] neg_lo:[1,0,0] neg_hi:[1,0,0]
	v_pk_fma_f32 v[72:73], v[246:247], v[254:255], 1.0 op_sel_hi:[1,1,0] neg_lo:[1,0,0] neg_hi:[1,0,0]
	v_pk_fma_f32 v[252:253], v[250:251], v[248:249], v[248:249]
	v_pk_fma_f32 v[74:75], v[72:73], v[254:255], v[254:255]
	v_pk_fma_f32 v[250:251], v[244:245], v[252:253], 1.0 op_sel_hi:[1,1,0] neg_lo:[1,0,0] neg_hi:[1,0,0]
	v_pk_fma_f32 v[72:73], v[246:247], v[74:75], 1.0 op_sel_hi:[1,1,0] neg_lo:[1,0,0] neg_hi:[1,0,0]
	v_pk_fma_f32 v[252:253], v[250:251], v[248:249], v[252:253]
	v_pk_fma_f32 v[74:75], v[72:73], v[254:255], v[74:75]
	v_div_fixup_f32 v244, v252, v244, 1.0
	v_div_fixup_f32 v245, v253, v245, 1.0
	v_div_fixup_f32 v246, v74, v246, 1.0
	v_div_fixup_f32 v247, v75, v247, 1.0
	v_lshlrev_b32_e32 v84, 16, v76
	v_and_b32_e32 v85, 0xffff0000, v76
	v_lshlrev_b32_e32 v86, 16, v78
	v_and_b32_e32 v87, 0xffff0000, v78
	v_lshlrev_b32_e32 v78, 16, v79
	v_and_b32_e32 v79, 0xffff0000, v79
	v_lshlrev_b32_e32 v76, 16, v77
	v_and_b32_e32 v77, 0xffff0000, v77
	v_pk_fma_f32 v[68:69], v[68:69], v[242:243], v[84:85]
	v_pk_fma_f32 v[72:73], v[66:67], v[246:247], v[78:79]
	v_pk_fma_f32 v[66:67], v[64:65], v[240:241], v[86:87]
	v_cvt_pk_bf16_f32 v64, v68, v69
	v_pk_fma_f32 v[70:71], v[70:71], v[244:245], v[76:77]
	s_nop 0
	v_cvt_pk_bf16_f32 v65, v70, v71
	v_cvt_pk_bf16_f32 v66, v66, v67
	v_cvt_pk_bf16_f32 v67, v72, v73
	buffer_store_dwordx4 v[64:67], v88, s[20:23], 0 offen offset:256 sc1
	s_nop 1
	v_add_u32_e32 v64, 0x4080, v158
	v_mad_i64_i32 v[66:67], s[6:7], v64, s77, 0
	v_lshl_add_u64 v[64:65], v[66:67], 1, s[26:27]
	v_lshl_add_u64 v[64:65], v[64:65], 0, v[142:143]
	v_add_co_u32_e32 v68, vcc, s78, v64
	s_nop 1
	v_addc_co_u32_e32 v69, vcc, 0, v65, vcc
	s_waitcnt vmcnt(7)
; __device__ __forceinline__ float sigmoidf_(float x) { return 1.0f / (1.0f + __expf(-x)); }
; __device__ __forceinline__ u32x4 pack8(const f32x4 v0, const f32x4 v1) { u32x4 w; w.x = pk2(v0[0], v0[1]); w.y = pk2(v0[2], v0[3]); w.z = pk2(v1[0], v1[1]); w.w = pk2(v1[2], v1[3]); return w; }
; __device__ __forceinline__ void unpack8(const u32x4 w, f32x4& v0, f32x4& v1) { v0 = (f32x4){bflo(w.x), bfhi(w.x), bflo(w.y), bfhi(w.y)}; v1 = (f32x4){bflo(w.z), bfhi(w.z), bflo(w.w), bfhi(w.w)}; }
;     __device__ __forceinline__ void operator()(const f32x4 (&acc)[2][2][4][2], const Unit& u, int wr, int wc, int fr, int fq) const {
;     ...
;                 const int row = row0 + ai * 128 + m * 16;
;                 const bf16_t* rowp = z + (size_t)row * DIN + col0;
; #pragma unroll
;                 for (int bj = 0; bj < 2; ++bj) {
;                     const u32x4 gw = *(const u32x4*)(rowp + O_GA + bj * 128);
;                     f32x4 g0, g1; unpack8(gw, g0, g1);
;                     f32x4 v0, v1;
; #pragma unroll
;                     for (int j = 0; j < 4; ++j) { v0[j] = sigmoidf_(g0[j]) * acc[ai][bj][m][0][j]; v1[j] = sigmoidf_(g1[j]) * acc[ai][bj][m][1][j]; }
;                     const u32x4 mw = *(const u32x4*)(rowp + bj * 128); f32x4 m0, m1; unpack8(mw, m0, m1); v0 += m0; v1 += m1;
;                     __builtin_amdgcn_raw_buffer_store_b128(pack8(v0, v1), rsrc, (unsigned)(((size_t)row * DIN + col0 + bj * 128) * 2), 0, 16  ); }
	v_mov_b32_e32 v70, v232
	v_mov_b32_e32 v71, v233
	v_mov_b32_e32 v72, v234
	v_mov_b32_e32 v73, v235
	v_mov_b32_e32 v74, v236
	v_mov_b32_e32 v75, v237
	v_mov_b32_e32 v76, v238
	v_mov_b32_e32 v77, v239
	v_add_u32_e32 v199, 0x133300, v198
	global_load_dwordx4 v[232:235], v199, s[26:27]
	v_add_u32_e32 v199, 0x132100, v198
	global_load_dwordx4 v[236:239], v199, s[26:27]
	s_mov_b32 s100, 0xbfb8aa3b
	v_lshlrev_b32_e32 v240, 16, v70
	v_and_b32_e32 v241, 0xffff0000, v70
	v_lshlrev_b32_e32 v242, 16, v72
	v_and_b32_e32 v243, 0xffff0000, v72
	v_lshlrev_b32_e32 v244, 16, v71
	v_and_b32_e32 v245, 0xffff0000, v71
	v_lshlrev_b32_e32 v246, 16, v73
	v_and_b32_e32 v247, 0xffff0000, v73
	v_pk_mul_f32 v[240:241], v[240:241], s[100:101] op_sel_hi:[1,0]
	v_pk_mul_f32 v[242:243], v[242:243], s[100:101] op_sel_hi:[1,0]
	v_pk_mul_f32 v[244:245], v[244:245], s[100:101] op_sel_hi:[1,0]
	v_pk_mul_f32 v[246:247], v[246:247], s[100:101] op_sel_hi:[1,0]
	v_exp_f32_e32 v240, v240
	v_exp_f32_e32 v241, v241
	v_exp_f32_e32 v242, v242
	v_exp_f32_e32 v243, v243
	v_exp_f32_e32 v244, v244
	v_exp_f32_e32 v245, v245
	v_exp_f32_e32 v246, v246
	v_exp_f32_e32 v247, v247
	s_nop 0
	v_pk_add_f32 v[240:241], v[240:241], 1.0 op_sel_hi:[1,0]
	v_pk_add_f32 v[242:243], v[242:243], 1.0 op_sel_hi:[1,0]
	v_pk_add_f32 v[244:245], v[244:245], 1.0 op_sel_hi:[1,0]
	v_pk_add_f32 v[246:247], v[246:247], 1.0 op_sel_hi:[1,0]
	v_rcp_f32_e32 v248, v240
	v_rcp_f32_e32 v249, v241
	v_rcp_f32_e32 v254, v242
	v_rcp_f32_e32 v255, v243
	v_pk_fma_f32 v[250:251], v[240:241], v[248:249], 1.0 op_sel_hi:[1,1,0] neg_lo:[1,0,0] neg_hi:[1,0,0]
	v_pk_fma_f32 v[70:71], v[242:243], v[254:255], 1.0 op_sel_hi:[1,1,0] neg_lo:[1,0,0] neg_hi:[1,0,0]
	v_pk_fma_f32 v[248:249], v[250:251], v[248:249], v[248:249]
	v_pk_fma_f32 v[254:255], v[70:71], v[254:255], v[254:255]
	v_pk_fma_f32 v[250:251], v[240:241], v[248:249], 1.0 op_sel_hi:[1,1,0] neg_lo:[1,0,0] neg_hi:[1,0,0]
	v_pk_fma_f32 v[70:71], v[242:243], v[254:255], 1.0 op_sel_hi:[1,1,0] neg_lo:[1,0,0] neg_hi:[1,0,0]
	v_pk_fma_f32 v[252:253], v[250:251], v[248:249], v[248:249]
	v_pk_fma_f32 v[72:73], v[70:71], v[254:255], v[254:255]
	v_pk_fma_f32 v[250:251], v[240:241], v[252:253], 1.0 op_sel_hi:[1,1,0] neg_lo:[1,0,0] neg_hi:[1,0,0]
	v_pk_fma_f32 v[70:71], v[242:243], v[72:73], 1.0 op_sel_hi:[1,1,0] neg_lo:[1,0,0] neg_hi:[1,0,0]
	v_pk_fma_f32 v[252:253], v[250:251], v[248:249], v[252:253]
	v_pk_fma_f32 v[72:73], v[70:71], v[254:255], v[72:73]
	v_div_fixup_f32 v240, v252, v240, 1.0
	v_div_fixup_f32 v241, v253, v241, 1.0
	v_div_fixup_f32 v242, v72, v242, 1.0
	v_div_fixup_f32 v243, v73, v243, 1.0
	v_rcp_f32_e32 v248, v244
	v_rcp_f32_e32 v249, v245
	v_rcp_f32_e32 v254, v246
	v_rcp_f32_e32 v255, v247
	v_pk_fma_f32 v[250:251], v[244:245], v[248:249], 1.0 op_sel_hi:[1,1,0] neg_lo:[1,0,0] neg_hi:[1,0,0]
	v_pk_fma_f32 v[70:71], v[246:247], v[254:255], 1.0 op_sel_hi:[1,1,0] neg_lo:[1,0,0] neg_hi:[1,0,0]
	v_pk_fma_f32 v[248:249], v[250:251], v[248:249], v[248:249]
	v_pk_fma_f32 v[254:255], v[70:71], v[254:255], v[254:255]
	v_pk_fma_f32 v[250:251], v[244:245], v[248:249], 1.0 op_sel_hi:[1,1,0] neg_lo:[1,0,0] neg_hi:[1,0,0]
	v_pk_fma_f32 v[70:71], v[246:247], v[254:255], 1.0 op_sel_hi:[1,1,0] neg_lo:[1,0,0] neg_hi:[1,0,0]
	v_pk_fma_f32 v[252:253], v[250:251], v[248:249], v[248:249]
	v_pk_fma_f32 v[72:73], v[70:71], v[254:255], v[254:255]
	v_pk_fma_f32 v[250:251], v[244:245], v[252:253], 1.0 op_sel_hi:[1,1,0] neg_lo:[1,0,0] neg_hi:[1,0,0]
	v_pk_fma_f32 v[70:71], v[246:247], v[72:73], 1.0 op_sel_hi:[1,1,0] neg_lo:[1,0,0] neg_hi:[1,0,0]
	v_pk_fma_f32 v[252:253], v[250:251], v[248:249], v[252:253]
	v_pk_fma_f32 v[72:73], v[70:71], v[254:255], v[72:73]
	v_div_fixup_f32 v244, v252, v244, 1.0
	v_div_fixup_f32 v245, v253, v245, 1.0
	v_div_fixup_f32 v246, v72, v246, 1.0
	v_div_fixup_f32 v247, v73, v247, 1.0
	v_lshlrev_b32_e32 v82, 16, v74
	v_and_b32_e32 v83, 0xffff0000, v74
	v_lshlrev_b32_e32 v84, 16, v76
	v_and_b32_e32 v85, 0xffff0000, v76
	v_lshlrev_b32_e32 v76, 16, v77
	v_and_b32_e32 v77, 0xffff0000, v77
	v_lshlrev_b32_e32 v74, 16, v75
	v_and_b32_e32 v75, 0xffff0000, v75
	v_pk_fma_f32 v[60:61], v[60:61], v[240:241], v[82:83]
	v_pk_fma_f32 v[70:71], v[58:59], v[246:247], v[76:77]
	v_pk_fma_f32 v[58:59], v[56:57], v[242:243], v[84:85]
	v_add_lshl_u32 v72, v140, v66, 1
	v_pk_fma_f32 v[62:63], v[62:63], v[244:245], v[74:75]
	v_cvt_pk_bf16_f32 v56, v60, v61
	s_nop 0
	v_cvt_pk_bf16_f32 v57, v62, v63
	v_cvt_pk_bf16_f32 v58, v58, v59
	v_cvt_pk_bf16_f32 v59, v70, v71
	buffer_store_dwordx4 v[56:59], v72, s[20:23], 0 offen sc1
	s_nop 0
	s_waitcnt vmcnt(7)
; __device__ __forceinline__ float sigmoidf_(float x) { return 1.0f / (1.0f + __expf(-x)); }
; __device__ __forceinline__ u32x4 pack8(const f32x4 v0, const f32x4 v1) { u32x4 w; w.x = pk2(v0[0], v0[1]); w.y = pk2(v0[2], v0[3]); w.z = pk2(v1[0], v1[1]); w.w = pk2(v1[2], v1[3]); return w; }
; __device__ __forceinline__ void unpack8(const u32x4 w, f32x4& v0, f32x4& v1) { v0 = (f32x4){bflo(w.x), bfhi(w.x), bflo(w.y), bfhi(w.y)}; v1 = (f32x4){bflo(w.z), bfhi(w.z), bflo(w.w), bfhi(w.w)}; }
;     __device__ __forceinline__ void operator()(const f32x4 (&acc)[2][2][4][2], const Unit& u, int wr, int wc, int fr, int fq) const {
;     ...
;                 const int row = row0 + ai * 128 + m * 16;
;                 const bf16_t* rowp = z + (size_t)row * DIN + col0;
; #pragma unroll
;                 for (int bj = 0; bj < 2; ++bj) {
;                     const u32x4 gw = *(const u32x4*)(rowp + O_GA + bj * 128);
;                     f32x4 g0, g1; unpack8(gw, g0, g1);
;                     f32x4 v0, v1;
; #pragma unroll
;                     for (int j = 0; j < 4; ++j) { v0[j] = sigmoidf_(g0[j]) * acc[ai][bj][m][0][j]; v1[j] = sigmoidf_(g1[j]) * acc[ai][bj][m][1][j]; }
;                     const u32x4 mw = *(const u32x4*)(rowp + bj * 128); f32x4 m0, m1; unpack8(mw, m0, m1); v0 += m0; v1 += m1;
;                     __builtin_amdgcn_raw_buffer_store_b128(pack8(v0, v1), rsrc, (unsigned)(((size_t)row * DIN + col0 + bj * 128) * 2), 0, 16  ); }
	v_mov_b32_e32 v56, v200
	v_mov_b32_e32 v57, v201
	v_mov_b32_e32 v58, v202
	v_mov_b32_e32 v59, v203
	v_mov_b32_e32 v60, v204
	v_mov_b32_e32 v61, v205
	v_mov_b32_e32 v62, v206
	v_mov_b32_e32 v63, v207
	v_add_u32_e32 v199, 0x155200, v198
	global_load_dwordx4 v[200:203], v199, s[26:27]
	v_add_u32_e32 v199, 0x154000, v198
	global_load_dwordx4 v[204:207], v199, s[26:27]
	s_mov_b32 s100, 0xbfb8aa3b
	v_lshlrev_b32_e32 v240, 16, v58
	v_and_b32_e32 v241, 0xffff0000, v58
	v_lshlrev_b32_e32 v242, 16, v56
	v_and_b32_e32 v243, 0xffff0000, v56
	v_lshlrev_b32_e32 v244, 16, v57
	v_and_b32_e32 v245, 0xffff0000, v57
	v_lshlrev_b32_e32 v246, 16, v59
	v_and_b32_e32 v247, 0xffff0000, v59
	v_pk_mul_f32 v[240:241], v[240:241], s[100:101] op_sel_hi:[1,0]
	v_pk_mul_f32 v[242:243], v[242:243], s[100:101] op_sel_hi:[1,0]
	v_pk_mul_f32 v[244:245], v[244:245], s[100:101] op_sel_hi:[1,0]
	v_pk_mul_f32 v[246:247], v[246:247], s[100:101] op_sel_hi:[1,0]
	v_exp_f32_e32 v240, v240
	v_exp_f32_e32 v241, v241
	v_exp_f32_e32 v242, v242
	v_exp_f32_e32 v243, v243
	v_exp_f32_e32 v244, v244
	v_exp_f32_e32 v245, v245
	v_exp_f32_e32 v246, v246
	v_exp_f32_e32 v247, v247
	s_nop 0
	v_pk_add_f32 v[240:241], v[240:241], 1.0 op_sel_hi:[1,0]
	v_pk_add_f32 v[242:243], v[242:243], 1.0 op_sel_hi:[1,0]
	v_pk_add_f32 v[244:245], v[244:245], 1.0 op_sel_hi:[1,0]
	v_pk_add_f32 v[246:247], v[246:247], 1.0 op_sel_hi:[1,0]
	v_rcp_f32_e32 v248, v240
	v_rcp_f32_e32 v249, v241
	v_rcp_f32_e32 v254, v242
	v_rcp_f32_e32 v255, v243
	v_pk_fma_f32 v[250:251], v[240:241], v[248:249], 1.0 op_sel_hi:[1,1,0] neg_lo:[1,0,0] neg_hi:[1,0,0]
	v_pk_fma_f32 v[56:57], v[242:243], v[254:255], 1.0 op_sel_hi:[1,1,0] neg_lo:[1,0,0] neg_hi:[1,0,0]
	v_pk_fma_f32 v[248:249], v[250:251], v[248:249], v[248:249]
	v_pk_fma_f32 v[254:255], v[56:57], v[254:255], v[254:255]
	v_pk_fma_f32 v[250:251], v[240:241], v[248:249], 1.0 op_sel_hi:[1,1,0] neg_lo:[1,0,0] neg_hi:[1,0,0]
	v_pk_fma_f32 v[56:57], v[242:243], v[254:255], 1.0 op_sel_hi:[1,1,0] neg_lo:[1,0,0] neg_hi:[1,0,0]
	v_pk_fma_f32 v[252:253], v[250:251], v[248:249], v[248:249]
	v_pk_fma_f32 v[58:59], v[56:57], v[254:255], v[254:255]
	v_pk_fma_f32 v[250:251], v[240:241], v[252:253], 1.0 op_sel_hi:[1,1,0] neg_lo:[1,0,0] neg_hi:[1,0,0]
	v_pk_fma_f32 v[56:57], v[242:243], v[58:59], 1.0 op_sel_hi:[1,1,0] neg_lo:[1,0,0] neg_hi:[1,0,0]
	v_pk_fma_f32 v[252:253], v[250:251], v[248:249], v[252:253]
	v_pk_fma_f32 v[58:59], v[56:57], v[254:255], v[58:59]
	v_div_fixup_f32 v240, v252, v240, 1.0
	v_div_fixup_f32 v241, v253, v241, 1.0
	v_div_fixup_f32 v242, v58, v242, 1.0
	v_div_fixup_f32 v243, v59, v243, 1.0
	v_rcp_f32_e32 v248, v244
	v_rcp_f32_e32 v249, v245
	v_rcp_f32_e32 v254, v246
	v_rcp_f32_e32 v255, v247
	v_pk_fma_f32 v[250:251], v[244:245], v[248:249], 1.0 op_sel_hi:[1,1,0] neg_lo:[1,0,0] neg_hi:[1,0,0]
	v_pk_fma_f32 v[56:57], v[246:247], v[254:255], 1.0 op_sel_hi:[1,1,0] neg_lo:[1,0,0] neg_hi:[1,0,0]
	v_pk_fma_f32 v[248:249], v[250:251], v[248:249], v[248:249]
	v_pk_fma_f32 v[254:255], v[56:57], v[254:255], v[254:255]
	v_pk_fma_f32 v[250:251], v[244:245], v[248:249], 1.0 op_sel_hi:[1,1,0] neg_lo:[1,0,0] neg_hi:[1,0,0]
	v_pk_fma_f32 v[56:57], v[246:247], v[254:255], 1.0 op_sel_hi:[1,1,0] neg_lo:[1,0,0] neg_hi:[1,0,0]
	v_pk_fma_f32 v[252:253], v[250:251], v[248:249], v[248:249]
	v_pk_fma_f32 v[58:59], v[56:57], v[254:255], v[254:255]
	v_pk_fma_f32 v[250:251], v[244:245], v[252:253], 1.0 op_sel_hi:[1,1,0] neg_lo:[1,0,0] neg_hi:[1,0,0]
	v_pk_fma_f32 v[56:57], v[246:247], v[58:59], 1.0 op_sel_hi:[1,1,0] neg_lo:[1,0,0] neg_hi:[1,0,0]
	v_pk_fma_f32 v[252:253], v[250:251], v[248:249], v[252:253]
	v_pk_fma_f32 v[58:59], v[56:57], v[254:255], v[58:59]
	v_div_fixup_f32 v244, v252, v244, 1.0
	v_div_fixup_f32 v245, v253, v245, 1.0
	v_div_fixup_f32 v246, v58, v246, 1.0
	v_div_fixup_f32 v247, v59, v247, 1.0
	v_lshlrev_b32_e32 v68, 16, v60
	v_and_b32_e32 v69, 0xffff0000, v60
	v_lshlrev_b32_e32 v70, 16, v62
	v_and_b32_e32 v71, 0xffff0000, v62
	v_lshlrev_b32_e32 v62, 16, v63
	v_and_b32_e32 v63, 0xffff0000, v63
	v_lshlrev_b32_e32 v60, 16, v61
	v_and_b32_e32 v61, 0xffff0000, v61
	v_pk_fma_f32 v[52:53], v[52:53], v[242:243], v[68:69]
	v_pk_fma_f32 v[56:57], v[50:51], v[246:247], v[62:63]
	v_pk_fma_f32 v[50:51], v[48:49], v[240:241], v[70:71]
	v_cvt_pk_bf16_f32 v48, v52, v53
	v_pk_fma_f32 v[54:55], v[54:55], v[244:245], v[60:61]
	s_nop 0
	v_cvt_pk_bf16_f32 v49, v54, v55
	v_cvt_pk_bf16_f32 v50, v50, v51
	v_cvt_pk_bf16_f32 v51, v56, v57
	buffer_store_dwordx4 v[48:51], v72, s[20:23], 0 offen offset:256 sc1
	s_nop 1
	v_add_u32_e32 v48, 0x4090, v158
	v_mad_i64_i32 v[50:51], s[6:7], v48, s77, 0
	v_lshl_add_u64 v[48:49], v[50:51], 1, s[26:27]
	v_lshl_add_u64 v[48:49], v[48:49], 0, v[142:143]
	v_add_co_u32_e32 v52, vcc, s78, v48
	s_nop 1
	v_addc_co_u32_e32 v53, vcc, 0, v49, vcc
	s_waitcnt vmcnt(7)
; __device__ __forceinline__ float sigmoidf_(float x) { return 1.0f / (1.0f + __expf(-x)); }
; __device__ __forceinline__ u32x4 pack8(const f32x4 v0, const f32x4 v1) { u32x4 w; w.x = pk2(v0[0], v0[1]); w.y = pk2(v0[2], v0[3]); w.z = pk2(v1[0], v1[1]); w.w = pk2(v1[2], v1[3]); return w; }
; __device__ __forceinline__ void unpack8(const u32x4 w, f32x4& v0, f32x4& v1) { v0 = (f32x4){bflo(w.x), bfhi(w.x), bflo(w.y), bfhi(w.y)}; v1 = (f32x4){bflo(w.z), bfhi(w.z), bflo(w.w), bfhi(w.w)}; }
;     __device__ __forceinline__ void operator()(const f32x4 (&acc)[2][2][4][2], const Unit& u, int wr, int wc, int fr, int fq) const {
;     ...
;                 const int row = row0 + ai * 128 + m * 16;
;                 const bf16_t* rowp = z + (size_t)row * DIN + col0;
; #pragma unroll
;                 for (int bj = 0; bj < 2; ++bj) {
;                     const u32x4 gw = *(const u32x4*)(rowp + O_GA + bj * 128);
;                     f32x4 g0, g1; unpack8(gw, g0, g1);
;                     f32x4 v0, v1;
; #pragma unroll
;                     for (int j = 0; j < 4; ++j) { v0[j] = sigmoidf_(g0[j]) * acc[ai][bj][m][0][j]; v1[j] = sigmoidf_(g1[j]) * acc[ai][bj][m][1][j]; }
;                     const u32x4 mw = *(const u32x4*)(rowp + bj * 128); f32x4 m0, m1; unpack8(mw, m0, m1); v0 += m0; v1 += m1;
;                     __builtin_amdgcn_raw_buffer_store_b128(pack8(v0, v1), rsrc, (unsigned)(((size_t)row * DIN + col0 + bj * 128) * 2), 0, 16  ); }
	v_mov_b32_e32 v54, v208
	v_mov_b32_e32 v55, v209
	v_mov_b32_e32 v56, v210
	v_mov_b32_e32 v57, v211
	v_mov_b32_e32 v58, v212
	v_mov_b32_e32 v59, v213
	v_mov_b32_e32 v60, v214
	v_mov_b32_e32 v61, v215
	v_add_u32_e32 v199, 0x155300, v198
	global_load_dwordx4 v[208:211], v199, s[26:27]
	v_add_u32_e32 v199, 0x154100, v198
	global_load_dwordx4 v[212:215], v199, s[26:27]
	s_mov_b32 s100, 0xbfb8aa3b
	v_lshlrev_b32_e32 v240, 16, v54
	v_and_b32_e32 v241, 0xffff0000, v54
	v_lshlrev_b32_e32 v242, 16, v56
	v_and_b32_e32 v243, 0xffff0000, v56
	v_lshlrev_b32_e32 v244, 16, v55
	v_and_b32_e32 v245, 0xffff0000, v55
	v_lshlrev_b32_e32 v246, 16, v57
	v_and_b32_e32 v247, 0xffff0000, v57
	v_pk_mul_f32 v[240:241], v[240:241], s[100:101] op_sel_hi:[1,0]
	v_pk_mul_f32 v[242:243], v[242:243], s[100:101] op_sel_hi:[1,0]
	v_pk_mul_f32 v[244:245], v[244:245], s[100:101] op_sel_hi:[1,0]
	v_pk_mul_f32 v[246:247], v[246:247], s[100:101] op_sel_hi:[1,0]
	v_exp_f32_e32 v240, v240
	v_exp_f32_e32 v241, v241
	v_exp_f32_e32 v242, v242
	v_exp_f32_e32 v243, v243
	v_exp_f32_e32 v244, v244
	v_exp_f32_e32 v245, v245
	v_exp_f32_e32 v246, v246
	v_exp_f32_e32 v247, v247
	s_nop 0
	v_pk_add_f32 v[240:241], v[240:241], 1.0 op_sel_hi:[1,0]
	v_pk_add_f32 v[242:243], v[242:243], 1.0 op_sel_hi:[1,0]
	v_pk_add_f32 v[244:245], v[244:245], 1.0 op_sel_hi:[1,0]
	v_pk_add_f32 v[246:247], v[246:247], 1.0 op_sel_hi:[1,0]
	v_rcp_f32_e32 v248, v240
	v_rcp_f32_e32 v249, v241
	v_rcp_f32_e32 v254, v242
	v_rcp_f32_e32 v255, v243
	v_pk_fma_f32 v[250:251], v[240:241], v[248:249], 1.0 op_sel_hi:[1,1,0] neg_lo:[1,0,0] neg_hi:[1,0,0]
	v_pk_fma_f32 v[54:55], v[242:243], v[254:255], 1.0 op_sel_hi:[1,1,0] neg_lo:[1,0,0] neg_hi:[1,0,0]
	v_pk_fma_f32 v[248:249], v[250:251], v[248:249], v[248:249]
	v_pk_fma_f32 v[254:255], v[54:55], v[254:255], v[254:255]
	v_pk_fma_f32 v[250:251], v[240:241], v[248:249], 1.0 op_sel_hi:[1,1,0] neg_lo:[1,0,0] neg_hi:[1,0,0]
	v_pk_fma_f32 v[54:55], v[242:243], v[254:255], 1.0 op_sel_hi:[1,1,0] neg_lo:[1,0,0] neg_hi:[1,0,0]
	v_pk_fma_f32 v[252:253], v[250:251], v[248:249], v[248:249]
	v_pk_fma_f32 v[56:57], v[54:55], v[254:255], v[254:255]
	v_pk_fma_f32 v[250:251], v[240:241], v[252:253], 1.0 op_sel_hi:[1,1,0] neg_lo:[1,0,0] neg_hi:[1,0,0]
	v_pk_fma_f32 v[54:55], v[242:243], v[56:57], 1.0 op_sel_hi:[1,1,0] neg_lo:[1,0,0] neg_hi:[1,0,0]
	v_pk_fma_f32 v[252:253], v[250:251], v[248:249], v[252:253]
	v_pk_fma_f32 v[56:57], v[54:55], v[254:255], v[56:57]
	v_div_fixup_f32 v240, v252, v240, 1.0
	v_div_fixup_f32 v241, v253, v241, 1.0
	v_div_fixup_f32 v242, v56, v242, 1.0
	v_div_fixup_f32 v243, v57, v243, 1.0
	v_rcp_f32_e32 v248, v244
	v_rcp_f32_e32 v249, v245
	v_rcp_f32_e32 v254, v246
	v_rcp_f32_e32 v255, v247
	v_pk_fma_f32 v[250:251], v[244:245], v[248:249], 1.0 op_sel_hi:[1,1,0] neg_lo:[1,0,0] neg_hi:[1,0,0]
	v_pk_fma_f32 v[54:55], v[246:247], v[254:255], 1.0 op_sel_hi:[1,1,0] neg_lo:[1,0,0] neg_hi:[1,0,0]
	v_pk_fma_f32 v[248:249], v[250:251], v[248:249], v[248:249]
	v_pk_fma_f32 v[254:255], v[54:55], v[254:255], v[254:255]
	v_pk_fma_f32 v[250:251], v[244:245], v[248:249], 1.0 op_sel_hi:[1,1,0] neg_lo:[1,0,0] neg_hi:[1,0,0]
	v_pk_fma_f32 v[54:55], v[246:247], v[254:255], 1.0 op_sel_hi:[1,1,0] neg_lo:[1,0,0] neg_hi:[1,0,0]
	v_pk_fma_f32 v[252:253], v[250:251], v[248:249], v[248:249]
	v_pk_fma_f32 v[56:57], v[54:55], v[254:255], v[254:255]
	v_pk_fma_f32 v[250:251], v[244:245], v[252:253], 1.0 op_sel_hi:[1,1,0] neg_lo:[1,0,0] neg_hi:[1,0,0]
	v_pk_fma_f32 v[54:55], v[246:247], v[56:57], 1.0 op_sel_hi:[1,1,0] neg_lo:[1,0,0] neg_hi:[1,0,0]
	v_pk_fma_f32 v[252:253], v[250:251], v[248:249], v[252:253]
	v_pk_fma_f32 v[56:57], v[54:55], v[254:255], v[56:57]
	v_div_fixup_f32 v244, v252, v244, 1.0
	v_div_fixup_f32 v245, v253, v245, 1.0
	v_div_fixup_f32 v246, v56, v246, 1.0
	v_div_fixup_f32 v247, v57, v247, 1.0
	v_lshlrev_b32_e32 v66, 16, v58
	v_and_b32_e32 v67, 0xffff0000, v58
	v_lshlrev_b32_e32 v68, 16, v60
	v_and_b32_e32 v69, 0xffff0000, v60
	v_lshlrev_b32_e32 v60, 16, v61
	v_and_b32_e32 v61, 0xffff0000, v61
	v_lshlrev_b32_e32 v58, 16, v59
	v_and_b32_e32 v59, 0xffff0000, v59
	v_pk_fma_f32 v[44:45], v[44:45], v[240:241], v[66:67]
	v_pk_fma_f32 v[54:55], v[42:43], v[246:247], v[60:61]
	v_pk_fma_f32 v[42:43], v[40:41], v[242:243], v[68:69]
	v_add_lshl_u32 v56, v140, v50, 1
	v_pk_fma_f32 v[46:47], v[46:47], v[244:245], v[58:59]
	v_cvt_pk_bf16_f32 v40, v44, v45
	s_nop 0
	v_cvt_pk_bf16_f32 v41, v46, v47
	v_cvt_pk_bf16_f32 v42, v42, v43
	v_cvt_pk_bf16_f32 v43, v54, v55
	buffer_store_dwordx4 v[40:43], v56, s[20:23], 0 offen sc1
	s_nop 0
	s_waitcnt vmcnt(7)
; __device__ __forceinline__ float sigmoidf_(float x) { return 1.0f / (1.0f + __expf(-x)); }
; __device__ __forceinline__ u32x4 pack8(const f32x4 v0, const f32x4 v1) { u32x4 w; w.x = pk2(v0[0], v0[1]); w.y = pk2(v0[2], v0[3]); w.z = pk2(v1[0], v1[1]); w.w = pk2(v1[2], v1[3]); return w; }
; __device__ __forceinline__ void unpack8(const u32x4 w, f32x4& v0, f32x4& v1) { v0 = (f32x4){bflo(w.x), bfhi(w.x), bflo(w.y), bfhi(w.y)}; v1 = (f32x4){bflo(w.z), bfhi(w.z), bflo(w.w), bfhi(w.w)}; }
;     __device__ __forceinline__ void operator()(const f32x4 (&acc)[2][2][4][2], const Unit& u, int wr, int wc, int fr, int fq) const {
;     ...
;                 const int row = row0 + ai * 128 + m * 16;
;                 const bf16_t* rowp = z + (size_t)row * DIN + col0;
; #pragma unroll
;                 for (int bj = 0; bj < 2; ++bj) {
;                     const u32x4 gw = *(const u32x4*)(rowp + O_GA + bj * 128);
;                     f32x4 g0, g1; unpack8(gw, g0, g1);
;                     f32x4 v0, v1;
; #pragma unroll
;                     for (int j = 0; j < 4; ++j) { v0[j] = sigmoidf_(g0[j]) * acc[ai][bj][m][0][j]; v1[j] = sigmoidf_(g1[j]) * acc[ai][bj][m][1][j]; }
;                     const u32x4 mw = *(const u32x4*)(rowp + bj * 128); f32x4 m0, m1; unpack8(mw, m0, m1); v0 += m0; v1 += m1;
;                     __builtin_amdgcn_raw_buffer_store_b128(pack8(v0, v1), rsrc, (unsigned)(((size_t)row * DIN + col0 + bj * 128) * 2), 0, 16  ); }
	v_mov_b32_e32 v40, v232
	v_mov_b32_e32 v41, v233
	v_mov_b32_e32 v42, v234
	v_mov_b32_e32 v43, v235
	v_mov_b32_e32 v44, v236
	v_mov_b32_e32 v45, v237
	v_mov_b32_e32 v46, v238
	v_mov_b32_e32 v47, v239
	v_add_u32_e32 v199, 0x177200, v198
	global_load_dwordx4 v[232:235], v199, s[26:27]
	v_add_u32_e32 v199, 0x176000, v198
	global_load_dwordx4 v[236:239], v199, s[26:27]
	s_mov_b32 s100, 0xbfb8aa3b
	v_lshlrev_b32_e32 v240, 16, v42
	v_and_b32_e32 v241, 0xffff0000, v42
	v_lshlrev_b32_e32 v242, 16, v40
	v_and_b32_e32 v243, 0xffff0000, v40
	v_lshlrev_b32_e32 v244, 16, v41
	v_and_b32_e32 v245, 0xffff0000, v41
	v_lshlrev_b32_e32 v246, 16, v43
	v_and_b32_e32 v247, 0xffff0000, v43
	v_pk_mul_f32 v[240:241], v[240:241], s[100:101] op_sel_hi:[1,0]
	v_pk_mul_f32 v[242:243], v[242:243], s[100:101] op_sel_hi:[1,0]
	v_pk_mul_f32 v[244:245], v[244:245], s[100:101] op_sel_hi:[1,0]
	v_pk_mul_f32 v[246:247], v[246:247], s[100:101] op_sel_hi:[1,0]
	v_exp_f32_e32 v240, v240
	v_exp_f32_e32 v241, v241
	v_exp_f32_e32 v242, v242
	v_exp_f32_e32 v243, v243
	v_exp_f32_e32 v244, v244
	v_exp_f32_e32 v245, v245
	v_exp_f32_e32 v246, v246
	v_exp_f32_e32 v247, v247
	s_nop 0
	v_pk_add_f32 v[240:241], v[240:241], 1.0 op_sel_hi:[1,0]
	v_pk_add_f32 v[242:243], v[242:243], 1.0 op_sel_hi:[1,0]
	v_pk_add_f32 v[244:245], v[244:245], 1.0 op_sel_hi:[1,0]
	v_pk_add_f32 v[246:247], v[246:247], 1.0 op_sel_hi:[1,0]
	v_rcp_f32_e32 v248, v240
	v_rcp_f32_e32 v249, v241
	v_rcp_f32_e32 v254, v242
	v_rcp_f32_e32 v255, v243
	v_pk_fma_f32 v[250:251], v[240:241], v[248:249], 1.0 op_sel_hi:[1,1,0] neg_lo:[1,0,0] neg_hi:[1,0,0]
	v_pk_fma_f32 v[40:41], v[242:243], v[254:255], 1.0 op_sel_hi:[1,1,0] neg_lo:[1,0,0] neg_hi:[1,0,0]
	v_pk_fma_f32 v[248:249], v[250:251], v[248:249], v[248:249]
	v_pk_fma_f32 v[254:255], v[40:41], v[254:255], v[254:255]
	v_pk_fma_f32 v[250:251], v[240:241], v[248:249], 1.0 op_sel_hi:[1,1,0] neg_lo:[1,0,0] neg_hi:[1,0,0]
	v_pk_fma_f32 v[40:41], v[242:243], v[254:255], 1.0 op_sel_hi:[1,1,0] neg_lo:[1,0,0] neg_hi:[1,0,0]
	v_pk_fma_f32 v[252:253], v[250:251], v[248:249], v[248:249]
	v_pk_fma_f32 v[42:43], v[40:41], v[254:255], v[254:255]
	v_pk_fma_f32 v[250:251], v[240:241], v[252:253], 1.0 op_sel_hi:[1,1,0] neg_lo:[1,0,0] neg_hi:[1,0,0]
	v_pk_fma_f32 v[40:41], v[242:243], v[42:43], 1.0 op_sel_hi:[1,1,0] neg_lo:[1,0,0] neg_hi:[1,0,0]
	v_pk_fma_f32 v[252:253], v[250:251], v[248:249], v[252:253]
	v_pk_fma_f32 v[42:43], v[40:41], v[254:255], v[42:43]
	v_div_fixup_f32 v240, v252, v240, 1.0
	v_div_fixup_f32 v241, v253, v241, 1.0
	v_div_fixup_f32 v242, v42, v242, 1.0
	v_div_fixup_f32 v243, v43, v243, 1.0
	v_rcp_f32_e32 v248, v244
	v_rcp_f32_e32 v249, v245
	v_rcp_f32_e32 v254, v246
	v_rcp_f32_e32 v255, v247
	v_pk_fma_f32 v[250:251], v[244:245], v[248:249], 1.0 op_sel_hi:[1,1,0] neg_lo:[1,0,0] neg_hi:[1,0,0]
	v_pk_fma_f32 v[40:41], v[246:247], v[254:255], 1.0 op_sel_hi:[1,1,0] neg_lo:[1,0,0] neg_hi:[1,0,0]
	v_pk_fma_f32 v[248:249], v[250:251], v[248:249], v[248:249]
	v_pk_fma_f32 v[254:255], v[40:41], v[254:255], v[254:255]
	v_pk_fma_f32 v[250:251], v[244:245], v[248:249], 1.0 op_sel_hi:[1,1,0] neg_lo:[1,0,0] neg_hi:[1,0,0]
	v_pk_fma_f32 v[40:41], v[246:247], v[254:255], 1.0 op_sel_hi:[1,1,0] neg_lo:[1,0,0] neg_hi:[1,0,0]
	v_pk_fma_f32 v[252:253], v[250:251], v[248:249], v[248:249]
	v_pk_fma_f32 v[42:43], v[40:41], v[254:255], v[254:255]
	v_pk_fma_f32 v[250:251], v[244:245], v[252:253], 1.0 op_sel_hi:[1,1,0] neg_lo:[1,0,0] neg_hi:[1,0,0]
	v_pk_fma_f32 v[40:41], v[246:247], v[42:43], 1.0 op_sel_hi:[1,1,0] neg_lo:[1,0,0] neg_hi:[1,0,0]
	v_pk_fma_f32 v[252:253], v[250:251], v[248:249], v[252:253]
	v_pk_fma_f32 v[42:43], v[40:41], v[254:255], v[42:43]
	v_div_fixup_f32 v244, v252, v244, 1.0
	v_div_fixup_f32 v245, v253, v245, 1.0
	v_div_fixup_f32 v246, v42, v246, 1.0
	v_div_fixup_f32 v247, v43, v247, 1.0
	v_lshlrev_b32_e32 v52, 16, v44
	v_and_b32_e32 v53, 0xffff0000, v44
	v_lshlrev_b32_e32 v54, 16, v46
	v_and_b32_e32 v55, 0xffff0000, v46
	v_lshlrev_b32_e32 v46, 16, v47
	v_and_b32_e32 v47, 0xffff0000, v47
	v_lshlrev_b32_e32 v44, 16, v45
	v_and_b32_e32 v45, 0xffff0000, v45
	v_pk_fma_f32 v[36:37], v[36:37], v[242:243], v[52:53]
	v_pk_fma_f32 v[40:41], v[34:35], v[246:247], v[46:47]
	v_pk_fma_f32 v[34:35], v[32:33], v[240:241], v[54:55]
	v_cvt_pk_bf16_f32 v32, v36, v37
	v_pk_fma_f32 v[38:39], v[38:39], v[244:245], v[44:45]
	s_nop 0
	v_cvt_pk_bf16_f32 v33, v38, v39
	v_cvt_pk_bf16_f32 v34, v34, v35
	v_cvt_pk_bf16_f32 v35, v40, v41
	buffer_store_dwordx4 v[32:35], v56, s[20:23], 0 offen offset:256 sc1
	s_nop 1
	v_add_u32_e32 v32, 0x40a0, v158
	v_mad_i64_i32 v[34:35], s[6:7], v32, s77, 0
	v_lshl_add_u64 v[32:33], v[34:35], 1, s[26:27]
	v_lshl_add_u64 v[32:33], v[32:33], 0, v[142:143]
	v_add_co_u32_e32 v36, vcc, s78, v32
	s_nop 1
	v_addc_co_u32_e32 v37, vcc, 0, v33, vcc
	s_waitcnt vmcnt(7)
; __device__ __forceinline__ float sigmoidf_(float x) { return 1.0f / (1.0f + __expf(-x)); }
; __device__ __forceinline__ u32x4 pack8(const f32x4 v0, const f32x4 v1) { u32x4 w; w.x = pk2(v0[0], v0[1]); w.y = pk2(v0[2], v0[3]); w.z = pk2(v1[0], v1[1]); w.w = pk2(v1[2], v1[3]); return w; }
; __device__ __forceinline__ void unpack8(const u32x4 w, f32x4& v0, f32x4& v1) { v0 = (f32x4){bflo(w.x), bfhi(w.x), bflo(w.y), bfhi(w.y)}; v1 = (f32x4){bflo(w.z), bfhi(w.z), bflo(w.w), bfhi(w.w)}; }
;     __device__ __forceinline__ void operator()(const f32x4 (&acc)[2][2][4][2], const Unit& u, int wr, int wc, int fr, int fq) const {
;     ...
;                 const int row = row0 + ai * 128 + m * 16;
;                 const bf16_t* rowp = z + (size_t)row * DIN + col0;
; #pragma unroll
;                 for (int bj = 0; bj < 2; ++bj) {
;                     const u32x4 gw = *(const u32x4*)(rowp + O_GA + bj * 128);
;                     f32x4 g0, g1; unpack8(gw, g0, g1);
;                     f32x4 v0, v1;
; #pragma unroll
;                     for (int j = 0; j < 4; ++j) { v0[j] = sigmoidf_(g0[j]) * acc[ai][bj][m][0][j]; v1[j] = sigmoidf_(g1[j]) * acc[ai][bj][m][1][j]; }
;                     const u32x4 mw = *(const u32x4*)(rowp + bj * 128); f32x4 m0, m1; unpack8(mw, m0, m1); v0 += m0; v1 += m1;
;                     __builtin_amdgcn_raw_buffer_store_b128(pack8(v0, v1), rsrc, (unsigned)(((size_t)row * DIN + col0 + bj * 128) * 2), 0, 16  ); }
	v_mov_b32_e32 v38, v200
	v_mov_b32_e32 v39, v201
	v_mov_b32_e32 v40, v202
	v_mov_b32_e32 v41, v203
	v_mov_b32_e32 v42, v204
	v_mov_b32_e32 v43, v205
	v_mov_b32_e32 v44, v206
	v_mov_b32_e32 v45, v207
	v_add_u32_e32 v199, 0x177300, v198
	global_load_dwordx4 v[200:203], v199, s[26:27]
	v_add_u32_e32 v199, 0x176100, v198
	global_load_dwordx4 v[204:207], v199, s[26:27]
	s_mov_b32 s100, 0xbfb8aa3b
	v_lshlrev_b32_e32 v240, 16, v38
	v_and_b32_e32 v241, 0xffff0000, v38
	v_lshlrev_b32_e32 v242, 16, v40
	v_and_b32_e32 v243, 0xffff0000, v40
	v_lshlrev_b32_e32 v244, 16, v39
	v_and_b32_e32 v245, 0xffff0000, v39
	v_lshlrev_b32_e32 v246, 16, v41
	v_and_b32_e32 v247, 0xffff0000, v41
	v_pk_mul_f32 v[240:241], v[240:241], s[100:101] op_sel_hi:[1,0]
	v_pk_mul_f32 v[242:243], v[242:243], s[100:101] op_sel_hi:[1,0]
	v_pk_mul_f32 v[244:245], v[244:245], s[100:101] op_sel_hi:[1,0]
	v_pk_mul_f32 v[246:247], v[246:247], s[100:101] op_sel_hi:[1,0]
	v_exp_f32_e32 v240, v240
	v_exp_f32_e32 v241, v241
	v_exp_f32_e32 v242, v242
	v_exp_f32_e32 v243, v243
	v_exp_f32_e32 v244, v244
	v_exp_f32_e32 v245, v245
	v_exp_f32_e32 v246, v246
	v_exp_f32_e32 v247, v247
	s_nop 0
	v_pk_add_f32 v[240:241], v[240:241], 1.0 op_sel_hi:[1,0]
	v_pk_add_f32 v[242:243], v[242:243], 1.0 op_sel_hi:[1,0]
	v_pk_add_f32 v[244:245], v[244:245], 1.0 op_sel_hi:[1,0]
	v_pk_add_f32 v[246:247], v[246:247], 1.0 op_sel_hi:[1,0]
	v_rcp_f32_e32 v248, v240
	v_rcp_f32_e32 v249, v241
	v_rcp_f32_e32 v254, v242
	v_rcp_f32_e32 v255, v243
	v_pk_fma_f32 v[250:251], v[240:241], v[248:249], 1.0 op_sel_hi:[1,1,0] neg_lo:[1,0,0] neg_hi:[1,0,0]
	v_pk_fma_f32 v[38:39], v[242:243], v[254:255], 1.0 op_sel_hi:[1,1,0] neg_lo:[1,0,0] neg_hi:[1,0,0]
	v_pk_fma_f32 v[248:249], v[250:251], v[248:249], v[248:249]
	v_pk_fma_f32 v[254:255], v[38:39], v[254:255], v[254:255]
	v_pk_fma_f32 v[250:251], v[240:241], v[248:249], 1.0 op_sel_hi:[1,1,0] neg_lo:[1,0,0] neg_hi:[1,0,0]
	v_pk_fma_f32 v[38:39], v[242:243], v[254:255], 1.0 op_sel_hi:[1,1,0] neg_lo:[1,0,0] neg_hi:[1,0,0]
	v_pk_fma_f32 v[252:253], v[250:251], v[248:249], v[248:249]
	v_pk_fma_f32 v[40:41], v[38:39], v[254:255], v[254:255]
	v_pk_fma_f32 v[250:251], v[240:241], v[252:253], 1.0 op_sel_hi:[1,1,0] neg_lo:[1,0,0] neg_hi:[1,0,0]
	v_pk_fma_f32 v[38:39], v[242:243], v[40:41], 1.0 op_sel_hi:[1,1,0] neg_lo:[1,0,0] neg_hi:[1,0,0]
	v_pk_fma_f32 v[252:253], v[250:251], v[248:249], v[252:253]
	v_pk_fma_f32 v[40:41], v[38:39], v[254:255], v[40:41]
	v_div_fixup_f32 v240, v252, v240, 1.0
	v_div_fixup_f32 v241, v253, v241, 1.0
	v_div_fixup_f32 v242, v40, v242, 1.0
	v_div_fixup_f32 v243, v41, v243, 1.0
	v_rcp_f32_e32 v248, v244
	v_rcp_f32_e32 v249, v245
	v_rcp_f32_e32 v254, v246
	v_rcp_f32_e32 v255, v247
	v_pk_fma_f32 v[250:251], v[244:245], v[248:249], 1.0 op_sel_hi:[1,1,0] neg_lo:[1,0,0] neg_hi:[1,0,0]
	v_pk_fma_f32 v[38:39], v[246:247], v[254:255], 1.0 op_sel_hi:[1,1,0] neg_lo:[1,0,0] neg_hi:[1,0,0]
	v_pk_fma_f32 v[248:249], v[250:251], v[248:249], v[248:249]
	v_pk_fma_f32 v[254:255], v[38:39], v[254:255], v[254:255]
	v_pk_fma_f32 v[250:251], v[244:245], v[248:249], 1.0 op_sel_hi:[1,1,0] neg_lo:[1,0,0] neg_hi:[1,0,0]
	v_pk_fma_f32 v[38:39], v[246:247], v[254:255], 1.0 op_sel_hi:[1,1,0] neg_lo:[1,0,0] neg_hi:[1,0,0]
	v_pk_fma_f32 v[252:253], v[250:251], v[248:249], v[248:249]
	v_pk_fma_f32 v[40:41], v[38:39], v[254:255], v[254:255]
	v_pk_fma_f32 v[250:251], v[244:245], v[252:253], 1.0 op_sel_hi:[1,1,0] neg_lo:[1,0,0] neg_hi:[1,0,0]
	v_pk_fma_f32 v[38:39], v[246:247], v[40:41], 1.0 op_sel_hi:[1,1,0] neg_lo:[1,0,0] neg_hi:[1,0,0]
	v_pk_fma_f32 v[252:253], v[250:251], v[248:249], v[252:253]
	v_pk_fma_f32 v[40:41], v[38:39], v[254:255], v[40:41]
	v_div_fixup_f32 v244, v252, v244, 1.0
	v_div_fixup_f32 v245, v253, v245, 1.0
	v_div_fixup_f32 v246, v40, v246, 1.0
	v_div_fixup_f32 v247, v41, v247, 1.0
	v_lshlrev_b32_e32 v50, 16, v42
	v_and_b32_e32 v51, 0xffff0000, v42
	v_lshlrev_b32_e32 v52, 16, v44
	v_and_b32_e32 v53, 0xffff0000, v44
	v_lshlrev_b32_e32 v44, 16, v45
	v_and_b32_e32 v45, 0xffff0000, v45
	v_lshlrev_b32_e32 v42, 16, v43
	v_and_b32_e32 v43, 0xffff0000, v43
	v_pk_fma_f32 v[28:29], v[28:29], v[240:241], v[50:51]
	v_pk_fma_f32 v[38:39], v[26:27], v[246:247], v[44:45]
	v_pk_fma_f32 v[26:27], v[24:25], v[242:243], v[52:53]
	v_add_lshl_u32 v40, v140, v34, 1
	v_pk_fma_f32 v[30:31], v[30:31], v[244:245], v[42:43]
	v_cvt_pk_bf16_f32 v24, v28, v29
	s_nop 0
	v_cvt_pk_bf16_f32 v25, v30, v31
	v_cvt_pk_bf16_f32 v26, v26, v27
	v_cvt_pk_bf16_f32 v27, v38, v39
	buffer_store_dwordx4 v[24:27], v40, s[20:23], 0 offen sc1
	s_nop 0
	s_waitcnt vmcnt(7)
; __device__ __forceinline__ float sigmoidf_(float x) { return 1.0f / (1.0f + __expf(-x)); }
; __device__ __forceinline__ u32x4 pack8(const f32x4 v0, const f32x4 v1) { u32x4 w; w.x = pk2(v0[0], v0[1]); w.y = pk2(v0[2], v0[3]); w.z = pk2(v1[0], v1[1]); w.w = pk2(v1[2], v1[3]); return w; }
; __device__ __forceinline__ void unpack8(const u32x4 w, f32x4& v0, f32x4& v1) { v0 = (f32x4){bflo(w.x), bfhi(w.x), bflo(w.y), bfhi(w.y)}; v1 = (f32x4){bflo(w.z), bfhi(w.z), bflo(w.w), bfhi(w.w)}; }
;     __device__ __forceinline__ void operator()(const f32x4 (&acc)[2][2][4][2], const Unit& u, int wr, int wc, int fr, int fq) const {
;     ...
;                 const int row = row0 + ai * 128 + m * 16;
;                 const bf16_t* rowp = z + (size_t)row * DIN + col0;
; #pragma unroll
;                 for (int bj = 0; bj < 2; ++bj) {
;                     const u32x4 gw = *(const u32x4*)(rowp + O_GA + bj * 128);
;                     f32x4 g0, g1; unpack8(gw, g0, g1);
;                     f32x4 v0, v1;
; #pragma unroll
;                     for (int j = 0; j < 4; ++j) { v0[j] = sigmoidf_(g0[j]) * acc[ai][bj][m][0][j]; v1[j] = sigmoidf_(g1[j]) * acc[ai][bj][m][1][j]; }
;                     const u32x4 mw = *(const u32x4*)(rowp + bj * 128); f32x4 m0, m1; unpack8(mw, m0, m1); v0 += m0; v1 += m1;
;                     __builtin_amdgcn_raw_buffer_store_b128(pack8(v0, v1), rsrc, (unsigned)(((size_t)row * DIN + col0 + bj * 128) * 2), 0, 16  ); }
	v_mov_b32_e32 v24, v208
	v_mov_b32_e32 v25, v209
	v_mov_b32_e32 v26, v210
	v_mov_b32_e32 v27, v211
	v_mov_b32_e32 v28, v212
	v_mov_b32_e32 v29, v213
	v_mov_b32_e32 v30, v214
	v_mov_b32_e32 v31, v215
	s_mov_b32 s100, 0xbfb8aa3b
	v_lshlrev_b32_e32 v240, 16, v26
	v_and_b32_e32 v241, 0xffff0000, v26
	v_lshlrev_b32_e32 v242, 16, v24
	v_and_b32_e32 v243, 0xffff0000, v24
	v_lshlrev_b32_e32 v244, 16, v25
	v_and_b32_e32 v245, 0xffff0000, v25
	v_lshlrev_b32_e32 v246, 16, v27
	v_and_b32_e32 v247, 0xffff0000, v27
	v_pk_mul_f32 v[240:241], v[240:241], s[100:101] op_sel_hi:[1,0]
	v_pk_mul_f32 v[242:243], v[242:243], s[100:101] op_sel_hi:[1,0]
	v_pk_mul_f32 v[244:245], v[244:245], s[100:101] op_sel_hi:[1,0]
	v_pk_mul_f32 v[246:247], v[246:247], s[100:101] op_sel_hi:[1,0]
	v_exp_f32_e32 v240, v240
	v_exp_f32_e32 v241, v241
	v_exp_f32_e32 v242, v242
	v_exp_f32_e32 v243, v243
	v_exp_f32_e32 v244, v244
	v_exp_f32_e32 v245, v245
	v_exp_f32_e32 v246, v246
	v_exp_f32_e32 v247, v247
	s_nop 0
	v_pk_add_f32 v[240:241], v[240:241], 1.0 op_sel_hi:[1,0]
	v_pk_add_f32 v[242:243], v[242:243], 1.0 op_sel_hi:[1,0]
	v_pk_add_f32 v[244:245], v[244:245], 1.0 op_sel_hi:[1,0]
	v_pk_add_f32 v[246:247], v[246:247], 1.0 op_sel_hi:[1,0]
	v_rcp_f32_e32 v248, v240
	v_rcp_f32_e32 v249, v241
	v_rcp_f32_e32 v254, v242
	v_rcp_f32_e32 v255, v243
	v_pk_fma_f32 v[250:251], v[240:241], v[248:249], 1.0 op_sel_hi:[1,1,0] neg_lo:[1,0,0] neg_hi:[1,0,0]
	v_pk_fma_f32 v[24:25], v[242:243], v[254:255], 1.0 op_sel_hi:[1,1,0] neg_lo:[1,0,0] neg_hi:[1,0,0]
	v_pk_fma_f32 v[248:249], v[250:251], v[248:249], v[248:249]
	v_pk_fma_f32 v[254:255], v[24:25], v[254:255], v[254:255]
	v_pk_fma_f32 v[250:251], v[240:241], v[248:249], 1.0 op_sel_hi:[1,1,0] neg_lo:[1,0,0] neg_hi:[1,0,0]
	v_pk_fma_f32 v[24:25], v[242:243], v[254:255], 1.0 op_sel_hi:[1,1,0] neg_lo:[1,0,0] neg_hi:[1,0,0]
	v_pk_fma_f32 v[252:253], v[250:251], v[248:249], v[248:249]
	v_pk_fma_f32 v[26:27], v[24:25], v[254:255], v[254:255]
	v_pk_fma_f32 v[250:251], v[240:241], v[252:253], 1.0 op_sel_hi:[1,1,0] neg_lo:[1,0,0] neg_hi:[1,0,0]
	v_pk_fma_f32 v[24:25], v[242:243], v[26:27], 1.0 op_sel_hi:[1,1,0] neg_lo:[1,0,0] neg_hi:[1,0,0]
	v_pk_fma_f32 v[252:253], v[250:251], v[248:249], v[252:253]
	v_pk_fma_f32 v[26:27], v[24:25], v[254:255], v[26:27]
	v_div_fixup_f32 v240, v252, v240, 1.0
	v_div_fixup_f32 v241, v253, v241, 1.0
	v_div_fixup_f32 v242, v26, v242, 1.0
	v_div_fixup_f32 v243, v27, v243, 1.0
	v_rcp_f32_e32 v248, v244
	v_rcp_f32_e32 v249, v245
	v_rcp_f32_e32 v254, v246
	v_rcp_f32_e32 v255, v247
	v_pk_fma_f32 v[250:251], v[244:245], v[248:249], 1.0 op_sel_hi:[1,1,0] neg_lo:[1,0,0] neg_hi:[1,0,0]
	v_pk_fma_f32 v[24:25], v[246:247], v[254:255], 1.0 op_sel_hi:[1,1,0] neg_lo:[1,0,0] neg_hi:[1,0,0]
	v_pk_fma_f32 v[248:249], v[250:251], v[248:249], v[248:249]
	v_pk_fma_f32 v[254:255], v[24:25], v[254:255], v[254:255]
	v_pk_fma_f32 v[250:251], v[244:245], v[248:249], 1.0 op_sel_hi:[1,1,0] neg_lo:[1,0,0] neg_hi:[1,0,0]
	v_pk_fma_f32 v[24:25], v[246:247], v[254:255], 1.0 op_sel_hi:[1,1,0] neg_lo:[1,0,0] neg_hi:[1,0,0]
	v_pk_fma_f32 v[252:253], v[250:251], v[248:249], v[248:249]
	v_pk_fma_f32 v[26:27], v[24:25], v[254:255], v[254:255]
	v_pk_fma_f32 v[250:251], v[244:245], v[252:253], 1.0 op_sel_hi:[1,1,0] neg_lo:[1,0,0] neg_hi:[1,0,0]
	v_pk_fma_f32 v[24:25], v[246:247], v[26:27], 1.0 op_sel_hi:[1,1,0] neg_lo:[1,0,0] neg_hi:[1,0,0]
	v_pk_fma_f32 v[252:253], v[250:251], v[248:249], v[252:253]
	v_pk_fma_f32 v[26:27], v[24:25], v[254:255], v[26:27]
	v_div_fixup_f32 v244, v252, v244, 1.0
	v_div_fixup_f32 v245, v253, v245, 1.0
	v_div_fixup_f32 v246, v26, v246, 1.0
	v_div_fixup_f32 v247, v27, v247, 1.0
	v_lshlrev_b32_e32 v36, 16, v28
	v_and_b32_e32 v37, 0xffff0000, v28
	v_lshlrev_b32_e32 v38, 16, v30
	v_and_b32_e32 v39, 0xffff0000, v30
	v_lshlrev_b32_e32 v30, 16, v31
	v_and_b32_e32 v31, 0xffff0000, v31
	v_lshlrev_b32_e32 v28, 16, v29
	v_and_b32_e32 v29, 0xffff0000, v29
	v_pk_fma_f32 v[20:21], v[20:21], v[242:243], v[36:37]
	v_pk_fma_f32 v[24:25], v[18:19], v[246:247], v[30:31]
	v_pk_fma_f32 v[18:19], v[16:17], v[240:241], v[38:39]
	v_cvt_pk_bf16_f32 v16, v20, v21
	v_pk_fma_f32 v[22:23], v[22:23], v[244:245], v[28:29]
	s_nop 0
	v_cvt_pk_bf16_f32 v17, v22, v23
	v_cvt_pk_bf16_f32 v18, v18, v19
	v_cvt_pk_bf16_f32 v19, v24, v25
	buffer_store_dwordx4 v[16:19], v40, s[20:23], 0 offen offset:256 sc1
	s_nop 1
	v_add_u32_e32 v16, 0x40b0, v158
	v_mad_i64_i32 v[18:19], s[6:7], v16, s77, 0
	v_lshl_add_u64 v[16:17], v[18:19], 1, s[26:27]
	v_lshl_add_u64 v[16:17], v[16:17], 0, v[142:143]
	v_add_co_u32_e32 v20, vcc, s78, v16
	s_nop 1
	v_addc_co_u32_e32 v21, vcc, 0, v17, vcc
	s_waitcnt vmcnt(5)
; __device__ __forceinline__ float sigmoidf_(float x) { return 1.0f / (1.0f + __expf(-x)); }
; __device__ __forceinline__ u32x4 pack8(const f32x4 v0, const f32x4 v1) { u32x4 w; w.x = pk2(v0[0], v0[1]); w.y = pk2(v0[2], v0[3]); w.z = pk2(v1[0], v1[1]); w.w = pk2(v1[2], v1[3]); return w; }
; __device__ __forceinline__ void unpack8(const u32x4 w, f32x4& v0, f32x4& v1) { v0 = (f32x4){bflo(w.x), bfhi(w.x), bflo(w.y), bfhi(w.y)}; v1 = (f32x4){bflo(w.z), bfhi(w.z), bflo(w.w), bfhi(w.w)}; }
;     __device__ __forceinline__ void operator()(const f32x4 (&acc)[2][2][4][2], const Unit& u, int wr, int wc, int fr, int fq) const {
;     ...
;                 const int row = row0 + ai * 128 + m * 16;
;                 const bf16_t* rowp = z + (size_t)row * DIN + col0;
; #pragma unroll
;                 for (int bj = 0; bj < 2; ++bj) {
;                     const u32x4 gw = *(const u32x4*)(rowp + O_GA + bj * 128);
;                     f32x4 g0, g1; unpack8(gw, g0, g1);
;                     f32x4 v0, v1;
; #pragma unroll
;                     for (int j = 0; j < 4; ++j) { v0[j] = sigmoidf_(g0[j]) * acc[ai][bj][m][0][j]; v1[j] = sigmoidf_(g1[j]) * acc[ai][bj][m][1][j]; }
;                     const u32x4 mw = *(const u32x4*)(rowp + bj * 128); f32x4 m0, m1; unpack8(mw, m0, m1); v0 += m0; v1 += m1;
;                     __builtin_amdgcn_raw_buffer_store_b128(pack8(v0, v1), rsrc, (unsigned)(((size_t)row * DIN + col0 + bj * 128) * 2), 0, 16  ); }
	v_mov_b32_e32 v22, v232
	v_mov_b32_e32 v23, v233
	v_mov_b32_e32 v24, v234
	v_mov_b32_e32 v25, v235
	v_mov_b32_e32 v26, v236
	v_mov_b32_e32 v27, v237
	v_mov_b32_e32 v28, v238
	v_mov_b32_e32 v29, v239
	s_mov_b32 s100, 0xbfb8aa3b
	v_lshlrev_b32_e32 v240, 16, v22
	v_and_b32_e32 v241, 0xffff0000, v22
	v_lshlrev_b32_e32 v242, 16, v24
	v_and_b32_e32 v243, 0xffff0000, v24
	v_lshlrev_b32_e32 v244, 16, v23
	v_and_b32_e32 v245, 0xffff0000, v23
	v_lshlrev_b32_e32 v246, 16, v25
	v_and_b32_e32 v247, 0xffff0000, v25
	v_pk_mul_f32 v[240:241], v[240:241], s[100:101] op_sel_hi:[1,0]
	v_pk_mul_f32 v[242:243], v[242:243], s[100:101] op_sel_hi:[1,0]
	v_pk_mul_f32 v[244:245], v[244:245], s[100:101] op_sel_hi:[1,0]
	v_pk_mul_f32 v[246:247], v[246:247], s[100:101] op_sel_hi:[1,0]
	v_exp_f32_e32 v240, v240
	v_exp_f32_e32 v241, v241
	v_exp_f32_e32 v242, v242
	v_exp_f32_e32 v243, v243
	v_exp_f32_e32 v244, v244
	v_exp_f32_e32 v245, v245
	v_exp_f32_e32 v246, v246
	v_exp_f32_e32 v247, v247
	s_nop 0
	v_pk_add_f32 v[240:241], v[240:241], 1.0 op_sel_hi:[1,0]
	v_pk_add_f32 v[242:243], v[242:243], 1.0 op_sel_hi:[1,0]
	v_pk_add_f32 v[244:245], v[244:245], 1.0 op_sel_hi:[1,0]
	v_pk_add_f32 v[246:247], v[246:247], 1.0 op_sel_hi:[1,0]
	v_rcp_f32_e32 v248, v240
	v_rcp_f32_e32 v249, v241
	v_rcp_f32_e32 v254, v242
	v_rcp_f32_e32 v255, v243
	v_pk_fma_f32 v[250:251], v[240:241], v[248:249], 1.0 op_sel_hi:[1,1,0] neg_lo:[1,0,0] neg_hi:[1,0,0]
	v_pk_fma_f32 v[22:23], v[242:243], v[254:255], 1.0 op_sel_hi:[1,1,0] neg_lo:[1,0,0] neg_hi:[1,0,0]
	v_pk_fma_f32 v[248:249], v[250:251], v[248:249], v[248:249]
	v_pk_fma_f32 v[254:255], v[22:23], v[254:255], v[254:255]
	v_pk_fma_f32 v[250:251], v[240:241], v[248:249], 1.0 op_sel_hi:[1,1,0] neg_lo:[1,0,0] neg_hi:[1,0,0]
	v_pk_fma_f32 v[22:23], v[242:243], v[254:255], 1.0 op_sel_hi:[1,1,0] neg_lo:[1,0,0] neg_hi:[1,0,0]
	v_pk_fma_f32 v[252:253], v[250:251], v[248:249], v[248:249]
	v_pk_fma_f32 v[24:25], v[22:23], v[254:255], v[254:255]
	v_pk_fma_f32 v[250:251], v[240:241], v[252:253], 1.0 op_sel_hi:[1,1,0] neg_lo:[1,0,0] neg_hi:[1,0,0]
	v_pk_fma_f32 v[22:23], v[242:243], v[24:25], 1.0 op_sel_hi:[1,1,0] neg_lo:[1,0,0] neg_hi:[1,0,0]
	v_pk_fma_f32 v[252:253], v[250:251], v[248:249], v[252:253]
	v_pk_fma_f32 v[24:25], v[22:23], v[254:255], v[24:25]
	v_div_fixup_f32 v240, v252, v240, 1.0
	v_div_fixup_f32 v241, v253, v241, 1.0
	v_div_fixup_f32 v242, v24, v242, 1.0
	v_div_fixup_f32 v243, v25, v243, 1.0
	v_rcp_f32_e32 v248, v244
	v_rcp_f32_e32 v249, v245
	v_rcp_f32_e32 v254, v246
	v_rcp_f32_e32 v255, v247
	v_pk_fma_f32 v[250:251], v[244:245], v[248:249], 1.0 op_sel_hi:[1,1,0] neg_lo:[1,0,0] neg_hi:[1,0,0]
	v_pk_fma_f32 v[22:23], v[246:247], v[254:255], 1.0 op_sel_hi:[1,1,0] neg_lo:[1,0,0] neg_hi:[1,0,0]
	v_pk_fma_f32 v[248:249], v[250:251], v[248:249], v[248:249]
	v_pk_fma_f32 v[254:255], v[22:23], v[254:255], v[254:255]
	v_pk_fma_f32 v[250:251], v[244:245], v[248:249], 1.0 op_sel_hi:[1,1,0] neg_lo:[1,0,0] neg_hi:[1,0,0]
	v_pk_fma_f32 v[22:23], v[246:247], v[254:255], 1.0 op_sel_hi:[1,1,0] neg_lo:[1,0,0] neg_hi:[1,0,0]
	v_pk_fma_f32 v[252:253], v[250:251], v[248:249], v[248:249]
	v_pk_fma_f32 v[24:25], v[22:23], v[254:255], v[254:255]
	v_pk_fma_f32 v[250:251], v[244:245], v[252:253], 1.0 op_sel_hi:[1,1,0] neg_lo:[1,0,0] neg_hi:[1,0,0]
	v_pk_fma_f32 v[22:23], v[246:247], v[24:25], 1.0 op_sel_hi:[1,1,0] neg_lo:[1,0,0] neg_hi:[1,0,0]
	v_pk_fma_f32 v[252:253], v[250:251], v[248:249], v[252:253]
	v_pk_fma_f32 v[24:25], v[22:23], v[254:255], v[24:25]
	v_div_fixup_f32 v244, v252, v244, 1.0
	v_div_fixup_f32 v245, v253, v245, 1.0
	v_div_fixup_f32 v246, v24, v246, 1.0
	v_div_fixup_f32 v247, v25, v247, 1.0
	v_lshlrev_b32_e32 v34, 16, v26
	v_and_b32_e32 v35, 0xffff0000, v26
	v_lshlrev_b32_e32 v36, 16, v28
	v_and_b32_e32 v37, 0xffff0000, v28
	v_lshlrev_b32_e32 v28, 16, v29
	v_and_b32_e32 v29, 0xffff0000, v29
	v_lshlrev_b32_e32 v26, 16, v27
	v_and_b32_e32 v27, 0xffff0000, v27
	v_pk_fma_f32 v[12:13], v[12:13], v[240:241], v[34:35]
	v_pk_fma_f32 v[22:23], v[10:11], v[246:247], v[28:29]
	v_pk_fma_f32 v[10:11], v[8:9], v[242:243], v[36:37]
	v_add_lshl_u32 v24, v140, v18, 1
	v_pk_fma_f32 v[14:15], v[14:15], v[244:245], v[26:27]
	v_cvt_pk_bf16_f32 v8, v12, v13
	s_nop 0
	v_cvt_pk_bf16_f32 v9, v14, v15
	v_cvt_pk_bf16_f32 v10, v10, v11
	v_cvt_pk_bf16_f32 v11, v22, v23
	buffer_store_dwordx4 v[8:11], v24, s[20:23], 0 offen sc1
	s_nop 0
	s_waitcnt vmcnt(3)
; __device__ __forceinline__ float sigmoidf_(float x) { return 1.0f / (1.0f + __expf(-x)); }
; __device__ __forceinline__ u32x4 pack8(const f32x4 v0, const f32x4 v1) { u32x4 w; w.x = pk2(v0[0], v0[1]); w.y = pk2(v0[2], v0[3]); w.z = pk2(v1[0], v1[1]); w.w = pk2(v1[2], v1[3]); return w; }
; __device__ __forceinline__ void unpack8(const u32x4 w, f32x4& v0, f32x4& v1) { v0 = (f32x4){bflo(w.x), bfhi(w.x), bflo(w.y), bfhi(w.y)}; v1 = (f32x4){bflo(w.z), bfhi(w.z), bflo(w.w), bfhi(w.w)}; }
;     __device__ __forceinline__ void operator()(const f32x4 (&acc)[2][2][4][2], const Unit& u, int wr, int wc, int fr, int fq) const {
;     ...
;                 for (int bj = 0; bj < 2; ++bj) {
;                     const u32x4 gw = *(const u32x4*)(rowp + O_GA + bj * 128);
;                     f32x4 g0, g1; unpack8(gw, g0, g1);
;                     f32x4 v0, v1;
; #pragma unroll
;                     for (int j = 0; j < 4; ++j) { v0[j] = sigmoidf_(g0[j]) * acc[ai][bj][m][0][j]; v1[j] = sigmoidf_(g1[j]) * acc[ai][bj][m][1][j]; }
;                     const u32x4 mw = *(const u32x4*)(rowp + bj * 128); f32x4 m0, m1; unpack8(mw, m0, m1); v0 += m0; v1 += m1;
;                     __builtin_amdgcn_raw_buffer_store_b128(pack8(v0, v1), rsrc, (unsigned)(((size_t)row * DIN + col0 + bj * 128) * 2), 0, 16  ); }
;             }
;         asm volatile("s_waitcnt vmcnt(0)" ::: "memory");
;         if (fr == 0 && fq == 0) (void)__hip_atomic_fetch_add(ready + 64 * (pm_off + u.pm), 1u, __ATOMIC_RELAXED, __HIP_MEMORY_SCOPE_AGENT);
	v_mov_b32_e32 v8, v200
	v_mov_b32_e32 v9, v201
	v_mov_b32_e32 v10, v202
	v_mov_b32_e32 v11, v203
	v_mov_b32_e32 v12, v204
	v_mov_b32_e32 v13, v205
	v_mov_b32_e32 v14, v206
	v_mov_b32_e32 v15, v207
	s_mov_b32 s100, 0xbfb8aa3b
	v_lshlrev_b32_e32 v240, 16, v10
	v_and_b32_e32 v241, 0xffff0000, v10
	v_lshlrev_b32_e32 v242, 16, v8
	v_and_b32_e32 v243, 0xffff0000, v8
	v_lshlrev_b32_e32 v244, 16, v9
	v_and_b32_e32 v245, 0xffff0000, v9
	v_lshlrev_b32_e32 v246, 16, v11
	v_and_b32_e32 v247, 0xffff0000, v11
	v_pk_mul_f32 v[240:241], v[240:241], s[100:101] op_sel_hi:[1,0]
	v_pk_mul_f32 v[242:243], v[242:243], s[100:101] op_sel_hi:[1,0]
	v_pk_mul_f32 v[244:245], v[244:245], s[100:101] op_sel_hi:[1,0]
	v_pk_mul_f32 v[246:247], v[246:247], s[100:101] op_sel_hi:[1,0]
	v_exp_f32_e32 v240, v240
	v_exp_f32_e32 v241, v241
	v_exp_f32_e32 v242, v242
	v_exp_f32_e32 v243, v243
	v_exp_f32_e32 v244, v244
	v_exp_f32_e32 v245, v245
	v_exp_f32_e32 v246, v246
	v_exp_f32_e32 v247, v247
	s_nop 0
	v_pk_add_f32 v[240:241], v[240:241], 1.0 op_sel_hi:[1,0]
	v_pk_add_f32 v[242:243], v[242:243], 1.0 op_sel_hi:[1,0]
	v_pk_add_f32 v[244:245], v[244:245], 1.0 op_sel_hi:[1,0]
	v_pk_add_f32 v[246:247], v[246:247], 1.0 op_sel_hi:[1,0]
	v_rcp_f32_e32 v248, v240
	v_rcp_f32_e32 v249, v241
	v_rcp_f32_e32 v254, v242
	v_rcp_f32_e32 v255, v243
	v_pk_fma_f32 v[250:251], v[240:241], v[248:249], 1.0 op_sel_hi:[1,1,0] neg_lo:[1,0,0] neg_hi:[1,0,0]
	v_pk_fma_f32 v[8:9], v[242:243], v[254:255], 1.0 op_sel_hi:[1,1,0] neg_lo:[1,0,0] neg_hi:[1,0,0]
	v_pk_fma_f32 v[248:249], v[250:251], v[248:249], v[248:249]
	v_pk_fma_f32 v[254:255], v[8:9], v[254:255], v[254:255]
	v_pk_fma_f32 v[250:251], v[240:241], v[248:249], 1.0 op_sel_hi:[1,1,0] neg_lo:[1,0,0] neg_hi:[1,0,0]
	v_pk_fma_f32 v[8:9], v[242:243], v[254:255], 1.0 op_sel_hi:[1,1,0] neg_lo:[1,0,0] neg_hi:[1,0,0]
	v_pk_fma_f32 v[252:253], v[250:251], v[248:249], v[248:249]
	v_pk_fma_f32 v[10:11], v[8:9], v[254:255], v[254:255]
	v_pk_fma_f32 v[250:251], v[240:241], v[252:253], 1.0 op_sel_hi:[1,1,0] neg_lo:[1,0,0] neg_hi:[1,0,0]
	v_pk_fma_f32 v[8:9], v[242:243], v[10:11], 1.0 op_sel_hi:[1,1,0] neg_lo:[1,0,0] neg_hi:[1,0,0]
	v_pk_fma_f32 v[252:253], v[250:251], v[248:249], v[252:253]
	v_pk_fma_f32 v[10:11], v[8:9], v[254:255], v[10:11]
	v_div_fixup_f32 v240, v252, v240, 1.0
	v_div_fixup_f32 v241, v253, v241, 1.0
	v_div_fixup_f32 v242, v10, v242, 1.0
	v_div_fixup_f32 v243, v11, v243, 1.0
	v_rcp_f32_e32 v248, v244
	v_rcp_f32_e32 v249, v245
	v_rcp_f32_e32 v254, v246
	v_rcp_f32_e32 v255, v247
	v_pk_fma_f32 v[250:251], v[244:245], v[248:249], 1.0 op_sel_hi:[1,1,0] neg_lo:[1,0,0] neg_hi:[1,0,0]
	v_pk_fma_f32 v[8:9], v[246:247], v[254:255], 1.0 op_sel_hi:[1,1,0] neg_lo:[1,0,0] neg_hi:[1,0,0]
	v_pk_fma_f32 v[248:249], v[250:251], v[248:249], v[248:249]
	v_pk_fma_f32 v[254:255], v[8:9], v[254:255], v[254:255]
	v_pk_fma_f32 v[250:251], v[244:245], v[248:249], 1.0 op_sel_hi:[1,1,0] neg_lo:[1,0,0] neg_hi:[1,0,0]
	v_pk_fma_f32 v[8:9], v[246:247], v[254:255], 1.0 op_sel_hi:[1,1,0] neg_lo:[1,0,0] neg_hi:[1,0,0]
	v_pk_fma_f32 v[252:253], v[250:251], v[248:249], v[248:249]
	v_pk_fma_f32 v[10:11], v[8:9], v[254:255], v[254:255]
	v_pk_fma_f32 v[250:251], v[244:245], v[252:253], 1.0 op_sel_hi:[1,1,0] neg_lo:[1,0,0] neg_hi:[1,0,0]
	v_pk_fma_f32 v[8:9], v[246:247], v[10:11], 1.0 op_sel_hi:[1,1,0] neg_lo:[1,0,0] neg_hi:[1,0,0]
	v_pk_fma_f32 v[252:253], v[250:251], v[248:249], v[252:253]
	v_pk_fma_f32 v[10:11], v[8:9], v[254:255], v[10:11]
	v_div_fixup_f32 v244, v252, v244, 1.0
	v_div_fixup_f32 v245, v253, v245, 1.0
	v_div_fixup_f32 v246, v10, v246, 1.0
	v_div_fixup_f32 v247, v11, v247, 1.0
	v_lshlrev_b32_e32 v20, 16, v12
	v_and_b32_e32 v21, 0xffff0000, v12
	v_lshlrev_b32_e32 v22, 16, v14
	v_and_b32_e32 v23, 0xffff0000, v14
	v_lshlrev_b32_e32 v14, 16, v15
	v_and_b32_e32 v15, 0xffff0000, v15
	v_lshlrev_b32_e32 v12, 16, v13
	v_and_b32_e32 v13, 0xffff0000, v13
	v_pk_fma_f32 v[4:5], v[4:5], v[242:243], v[20:21]
	v_pk_fma_f32 v[8:9], v[2:3], v[246:247], v[14:15]
	v_pk_fma_f32 v[2:3], v[0:1], v[240:241], v[22:23]
	v_pk_fma_f32 v[6:7], v[6:7], v[244:245], v[12:13]
	v_cvt_pk_bf16_f32 v0, v4, v5
	s_nop 0
	v_cvt_pk_bf16_f32 v1, v6, v7
	v_cvt_pk_bf16_f32 v2, v2, v3
	v_cvt_pk_bf16_f32 v3, v8, v9
	buffer_store_dwordx4 v[0:3], v24, s[20:23], 0 offen offset:256 sc1
	s_waitcnt vmcnt(0)
	s_and_saveexec_b64 s[12:13], s[10:11]
	s_cbranch_execz .LBB0_715
	s_mov_b64 s[14:15], exec
	v_mbcnt_lo_u32_b32 v0, s14, 0
	v_mbcnt_hi_u32_b32 v0, s15, v0
	v_cmp_eq_u32_e32 vcc, 0, v0
	s_and_b64 s[6:7], exec, vcc
	s_mov_b64 exec, s[6:7]
	s_cbranch_execz .LBB0_715
	s_lshl_b32 s6, s79, 6
	s_addk_i32 s6, 0x1000
	s_ashr_i32 s7, s6, 31
	s_lshl_b64 s[6:7], s[6:7], 2
	s_add_u32 s6, s34, s6
	s_addc_u32 s7, s35, s7
	s_bcnt1_i32_b64 s8, s[14:15]
	v_mov_b32_e32 v0, s8
	global_atomic_add v131, v0, s[6:7]
	s_branch .LBB0_715

; #define PG8_STAGE(bufoff, gbase, voff) do { _Pragma("unroll") for (int _i = 0; _i < 2; ++_i) \
;         __builtin_amdgcn_global_load_lds((const unsigned*)((const char*)(gbase) + (voff)[_i]), (LAS unsigned*)(lds + (bufoff) + ldsw + _i * 8192), 16, 0, 0); } while (0)
; #define PG8_LDA(dst, b, h) do { _Pragma("unroll") for (int m = 0; m < 4; ++m) _Pragma("unroll") for (int k = 0; k < 2; ++k) dst[m][k] = *(const LAS bf16x8*)(lds + PG8_SA(b, h) + aoff + m * 2048 + k * 1024); } while (0)
; #define PG8_LDB(dst, b, h) do { _Pragma("unroll") for (int n = 0; n < 2; ++n) _Pragma("unroll") for (int k = 0; k < 2; ++k) dst[n][k] = *(const LAS bf16x8*)(lds + PG8_SB(b, h) + boff + n * 2048 + k * 1024); } while (0)
; #define PG8_MMA(ai, bj, At, Bt) do { __builtin_amdgcn_s_setprio(1); _Pragma("unroll") for (int m = 0; m < 4; ++m) _Pragma("unroll") for (int n = 0; n < 2; ++n) _Pragma("unroll") for (int k = 0; k < 2; ++k) \
;         acc[ai][bj][m][n] = __builtin_amdgcn_mfma_f32_16x16x32_bf16(Bt[n][k], At[m][k], acc[ai][bj][m][n], 0, 0, 0); __builtin_amdgcn_s_setprio(0); } while (0)
; #define PG8_WAIT_V(n) asm volatile("s_waitcnt vmcnt(" #n ")" ::: "memory")
; #define PG8_WAIT_L(n) asm volatile("s_waitcnt lgkmcnt(" #n ")" ::: "memory")
; #define PG8_BAR __builtin_amdgcn_s_barrier()
; #define PG8_SCHED __builtin_amdgcn_sched_barrier(0)
;     ...
;             PG8_LDB(B0, 0, 0); PG8_SCHED; PG8_LDA(At, 0, 0); PG8_STAGE(PG8_SA(1, 1), a1 + hA, voffA);
;             PG8_WAIT_L(8); PG8_BAR; PG8_WAIT_L(0); PG8_MMA(0, 0, At, B0); PG8_BAR; PG8_SCHED;
;             PG8_LDB(B1, 0, 1); PG8_STAGE(PG8_SB(0, 0), b2, voffB);
;             PG8_BAR; PG8_WAIT_L(0); PG8_MMA(0, 1, At, B1); PG8_BAR;
;             PG8_LDA(At, 0, 1); PG8_STAGE(PG8_SA(0, 0), a2, voffA);
;             PG8_BAR; PG8_WAIT_L(0); PG8_MMA(1, 0, At, B0); PG8_BAR; PG8_SCHED;
;             PG8_STAGE(PG8_SB(0, 1), b2 + hB, voffB);
;             PG8_WAIT_V(6); PG8_BAR; PG8_MMA(1, 1, At, B1); PG8_BAR;
.LBB0_1841:
	ds_read_b128 v[146:149], v159
	ds_read_b128 v[150:153], v159 offset:1024
	ds_read_b128 v[162:165], v159 offset:2048
	ds_read_b128 v[170:173], v159 offset:3072
	s_add_u32 s14, s12, 0xfffe0080
	s_addc_u32 s15, s13, -1
	s_cmp_eq_u32 s45, 4
	s_cselect_b32 s17, s7, s15
	s_cselect_b32 s16, s18, s14
	s_cselect_b32 s15, s19, s44
	s_cselect_b32 s14, s33, s39
	v_lshl_add_u64 v[154:155], s[12:13], 0, v[138:139]
	s_add_i32 m0, s62, 0xc000
	ds_read_b128 v[174:177], v160
	ds_read_b128 v[178:181], v160 offset:1024
	ds_read_b128 v[182:185], v160 offset:2048
	ds_read_b128 v[186:189], v160 offset:3072
	ds_read_b128 v[190:193], v160 offset:4096
	ds_read_b128 v[194:197], v160 offset:5120
	ds_read_b128 v[198:201], v160 offset:6144
	ds_read_b128 v[202:205], v160 offset:7168
	global_load_lds_dwordx4 v[154:155], off
	v_lshl_add_u64 v[154:155], s[12:13], 0, v[136:137]
	s_add_i32 m0, s62, 0xe000
	s_nop 0
	global_load_lds_dwordx4 v[154:155], off
	s_waitcnt lgkmcnt(8)
	s_barrier
	s_waitcnt lgkmcnt(0)
	s_setprio 1
	s_waitcnt lgkmcnt(0)
	v_mfma_f32_16x16x32_bf16 v[124:127], v[146:149], v[174:177], v[124:127]
	v_mfma_f32_16x16x32_bf16 v[120:123], v[162:165], v[174:177], v[120:123]
	v_mfma_f32_16x16x32_bf16 v[108:111], v[146:149], v[182:185], v[108:111]
	v_mfma_f32_16x16x32_bf16 v[104:107], v[162:165], v[182:185], v[104:107]
	v_mfma_f32_16x16x32_bf16 v[92:95], v[146:149], v[190:193], v[92:95]
	v_mfma_f32_16x16x32_bf16 v[88:91], v[162:165], v[190:193], v[88:91]
	v_mfma_f32_16x16x32_bf16 v[76:79], v[146:149], v[198:201], v[76:79]
	v_mfma_f32_16x16x32_bf16 v[72:75], v[162:165], v[198:201], v[72:75]
	v_mfma_f32_16x16x32_bf16 v[124:127], v[150:153], v[178:181], v[124:127]
	v_mfma_f32_16x16x32_bf16 v[120:123], v[170:173], v[178:181], v[120:123]
	v_mfma_f32_16x16x32_bf16 v[108:111], v[150:153], v[186:189], v[108:111]
	v_mfma_f32_16x16x32_bf16 v[104:107], v[170:173], v[186:189], v[104:107]
	v_mfma_f32_16x16x32_bf16 v[92:95], v[150:153], v[194:197], v[92:95]
	v_mfma_f32_16x16x32_bf16 v[88:91], v[170:173], v[194:197], v[88:91]
	v_mfma_f32_16x16x32_bf16 v[76:79], v[150:153], v[202:205], v[76:79]
	v_mfma_f32_16x16x32_bf16 v[72:75], v[170:173], v[202:205], v[72:75]
	s_setprio 0
	s_barrier
	s_add_i32 s55, s71, s61
	v_lshl_add_u64 v[154:155], s[14:15], 0, v[130:131]
	s_mov_b32 m0, s55
	ds_read_b128 v[206:209], v161
	ds_read_b128 v[210:213], v161 offset:1024
	ds_read_b128 v[214:217], v161 offset:2048
	ds_read_b128 v[218:221], v161 offset:3072
	global_load_lds_dwordx4 v[154:155], off
	v_lshl_add_u64 v[222:223], s[14:15], 0, v[134:135]
	s_add_i32 m0, s55, 0x2000
	s_nop 0
	global_load_lds_dwordx4 v[222:223], off
	s_barrier
	s_waitcnt lgkmcnt(0)
	s_setprio 1
	s_waitcnt lgkmcnt(0)
	v_mfma_f32_16x16x32_bf16 v[116:119], v[206:209], v[174:177], v[116:119]
	v_mfma_f32_16x16x32_bf16 v[112:115], v[214:217], v[174:177], v[112:115]
	v_mfma_f32_16x16x32_bf16 v[100:103], v[206:209], v[182:185], v[100:103]
	v_mfma_f32_16x16x32_bf16 v[96:99], v[214:217], v[182:185], v[96:99]
	v_mfma_f32_16x16x32_bf16 v[84:87], v[206:209], v[190:193], v[84:87]
	v_mfma_f32_16x16x32_bf16 v[80:83], v[214:217], v[190:193], v[80:83]
	v_mfma_f32_16x16x32_bf16 v[68:71], v[206:209], v[198:201], v[68:71]
	v_mfma_f32_16x16x32_bf16 v[64:67], v[214:217], v[198:201], v[64:67]
	v_mfma_f32_16x16x32_bf16 v[116:119], v[210:213], v[178:181], v[116:119]
	v_mfma_f32_16x16x32_bf16 v[112:115], v[218:221], v[178:181], v[112:115]
	v_mfma_f32_16x16x32_bf16 v[100:103], v[210:213], v[186:189], v[100:103]
	v_mfma_f32_16x16x32_bf16 v[96:99], v[218:221], v[186:189], v[96:99]
	v_mfma_f32_16x16x32_bf16 v[84:87], v[210:213], v[194:197], v[84:87]
	v_mfma_f32_16x16x32_bf16 v[80:83], v[218:221], v[194:197], v[80:83]
	v_mfma_f32_16x16x32_bf16 v[68:71], v[210:213], v[202:205], v[68:71]
	v_mfma_f32_16x16x32_bf16 v[64:67], v[218:221], v[202:205], v[64:67]
	s_setprio 0
	s_mov_b32 m0, s62
	v_lshl_add_u64 v[224:225], s[16:17], 0, v[128:129]
	s_barrier
	ds_read_b128 v[174:177], v160 offset:16384
	ds_read_b128 v[178:181], v160 offset:17408
	ds_read_b128 v[182:185], v160 offset:18432
	ds_read_b128 v[186:189], v160 offset:19456
	ds_read_b128 v[190:193], v160 offset:20480
	ds_read_b128 v[194:197], v160 offset:21504
	ds_read_b128 v[198:201], v160 offset:22528
	ds_read_b128 v[202:205], v160 offset:23552
	global_load_lds_dwordx4 v[224:225], off
	v_lshl_add_u64 v[226:227], s[16:17], 0, v[132:133]
	s_mov_b32 m0, s63
	s_nop 0
	global_load_lds_dwordx4 v[226:227], off
	s_barrier
	s_waitcnt lgkmcnt(0)
	s_setprio 1
	s_waitcnt lgkmcnt(0)
	v_mfma_f32_16x16x32_bf16 v[60:63], v[146:149], v[174:177], v[60:63]
	v_mfma_f32_16x16x32_bf16 v[56:59], v[162:165], v[174:177], v[56:59]
	v_mfma_f32_16x16x32_bf16 v[44:47], v[146:149], v[182:185], v[44:47]
	v_mfma_f32_16x16x32_bf16 v[40:43], v[162:165], v[182:185], v[40:43]
	v_mfma_f32_16x16x32_bf16 v[28:31], v[146:149], v[190:193], v[28:31]
	v_mfma_f32_16x16x32_bf16 v[24:27], v[162:165], v[190:193], v[24:27]
	v_mfma_f32_16x16x32_bf16 v[12:15], v[146:149], v[198:201], v[12:15]
	v_mfma_f32_16x16x32_bf16 v[8:11], v[162:165], v[198:201], v[8:11]
	v_mfma_f32_16x16x32_bf16 v[60:63], v[150:153], v[178:181], v[60:63]
	v_mfma_f32_16x16x32_bf16 v[56:59], v[170:173], v[178:181], v[56:59]
	v_mfma_f32_16x16x32_bf16 v[44:47], v[150:153], v[186:189], v[44:47]
	v_mfma_f32_16x16x32_bf16 v[40:43], v[170:173], v[186:189], v[40:43]
	v_mfma_f32_16x16x32_bf16 v[28:31], v[150:153], v[194:197], v[28:31]
	v_mfma_f32_16x16x32_bf16 v[24:27], v[170:173], v[194:197], v[24:27]
	v_mfma_f32_16x16x32_bf16 v[12:15], v[150:153], v[202:205], v[12:15]
	v_mfma_f32_16x16x32_bf16 v[8:11], v[170:173], v[202:205], v[8:11]
	s_setprio 0
	s_barrier
; #define PG8_STAGE(bufoff, gbase, voff) do { _Pragma("unroll") for (int _i = 0; _i < 2; ++_i) \
;         __builtin_amdgcn_global_load_lds((const unsigned*)((const char*)(gbase) + (voff)[_i]), (LAS unsigned*)(lds + (bufoff) + ldsw + _i * 8192), 16, 0, 0); } while (0)
; #define PG8_LDA(dst, b, h) do { _Pragma("unroll") for (int m = 0; m < 4; ++m) _Pragma("unroll") for (int k = 0; k < 2; ++k) dst[m][k] = *(const LAS bf16x8*)(lds + PG8_SA(b, h) + aoff + m * 2048 + k * 1024); } while (0)
; #define PG8_LDB(dst, b, h) do { _Pragma("unroll") for (int n = 0; n < 2; ++n) _Pragma("unroll") for (int k = 0; k < 2; ++k) dst[n][k] = *(const LAS bf16x8*)(lds + PG8_SB(b, h) + boff + n * 2048 + k * 1024); } while (0)
; #define PG8_MMA(ai, bj, At, Bt) do { __builtin_amdgcn_s_setprio(1); _Pragma("unroll") for (int m = 0; m < 4; ++m) _Pragma("unroll") for (int n = 0; n < 2; ++n) _Pragma("unroll") for (int k = 0; k < 2; ++k) \
;         acc[ai][bj][m][n] = __builtin_amdgcn_mfma_f32_16x16x32_bf16(Bt[n][k], At[m][k], acc[ai][bj][m][n], 0, 0, 0); __builtin_amdgcn_s_setprio(0); } while (0)
; #define PG8_WAIT_V(n) asm volatile("s_waitcnt vmcnt(" #n ")" ::: "memory")
; #define PG8_WAIT_L(n) asm volatile("s_waitcnt lgkmcnt(" #n ")" ::: "memory")
; #define PG8_BAR __builtin_amdgcn_s_barrier()
; #define PG8_SCHED __builtin_amdgcn_sched_barrier(0)
;     ...
;             PG8_WAIT_V(6); PG8_BAR; PG8_MMA(1, 1, At, B1); PG8_BAR;
;             PG8_LDB(B0, 1, 0); PG8_SCHED; PG8_LDA(At, 1, 0); PG8_STAGE(PG8_SA(0, 1), a2 + hA, voffA);
;             PG8_WAIT_L(8); PG8_BAR; PG8_WAIT_L(0); PG8_MMA(0, 0, At, B0); PG8_BAR; PG8_SCHED;
;             PG8_LDB(B1, 1, 1); PG8_STAGE(PG8_SB(1, 0), b3, voffB);
;             PG8_BAR; PG8_WAIT_L(0); PG8_MMA(0, 1, At, B1); PG8_BAR;
;             PG8_LDA(At, 1, 1); PG8_STAGE(PG8_SA(1, 0), a3, voffA);
;             PG8_BAR; PG8_WAIT_L(0); PG8_MMA(1, 0, At, B0); PG8_BAR; PG8_SCHED;
	s_add_u32 s76, s14, 0x20000
	s_addc_u32 s77, s15, 0
	s_add_i32 s55, s72, s61
	v_lshl_add_u64 v[146:147], s[76:77], 0, v[130:131]
	s_mov_b32 m0, s55
	s_nop 0
	global_load_lds_dwordx4 v[146:147], off
	v_lshl_add_u64 v[146:147], s[76:77], 0, v[134:135]
	s_add_i32 m0, s55, 0x2000
	s_nop 0
	global_load_lds_dwordx4 v[146:147], off
	s_waitcnt vmcnt(6)
	s_barrier
	s_setprio 1
	v_mfma_f32_16x16x32_bf16 v[52:55], v[206:209], v[174:177], v[52:55]
	v_mfma_f32_16x16x32_bf16 v[48:51], v[214:217], v[174:177], v[48:51]
	v_mfma_f32_16x16x32_bf16 v[36:39], v[206:209], v[182:185], v[36:39]
	v_mfma_f32_16x16x32_bf16 v[32:35], v[214:217], v[182:185], v[32:35]
	v_mfma_f32_16x16x32_bf16 v[20:23], v[206:209], v[190:193], v[20:23]
	v_mfma_f32_16x16x32_bf16 v[16:19], v[214:217], v[190:193], v[16:19]
	v_mfma_f32_16x16x32_bf16 v[4:7], v[206:209], v[198:201], v[4:7]
	v_mfma_f32_16x16x32_bf16 v[0:3], v[214:217], v[198:201], v[0:3]
	v_mfma_f32_16x16x32_bf16 v[52:55], v[210:213], v[178:181], v[52:55]
	v_mfma_f32_16x16x32_bf16 v[48:51], v[218:221], v[178:181], v[48:51]
	v_mfma_f32_16x16x32_bf16 v[36:39], v[210:213], v[186:189], v[36:39]
	v_mfma_f32_16x16x32_bf16 v[32:35], v[218:221], v[186:189], v[32:35]
	v_mfma_f32_16x16x32_bf16 v[20:23], v[210:213], v[194:197], v[20:23]
	v_mfma_f32_16x16x32_bf16 v[16:19], v[218:221], v[194:197], v[16:19]
	v_mfma_f32_16x16x32_bf16 v[4:7], v[210:213], v[202:205], v[4:7]
	v_mfma_f32_16x16x32_bf16 v[0:3], v[218:221], v[202:205], v[0:3]
	s_setprio 0
	s_add_i32 s55, 0, 0x18000
	v_add_u32_e32 v169, s55, v157
	s_barrier
	ds_read_b128 v[146:149], v169
	ds_read_b128 v[150:153], v169 offset:1024
	ds_read_b128 v[162:165], v169 offset:2048
	ds_read_b128 v[170:173], v169 offset:3072
	s_add_u32 s16, s16, 0x20000
	s_addc_u32 s17, s17, 0
	s_mov_b32 m0, s64
	v_lshl_add_u64 v[206:207], s[16:17], 0, v[128:129]
	ds_read_b128 v[174:177], v160 offset:32768
	ds_read_b128 v[178:181], v160 offset:33792
	ds_read_b128 v[182:185], v160 offset:34816
	ds_read_b128 v[186:189], v160 offset:35840
	ds_read_b128 v[190:193], v160 offset:36864
	ds_read_b128 v[194:197], v160 offset:37888
	ds_read_b128 v[198:201], v160 offset:38912
	ds_read_b128 v[202:205], v160 offset:39936
	global_load_lds_dwordx4 v[206:207], off
	v_lshl_add_u64 v[206:207], s[16:17], 0, v[132:133]
	s_mov_b32 m0, s65
	s_nop 0
	global_load_lds_dwordx4 v[206:207], off
	s_waitcnt lgkmcnt(8)
	s_barrier
	s_waitcnt lgkmcnt(0)
	s_setprio 1
	s_waitcnt lgkmcnt(0)
	v_mfma_f32_16x16x32_bf16 v[124:127], v[146:149], v[174:177], v[124:127]
	v_mfma_f32_16x16x32_bf16 v[120:123], v[162:165], v[174:177], v[120:123]
	v_mfma_f32_16x16x32_bf16 v[108:111], v[146:149], v[182:185], v[108:111]
	v_mfma_f32_16x16x32_bf16 v[104:107], v[162:165], v[182:185], v[104:107]
	v_mfma_f32_16x16x32_bf16 v[92:95], v[146:149], v[190:193], v[92:95]
	v_mfma_f32_16x16x32_bf16 v[88:91], v[162:165], v[190:193], v[88:91]
	v_mfma_f32_16x16x32_bf16 v[76:79], v[146:149], v[198:201], v[76:79]
	v_mfma_f32_16x16x32_bf16 v[72:75], v[162:165], v[198:201], v[72:75]
	v_mfma_f32_16x16x32_bf16 v[124:127], v[150:153], v[178:181], v[124:127]
	v_mfma_f32_16x16x32_bf16 v[120:123], v[170:173], v[178:181], v[120:123]
	v_mfma_f32_16x16x32_bf16 v[108:111], v[150:153], v[186:189], v[108:111]
	v_mfma_f32_16x16x32_bf16 v[104:107], v[170:173], v[186:189], v[104:107]
	v_mfma_f32_16x16x32_bf16 v[92:95], v[150:153], v[194:197], v[92:95]
	v_mfma_f32_16x16x32_bf16 v[88:91], v[170:173], v[194:197], v[88:91]
	v_mfma_f32_16x16x32_bf16 v[76:79], v[150:153], v[202:205], v[76:79]
	v_mfma_f32_16x16x32_bf16 v[72:75], v[170:173], v[202:205], v[72:75]
	s_setprio 0
	s_barrier
	s_add_i32 s16, 0, 0x1c000
	s_add_i32 s17, s55, s61
	v_add_u32_e32 v169, s16, v157
	v_lshl_add_u64 v[154:155], v[154:155], 0, s[40:41]
	s_mov_b32 m0, s17
	ds_read_b128 v[206:209], v169
	ds_read_b128 v[210:213], v169 offset:1024
	ds_read_b128 v[214:217], v169 offset:2048
	ds_read_b128 v[218:221], v169 offset:3072
	global_load_lds_dwordx4 v[154:155], off
	v_lshl_add_u64 v[154:155], v[222:223], 0, s[40:41]
	s_add_i32 m0, s17, 0x2000
	s_nop 0
	global_load_lds_dwordx4 v[154:155], off
	s_barrier
	s_waitcnt lgkmcnt(0)
	s_setprio 1
	s_waitcnt lgkmcnt(0)
	v_mfma_f32_16x16x32_bf16 v[116:119], v[206:209], v[174:177], v[116:119]
	v_mfma_f32_16x16x32_bf16 v[112:115], v[214:217], v[174:177], v[112:115]
	v_mfma_f32_16x16x32_bf16 v[100:103], v[206:209], v[182:185], v[100:103]
	v_mfma_f32_16x16x32_bf16 v[96:99], v[214:217], v[182:185], v[96:99]
	v_mfma_f32_16x16x32_bf16 v[84:87], v[206:209], v[190:193], v[84:87]
	v_mfma_f32_16x16x32_bf16 v[80:83], v[214:217], v[190:193], v[80:83]
	v_mfma_f32_16x16x32_bf16 v[68:71], v[206:209], v[198:201], v[68:71]
	v_mfma_f32_16x16x32_bf16 v[64:67], v[214:217], v[198:201], v[64:67]
	v_mfma_f32_16x16x32_bf16 v[116:119], v[210:213], v[178:181], v[116:119]
	v_mfma_f32_16x16x32_bf16 v[112:115], v[218:221], v[178:181], v[112:115]
	v_mfma_f32_16x16x32_bf16 v[100:103], v[210:213], v[186:189], v[100:103]
	v_mfma_f32_16x16x32_bf16 v[96:99], v[218:221], v[186:189], v[96:99]
	v_mfma_f32_16x16x32_bf16 v[84:87], v[210:213], v[194:197], v[84:87]
	v_mfma_f32_16x16x32_bf16 v[80:83], v[218:221], v[194:197], v[80:83]
	v_mfma_f32_16x16x32_bf16 v[68:71], v[210:213], v[202:205], v[68:71]
	v_mfma_f32_16x16x32_bf16 v[64:67], v[218:221], v[202:205], v[64:67]
	s_setprio 0
	s_mov_b32 m0, s67
	v_lshl_add_u64 v[154:155], v[224:225], 0, s[40:41]
	s_barrier
	ds_read_b128 v[174:177], v160 offset:49152
	ds_read_b128 v[178:181], v160 offset:50176
	ds_read_b128 v[182:185], v160 offset:51200
	ds_read_b128 v[186:189], v160 offset:52224
	ds_read_b128 v[190:193], v160 offset:53248
	ds_read_b128 v[194:197], v160 offset:54272
	ds_read_b128 v[198:201], v160 offset:55296
	ds_read_b128 v[202:205], v160 offset:56320
	global_load_lds_dwordx4 v[154:155], off
	v_lshl_add_u64 v[154:155], v[226:227], 0, s[40:41]
	s_mov_b32 m0, s68
	s_nop 0
	global_load_lds_dwordx4 v[154:155], off
	s_barrier
; __device__ __forceinline__ float sigmoidf_(float x) { return 1.0f / (1.0f + __expf(-x)); }
; #define PG8_STAGE(bufoff, gbase, voff) do { _Pragma("unroll") for (int _i = 0; _i < 2; ++_i) \
;         __builtin_amdgcn_global_load_lds((const unsigned*)((const char*)(gbase) + (voff)[_i]), (LAS unsigned*)(lds + (bufoff) + ldsw + _i * 8192), 16, 0, 0); } while (0)
; #define PG8_MMA(ai, bj, At, Bt) do { __builtin_amdgcn_s_setprio(1); _Pragma("unroll") for (int m = 0; m < 4; ++m) _Pragma("unroll") for (int n = 0; n < 2; ++n) _Pragma("unroll") for (int k = 0; k < 2; ++k) \
;         acc[ai][bj][m][n] = __builtin_amdgcn_mfma_f32_16x16x32_bf16(Bt[n][k], At[m][k], acc[ai][bj][m][n], 0, 0, 0); __builtin_amdgcn_s_setprio(0); } while (0)
; #define PG8_WAIT_V(n) asm volatile("s_waitcnt vmcnt(" #n ")" ::: "memory")
; #define PG8_WAIT_L(n) asm volatile("s_waitcnt lgkmcnt(" #n ")" ::: "memory")
; #define PG8_BAR __builtin_amdgcn_s_barrier()
; #define PG8_SCHED __builtin_amdgcn_sched_barrier(0)
; __device__ __forceinline__ void unpack8(const u32x4 w, f32x4& v0, f32x4& v1) { v0 = (f32x4){bflo(w.x), bfhi(w.x), bflo(w.y), bfhi(w.y)}; v1 = (f32x4){bflo(w.z), bfhi(w.z), bflo(w.w), bfhi(w.w)}; }
;     ...
;             PG8_BAR; PG8_WAIT_L(0); PG8_MMA(1, 0, At, B0); PG8_BAR; PG8_SCHED;
;             PG8_STAGE(PG8_SB(1, 1), b3 + hB, voffB);
;             PG8_WAIT_V(6); PG8_BAR; PG8_MMA(1, 1, At, B1); PG8_BAR;
;     __device__ __forceinline__ void operator()(const f32x4 (&acc)[2][2][4][2], const Unit& u, int wr, int wc, int fr, int fq) const {
;     ...
;                 const int row = row0 + ai * 128 + m * 16;
;                 const bf16_t* rowp = z + (size_t)row * DIN + col0;
; #pragma unroll
;                 for (int bj = 0; bj < 2; ++bj) {
;                     const u32x4 gw = *(const u32x4*)(rowp + O_GA + bj * 128);
;                     f32x4 g0, g1; unpack8(gw, g0, g1);
;                     f32x4 v0, v1;
; #pragma unroll
;                     for (int j = 0; j < 4; ++j) { v0[j] = sigmoidf_(g0[j]) * acc[ai][bj][m][0][j]; v1[j] = sigmoidf_(g1[j]) * acc[ai][bj][m][1][j]; }
	s_waitcnt lgkmcnt(0)
	s_setprio 1
	s_waitcnt lgkmcnt(0)
	v_mfma_f32_16x16x32_bf16 v[60:63], v[146:149], v[174:177], v[60:63]
	v_mfma_f32_16x16x32_bf16 v[56:59], v[162:165], v[174:177], v[56:59]
	v_mfma_f32_16x16x32_bf16 v[44:47], v[146:149], v[182:185], v[44:47]
	v_mfma_f32_16x16x32_bf16 v[40:43], v[162:165], v[182:185], v[40:43]
	v_mfma_f32_16x16x32_bf16 v[28:31], v[146:149], v[190:193], v[28:31]
	v_mfma_f32_16x16x32_bf16 v[24:27], v[162:165], v[190:193], v[24:27]
	v_mfma_f32_16x16x32_bf16 v[12:15], v[146:149], v[198:201], v[12:15]
	v_mfma_f32_16x16x32_bf16 v[8:11], v[162:165], v[198:201], v[8:11]
	v_mfma_f32_16x16x32_bf16 v[60:63], v[150:153], v[178:181], v[60:63]
	v_mfma_f32_16x16x32_bf16 v[56:59], v[170:173], v[178:181], v[56:59]
	v_mfma_f32_16x16x32_bf16 v[44:47], v[150:153], v[186:189], v[44:47]
	v_mfma_f32_16x16x32_bf16 v[40:43], v[170:173], v[186:189], v[40:43]
	v_mfma_f32_16x16x32_bf16 v[28:31], v[150:153], v[194:197], v[28:31]
	v_mfma_f32_16x16x32_bf16 v[24:27], v[170:173], v[194:197], v[24:27]
	v_mfma_f32_16x16x32_bf16 v[12:15], v[150:153], v[202:205], v[12:15]
	v_mfma_f32_16x16x32_bf16 v[8:11], v[170:173], v[202:205], v[8:11]
	s_setprio 0
	s_barrier
	s_add_u32 s14, s14, 0x20080
	s_addc_u32 s15, s15, 0
	s_add_i32 s16, s16, s61
	v_lshl_add_u64 v[146:147], s[14:15], 0, v[130:131]
	s_mov_b32 m0, s16
	s_nop 0
	global_load_lds_dwordx4 v[146:147], off
	v_lshl_add_u64 v[146:147], s[14:15], 0, v[134:135]
	s_add_i32 m0, s16, 0x2000
	s_nop 0
	global_load_lds_dwordx4 v[146:147], off
	s_waitcnt vmcnt(6)
	s_barrier
	s_setprio 1
	v_mfma_f32_16x16x32_bf16 v[52:55], v[206:209], v[174:177], v[52:55]
	v_mfma_f32_16x16x32_bf16 v[48:51], v[214:217], v[174:177], v[48:51]
	v_mfma_f32_16x16x32_bf16 v[36:39], v[206:209], v[182:185], v[36:39]
	v_mfma_f32_16x16x32_bf16 v[32:35], v[214:217], v[182:185], v[32:35]
	v_mfma_f32_16x16x32_bf16 v[20:23], v[206:209], v[190:193], v[20:23]
	v_mfma_f32_16x16x32_bf16 v[16:19], v[214:217], v[190:193], v[16:19]
	v_mfma_f32_16x16x32_bf16 v[4:7], v[206:209], v[198:201], v[4:7]
	v_mfma_f32_16x16x32_bf16 v[0:3], v[214:217], v[198:201], v[0:3]
	v_mfma_f32_16x16x32_bf16 v[52:55], v[210:213], v[178:181], v[52:55]
	v_mfma_f32_16x16x32_bf16 v[48:51], v[218:221], v[178:181], v[48:51]
	v_mfma_f32_16x16x32_bf16 v[36:39], v[210:213], v[186:189], v[36:39]
	v_mfma_f32_16x16x32_bf16 v[32:35], v[218:221], v[186:189], v[32:35]
	v_mfma_f32_16x16x32_bf16 v[20:23], v[210:213], v[194:197], v[20:23]
	v_mfma_f32_16x16x32_bf16 v[16:19], v[218:221], v[194:197], v[16:19]
	v_mfma_f32_16x16x32_bf16 v[4:7], v[210:213], v[202:205], v[4:7]
	v_mfma_f32_16x16x32_bf16 v[0:3], v[218:221], v[202:205], v[0:3]
	s_setprio 0
	s_add_i32 s45, s45, 2
	s_add_u32 s39, s39, 0x100
	s_addc_u32 s44, s44, 0
	s_add_u32 s12, s12, 0x100
	s_addc_u32 s13, s13, 0
	s_cmp_gt_u32 s45, 5
	s_barrier
	s_cbranch_scc0 .LBB0_1841
	v_lshl_or_b32 v146, s6, 8, v158
	v_lshl_add_u32 v162, s75, 8, v156
	v_ashrrev_i32_e32 v147, 31, v146
	v_mad_i64_i32 v[154:155], s[6:7], v162, s73, 0
	v_lshl_add_u64 v[150:151], v[154:155], 1, s[36:37]
	v_lshlrev_b64 v[148:149], 1, v[146:147]
	v_lshl_add_u64 v[150:151], v[150:151], 0, v[148:149]
	v_add_co_u32_e32 v152, vcc, 0x1000, v150
	s_nop 1
	v_addc_co_u32_e32 v153, vcc, 0, v151, vcc
	v_subrev_u32_e32 v201, s36, v150
	v_add_u32_e32 v202, 0x1200, v201
	global_load_dwordx4 v[204:207], v202, s[36:37]
	v_add_u32_e32 v202, 0x0, v201
	global_load_dwordx4 v[208:211], v202, s[36:37]
	v_add_u32_e32 v202, 0x1300, v201
	global_load_dwordx4 v[212:215], v202, s[36:37]
	v_add_u32_e32 v202, 0x100, v201
	global_load_dwordx4 v[216:219], v202, s[36:37]
	v_add_u32_e32 v202, 0x23200, v201
	global_load_dwordx4 v[232:235], v202, s[36:37]
	v_add_u32_e32 v202, 0x22000, v201
	global_load_dwordx4 v[236:239], v202, s[36:37]
	s_waitcnt vmcnt(4)
	v_mov_b32_e32 v170, v204
	v_mov_b32_e32 v171, v205
	v_mov_b32_e32 v172, v206
	v_mov_b32_e32 v173, v207
	v_mov_b32_e32 v174, v208
	v_mov_b32_e32 v175, v209
	v_mov_b32_e32 v176, v210
	v_mov_b32_e32 v177, v211
	v_add_u32_e32 v202, 0x23300, v201
	global_load_dwordx4 v[204:207], v202, s[36:37]
	v_add_u32_e32 v202, 0x22100, v201
	global_load_dwordx4 v[208:211], v202, s[36:37]
	s_mov_b32 s100, 0xbfb8aa3b
	v_lshlrev_b32_e32 v240, 16, v170
	v_and_b32_e32 v241, 0xffff0000, v170
	v_lshlrev_b32_e32 v242, 16, v172
	v_and_b32_e32 v243, 0xffff0000, v172
	v_lshlrev_b32_e32 v244, 16, v173
	v_and_b32_e32 v245, 0xffff0000, v173
	v_lshlrev_b32_e32 v246, 16, v171
	v_and_b32_e32 v247, 0xffff0000, v171
	v_pk_mul_f32 v[240:241], v[240:241], s[100:101] op_sel_hi:[1,0]
	v_pk_mul_f32 v[242:243], v[242:243], s[100:101] op_sel_hi:[1,0]
	v_pk_mul_f32 v[244:245], v[244:245], s[100:101] op_sel_hi:[1,0]
	v_pk_mul_f32 v[246:247], v[246:247], s[100:101] op_sel_hi:[1,0]
	v_exp_f32_e32 v240, v240
	v_exp_f32_e32 v241, v241
	v_exp_f32_e32 v242, v242
	v_exp_f32_e32 v243, v243
	v_exp_f32_e32 v244, v244
	v_exp_f32_e32 v245, v245
	v_exp_f32_e32 v246, v246
	v_exp_f32_e32 v247, v247
	s_nop 0
	v_pk_add_f32 v[240:241], v[240:241], 1.0 op_sel_hi:[1,0]
	v_pk_add_f32 v[242:243], v[242:243], 1.0 op_sel_hi:[1,0]
	v_pk_add_f32 v[244:245], v[244:245], 1.0 op_sel_hi:[1,0]
	v_pk_add_f32 v[246:247], v[246:247], 1.0 op_sel_hi:[1,0]
	v_rcp_f32_e32 v248, v240
	v_rcp_f32_e32 v249, v241
	v_rcp_f32_e32 v254, v242
	v_rcp_f32_e32 v255, v243
	v_pk_fma_f32 v[250:251], v[240:241], v[248:249], 1.0 op_sel_hi:[1,1,0] neg_lo:[1,0,0] neg_hi:[1,0,0]
	v_pk_fma_f32 v[170:171], v[242:243], v[254:255], 1.0 op_sel_hi:[1,1,0] neg_lo:[1,0,0] neg_hi:[1,0,0]
	v_pk_fma_f32 v[248:249], v[250:251], v[248:249], v[248:249]
	v_pk_fma_f32 v[254:255], v[170:171], v[254:255], v[254:255]
; __device__ __forceinline__ float sigmoidf_(float x) { return 1.0f / (1.0f + __expf(-x)); }
; __device__ __forceinline__ u32x4 pack8(const f32x4 v0, const f32x4 v1) { u32x4 w; w.x = pk2(v0[0], v0[1]); w.y = pk2(v0[2], v0[3]); w.z = pk2(v1[0], v1[1]); w.w = pk2(v1[2], v1[3]); return w; }
; __device__ __forceinline__ void unpack8(const u32x4 w, f32x4& v0, f32x4& v1) { v0 = (f32x4){bflo(w.x), bfhi(w.x), bflo(w.y), bfhi(w.y)}; v1 = (f32x4){bflo(w.z), bfhi(w.z), bflo(w.w), bfhi(w.w)}; }
;     __device__ __forceinline__ void operator()(const f32x4 (&acc)[2][2][4][2], const Unit& u, int wr, int wc, int fr, int fq) const {
;     ...
;                 for (int bj = 0; bj < 2; ++bj) {
;                     const u32x4 gw = *(const u32x4*)(rowp + O_GA + bj * 128);
;                     f32x4 g0, g1; unpack8(gw, g0, g1);
;                     f32x4 v0, v1;
; #pragma unroll
;                     for (int j = 0; j < 4; ++j) { v0[j] = sigmoidf_(g0[j]) * acc[ai][bj][m][0][j]; v1[j] = sigmoidf_(g1[j]) * acc[ai][bj][m][1][j]; }
;                     const u32x4 mw = *(const u32x4*)(rowp + bj * 128); f32x4 m0, m1; unpack8(mw, m0, m1); v0 += m0; v1 += m1;
;                     __builtin_amdgcn_raw_buffer_store_b128(pack8(v0, v1), rsrc, (unsigned)(((size_t)row * DIN + col0 + bj * 128) * 2), 0, 16  ); }
	v_pk_fma_f32 v[250:251], v[240:241], v[248:249], 1.0 op_sel_hi:[1,1,0] neg_lo:[1,0,0] neg_hi:[1,0,0]
	v_pk_fma_f32 v[170:171], v[242:243], v[254:255], 1.0 op_sel_hi:[1,1,0] neg_lo:[1,0,0] neg_hi:[1,0,0]
	v_pk_fma_f32 v[252:253], v[250:251], v[248:249], v[248:249]
	v_pk_fma_f32 v[172:173], v[170:171], v[254:255], v[254:255]
	v_pk_fma_f32 v[250:251], v[240:241], v[252:253], 1.0 op_sel_hi:[1,1,0] neg_lo:[1,0,0] neg_hi:[1,0,0]
	v_pk_fma_f32 v[170:171], v[242:243], v[172:173], 1.0 op_sel_hi:[1,1,0] neg_lo:[1,0,0] neg_hi:[1,0,0]
	v_pk_fma_f32 v[252:253], v[250:251], v[248:249], v[252:253]
	v_pk_fma_f32 v[172:173], v[170:171], v[254:255], v[172:173]
	v_div_fixup_f32 v240, v252, v240, 1.0
	v_div_fixup_f32 v241, v253, v241, 1.0
	v_div_fixup_f32 v242, v172, v242, 1.0
	v_div_fixup_f32 v243, v173, v243, 1.0
	v_rcp_f32_e32 v248, v244
	v_rcp_f32_e32 v249, v245
	v_rcp_f32_e32 v254, v246
	v_rcp_f32_e32 v255, v247
	v_pk_fma_f32 v[250:251], v[244:245], v[248:249], 1.0 op_sel_hi:[1,1,0] neg_lo:[1,0,0] neg_hi:[1,0,0]
	v_pk_fma_f32 v[170:171], v[246:247], v[254:255], 1.0 op_sel_hi:[1,1,0] neg_lo:[1,0,0] neg_hi:[1,0,0]
	v_pk_fma_f32 v[248:249], v[250:251], v[248:249], v[248:249]
	v_pk_fma_f32 v[254:255], v[170:171], v[254:255], v[254:255]
	v_pk_fma_f32 v[250:251], v[244:245], v[248:249], 1.0 op_sel_hi:[1,1,0] neg_lo:[1,0,0] neg_hi:[1,0,0]
	v_pk_fma_f32 v[170:171], v[246:247], v[254:255], 1.0 op_sel_hi:[1,1,0] neg_lo:[1,0,0] neg_hi:[1,0,0]
	v_pk_fma_f32 v[252:253], v[250:251], v[248:249], v[248:249]
	v_pk_fma_f32 v[172:173], v[170:171], v[254:255], v[254:255]
	v_pk_fma_f32 v[250:251], v[244:245], v[252:253], 1.0 op_sel_hi:[1,1,0] neg_lo:[1,0,0] neg_hi:[1,0,0]
	v_pk_fma_f32 v[170:171], v[246:247], v[172:173], 1.0 op_sel_hi:[1,1,0] neg_lo:[1,0,0] neg_hi:[1,0,0]
	v_pk_fma_f32 v[252:253], v[250:251], v[248:249], v[252:253]
	v_pk_fma_f32 v[172:173], v[170:171], v[254:255], v[172:173]
	v_div_fixup_f32 v244, v252, v244, 1.0
	v_div_fixup_f32 v245, v253, v245, 1.0
	v_div_fixup_f32 v246, v172, v246, 1.0
	v_div_fixup_f32 v247, v173, v247, 1.0
	s_mov_b64 vcc, s[12:13]
	s_mov_b64 vcc, s[14:15]
	s_mov_b64 vcc, s[16:17]
	s_mov_b64 vcc, s[18:19]
	v_and_b32_e32 v181, 0xffff0000, v174
	v_lshlrev_b32_e32 v182, 16, v176
	v_lshlrev_b32_e32 v180, 16, v174
	v_and_b32_e32 v183, 0xffff0000, v176
	v_lshlrev_b32_e32 v176, 16, v177
	v_and_b32_e32 v177, 0xffff0000, v177
	v_lshlrev_b32_e32 v174, 16, v175
	v_and_b32_e32 v175, 0xffff0000, v175
	v_pk_fma_f32 v[124:125], v[124:125], v[240:241], v[180:181]
	v_pk_fma_f32 v[164:165], v[122:123], v[244:245], v[176:177]
	v_pk_fma_f32 v[122:123], v[120:121], v[242:243], v[182:183]
	v_add_lshl_u32 v147, v146, v154, 1
	v_pk_fma_f32 v[126:127], v[126:127], v[246:247], v[174:175]
	v_cvt_pk_bf16_f32 v120, v124, v125
	s_nop 0
	v_cvt_pk_bf16_f32 v121, v126, v127
	v_cvt_pk_bf16_f32 v122, v122, v123
	v_cvt_pk_bf16_f32 v123, v164, v165
	buffer_store_dwordx4 v[120:123], v147, s[20:23], 0 offen sc1
	s_nop 0
	s_waitcnt vmcnt(5)
	v_mov_b32_e32 v120, v212
	v_mov_b32_e32 v121, v213
	v_mov_b32_e32 v122, v214
	v_mov_b32_e32 v123, v215
	v_mov_b32_e32 v124, v216
	v_mov_b32_e32 v125, v217
	v_mov_b32_e32 v126, v218
	v_mov_b32_e32 v127, v219
	v_add_u32_e32 v202, 0x45200, v201
	global_load_dwordx4 v[212:215], v202, s[36:37]
	v_add_u32_e32 v202, 0x44000, v201
	global_load_dwordx4 v[216:219], v202, s[36:37]
	s_mov_b32 s100, 0xbfb8aa3b
	v_lshlrev_b32_e32 v240, 16, v120
	v_and_b32_e32 v241, 0xffff0000, v120
	v_lshlrev_b32_e32 v242, 16, v122
	v_and_b32_e32 v243, 0xffff0000, v122
	v_lshlrev_b32_e32 v244, 16, v121
	v_and_b32_e32 v245, 0xffff0000, v121
	v_lshlrev_b32_e32 v246, 16, v123
	v_and_b32_e32 v247, 0xffff0000, v123
	v_pk_mul_f32 v[240:241], v[240:241], s[100:101] op_sel_hi:[1,0]
	v_pk_mul_f32 v[242:243], v[242:243], s[100:101] op_sel_hi:[1,0]
	v_pk_mul_f32 v[244:245], v[244:245], s[100:101] op_sel_hi:[1,0]
	v_pk_mul_f32 v[246:247], v[246:247], s[100:101] op_sel_hi:[1,0]
	v_exp_f32_e32 v240, v240
	v_exp_f32_e32 v241, v241
	v_exp_f32_e32 v242, v242
	v_exp_f32_e32 v243, v243
	v_exp_f32_e32 v244, v244
	v_exp_f32_e32 v245, v245
	v_exp_f32_e32 v246, v246
	v_exp_f32_e32 v247, v247
	s_nop 0
	v_pk_add_f32 v[240:241], v[240:241], 1.0 op_sel_hi:[1,0]
	v_pk_add_f32 v[242:243], v[242:243], 1.0 op_sel_hi:[1,0]
	v_pk_add_f32 v[244:245], v[244:245], 1.0 op_sel_hi:[1,0]
	v_pk_add_f32 v[246:247], v[246:247], 1.0 op_sel_hi:[1,0]
	v_rcp_f32_e32 v248, v240
	v_rcp_f32_e32 v249, v241
	v_rcp_f32_e32 v254, v242
	v_rcp_f32_e32 v255, v243
	v_pk_fma_f32 v[250:251], v[240:241], v[248:249], 1.0 op_sel_hi:[1,1,0] neg_lo:[1,0,0] neg_hi:[1,0,0]
	v_pk_fma_f32 v[120:121], v[242:243], v[254:255], 1.0 op_sel_hi:[1,1,0] neg_lo:[1,0,0] neg_hi:[1,0,0]
	v_pk_fma_f32 v[248:249], v[250:251], v[248:249], v[248:249]
	v_pk_fma_f32 v[254:255], v[120:121], v[254:255], v[254:255]
	v_pk_fma_f32 v[250:251], v[240:241], v[248:249], 1.0 op_sel_hi:[1,1,0] neg_lo:[1,0,0] neg_hi:[1,0,0]
	v_pk_fma_f32 v[120:121], v[242:243], v[254:255], 1.0 op_sel_hi:[1,1,0] neg_lo:[1,0,0] neg_hi:[1,0,0]
	v_pk_fma_f32 v[252:253], v[250:251], v[248:249], v[248:249]
	v_pk_fma_f32 v[122:123], v[120:121], v[254:255], v[254:255]
	v_pk_fma_f32 v[250:251], v[240:241], v[252:253], 1.0 op_sel_hi:[1,1,0] neg_lo:[1,0,0] neg_hi:[1,0,0]
	v_pk_fma_f32 v[120:121], v[242:243], v[122:123], 1.0 op_sel_hi:[1,1,0] neg_lo:[1,0,0] neg_hi:[1,0,0]
	v_pk_fma_f32 v[252:253], v[250:251], v[248:249], v[252:253]
	v_pk_fma_f32 v[122:123], v[120:121], v[254:255], v[122:123]
	v_div_fixup_f32 v240, v252, v240, 1.0
	v_div_fixup_f32 v241, v253, v241, 1.0
	v_div_fixup_f32 v242, v122, v242, 1.0
	v_div_fixup_f32 v243, v123, v243, 1.0
	v_rcp_f32_e32 v248, v244
	v_rcp_f32_e32 v249, v245
; __device__ __forceinline__ float sigmoidf_(float x) { return 1.0f / (1.0f + __expf(-x)); }
; __device__ __forceinline__ u32x4 pack8(const f32x4 v0, const f32x4 v1) { u32x4 w; w.x = pk2(v0[0], v0[1]); w.y = pk2(v0[2], v0[3]); w.z = pk2(v1[0], v1[1]); w.w = pk2(v1[2], v1[3]); return w; }
; __device__ __forceinline__ void unpack8(const u32x4 w, f32x4& v0, f32x4& v1) { v0 = (f32x4){bflo(w.x), bfhi(w.x), bflo(w.y), bfhi(w.y)}; v1 = (f32x4){bflo(w.z), bfhi(w.z), bflo(w.w), bfhi(w.w)}; }
;     __device__ __forceinline__ void operator()(const f32x4 (&acc)[2][2][4][2], const Unit& u, int wr, int wc, int fr, int fq) const {
;     ...
;                 const int row = row0 + ai * 128 + m * 16;
;                 const bf16_t* rowp = z + (size_t)row * DIN + col0;
; #pragma unroll
;                 for (int bj = 0; bj < 2; ++bj) {
;                     const u32x4 gw = *(const u32x4*)(rowp + O_GA + bj * 128);
;                     f32x4 g0, g1; unpack8(gw, g0, g1);
;                     f32x4 v0, v1;
; #pragma unroll
;                     for (int j = 0; j < 4; ++j) { v0[j] = sigmoidf_(g0[j]) * acc[ai][bj][m][0][j]; v1[j] = sigmoidf_(g1[j]) * acc[ai][bj][m][1][j]; }
;                     const u32x4 mw = *(const u32x4*)(rowp + bj * 128); f32x4 m0, m1; unpack8(mw, m0, m1); v0 += m0; v1 += m1;
;                     __builtin_amdgcn_raw_buffer_store_b128(pack8(v0, v1), rsrc, (unsigned)(((size_t)row * DIN + col0 + bj * 128) * 2), 0, 16  ); }
	v_rcp_f32_e32 v254, v246
	v_rcp_f32_e32 v255, v247
	v_pk_fma_f32 v[250:251], v[244:245], v[248:249], 1.0 op_sel_hi:[1,1,0] neg_lo:[1,0,0] neg_hi:[1,0,0]
	v_pk_fma_f32 v[120:121], v[246:247], v[254:255], 1.0 op_sel_hi:[1,1,0] neg_lo:[1,0,0] neg_hi:[1,0,0]
	v_pk_fma_f32 v[248:249], v[250:251], v[248:249], v[248:249]
	v_pk_fma_f32 v[254:255], v[120:121], v[254:255], v[254:255]
	v_pk_fma_f32 v[250:251], v[244:245], v[248:249], 1.0 op_sel_hi:[1,1,0] neg_lo:[1,0,0] neg_hi:[1,0,0]
	v_pk_fma_f32 v[120:121], v[246:247], v[254:255], 1.0 op_sel_hi:[1,1,0] neg_lo:[1,0,0] neg_hi:[1,0,0]
	v_pk_fma_f32 v[252:253], v[250:251], v[248:249], v[248:249]
	v_pk_fma_f32 v[122:123], v[120:121], v[254:255], v[254:255]
	v_pk_fma_f32 v[250:251], v[244:245], v[252:253], 1.0 op_sel_hi:[1,1,0] neg_lo:[1,0,0] neg_hi:[1,0,0]
	v_pk_fma_f32 v[120:121], v[246:247], v[122:123], 1.0 op_sel_hi:[1,1,0] neg_lo:[1,0,0] neg_hi:[1,0,0]
	v_pk_fma_f32 v[252:253], v[250:251], v[248:249], v[252:253]
	v_pk_fma_f32 v[122:123], v[120:121], v[254:255], v[122:123]
	v_div_fixup_f32 v244, v252, v244, 1.0
	v_div_fixup_f32 v245, v253, v245, 1.0
	v_div_fixup_f32 v246, v122, v246, 1.0
	v_div_fixup_f32 v247, v123, v247, 1.0
	v_lshlrev_b32_e32 v154, 16, v124
	v_and_b32_e32 v155, 0xffff0000, v124
	v_lshlrev_b32_e32 v164, 16, v126
	v_and_b32_e32 v165, 0xffff0000, v126
	v_lshlrev_b32_e32 v126, 16, v127
	v_and_b32_e32 v127, 0xffff0000, v127
	v_lshlrev_b32_e32 v124, 16, v125
	v_and_b32_e32 v125, 0xffff0000, v125
	v_pk_fma_f32 v[116:117], v[116:117], v[240:241], v[154:155]
	v_pk_fma_f32 v[120:121], v[114:115], v[246:247], v[126:127]
	v_pk_fma_f32 v[114:115], v[112:113], v[242:243], v[164:165]
	v_cvt_pk_bf16_f32 v112, v116, v117
	v_pk_fma_f32 v[118:119], v[118:119], v[244:245], v[124:125]
	s_nop 0
	v_cvt_pk_bf16_f32 v113, v118, v119
	v_cvt_pk_bf16_f32 v114, v114, v115
	v_cvt_pk_bf16_f32 v115, v120, v121
	buffer_store_dwordx4 v[112:115], v147, s[20:23], 0 offen offset:256 sc1
	s_nop 1
	v_or_b32_e32 v112, 16, v162
	v_mad_i64_i32 v[114:115], s[6:7], v112, s73, 0
	v_lshl_add_u64 v[112:113], v[114:115], 1, s[36:37]
	v_lshl_add_u64 v[112:113], v[112:113], 0, v[148:149]
	v_add_co_u32_e32 v116, vcc, s74, v112
	s_nop 1
	v_addc_co_u32_e32 v117, vcc, 0, v113, vcc
	s_waitcnt vmcnt(6)
	v_mov_b32_e32 v118, v232
	v_mov_b32_e32 v119, v233
	v_mov_b32_e32 v120, v234
	v_mov_b32_e32 v121, v235
	v_mov_b32_e32 v122, v236
	v_mov_b32_e32 v123, v237
	v_mov_b32_e32 v124, v238
	v_mov_b32_e32 v125, v239
	v_add_u32_e32 v202, 0x45300, v201
	global_load_dwordx4 v[232:235], v202, s[36:37]
	v_add_u32_e32 v202, 0x44100, v201
	global_load_dwordx4 v[236:239], v202, s[36:37]
	s_mov_b32 s100, 0xbfb8aa3b
	v_lshlrev_b32_e32 v240, 16, v118
	v_and_b32_e32 v241, 0xffff0000, v118
	v_lshlrev_b32_e32 v242, 16, v120
	v_and_b32_e32 v243, 0xffff0000, v120
	v_lshlrev_b32_e32 v244, 16, v119
	v_and_b32_e32 v245, 0xffff0000, v119
	v_lshlrev_b32_e32 v246, 16, v121
	v_and_b32_e32 v247, 0xffff0000, v121
	v_pk_mul_f32 v[240:241], v[240:241], s[100:101] op_sel_hi:[1,0]
	v_pk_mul_f32 v[242:243], v[242:243], s[100:101] op_sel_hi:[1,0]
	v_pk_mul_f32 v[244:245], v[244:245], s[100:101] op_sel_hi:[1,0]
	v_pk_mul_f32 v[246:247], v[246:247], s[100:101] op_sel_hi:[1,0]
	v_exp_f32_e32 v240, v240
	v_exp_f32_e32 v241, v241
	v_exp_f32_e32 v242, v242
	v_exp_f32_e32 v243, v243
	v_exp_f32_e32 v244, v244
	v_exp_f32_e32 v245, v245
	v_exp_f32_e32 v246, v246
	v_exp_f32_e32 v247, v247
	s_nop 0
	v_pk_add_f32 v[240:241], v[240:241], 1.0 op_sel_hi:[1,0]
	v_pk_add_f32 v[242:243], v[242:243], 1.0 op_sel_hi:[1,0]
	v_pk_add_f32 v[244:245], v[244:245], 1.0 op_sel_hi:[1,0]
	v_pk_add_f32 v[246:247], v[246:247], 1.0 op_sel_hi:[1,0]
	v_rcp_f32_e32 v248, v240
	v_rcp_f32_e32 v249, v241
	v_rcp_f32_e32 v254, v242
	v_rcp_f32_e32 v255, v243
	v_pk_fma_f32 v[250:251], v[240:241], v[248:249], 1.0 op_sel_hi:[1,1,0] neg_lo:[1,0,0] neg_hi:[1,0,0]
	v_pk_fma_f32 v[118:119], v[242:243], v[254:255], 1.0 op_sel_hi:[1,1,0] neg_lo:[1,0,0] neg_hi:[1,0,0]
	v_pk_fma_f32 v[248:249], v[250:251], v[248:249], v[248:249]
	v_pk_fma_f32 v[254:255], v[118:119], v[254:255], v[254:255]
	v_pk_fma_f32 v[250:251], v[240:241], v[248:249], 1.0 op_sel_hi:[1,1,0] neg_lo:[1,0,0] neg_hi:[1,0,0]
	v_pk_fma_f32 v[118:119], v[242:243], v[254:255], 1.0 op_sel_hi:[1,1,0] neg_lo:[1,0,0] neg_hi:[1,0,0]
	v_pk_fma_f32 v[252:253], v[250:251], v[248:249], v[248:249]
	v_pk_fma_f32 v[120:121], v[118:119], v[254:255], v[254:255]
	v_pk_fma_f32 v[250:251], v[240:241], v[252:253], 1.0 op_sel_hi:[1,1,0] neg_lo:[1,0,0] neg_hi:[1,0,0]
	v_pk_fma_f32 v[118:119], v[242:243], v[120:121], 1.0 op_sel_hi:[1,1,0] neg_lo:[1,0,0] neg_hi:[1,0,0]
	v_pk_fma_f32 v[252:253], v[250:251], v[248:249], v[252:253]
	v_pk_fma_f32 v[120:121], v[118:119], v[254:255], v[120:121]
	v_div_fixup_f32 v240, v252, v240, 1.0
	v_div_fixup_f32 v241, v253, v241, 1.0
	v_div_fixup_f32 v242, v120, v242, 1.0
	v_div_fixup_f32 v243, v121, v243, 1.0
	v_rcp_f32_e32 v248, v244
	v_rcp_f32_e32 v249, v245
	v_rcp_f32_e32 v254, v246
	v_rcp_f32_e32 v255, v247
	v_pk_fma_f32 v[250:251], v[244:245], v[248:249], 1.0 op_sel_hi:[1,1,0] neg_lo:[1,0,0] neg_hi:[1,0,0]
	v_pk_fma_f32 v[118:119], v[246:247], v[254:255], 1.0 op_sel_hi:[1,1,0] neg_lo:[1,0,0] neg_hi:[1,0,0]
	v_pk_fma_f32 v[248:249], v[250:251], v[248:249], v[248:249]
	v_pk_fma_f32 v[254:255], v[118:119], v[254:255], v[254:255]
	v_pk_fma_f32 v[250:251], v[244:245], v[248:249], 1.0 op_sel_hi:[1,1,0] neg_lo:[1,0,0] neg_hi:[1,0,0]
	v_pk_fma_f32 v[118:119], v[246:247], v[254:255], 1.0 op_sel_hi:[1,1,0] neg_lo:[1,0,0] neg_hi:[1,0,0]
	v_pk_fma_f32 v[252:253], v[250:251], v[248:249], v[248:249]
	v_pk_fma_f32 v[120:121], v[118:119], v[254:255], v[254:255]
	v_pk_fma_f32 v[250:251], v[244:245], v[252:253], 1.0 op_sel_hi:[1,1,0] neg_lo:[1,0,0] neg_hi:[1,0,0]
	v_pk_fma_f32 v[118:119], v[246:247], v[120:121], 1.0 op_sel_hi:[1,1,0] neg_lo:[1,0,0] neg_hi:[1,0,0]
	v_pk_fma_f32 v[252:253], v[250:251], v[248:249], v[252:253]
	v_pk_fma_f32 v[120:121], v[118:119], v[254:255], v[120:121]
	v_div_fixup_f32 v244, v252, v244, 1.0
	v_div_fixup_f32 v245, v253, v245, 1.0
	v_div_fixup_f32 v246, v120, v246, 1.0
	v_div_fixup_f32 v247, v121, v247, 1.0
	v_and_b32_e32 v155, 0xffff0000, v124
	v_lshlrev_b32_e32 v152, 16, v122
	v_and_b32_e32 v153, 0xffff0000, v122
	v_lshlrev_b32_e32 v154, 16, v124
	v_lshlrev_b32_e32 v124, 16, v125
	v_and_b32_e32 v125, 0xffff0000, v125
	v_lshlrev_b32_e32 v122, 16, v123
	v_and_b32_e32 v123, 0xffff0000, v123
	v_pk_fma_f32 v[108:109], v[108:109], v[240:241], v[152:153]
	v_pk_fma_f32 v[118:119], v[106:107], v[246:247], v[124:125]
	v_pk_fma_f32 v[106:107], v[104:105], v[242:243], v[154:155]
	v_add_lshl_u32 v120, v146, v114, 1
	v_pk_fma_f32 v[110:111], v[110:111], v[244:245], v[122:123]
	v_cvt_pk_bf16_f32 v104, v108, v109
	s_nop 0
	v_cvt_pk_bf16_f32 v105, v110, v111
	v_cvt_pk_bf16_f32 v106, v106, v107
	v_cvt_pk_bf16_f32 v107, v118, v119
	buffer_store_dwordx4 v[104:107], v120, s[20:23], 0 offen sc1
	s_nop 0
	s_waitcnt vmcnt(7)
; __device__ __forceinline__ float sigmoidf_(float x) { return 1.0f / (1.0f + __expf(-x)); }
; __device__ __forceinline__ u32x4 pack8(const f32x4 v0, const f32x4 v1) { u32x4 w; w.x = pk2(v0[0], v0[1]); w.y = pk2(v0[2], v0[3]); w.z = pk2(v1[0], v1[1]); w.w = pk2(v1[2], v1[3]); return w; }
; __device__ __forceinline__ void unpack8(const u32x4 w, f32x4& v0, f32x4& v1) { v0 = (f32x4){bflo(w.x), bfhi(w.x), bflo(w.y), bfhi(w.y)}; v1 = (f32x4){bflo(w.z), bfhi(w.z), bflo(w.w), bfhi(w.w)}; }
;     __device__ __forceinline__ void operator()(const f32x4 (&acc)[2][2][4][2], const Unit& u, int wr, int wc, int fr, int fq) const {
;     ...
;                 const int row = row0 + ai * 128 + m * 16;
;                 const bf16_t* rowp = z + (size_t)row * DIN + col0;
; #pragma unroll
;                 for (int bj = 0; bj < 2; ++bj) {
;                     const u32x4 gw = *(const u32x4*)(rowp + O_GA + bj * 128);
;                     f32x4 g0, g1; unpack8(gw, g0, g1);
;                     f32x4 v0, v1;
; #pragma unroll
;                     for (int j = 0; j < 4; ++j) { v0[j] = sigmoidf_(g0[j]) * acc[ai][bj][m][0][j]; v1[j] = sigmoidf_(g1[j]) * acc[ai][bj][m][1][j]; }
;                     const u32x4 mw = *(const u32x4*)(rowp + bj * 128); f32x4 m0, m1; unpack8(mw, m0, m1); v0 += m0; v1 += m1;
;                     __builtin_amdgcn_raw_buffer_store_b128(pack8(v0, v1), rsrc, (unsigned)(((size_t)row * DIN + col0 + bj * 128) * 2), 0, 16  ); }
	v_mov_b32_e32 v104, v204
	v_mov_b32_e32 v105, v205
	v_mov_b32_e32 v106, v206
	v_mov_b32_e32 v107, v207
	v_mov_b32_e32 v108, v208
	v_mov_b32_e32 v109, v209
	v_mov_b32_e32 v110, v210
	v_mov_b32_e32 v111, v211
	v_add_u32_e32 v202, 0x67200, v201
	global_load_dwordx4 v[204:207], v202, s[36:37]
	v_add_u32_e32 v202, 0x66000, v201
	global_load_dwordx4 v[208:211], v202, s[36:37]
	s_mov_b32 s100, 0xbfb8aa3b
	v_lshlrev_b32_e32 v240, 16, v106
	v_and_b32_e32 v241, 0xffff0000, v106
	v_lshlrev_b32_e32 v242, 16, v104
	v_and_b32_e32 v243, 0xffff0000, v104
	v_lshlrev_b32_e32 v244, 16, v105
	v_and_b32_e32 v245, 0xffff0000, v105
	v_lshlrev_b32_e32 v246, 16, v107
	v_and_b32_e32 v247, 0xffff0000, v107
	v_pk_mul_f32 v[240:241], v[240:241], s[100:101] op_sel_hi:[1,0]
	v_pk_mul_f32 v[242:243], v[242:243], s[100:101] op_sel_hi:[1,0]
	v_pk_mul_f32 v[244:245], v[244:245], s[100:101] op_sel_hi:[1,0]
	v_pk_mul_f32 v[246:247], v[246:247], s[100:101] op_sel_hi:[1,0]
	v_exp_f32_e32 v240, v240
	v_exp_f32_e32 v241, v241
	v_exp_f32_e32 v242, v242
	v_exp_f32_e32 v243, v243
	v_exp_f32_e32 v244, v244
	v_exp_f32_e32 v245, v245
	v_exp_f32_e32 v246, v246
	v_exp_f32_e32 v247, v247
	s_nop 0
	v_pk_add_f32 v[240:241], v[240:241], 1.0 op_sel_hi:[1,0]
	v_pk_add_f32 v[242:243], v[242:243], 1.0 op_sel_hi:[1,0]
	v_pk_add_f32 v[244:245], v[244:245], 1.0 op_sel_hi:[1,0]
	v_pk_add_f32 v[246:247], v[246:247], 1.0 op_sel_hi:[1,0]
	v_rcp_f32_e32 v248, v240
	v_rcp_f32_e32 v249, v241
	v_rcp_f32_e32 v254, v242
	v_rcp_f32_e32 v255, v243
	v_pk_fma_f32 v[250:251], v[240:241], v[248:249], 1.0 op_sel_hi:[1,1,0] neg_lo:[1,0,0] neg_hi:[1,0,0]
	v_pk_fma_f32 v[104:105], v[242:243], v[254:255], 1.0 op_sel_hi:[1,1,0] neg_lo:[1,0,0] neg_hi:[1,0,0]
	v_pk_fma_f32 v[248:249], v[250:251], v[248:249], v[248:249]
	v_pk_fma_f32 v[254:255], v[104:105], v[254:255], v[254:255]
	v_pk_fma_f32 v[250:251], v[240:241], v[248:249], 1.0 op_sel_hi:[1,1,0] neg_lo:[1,0,0] neg_hi:[1,0,0]
	v_pk_fma_f32 v[104:105], v[242:243], v[254:255], 1.0 op_sel_hi:[1,1,0] neg_lo:[1,0,0] neg_hi:[1,0,0]
	v_pk_fma_f32 v[252:253], v[250:251], v[248:249], v[248:249]
	v_pk_fma_f32 v[106:107], v[104:105], v[254:255], v[254:255]
	v_pk_fma_f32 v[250:251], v[240:241], v[252:253], 1.0 op_sel_hi:[1,1,0] neg_lo:[1,0,0] neg_hi:[1,0,0]
	v_pk_fma_f32 v[104:105], v[242:243], v[106:107], 1.0 op_sel_hi:[1,1,0] neg_lo:[1,0,0] neg_hi:[1,0,0]
	v_pk_fma_f32 v[252:253], v[250:251], v[248:249], v[252:253]
	v_pk_fma_f32 v[106:107], v[104:105], v[254:255], v[106:107]
	v_div_fixup_f32 v240, v252, v240, 1.0
	v_div_fixup_f32 v241, v253, v241, 1.0
	v_div_fixup_f32 v242, v106, v242, 1.0
	v_div_fixup_f32 v243, v107, v243, 1.0
	v_rcp_f32_e32 v248, v244
	v_rcp_f32_e32 v249, v245
	v_rcp_f32_e32 v254, v246
	v_rcp_f32_e32 v255, v247
	v_pk_fma_f32 v[250:251], v[244:245], v[248:249], 1.0 op_sel_hi:[1,1,0] neg_lo:[1,0,0] neg_hi:[1,0,0]
	v_pk_fma_f32 v[104:105], v[246:247], v[254:255], 1.0 op_sel_hi:[1,1,0] neg_lo:[1,0,0] neg_hi:[1,0,0]
	v_pk_fma_f32 v[248:249], v[250:251], v[248:249], v[248:249]
	v_pk_fma_f32 v[254:255], v[104:105], v[254:255], v[254:255]
	v_pk_fma_f32 v[250:251], v[244:245], v[248:249], 1.0 op_sel_hi:[1,1,0] neg_lo:[1,0,0] neg_hi:[1,0,0]
	v_pk_fma_f32 v[104:105], v[246:247], v[254:255], 1.0 op_sel_hi:[1,1,0] neg_lo:[1,0,0] neg_hi:[1,0,0]
	v_pk_fma_f32 v[252:253], v[250:251], v[248:249], v[248:249]
	v_pk_fma_f32 v[106:107], v[104:105], v[254:255], v[254:255]
	v_pk_fma_f32 v[250:251], v[244:245], v[252:253], 1.0 op_sel_hi:[1,1,0] neg_lo:[1,0,0] neg_hi:[1,0,0]
	v_pk_fma_f32 v[104:105], v[246:247], v[106:107], 1.0 op_sel_hi:[1,1,0] neg_lo:[1,0,0] neg_hi:[1,0,0]
	v_pk_fma_f32 v[252:253], v[250:251], v[248:249], v[252:253]
	v_pk_fma_f32 v[106:107], v[104:105], v[254:255], v[106:107]
	v_div_fixup_f32 v244, v252, v244, 1.0
	v_div_fixup_f32 v245, v253, v245, 1.0
	v_div_fixup_f32 v246, v106, v246, 1.0
	v_div_fixup_f32 v247, v107, v247, 1.0
	v_lshlrev_b32_e32 v116, 16, v108
	v_and_b32_e32 v117, 0xffff0000, v108
	v_lshlrev_b32_e32 v118, 16, v110
	v_and_b32_e32 v119, 0xffff0000, v110
	v_lshlrev_b32_e32 v110, 16, v111
	v_and_b32_e32 v111, 0xffff0000, v111
	v_lshlrev_b32_e32 v108, 16, v109
	v_and_b32_e32 v109, 0xffff0000, v109
	v_pk_fma_f32 v[100:101], v[100:101], v[242:243], v[116:117]
	v_pk_fma_f32 v[104:105], v[98:99], v[246:247], v[110:111]
	v_pk_fma_f32 v[98:99], v[96:97], v[240:241], v[118:119]
	v_cvt_pk_bf16_f32 v96, v100, v101
	v_pk_fma_f32 v[102:103], v[102:103], v[244:245], v[108:109]
	s_nop 0
	v_cvt_pk_bf16_f32 v97, v102, v103
	v_cvt_pk_bf16_f32 v98, v98, v99
	v_cvt_pk_bf16_f32 v99, v104, v105
	buffer_store_dwordx4 v[96:99], v120, s[20:23], 0 offen offset:256 sc1
	s_nop 1
	v_or_b32_e32 v96, 32, v162
	v_mad_i64_i32 v[98:99], s[6:7], v96, s73, 0
	v_lshl_add_u64 v[96:97], v[98:99], 1, s[36:37]
	v_lshl_add_u64 v[96:97], v[96:97], 0, v[148:149]
	v_add_co_u32_e32 v100, vcc, s74, v96
	s_nop 1
	v_addc_co_u32_e32 v101, vcc, 0, v97, vcc
	s_waitcnt vmcnt(7)
; __device__ __forceinline__ float sigmoidf_(float x) { return 1.0f / (1.0f + __expf(-x)); }
; __device__ __forceinline__ u32x4 pack8(const f32x4 v0, const f32x4 v1) { u32x4 w; w.x = pk2(v0[0], v0[1]); w.y = pk2(v0[2], v0[3]); w.z = pk2(v1[0], v1[1]); w.w = pk2(v1[2], v1[3]); return w; }
; __device__ __forceinline__ void unpack8(const u32x4 w, f32x4& v0, f32x4& v1) { v0 = (f32x4){bflo(w.x), bfhi(w.x), bflo(w.y), bfhi(w.y)}; v1 = (f32x4){bflo(w.z), bfhi(w.z), bflo(w.w), bfhi(w.w)}; }
;     __device__ __forceinline__ void operator()(const f32x4 (&acc)[2][2][4][2], const Unit& u, int wr, int wc, int fr, int fq) const {
;     ...
;                 for (int bj = 0; bj < 2; ++bj) {
;                     const u32x4 gw = *(const u32x4*)(rowp + O_GA + bj * 128);
;                     f32x4 g0, g1; unpack8(gw, g0, g1);
;                     f32x4 v0, v1;
; #pragma unroll
;                     for (int j = 0; j < 4; ++j) { v0[j] = sigmoidf_(g0[j]) * acc[ai][bj][m][0][j]; v1[j] = sigmoidf_(g1[j]) * acc[ai][bj][m][1][j]; }
;                     const u32x4 mw = *(const u32x4*)(rowp + bj * 128); f32x4 m0, m1; unpack8(mw, m0, m1); v0 += m0; v1 += m1;
;                     __builtin_amdgcn_raw_buffer_store_b128(pack8(v0, v1), rsrc, (unsigned)(((size_t)row * DIN + col0 + bj * 128) * 2), 0, 16  ); }
	v_mov_b32_e32 v102, v212
	v_mov_b32_e32 v103, v213
	v_mov_b32_e32 v104, v214
	v_mov_b32_e32 v105, v215
	v_mov_b32_e32 v106, v216
	v_mov_b32_e32 v107, v217
	v_mov_b32_e32 v108, v218
	v_mov_b32_e32 v109, v219
	v_add_u32_e32 v202, 0x67300, v201
	global_load_dwordx4 v[212:215], v202, s[36:37]
	v_add_u32_e32 v202, 0x66100, v201
	global_load_dwordx4 v[216:219], v202, s[36:37]
	s_mov_b32 s100, 0xbfb8aa3b
	v_lshlrev_b32_e32 v240, 16, v102
	v_and_b32_e32 v241, 0xffff0000, v102
	v_lshlrev_b32_e32 v242, 16, v104
	v_and_b32_e32 v243, 0xffff0000, v104
	v_lshlrev_b32_e32 v244, 16, v103
	v_and_b32_e32 v245, 0xffff0000, v103
	v_lshlrev_b32_e32 v246, 16, v105
	v_and_b32_e32 v247, 0xffff0000, v105
	v_pk_mul_f32 v[240:241], v[240:241], s[100:101] op_sel_hi:[1,0]
	v_pk_mul_f32 v[242:243], v[242:243], s[100:101] op_sel_hi:[1,0]
	v_pk_mul_f32 v[244:245], v[244:245], s[100:101] op_sel_hi:[1,0]
	v_pk_mul_f32 v[246:247], v[246:247], s[100:101] op_sel_hi:[1,0]
	v_exp_f32_e32 v240, v240
	v_exp_f32_e32 v241, v241
	v_exp_f32_e32 v242, v242
	v_exp_f32_e32 v243, v243
	v_exp_f32_e32 v244, v244
	v_exp_f32_e32 v245, v245
	v_exp_f32_e32 v246, v246
	v_exp_f32_e32 v247, v247
	s_nop 0
	v_pk_add_f32 v[240:241], v[240:241], 1.0 op_sel_hi:[1,0]
	v_pk_add_f32 v[242:243], v[242:243], 1.0 op_sel_hi:[1,0]
	v_pk_add_f32 v[244:245], v[244:245], 1.0 op_sel_hi:[1,0]
	v_pk_add_f32 v[246:247], v[246:247], 1.0 op_sel_hi:[1,0]
	v_rcp_f32_e32 v248, v240
	v_rcp_f32_e32 v249, v241
	v_rcp_f32_e32 v254, v242
	v_rcp_f32_e32 v255, v243
	v_pk_fma_f32 v[250:251], v[240:241], v[248:249], 1.0 op_sel_hi:[1,1,0] neg_lo:[1,0,0] neg_hi:[1,0,0]
	v_pk_fma_f32 v[102:103], v[242:243], v[254:255], 1.0 op_sel_hi:[1,1,0] neg_lo:[1,0,0] neg_hi:[1,0,0]
	v_pk_fma_f32 v[248:249], v[250:251], v[248:249], v[248:249]
	v_pk_fma_f32 v[254:255], v[102:103], v[254:255], v[254:255]
	v_pk_fma_f32 v[250:251], v[240:241], v[248:249], 1.0 op_sel_hi:[1,1,0] neg_lo:[1,0,0] neg_hi:[1,0,0]
	v_pk_fma_f32 v[102:103], v[242:243], v[254:255], 1.0 op_sel_hi:[1,1,0] neg_lo:[1,0,0] neg_hi:[1,0,0]
	v_pk_fma_f32 v[252:253], v[250:251], v[248:249], v[248:249]
	v_pk_fma_f32 v[104:105], v[102:103], v[254:255], v[254:255]
	v_pk_fma_f32 v[250:251], v[240:241], v[252:253], 1.0 op_sel_hi:[1,1,0] neg_lo:[1,0,0] neg_hi:[1,0,0]
	v_pk_fma_f32 v[102:103], v[242:243], v[104:105], 1.0 op_sel_hi:[1,1,0] neg_lo:[1,0,0] neg_hi:[1,0,0]
	v_pk_fma_f32 v[252:253], v[250:251], v[248:249], v[252:253]
	v_pk_fma_f32 v[104:105], v[102:103], v[254:255], v[104:105]
	v_div_fixup_f32 v240, v252, v240, 1.0
	v_div_fixup_f32 v241, v253, v241, 1.0
	v_div_fixup_f32 v242, v104, v242, 1.0
	v_div_fixup_f32 v243, v105, v243, 1.0
	v_rcp_f32_e32 v248, v244
	v_rcp_f32_e32 v249, v245
	v_rcp_f32_e32 v254, v246
	v_rcp_f32_e32 v255, v247
	v_pk_fma_f32 v[250:251], v[244:245], v[248:249], 1.0 op_sel_hi:[1,1,0] neg_lo:[1,0,0] neg_hi:[1,0,0]
	v_pk_fma_f32 v[102:103], v[246:247], v[254:255], 1.0 op_sel_hi:[1,1,0] neg_lo:[1,0,0] neg_hi:[1,0,0]
	v_pk_fma_f32 v[248:249], v[250:251], v[248:249], v[248:249]
	v_pk_fma_f32 v[254:255], v[102:103], v[254:255], v[254:255]
	v_pk_fma_f32 v[250:251], v[244:245], v[248:249], 1.0 op_sel_hi:[1,1,0] neg_lo:[1,0,0] neg_hi:[1,0,0]
	v_pk_fma_f32 v[102:103], v[246:247], v[254:255], 1.0 op_sel_hi:[1,1,0] neg_lo:[1,0,0] neg_hi:[1,0,0]
	v_pk_fma_f32 v[252:253], v[250:251], v[248:249], v[248:249]
	v_pk_fma_f32 v[104:105], v[102:103], v[254:255], v[254:255]
	v_pk_fma_f32 v[250:251], v[244:245], v[252:253], 1.0 op_sel_hi:[1,1,0] neg_lo:[1,0,0] neg_hi:[1,0,0]
	v_pk_fma_f32 v[102:103], v[246:247], v[104:105], 1.0 op_sel_hi:[1,1,0] neg_lo:[1,0,0] neg_hi:[1,0,0]
	v_pk_fma_f32 v[252:253], v[250:251], v[248:249], v[252:253]
	v_pk_fma_f32 v[104:105], v[102:103], v[254:255], v[104:105]
	v_div_fixup_f32 v244, v252, v244, 1.0
	v_div_fixup_f32 v245, v253, v245, 1.0
	v_div_fixup_f32 v246, v104, v246, 1.0
	v_div_fixup_f32 v247, v105, v247, 1.0
	v_lshlrev_b32_e32 v114, 16, v106
	v_and_b32_e32 v115, 0xffff0000, v106
	v_lshlrev_b32_e32 v116, 16, v108
	v_and_b32_e32 v117, 0xffff0000, v108
	v_lshlrev_b32_e32 v108, 16, v109
	v_and_b32_e32 v109, 0xffff0000, v109
	v_lshlrev_b32_e32 v106, 16, v107
	v_and_b32_e32 v107, 0xffff0000, v107
	v_pk_fma_f32 v[92:93], v[92:93], v[240:241], v[114:115]
	v_pk_fma_f32 v[102:103], v[90:91], v[246:247], v[108:109]
	v_pk_fma_f32 v[90:91], v[88:89], v[242:243], v[116:117]
	v_add_lshl_u32 v104, v146, v98, 1
	v_pk_fma_f32 v[94:95], v[94:95], v[244:245], v[106:107]
	v_cvt_pk_bf16_f32 v88, v92, v93
	s_nop 0
	v_cvt_pk_bf16_f32 v89, v94, v95
	v_cvt_pk_bf16_f32 v90, v90, v91
	v_cvt_pk_bf16_f32 v91, v102, v103
	buffer_store_dwordx4 v[88:91], v104, s[20:23], 0 offen sc1
	s_nop 0
	s_waitcnt vmcnt(7)
; __device__ __forceinline__ float sigmoidf_(float x) { return 1.0f / (1.0f + __expf(-x)); }
; __device__ __forceinline__ u32x4 pack8(const f32x4 v0, const f32x4 v1) { u32x4 w; w.x = pk2(v0[0], v0[1]); w.y = pk2(v0[2], v0[3]); w.z = pk2(v1[0], v1[1]); w.w = pk2(v1[2], v1[3]); return w; }
; __device__ __forceinline__ void unpack8(const u32x4 w, f32x4& v0, f32x4& v1) { v0 = (f32x4){bflo(w.x), bfhi(w.x), bflo(w.y), bfhi(w.y)}; v1 = (f32x4){bflo(w.z), bfhi(w.z), bflo(w.w), bfhi(w.w)}; }
;     __device__ __forceinline__ void operator()(const f32x4 (&acc)[2][2][4][2], const Unit& u, int wr, int wc, int fr, int fq) const {
;     ...
;                 const int row = row0 + ai * 128 + m * 16;
;                 const bf16_t* rowp = z + (size_t)row * DIN + col0;
; #pragma unroll
;                 for (int bj = 0; bj < 2; ++bj) {
;                     const u32x4 gw = *(const u32x4*)(rowp + O_GA + bj * 128);
;                     f32x4 g0, g1; unpack8(gw, g0, g1);
;                     f32x4 v0, v1;
; #pragma unroll
;                     for (int j = 0; j < 4; ++j) { v0[j] = sigmoidf_(g0[j]) * acc[ai][bj][m][0][j]; v1[j] = sigmoidf_(g1[j]) * acc[ai][bj][m][1][j]; }
;                     const u32x4 mw = *(const u32x4*)(rowp + bj * 128); f32x4 m0, m1; unpack8(mw, m0, m1); v0 += m0; v1 += m1;
;                     __builtin_amdgcn_raw_buffer_store_b128(pack8(v0, v1), rsrc, (unsigned)(((size_t)row * DIN + col0 + bj * 128) * 2), 0, 16  ); }
	v_mov_b32_e32 v88, v232
	v_mov_b32_e32 v89, v233
	v_mov_b32_e32 v90, v234
	v_mov_b32_e32 v91, v235
	v_mov_b32_e32 v92, v236
	v_mov_b32_e32 v93, v237
	v_mov_b32_e32 v94, v238
	v_mov_b32_e32 v95, v239
	v_add_u32_e32 v202, 0x111200, v201
	global_load_dwordx4 v[232:235], v202, s[36:37]
	v_add_u32_e32 v202, 0x110000, v201
	global_load_dwordx4 v[236:239], v202, s[36:37]
	s_mov_b32 s100, 0xbfb8aa3b
	v_lshlrev_b32_e32 v240, 16, v90
	v_and_b32_e32 v241, 0xffff0000, v90
	v_lshlrev_b32_e32 v242, 16, v88
	v_and_b32_e32 v243, 0xffff0000, v88
	v_lshlrev_b32_e32 v244, 16, v89
	v_and_b32_e32 v245, 0xffff0000, v89
	v_lshlrev_b32_e32 v246, 16, v91
	v_and_b32_e32 v247, 0xffff0000, v91
	v_pk_mul_f32 v[240:241], v[240:241], s[100:101] op_sel_hi:[1,0]
	v_pk_mul_f32 v[242:243], v[242:243], s[100:101] op_sel_hi:[1,0]
	v_pk_mul_f32 v[244:245], v[244:245], s[100:101] op_sel_hi:[1,0]
	v_pk_mul_f32 v[246:247], v[246:247], s[100:101] op_sel_hi:[1,0]
	v_exp_f32_e32 v240, v240
	v_exp_f32_e32 v241, v241
	v_exp_f32_e32 v242, v242
	v_exp_f32_e32 v243, v243
	v_exp_f32_e32 v244, v244
	v_exp_f32_e32 v245, v245
	v_exp_f32_e32 v246, v246
	v_exp_f32_e32 v247, v247
	s_nop 0
	v_pk_add_f32 v[240:241], v[240:241], 1.0 op_sel_hi:[1,0]
	v_pk_add_f32 v[242:243], v[242:243], 1.0 op_sel_hi:[1,0]
	v_pk_add_f32 v[244:245], v[244:245], 1.0 op_sel_hi:[1,0]
	v_pk_add_f32 v[246:247], v[246:247], 1.0 op_sel_hi:[1,0]
	v_rcp_f32_e32 v248, v240
	v_rcp_f32_e32 v249, v241
	v_rcp_f32_e32 v254, v242
	v_rcp_f32_e32 v255, v243
	v_pk_fma_f32 v[250:251], v[240:241], v[248:249], 1.0 op_sel_hi:[1,1,0] neg_lo:[1,0,0] neg_hi:[1,0,0]
	v_pk_fma_f32 v[88:89], v[242:243], v[254:255], 1.0 op_sel_hi:[1,1,0] neg_lo:[1,0,0] neg_hi:[1,0,0]
	v_pk_fma_f32 v[248:249], v[250:251], v[248:249], v[248:249]
	v_pk_fma_f32 v[254:255], v[88:89], v[254:255], v[254:255]
	v_pk_fma_f32 v[250:251], v[240:241], v[248:249], 1.0 op_sel_hi:[1,1,0] neg_lo:[1,0,0] neg_hi:[1,0,0]
	v_pk_fma_f32 v[88:89], v[242:243], v[254:255], 1.0 op_sel_hi:[1,1,0] neg_lo:[1,0,0] neg_hi:[1,0,0]
	v_pk_fma_f32 v[252:253], v[250:251], v[248:249], v[248:249]
	v_pk_fma_f32 v[90:91], v[88:89], v[254:255], v[254:255]
	v_pk_fma_f32 v[250:251], v[240:241], v[252:253], 1.0 op_sel_hi:[1,1,0] neg_lo:[1,0,0] neg_hi:[1,0,0]
	v_pk_fma_f32 v[88:89], v[242:243], v[90:91], 1.0 op_sel_hi:[1,1,0] neg_lo:[1,0,0] neg_hi:[1,0,0]
	v_pk_fma_f32 v[252:253], v[250:251], v[248:249], v[252:253]
	v_pk_fma_f32 v[90:91], v[88:89], v[254:255], v[90:91]
	v_div_fixup_f32 v240, v252, v240, 1.0
	v_div_fixup_f32 v241, v253, v241, 1.0
	v_div_fixup_f32 v242, v90, v242, 1.0
	v_div_fixup_f32 v243, v91, v243, 1.0
	v_rcp_f32_e32 v248, v244
	v_rcp_f32_e32 v249, v245
	v_rcp_f32_e32 v254, v246
	v_rcp_f32_e32 v255, v247
	v_pk_fma_f32 v[250:251], v[244:245], v[248:249], 1.0 op_sel_hi:[1,1,0] neg_lo:[1,0,0] neg_hi:[1,0,0]
	v_pk_fma_f32 v[88:89], v[246:247], v[254:255], 1.0 op_sel_hi:[1,1,0] neg_lo:[1,0,0] neg_hi:[1,0,0]
	v_pk_fma_f32 v[248:249], v[250:251], v[248:249], v[248:249]
	v_pk_fma_f32 v[254:255], v[88:89], v[254:255], v[254:255]
	v_pk_fma_f32 v[250:251], v[244:245], v[248:249], 1.0 op_sel_hi:[1,1,0] neg_lo:[1,0,0] neg_hi:[1,0,0]
	v_pk_fma_f32 v[88:89], v[246:247], v[254:255], 1.0 op_sel_hi:[1,1,0] neg_lo:[1,0,0] neg_hi:[1,0,0]
	v_pk_fma_f32 v[252:253], v[250:251], v[248:249], v[248:249]
	v_pk_fma_f32 v[90:91], v[88:89], v[254:255], v[254:255]
	v_pk_fma_f32 v[250:251], v[244:245], v[252:253], 1.0 op_sel_hi:[1,1,0] neg_lo:[1,0,0] neg_hi:[1,0,0]
	v_pk_fma_f32 v[88:89], v[246:247], v[90:91], 1.0 op_sel_hi:[1,1,0] neg_lo:[1,0,0] neg_hi:[1,0,0]
	v_pk_fma_f32 v[252:253], v[250:251], v[248:249], v[252:253]
	v_pk_fma_f32 v[90:91], v[88:89], v[254:255], v[90:91]
	v_div_fixup_f32 v244, v252, v244, 1.0
	v_div_fixup_f32 v245, v253, v245, 1.0
	v_div_fixup_f32 v246, v90, v246, 1.0
	v_div_fixup_f32 v247, v91, v247, 1.0
	v_lshlrev_b32_e32 v100, 16, v92
	v_and_b32_e32 v101, 0xffff0000, v92
	v_lshlrev_b32_e32 v102, 16, v94
	v_and_b32_e32 v103, 0xffff0000, v94
	v_lshlrev_b32_e32 v94, 16, v95
	v_and_b32_e32 v95, 0xffff0000, v95
	v_lshlrev_b32_e32 v92, 16, v93
	v_and_b32_e32 v93, 0xffff0000, v93
	v_pk_fma_f32 v[84:85], v[84:85], v[242:243], v[100:101]
	v_pk_fma_f32 v[88:89], v[82:83], v[246:247], v[94:95]
	v_pk_fma_f32 v[82:83], v[80:81], v[240:241], v[102:103]
	v_cvt_pk_bf16_f32 v80, v84, v85
	v_pk_fma_f32 v[86:87], v[86:87], v[244:245], v[92:93]
	s_nop 0
	v_cvt_pk_bf16_f32 v81, v86, v87
	v_cvt_pk_bf16_f32 v82, v82, v83
	v_cvt_pk_bf16_f32 v83, v88, v89
	buffer_store_dwordx4 v[80:83], v104, s[20:23], 0 offen offset:256 sc1
	s_nop 1
	v_or_b32_e32 v80, 48, v162
	v_mad_i64_i32 v[82:83], s[6:7], v80, s73, 0
	v_lshl_add_u64 v[80:81], v[82:83], 1, s[36:37]
	v_lshl_add_u64 v[80:81], v[80:81], 0, v[148:149]
	v_add_co_u32_e32 v84, vcc, s74, v80
	s_nop 1
	v_addc_co_u32_e32 v85, vcc, 0, v81, vcc
	s_waitcnt vmcnt(7)
; __device__ __forceinline__ float sigmoidf_(float x) { return 1.0f / (1.0f + __expf(-x)); }
; __device__ __forceinline__ u32x4 pack8(const f32x4 v0, const f32x4 v1) { u32x4 w; w.x = pk2(v0[0], v0[1]); w.y = pk2(v0[2], v0[3]); w.z = pk2(v1[0], v1[1]); w.w = pk2(v1[2], v1[3]); return w; }
; __device__ __forceinline__ void unpack8(const u32x4 w, f32x4& v0, f32x4& v1) { v0 = (f32x4){bflo(w.x), bfhi(w.x), bflo(w.y), bfhi(w.y)}; v1 = (f32x4){bflo(w.z), bfhi(w.z), bflo(w.w), bfhi(w.w)}; }
;     __device__ __forceinline__ void operator()(const f32x4 (&acc)[2][2][4][2], const Unit& u, int wr, int wc, int fr, int fq) const {
;     ...
;                 for (int bj = 0; bj < 2; ++bj) {
;                     const u32x4 gw = *(const u32x4*)(rowp + O_GA + bj * 128);
;                     f32x4 g0, g1; unpack8(gw, g0, g1);
;                     f32x4 v0, v1;
; #pragma unroll
;                     for (int j = 0; j < 4; ++j) { v0[j] = sigmoidf_(g0[j]) * acc[ai][bj][m][0][j]; v1[j] = sigmoidf_(g1[j]) * acc[ai][bj][m][1][j]; }
;                     const u32x4 mw = *(const u32x4*)(rowp + bj * 128); f32x4 m0, m1; unpack8(mw, m0, m1); v0 += m0; v1 += m1;
;                     __builtin_amdgcn_raw_buffer_store_b128(pack8(v0, v1), rsrc, (unsigned)(((size_t)row * DIN + col0 + bj * 128) * 2), 0, 16  ); }
	v_mov_b32_e32 v86, v204
	v_mov_b32_e32 v87, v205
	v_mov_b32_e32 v88, v206
	v_mov_b32_e32 v89, v207
	v_mov_b32_e32 v90, v208
	v_mov_b32_e32 v91, v209
	v_mov_b32_e32 v92, v210
	v_mov_b32_e32 v93, v211
	v_add_u32_e32 v202, 0x111300, v201
	global_load_dwordx4 v[204:207], v202, s[36:37]
	v_add_u32_e32 v202, 0x110100, v201
	global_load_dwordx4 v[208:211], v202, s[36:37]
	s_mov_b32 s100, 0xbfb8aa3b
	v_lshlrev_b32_e32 v240, 16, v86
	v_and_b32_e32 v241, 0xffff0000, v86
	v_lshlrev_b32_e32 v242, 16, v88
	v_and_b32_e32 v243, 0xffff0000, v88
	v_lshlrev_b32_e32 v244, 16, v87
	v_and_b32_e32 v245, 0xffff0000, v87
	v_lshlrev_b32_e32 v246, 16, v89
	v_and_b32_e32 v247, 0xffff0000, v89
	v_pk_mul_f32 v[240:241], v[240:241], s[100:101] op_sel_hi:[1,0]
	v_pk_mul_f32 v[242:243], v[242:243], s[100:101] op_sel_hi:[1,0]
	v_pk_mul_f32 v[244:245], v[244:245], s[100:101] op_sel_hi:[1,0]
	v_pk_mul_f32 v[246:247], v[246:247], s[100:101] op_sel_hi:[1,0]
	v_exp_f32_e32 v240, v240
	v_exp_f32_e32 v241, v241
	v_exp_f32_e32 v242, v242
	v_exp_f32_e32 v243, v243
	v_exp_f32_e32 v244, v244
	v_exp_f32_e32 v245, v245
	v_exp_f32_e32 v246, v246
	v_exp_f32_e32 v247, v247
	s_nop 0
	v_pk_add_f32 v[240:241], v[240:241], 1.0 op_sel_hi:[1,0]
	v_pk_add_f32 v[242:243], v[242:243], 1.0 op_sel_hi:[1,0]
	v_pk_add_f32 v[244:245], v[244:245], 1.0 op_sel_hi:[1,0]
	v_pk_add_f32 v[246:247], v[246:247], 1.0 op_sel_hi:[1,0]
	v_rcp_f32_e32 v248, v240
	v_rcp_f32_e32 v249, v241
	v_rcp_f32_e32 v254, v242
	v_rcp_f32_e32 v255, v243
	v_pk_fma_f32 v[250:251], v[240:241], v[248:249], 1.0 op_sel_hi:[1,1,0] neg_lo:[1,0,0] neg_hi:[1,0,0]
	v_pk_fma_f32 v[86:87], v[242:243], v[254:255], 1.0 op_sel_hi:[1,1,0] neg_lo:[1,0,0] neg_hi:[1,0,0]
	v_pk_fma_f32 v[248:249], v[250:251], v[248:249], v[248:249]
	v_pk_fma_f32 v[254:255], v[86:87], v[254:255], v[254:255]
	v_pk_fma_f32 v[250:251], v[240:241], v[248:249], 1.0 op_sel_hi:[1,1,0] neg_lo:[1,0,0] neg_hi:[1,0,0]
	v_pk_fma_f32 v[86:87], v[242:243], v[254:255], 1.0 op_sel_hi:[1,1,0] neg_lo:[1,0,0] neg_hi:[1,0,0]
	v_pk_fma_f32 v[252:253], v[250:251], v[248:249], v[248:249]
	v_pk_fma_f32 v[88:89], v[86:87], v[254:255], v[254:255]
	v_pk_fma_f32 v[250:251], v[240:241], v[252:253], 1.0 op_sel_hi:[1,1,0] neg_lo:[1,0,0] neg_hi:[1,0,0]
	v_pk_fma_f32 v[86:87], v[242:243], v[88:89], 1.0 op_sel_hi:[1,1,0] neg_lo:[1,0,0] neg_hi:[1,0,0]
	v_pk_fma_f32 v[252:253], v[250:251], v[248:249], v[252:253]
	v_pk_fma_f32 v[88:89], v[86:87], v[254:255], v[88:89]
	v_div_fixup_f32 v240, v252, v240, 1.0
	v_div_fixup_f32 v241, v253, v241, 1.0
	v_div_fixup_f32 v242, v88, v242, 1.0
	v_div_fixup_f32 v243, v89, v243, 1.0
	v_rcp_f32_e32 v248, v244
	v_rcp_f32_e32 v249, v245
	v_rcp_f32_e32 v254, v246
	v_rcp_f32_e32 v255, v247
	v_pk_fma_f32 v[250:251], v[244:245], v[248:249], 1.0 op_sel_hi:[1,1,0] neg_lo:[1,0,0] neg_hi:[1,0,0]
	v_pk_fma_f32 v[86:87], v[246:247], v[254:255], 1.0 op_sel_hi:[1,1,0] neg_lo:[1,0,0] neg_hi:[1,0,0]
	v_pk_fma_f32 v[248:249], v[250:251], v[248:249], v[248:249]
	v_pk_fma_f32 v[254:255], v[86:87], v[254:255], v[254:255]
	v_pk_fma_f32 v[250:251], v[244:245], v[248:249], 1.0 op_sel_hi:[1,1,0] neg_lo:[1,0,0] neg_hi:[1,0,0]
	v_pk_fma_f32 v[86:87], v[246:247], v[254:255], 1.0 op_sel_hi:[1,1,0] neg_lo:[1,0,0] neg_hi:[1,0,0]
	v_pk_fma_f32 v[252:253], v[250:251], v[248:249], v[248:249]
	v_pk_fma_f32 v[88:89], v[86:87], v[254:255], v[254:255]
	v_pk_fma_f32 v[250:251], v[244:245], v[252:253], 1.0 op_sel_hi:[1,1,0] neg_lo:[1,0,0] neg_hi:[1,0,0]
	v_pk_fma_f32 v[86:87], v[246:247], v[88:89], 1.0 op_sel_hi:[1,1,0] neg_lo:[1,0,0] neg_hi:[1,0,0]
	v_pk_fma_f32 v[252:253], v[250:251], v[248:249], v[252:253]
	v_pk_fma_f32 v[88:89], v[86:87], v[254:255], v[88:89]
	v_div_fixup_f32 v244, v252, v244, 1.0
	v_div_fixup_f32 v245, v253, v245, 1.0
	v_div_fixup_f32 v246, v88, v246, 1.0
	v_div_fixup_f32 v247, v89, v247, 1.0
	v_lshlrev_b32_e32 v98, 16, v90
	v_and_b32_e32 v99, 0xffff0000, v90
	v_lshlrev_b32_e32 v100, 16, v92
	v_and_b32_e32 v101, 0xffff0000, v92
	v_lshlrev_b32_e32 v92, 16, v93
	v_and_b32_e32 v93, 0xffff0000, v93
	v_lshlrev_b32_e32 v90, 16, v91
	v_and_b32_e32 v91, 0xffff0000, v91
	v_pk_fma_f32 v[76:77], v[76:77], v[240:241], v[98:99]
	v_pk_fma_f32 v[86:87], v[74:75], v[246:247], v[92:93]
	v_pk_fma_f32 v[74:75], v[72:73], v[242:243], v[100:101]
	v_add_lshl_u32 v88, v146, v82, 1
	v_pk_fma_f32 v[78:79], v[78:79], v[244:245], v[90:91]
	v_cvt_pk_bf16_f32 v72, v76, v77
	s_nop 0
	v_cvt_pk_bf16_f32 v73, v78, v79
	v_cvt_pk_bf16_f32 v74, v74, v75
	v_cvt_pk_bf16_f32 v75, v86, v87
	buffer_store_dwordx4 v[72:75], v88, s[20:23], 0 offen sc1
	s_nop 0
	s_waitcnt vmcnt(7)
; __device__ __forceinline__ float sigmoidf_(float x) { return 1.0f / (1.0f + __expf(-x)); }
; __device__ __forceinline__ u32x4 pack8(const f32x4 v0, const f32x4 v1) { u32x4 w; w.x = pk2(v0[0], v0[1]); w.y = pk2(v0[2], v0[3]); w.z = pk2(v1[0], v1[1]); w.w = pk2(v1[2], v1[3]); return w; }
; __device__ __forceinline__ void unpack8(const u32x4 w, f32x4& v0, f32x4& v1) { v0 = (f32x4){bflo(w.x), bfhi(w.x), bflo(w.y), bfhi(w.y)}; v1 = (f32x4){bflo(w.z), bfhi(w.z), bflo(w.w), bfhi(w.w)}; }
;     __device__ __forceinline__ void operator()(const f32x4 (&acc)[2][2][4][2], const Unit& u, int wr, int wc, int fr, int fq) const {
;     ...
;                 const int row = row0 + ai * 128 + m * 16;
;                 const bf16_t* rowp = z + (size_t)row * DIN + col0;
; #pragma unroll
;                 for (int bj = 0; bj < 2; ++bj) {
;                     const u32x4 gw = *(const u32x4*)(rowp + O_GA + bj * 128);
;                     f32x4 g0, g1; unpack8(gw, g0, g1);
;                     f32x4 v0, v1;
; #pragma unroll
;                     for (int j = 0; j < 4; ++j) { v0[j] = sigmoidf_(g0[j]) * acc[ai][bj][m][0][j]; v1[j] = sigmoidf_(g1[j]) * acc[ai][bj][m][1][j]; }
;                     const u32x4 mw = *(const u32x4*)(rowp + bj * 128); f32x4 m0, m1; unpack8(mw, m0, m1); v0 += m0; v1 += m1;
;                     __builtin_amdgcn_raw_buffer_store_b128(pack8(v0, v1), rsrc, (unsigned)(((size_t)row * DIN + col0 + bj * 128) * 2), 0, 16  ); }
	v_mov_b32_e32 v72, v212
	v_mov_b32_e32 v73, v213
	v_mov_b32_e32 v74, v214
	v_mov_b32_e32 v75, v215
	v_mov_b32_e32 v76, v216
	v_mov_b32_e32 v77, v217
	v_mov_b32_e32 v78, v218
	v_mov_b32_e32 v79, v219
	v_add_u32_e32 v202, 0x133200, v201
	global_load_dwordx4 v[212:215], v202, s[36:37]
	v_add_u32_e32 v202, 0x132000, v201
	global_load_dwordx4 v[216:219], v202, s[36:37]
	s_mov_b32 s100, 0xbfb8aa3b
	v_lshlrev_b32_e32 v240, 16, v74
	v_and_b32_e32 v241, 0xffff0000, v74
	v_lshlrev_b32_e32 v242, 16, v72
	v_and_b32_e32 v243, 0xffff0000, v72
	v_lshlrev_b32_e32 v244, 16, v73
	v_and_b32_e32 v245, 0xffff0000, v73
	v_lshlrev_b32_e32 v246, 16, v75
	v_and_b32_e32 v247, 0xffff0000, v75
	v_pk_mul_f32 v[240:241], v[240:241], s[100:101] op_sel_hi:[1,0]
	v_pk_mul_f32 v[242:243], v[242:243], s[100:101] op_sel_hi:[1,0]
	v_pk_mul_f32 v[244:245], v[244:245], s[100:101] op_sel_hi:[1,0]
	v_pk_mul_f32 v[246:247], v[246:247], s[100:101] op_sel_hi:[1,0]
	v_exp_f32_e32 v240, v240
	v_exp_f32_e32 v241, v241
	v_exp_f32_e32 v242, v242
	v_exp_f32_e32 v243, v243
	v_exp_f32_e32 v244, v244
	v_exp_f32_e32 v245, v245
	v_exp_f32_e32 v246, v246
	v_exp_f32_e32 v247, v247
	s_nop 0
	v_pk_add_f32 v[240:241], v[240:241], 1.0 op_sel_hi:[1,0]
	v_pk_add_f32 v[242:243], v[242:243], 1.0 op_sel_hi:[1,0]
	v_pk_add_f32 v[244:245], v[244:245], 1.0 op_sel_hi:[1,0]
	v_pk_add_f32 v[246:247], v[246:247], 1.0 op_sel_hi:[1,0]
	v_rcp_f32_e32 v248, v240
	v_rcp_f32_e32 v249, v241
	v_rcp_f32_e32 v254, v242
	v_rcp_f32_e32 v255, v243
	v_pk_fma_f32 v[250:251], v[240:241], v[248:249], 1.0 op_sel_hi:[1,1,0] neg_lo:[1,0,0] neg_hi:[1,0,0]
	v_pk_fma_f32 v[72:73], v[242:243], v[254:255], 1.0 op_sel_hi:[1,1,0] neg_lo:[1,0,0] neg_hi:[1,0,0]
	v_pk_fma_f32 v[248:249], v[250:251], v[248:249], v[248:249]
	v_pk_fma_f32 v[254:255], v[72:73], v[254:255], v[254:255]
	v_pk_fma_f32 v[250:251], v[240:241], v[248:249], 1.0 op_sel_hi:[1,1,0] neg_lo:[1,0,0] neg_hi:[1,0,0]
	v_pk_fma_f32 v[72:73], v[242:243], v[254:255], 1.0 op_sel_hi:[1,1,0] neg_lo:[1,0,0] neg_hi:[1,0,0]
	v_pk_fma_f32 v[252:253], v[250:251], v[248:249], v[248:249]
	v_pk_fma_f32 v[74:75], v[72:73], v[254:255], v[254:255]
	v_pk_fma_f32 v[250:251], v[240:241], v[252:253], 1.0 op_sel_hi:[1,1,0] neg_lo:[1,0,0] neg_hi:[1,0,0]
	v_pk_fma_f32 v[72:73], v[242:243], v[74:75], 1.0 op_sel_hi:[1,1,0] neg_lo:[1,0,0] neg_hi:[1,0,0]
	v_pk_fma_f32 v[252:253], v[250:251], v[248:249], v[252:253]
	v_pk_fma_f32 v[74:75], v[72:73], v[254:255], v[74:75]
	v_div_fixup_f32 v240, v252, v240, 1.0
	v_div_fixup_f32 v241, v253, v241, 1.0
	v_div_fixup_f32 v242, v74, v242, 1.0
	v_div_fixup_f32 v243, v75, v243, 1.0
	v_rcp_f32_e32 v248, v244
	v_rcp_f32_e32 v249, v245
	v_rcp_f32_e32 v254, v246
	v_rcp_f32_e32 v255, v247
	v_pk_fma_f32 v[250:251], v[244:245], v[248:249], 1.0 op_sel_hi:[1,1,0] neg_lo:[1,0,0] neg_hi:[1,0,0]
	v_pk_fma_f32 v[72:73], v[246:247], v[254:255], 1.0 op_sel_hi:[1,1,0] neg_lo:[1,0,0] neg_hi:[1,0,0]
	v_pk_fma_f32 v[248:249], v[250:251], v[248:249], v[248:249]
	v_pk_fma_f32 v[254:255], v[72:73], v[254:255], v[254:255]
	v_pk_fma_f32 v[250:251], v[244:245], v[248:249], 1.0 op_sel_hi:[1,1,0] neg_lo:[1,0,0] neg_hi:[1,0,0]
	v_pk_fma_f32 v[72:73], v[246:247], v[254:255], 1.0 op_sel_hi:[1,1,0] neg_lo:[1,0,0] neg_hi:[1,0,0]
	v_pk_fma_f32 v[252:253], v[250:251], v[248:249], v[248:249]
	v_pk_fma_f32 v[74:75], v[72:73], v[254:255], v[254:255]
	v_pk_fma_f32 v[250:251], v[244:245], v[252:253], 1.0 op_sel_hi:[1,1,0] neg_lo:[1,0,0] neg_hi:[1,0,0]
	v_pk_fma_f32 v[72:73], v[246:247], v[74:75], 1.0 op_sel_hi:[1,1,0] neg_lo:[1,0,0] neg_hi:[1,0,0]
	v_pk_fma_f32 v[252:253], v[250:251], v[248:249], v[252:253]
	v_pk_fma_f32 v[74:75], v[72:73], v[254:255], v[74:75]
	v_div_fixup_f32 v244, v252, v244, 1.0
	v_div_fixup_f32 v245, v253, v245, 1.0
	v_div_fixup_f32 v246, v74, v246, 1.0
	v_div_fixup_f32 v247, v75, v247, 1.0
	v_lshlrev_b32_e32 v84, 16, v76
	v_and_b32_e32 v85, 0xffff0000, v76
	v_lshlrev_b32_e32 v86, 16, v78
	v_and_b32_e32 v87, 0xffff0000, v78
	v_lshlrev_b32_e32 v78, 16, v79
	v_and_b32_e32 v79, 0xffff0000, v79
	v_lshlrev_b32_e32 v76, 16, v77
	v_and_b32_e32 v77, 0xffff0000, v77
	v_pk_fma_f32 v[68:69], v[68:69], v[242:243], v[84:85]
	v_pk_fma_f32 v[72:73], v[66:67], v[246:247], v[78:79]
	v_pk_fma_f32 v[66:67], v[64:65], v[240:241], v[86:87]
	v_cvt_pk_bf16_f32 v64, v68, v69
	v_pk_fma_f32 v[70:71], v[70:71], v[244:245], v[76:77]
	s_nop 0
	v_cvt_pk_bf16_f32 v65, v70, v71
	v_cvt_pk_bf16_f32 v66, v66, v67
	v_cvt_pk_bf16_f32 v67, v72, v73
	buffer_store_dwordx4 v[64:67], v88, s[20:23], 0 offen offset:256 sc1
	s_nop 1
	v_add_u32_e32 v64, 0x80, v162
	v_mad_i64_i32 v[66:67], s[6:7], v64, s73, 0
	v_lshl_add_u64 v[64:65], v[66:67], 1, s[36:37]
	v_lshl_add_u64 v[64:65], v[64:65], 0, v[148:149]
	v_add_co_u32_e32 v68, vcc, s74, v64
	s_nop 1
	v_addc_co_u32_e32 v69, vcc, 0, v65, vcc
	s_waitcnt vmcnt(7)
; __device__ __forceinline__ float sigmoidf_(float x) { return 1.0f / (1.0f + __expf(-x)); }
; __device__ __forceinline__ u32x4 pack8(const f32x4 v0, const f32x4 v1) { u32x4 w; w.x = pk2(v0[0], v0[1]); w.y = pk2(v0[2], v0[3]); w.z = pk2(v1[0], v1[1]); w.w = pk2(v1[2], v1[3]); return w; }
; __device__ __forceinline__ void unpack8(const u32x4 w, f32x4& v0, f32x4& v1) { v0 = (f32x4){bflo(w.x), bfhi(w.x), bflo(w.y), bfhi(w.y)}; v1 = (f32x4){bflo(w.z), bfhi(w.z), bflo(w.w), bfhi(w.w)}; }
;     __device__ __forceinline__ void operator()(const f32x4 (&acc)[2][2][4][2], const Unit& u, int wr, int wc, int fr, int fq) const {
;     ...
;                 for (int bj = 0; bj < 2; ++bj) {
;                     const u32x4 gw = *(const u32x4*)(rowp + O_GA + bj * 128);
;                     f32x4 g0, g1; unpack8(gw, g0, g1);
;                     f32x4 v0, v1;
; #pragma unroll
;                     for (int j = 0; j < 4; ++j) { v0[j] = sigmoidf_(g0[j]) * acc[ai][bj][m][0][j]; v1[j] = sigmoidf_(g1[j]) * acc[ai][bj][m][1][j]; }
;                     const u32x4 mw = *(const u32x4*)(rowp + bj * 128); f32x4 m0, m1; unpack8(mw, m0, m1); v0 += m0; v1 += m1;
;                     __builtin_amdgcn_raw_buffer_store_b128(pack8(v0, v1), rsrc, (unsigned)(((size_t)row * DIN + col0 + bj * 128) * 2), 0, 16  ); }
	v_mov_b32_e32 v70, v232
	v_mov_b32_e32 v71, v233
	v_mov_b32_e32 v72, v234
	v_mov_b32_e32 v73, v235
	v_mov_b32_e32 v74, v236
	v_mov_b32_e32 v75, v237
	v_mov_b32_e32 v76, v238
	v_mov_b32_e32 v77, v239
	v_add_u32_e32 v202, 0x133300, v201
	global_load_dwordx4 v[232:235], v202, s[36:37]
	v_add_u32_e32 v202, 0x132100, v201
	global_load_dwordx4 v[236:239], v202, s[36:37]
	s_mov_b32 s100, 0xbfb8aa3b
	v_lshlrev_b32_e32 v240, 16, v70
	v_and_b32_e32 v241, 0xffff0000, v70
	v_lshlrev_b32_e32 v242, 16, v72
	v_and_b32_e32 v243, 0xffff0000, v72
	v_lshlrev_b32_e32 v244, 16, v71
	v_and_b32_e32 v245, 0xffff0000, v71
	v_lshlrev_b32_e32 v246, 16, v73
	v_and_b32_e32 v247, 0xffff0000, v73
	v_pk_mul_f32 v[240:241], v[240:241], s[100:101] op_sel_hi:[1,0]
	v_pk_mul_f32 v[242:243], v[242:243], s[100:101] op_sel_hi:[1,0]
	v_pk_mul_f32 v[244:245], v[244:245], s[100:101] op_sel_hi:[1,0]
	v_pk_mul_f32 v[246:247], v[246:247], s[100:101] op_sel_hi:[1,0]
	v_exp_f32_e32 v240, v240
	v_exp_f32_e32 v241, v241
	v_exp_f32_e32 v242, v242
	v_exp_f32_e32 v243, v243
	v_exp_f32_e32 v244, v244
	v_exp_f32_e32 v245, v245
	v_exp_f32_e32 v246, v246
	v_exp_f32_e32 v247, v247
	s_nop 0
	v_pk_add_f32 v[240:241], v[240:241], 1.0 op_sel_hi:[1,0]
	v_pk_add_f32 v[242:243], v[242:243], 1.0 op_sel_hi:[1,0]
	v_pk_add_f32 v[244:245], v[244:245], 1.0 op_sel_hi:[1,0]
	v_pk_add_f32 v[246:247], v[246:247], 1.0 op_sel_hi:[1,0]
	v_rcp_f32_e32 v248, v240
	v_rcp_f32_e32 v249, v241
	v_rcp_f32_e32 v254, v242
	v_rcp_f32_e32 v255, v243
	v_pk_fma_f32 v[250:251], v[240:241], v[248:249], 1.0 op_sel_hi:[1,1,0] neg_lo:[1,0,0] neg_hi:[1,0,0]
	v_pk_fma_f32 v[70:71], v[242:243], v[254:255], 1.0 op_sel_hi:[1,1,0] neg_lo:[1,0,0] neg_hi:[1,0,0]
	v_pk_fma_f32 v[248:249], v[250:251], v[248:249], v[248:249]
	v_pk_fma_f32 v[254:255], v[70:71], v[254:255], v[254:255]
	v_pk_fma_f32 v[250:251], v[240:241], v[248:249], 1.0 op_sel_hi:[1,1,0] neg_lo:[1,0,0] neg_hi:[1,0,0]
	v_pk_fma_f32 v[70:71], v[242:243], v[254:255], 1.0 op_sel_hi:[1,1,0] neg_lo:[1,0,0] neg_hi:[1,0,0]
	v_pk_fma_f32 v[252:253], v[250:251], v[248:249], v[248:249]
	v_pk_fma_f32 v[72:73], v[70:71], v[254:255], v[254:255]
	v_pk_fma_f32 v[250:251], v[240:241], v[252:253], 1.0 op_sel_hi:[1,1,0] neg_lo:[1,0,0] neg_hi:[1,0,0]
	v_pk_fma_f32 v[70:71], v[242:243], v[72:73], 1.0 op_sel_hi:[1,1,0] neg_lo:[1,0,0] neg_hi:[1,0,0]
	v_pk_fma_f32 v[252:253], v[250:251], v[248:249], v[252:253]
	v_pk_fma_f32 v[72:73], v[70:71], v[254:255], v[72:73]
	v_div_fixup_f32 v240, v252, v240, 1.0
	v_div_fixup_f32 v241, v253, v241, 1.0
	v_div_fixup_f32 v242, v72, v242, 1.0
	v_div_fixup_f32 v243, v73, v243, 1.0
	v_rcp_f32_e32 v248, v244
	v_rcp_f32_e32 v249, v245
	v_rcp_f32_e32 v254, v246
	v_rcp_f32_e32 v255, v247
	v_pk_fma_f32 v[250:251], v[244:245], v[248:249], 1.0 op_sel_hi:[1,1,0] neg_lo:[1,0,0] neg_hi:[1,0,0]
	v_pk_fma_f32 v[70:71], v[246:247], v[254:255], 1.0 op_sel_hi:[1,1,0] neg_lo:[1,0,0] neg_hi:[1,0,0]
	v_pk_fma_f32 v[248:249], v[250:251], v[248:249], v[248:249]
	v_pk_fma_f32 v[254:255], v[70:71], v[254:255], v[254:255]
	v_pk_fma_f32 v[250:251], v[244:245], v[248:249], 1.0 op_sel_hi:[1,1,0] neg_lo:[1,0,0] neg_hi:[1,0,0]
	v_pk_fma_f32 v[70:71], v[246:247], v[254:255], 1.0 op_sel_hi:[1,1,0] neg_lo:[1,0,0] neg_hi:[1,0,0]
	v_pk_fma_f32 v[252:253], v[250:251], v[248:249], v[248:249]
	v_pk_fma_f32 v[72:73], v[70:71], v[254:255], v[254:255]
	v_pk_fma_f32 v[250:251], v[244:245], v[252:253], 1.0 op_sel_hi:[1,1,0] neg_lo:[1,0,0] neg_hi:[1,0,0]
	v_pk_fma_f32 v[70:71], v[246:247], v[72:73], 1.0 op_sel_hi:[1,1,0] neg_lo:[1,0,0] neg_hi:[1,0,0]
	v_pk_fma_f32 v[252:253], v[250:251], v[248:249], v[252:253]
	v_pk_fma_f32 v[72:73], v[70:71], v[254:255], v[72:73]
	v_div_fixup_f32 v244, v252, v244, 1.0
	v_div_fixup_f32 v245, v253, v245, 1.0
	v_div_fixup_f32 v246, v72, v246, 1.0
	v_div_fixup_f32 v247, v73, v247, 1.0
	v_lshlrev_b32_e32 v82, 16, v74
	v_and_b32_e32 v83, 0xffff0000, v74
	v_lshlrev_b32_e32 v84, 16, v76
	v_and_b32_e32 v85, 0xffff0000, v76
	v_lshlrev_b32_e32 v76, 16, v77
	v_and_b32_e32 v77, 0xffff0000, v77
	v_lshlrev_b32_e32 v74, 16, v75
	v_and_b32_e32 v75, 0xffff0000, v75
	v_pk_fma_f32 v[60:61], v[60:61], v[240:241], v[82:83]
	v_pk_fma_f32 v[70:71], v[58:59], v[246:247], v[76:77]
	v_pk_fma_f32 v[58:59], v[56:57], v[242:243], v[84:85]
	v_add_lshl_u32 v72, v146, v66, 1
	v_pk_fma_f32 v[62:63], v[62:63], v[244:245], v[74:75]
	v_cvt_pk_bf16_f32 v56, v60, v61
	s_nop 0
	v_cvt_pk_bf16_f32 v57, v62, v63
	v_cvt_pk_bf16_f32 v58, v58, v59
	v_cvt_pk_bf16_f32 v59, v70, v71
	buffer_store_dwordx4 v[56:59], v72, s[20:23], 0 offen sc1
	s_nop 0
	s_waitcnt vmcnt(7)
; __device__ __forceinline__ float sigmoidf_(float x) { return 1.0f / (1.0f + __expf(-x)); }
; __device__ __forceinline__ u32x4 pack8(const f32x4 v0, const f32x4 v1) { u32x4 w; w.x = pk2(v0[0], v0[1]); w.y = pk2(v0[2], v0[3]); w.z = pk2(v1[0], v1[1]); w.w = pk2(v1[2], v1[3]); return w; }
; __device__ __forceinline__ void unpack8(const u32x4 w, f32x4& v0, f32x4& v1) { v0 = (f32x4){bflo(w.x), bfhi(w.x), bflo(w.y), bfhi(w.y)}; v1 = (f32x4){bflo(w.z), bfhi(w.z), bflo(w.w), bfhi(w.w)}; }
;     __device__ __forceinline__ void operator()(const f32x4 (&acc)[2][2][4][2], const Unit& u, int wr, int wc, int fr, int fq) const {
;     ...
;                 const int row = row0 + ai * 128 + m * 16;
;                 const bf16_t* rowp = z + (size_t)row * DIN + col0;
; #pragma unroll
;                 for (int bj = 0; bj < 2; ++bj) {
;                     const u32x4 gw = *(const u32x4*)(rowp + O_GA + bj * 128);
;                     f32x4 g0, g1; unpack8(gw, g0, g1);
;                     f32x4 v0, v1;
; #pragma unroll
;                     for (int j = 0; j < 4; ++j) { v0[j] = sigmoidf_(g0[j]) * acc[ai][bj][m][0][j]; v1[j] = sigmoidf_(g1[j]) * acc[ai][bj][m][1][j]; }
;                     const u32x4 mw = *(const u32x4*)(rowp + bj * 128); f32x4 m0, m1; unpack8(mw, m0, m1); v0 += m0; v1 += m1;
;                     __builtin_amdgcn_raw_buffer_store_b128(pack8(v0, v1), rsrc, (unsigned)(((size_t)row * DIN + col0 + bj * 128) * 2), 0, 16  ); }
	v_mov_b32_e32 v56, v204
	v_mov_b32_e32 v57, v205
	v_mov_b32_e32 v58, v206
	v_mov_b32_e32 v59, v207
	v_mov_b32_e32 v60, v208
	v_mov_b32_e32 v61, v209
	v_mov_b32_e32 v62, v210
	v_mov_b32_e32 v63, v211
	v_add_u32_e32 v202, 0x155200, v201
	global_load_dwordx4 v[204:207], v202, s[36:37]
	v_add_u32_e32 v202, 0x154000, v201
	global_load_dwordx4 v[208:211], v202, s[36:37]
	s_mov_b32 s100, 0xbfb8aa3b
	v_lshlrev_b32_e32 v240, 16, v58
	v_and_b32_e32 v241, 0xffff0000, v58
	v_lshlrev_b32_e32 v242, 16, v56
	v_and_b32_e32 v243, 0xffff0000, v56
	v_lshlrev_b32_e32 v244, 16, v57
	v_and_b32_e32 v245, 0xffff0000, v57
	v_lshlrev_b32_e32 v246, 16, v59
	v_and_b32_e32 v247, 0xffff0000, v59
	v_pk_mul_f32 v[240:241], v[240:241], s[100:101] op_sel_hi:[1,0]
	v_pk_mul_f32 v[242:243], v[242:243], s[100:101] op_sel_hi:[1,0]
	v_pk_mul_f32 v[244:245], v[244:245], s[100:101] op_sel_hi:[1,0]
	v_pk_mul_f32 v[246:247], v[246:247], s[100:101] op_sel_hi:[1,0]
	v_exp_f32_e32 v240, v240
	v_exp_f32_e32 v241, v241
	v_exp_f32_e32 v242, v242
	v_exp_f32_e32 v243, v243
	v_exp_f32_e32 v244, v244
	v_exp_f32_e32 v245, v245
	v_exp_f32_e32 v246, v246
	v_exp_f32_e32 v247, v247
	s_nop 0
	v_pk_add_f32 v[240:241], v[240:241], 1.0 op_sel_hi:[1,0]
	v_pk_add_f32 v[242:243], v[242:243], 1.0 op_sel_hi:[1,0]
	v_pk_add_f32 v[244:245], v[244:245], 1.0 op_sel_hi:[1,0]
	v_pk_add_f32 v[246:247], v[246:247], 1.0 op_sel_hi:[1,0]
	v_rcp_f32_e32 v248, v240
	v_rcp_f32_e32 v249, v241
	v_rcp_f32_e32 v254, v242
	v_rcp_f32_e32 v255, v243
	v_pk_fma_f32 v[250:251], v[240:241], v[248:249], 1.0 op_sel_hi:[1,1,0] neg_lo:[1,0,0] neg_hi:[1,0,0]
	v_pk_fma_f32 v[56:57], v[242:243], v[254:255], 1.0 op_sel_hi:[1,1,0] neg_lo:[1,0,0] neg_hi:[1,0,0]
	v_pk_fma_f32 v[248:249], v[250:251], v[248:249], v[248:249]
	v_pk_fma_f32 v[254:255], v[56:57], v[254:255], v[254:255]
	v_pk_fma_f32 v[250:251], v[240:241], v[248:249], 1.0 op_sel_hi:[1,1,0] neg_lo:[1,0,0] neg_hi:[1,0,0]
	v_pk_fma_f32 v[56:57], v[242:243], v[254:255], 1.0 op_sel_hi:[1,1,0] neg_lo:[1,0,0] neg_hi:[1,0,0]
	v_pk_fma_f32 v[252:253], v[250:251], v[248:249], v[248:249]
	v_pk_fma_f32 v[58:59], v[56:57], v[254:255], v[254:255]
	v_pk_fma_f32 v[250:251], v[240:241], v[252:253], 1.0 op_sel_hi:[1,1,0] neg_lo:[1,0,0] neg_hi:[1,0,0]
	v_pk_fma_f32 v[56:57], v[242:243], v[58:59], 1.0 op_sel_hi:[1,1,0] neg_lo:[1,0,0] neg_hi:[1,0,0]
	v_pk_fma_f32 v[252:253], v[250:251], v[248:249], v[252:253]
	v_pk_fma_f32 v[58:59], v[56:57], v[254:255], v[58:59]
	v_div_fixup_f32 v240, v252, v240, 1.0
	v_div_fixup_f32 v241, v253, v241, 1.0
	v_div_fixup_f32 v242, v58, v242, 1.0
	v_div_fixup_f32 v243, v59, v243, 1.0
	v_rcp_f32_e32 v248, v244
	v_rcp_f32_e32 v249, v245
	v_rcp_f32_e32 v254, v246
	v_rcp_f32_e32 v255, v247
	v_pk_fma_f32 v[250:251], v[244:245], v[248:249], 1.0 op_sel_hi:[1,1,0] neg_lo:[1,0,0] neg_hi:[1,0,0]
	v_pk_fma_f32 v[56:57], v[246:247], v[254:255], 1.0 op_sel_hi:[1,1,0] neg_lo:[1,0,0] neg_hi:[1,0,0]
	v_pk_fma_f32 v[248:249], v[250:251], v[248:249], v[248:249]
	v_pk_fma_f32 v[254:255], v[56:57], v[254:255], v[254:255]
	v_pk_fma_f32 v[250:251], v[244:245], v[248:249], 1.0 op_sel_hi:[1,1,0] neg_lo:[1,0,0] neg_hi:[1,0,0]
	v_pk_fma_f32 v[56:57], v[246:247], v[254:255], 1.0 op_sel_hi:[1,1,0] neg_lo:[1,0,0] neg_hi:[1,0,0]
	v_pk_fma_f32 v[252:253], v[250:251], v[248:249], v[248:249]
	v_pk_fma_f32 v[58:59], v[56:57], v[254:255], v[254:255]
	v_pk_fma_f32 v[250:251], v[244:245], v[252:253], 1.0 op_sel_hi:[1,1,0] neg_lo:[1,0,0] neg_hi:[1,0,0]
	v_pk_fma_f32 v[56:57], v[246:247], v[58:59], 1.0 op_sel_hi:[1,1,0] neg_lo:[1,0,0] neg_hi:[1,0,0]
	v_pk_fma_f32 v[252:253], v[250:251], v[248:249], v[252:253]
	v_pk_fma_f32 v[58:59], v[56:57], v[254:255], v[58:59]
	v_div_fixup_f32 v244, v252, v244, 1.0
	v_div_fixup_f32 v245, v253, v245, 1.0
	v_div_fixup_f32 v246, v58, v246, 1.0
	v_div_fixup_f32 v247, v59, v247, 1.0
	v_lshlrev_b32_e32 v68, 16, v60
	v_and_b32_e32 v69, 0xffff0000, v60
	v_lshlrev_b32_e32 v70, 16, v62
	v_and_b32_e32 v71, 0xffff0000, v62
	v_lshlrev_b32_e32 v62, 16, v63
	v_and_b32_e32 v63, 0xffff0000, v63
	v_lshlrev_b32_e32 v60, 16, v61
	v_and_b32_e32 v61, 0xffff0000, v61
	v_pk_fma_f32 v[52:53], v[52:53], v[242:243], v[68:69]
	v_pk_fma_f32 v[56:57], v[50:51], v[246:247], v[62:63]
	v_pk_fma_f32 v[50:51], v[48:49], v[240:241], v[70:71]
	v_cvt_pk_bf16_f32 v48, v52, v53
	v_pk_fma_f32 v[54:55], v[54:55], v[244:245], v[60:61]
	s_nop 0
	v_cvt_pk_bf16_f32 v49, v54, v55
	v_cvt_pk_bf16_f32 v50, v50, v51
	v_cvt_pk_bf16_f32 v51, v56, v57
	buffer_store_dwordx4 v[48:51], v72, s[20:23], 0 offen offset:256 sc1
	s_nop 1
	v_add_u32_e32 v48, 0x90, v162
	v_mad_i64_i32 v[50:51], s[6:7], v48, s73, 0
	v_lshl_add_u64 v[48:49], v[50:51], 1, s[36:37]
	v_lshl_add_u64 v[48:49], v[48:49], 0, v[148:149]
	v_add_co_u32_e32 v52, vcc, s74, v48
	s_nop 1
	v_addc_co_u32_e32 v53, vcc, 0, v49, vcc
	s_waitcnt vmcnt(7)
; __device__ __forceinline__ float sigmoidf_(float x) { return 1.0f / (1.0f + __expf(-x)); }
; __device__ __forceinline__ u32x4 pack8(const f32x4 v0, const f32x4 v1) { u32x4 w; w.x = pk2(v0[0], v0[1]); w.y = pk2(v0[2], v0[3]); w.z = pk2(v1[0], v1[1]); w.w = pk2(v1[2], v1[3]); return w; }
; __device__ __forceinline__ void unpack8(const u32x4 w, f32x4& v0, f32x4& v1) { v0 = (f32x4){bflo(w.x), bfhi(w.x), bflo(w.y), bfhi(w.y)}; v1 = (f32x4){bflo(w.z), bfhi(w.z), bflo(w.w), bfhi(w.w)}; }
;     __device__ __forceinline__ void operator()(const f32x4 (&acc)[2][2][4][2], const Unit& u, int wr, int wc, int fr, int fq) const {
;     ...
;                 for (int bj = 0; bj < 2; ++bj) {
;                     const u32x4 gw = *(const u32x4*)(rowp + O_GA + bj * 128);
;                     f32x4 g0, g1; unpack8(gw, g0, g1);
;                     f32x4 v0, v1;
; #pragma unroll
;                     for (int j = 0; j < 4; ++j) { v0[j] = sigmoidf_(g0[j]) * acc[ai][bj][m][0][j]; v1[j] = sigmoidf_(g1[j]) * acc[ai][bj][m][1][j]; }
;                     const u32x4 mw = *(const u32x4*)(rowp + bj * 128); f32x4 m0, m1; unpack8(mw, m0, m1); v0 += m0; v1 += m1;
;                     __builtin_amdgcn_raw_buffer_store_b128(pack8(v0, v1), rsrc, (unsigned)(((size_t)row * DIN + col0 + bj * 128) * 2), 0, 16  ); }
	v_mov_b32_e32 v54, v212
	v_mov_b32_e32 v55, v213
	v_mov_b32_e32 v56, v214
	v_mov_b32_e32 v57, v215
	v_mov_b32_e32 v58, v216
	v_mov_b32_e32 v59, v217
	v_mov_b32_e32 v60, v218
	v_mov_b32_e32 v61, v219
	v_add_u32_e32 v202, 0x155300, v201
	global_load_dwordx4 v[212:215], v202, s[36:37]
	v_add_u32_e32 v202, 0x154100, v201
	global_load_dwordx4 v[216:219], v202, s[36:37]
	s_mov_b32 s100, 0xbfb8aa3b
	v_lshlrev_b32_e32 v240, 16, v54
	v_and_b32_e32 v241, 0xffff0000, v54
	v_lshlrev_b32_e32 v242, 16, v56
	v_and_b32_e32 v243, 0xffff0000, v56
	v_lshlrev_b32_e32 v244, 16, v55
	v_and_b32_e32 v245, 0xffff0000, v55
	v_lshlrev_b32_e32 v246, 16, v57
	v_and_b32_e32 v247, 0xffff0000, v57
	v_pk_mul_f32 v[240:241], v[240:241], s[100:101] op_sel_hi:[1,0]
	v_pk_mul_f32 v[242:243], v[242:243], s[100:101] op_sel_hi:[1,0]
	v_pk_mul_f32 v[244:245], v[244:245], s[100:101] op_sel_hi:[1,0]
	v_pk_mul_f32 v[246:247], v[246:247], s[100:101] op_sel_hi:[1,0]
	v_exp_f32_e32 v240, v240
	v_exp_f32_e32 v241, v241
	v_exp_f32_e32 v242, v242
	v_exp_f32_e32 v243, v243
	v_exp_f32_e32 v244, v244
	v_exp_f32_e32 v245, v245
	v_exp_f32_e32 v246, v246
	v_exp_f32_e32 v247, v247
	s_nop 0
	v_pk_add_f32 v[240:241], v[240:241], 1.0 op_sel_hi:[1,0]
	v_pk_add_f32 v[242:243], v[242:243], 1.0 op_sel_hi:[1,0]
	v_pk_add_f32 v[244:245], v[244:245], 1.0 op_sel_hi:[1,0]
	v_pk_add_f32 v[246:247], v[246:247], 1.0 op_sel_hi:[1,0]
	v_rcp_f32_e32 v248, v240
	v_rcp_f32_e32 v249, v241
	v_rcp_f32_e32 v254, v242
	v_rcp_f32_e32 v255, v243
	v_pk_fma_f32 v[250:251], v[240:241], v[248:249], 1.0 op_sel_hi:[1,1,0] neg_lo:[1,0,0] neg_hi:[1,0,0]
	v_pk_fma_f32 v[54:55], v[242:243], v[254:255], 1.0 op_sel_hi:[1,1,0] neg_lo:[1,0,0] neg_hi:[1,0,0]
	v_pk_fma_f32 v[248:249], v[250:251], v[248:249], v[248:249]
	v_pk_fma_f32 v[254:255], v[54:55], v[254:255], v[254:255]
	v_pk_fma_f32 v[250:251], v[240:241], v[248:249], 1.0 op_sel_hi:[1,1,0] neg_lo:[1,0,0] neg_hi:[1,0,0]
	v_pk_fma_f32 v[54:55], v[242:243], v[254:255], 1.0 op_sel_hi:[1,1,0] neg_lo:[1,0,0] neg_hi:[1,0,0]
	v_pk_fma_f32 v[252:253], v[250:251], v[248:249], v[248:249]
	v_pk_fma_f32 v[56:57], v[54:55], v[254:255], v[254:255]
	v_pk_fma_f32 v[250:251], v[240:241], v[252:253], 1.0 op_sel_hi:[1,1,0] neg_lo:[1,0,0] neg_hi:[1,0,0]
	v_pk_fma_f32 v[54:55], v[242:243], v[56:57], 1.0 op_sel_hi:[1,1,0] neg_lo:[1,0,0] neg_hi:[1,0,0]
	v_pk_fma_f32 v[252:253], v[250:251], v[248:249], v[252:253]
	v_pk_fma_f32 v[56:57], v[54:55], v[254:255], v[56:57]
	v_div_fixup_f32 v240, v252, v240, 1.0
	v_div_fixup_f32 v241, v253, v241, 1.0
	v_div_fixup_f32 v242, v56, v242, 1.0
	v_div_fixup_f32 v243, v57, v243, 1.0
	v_rcp_f32_e32 v248, v244
	v_rcp_f32_e32 v249, v245
	v_rcp_f32_e32 v254, v246
	v_rcp_f32_e32 v255, v247
	v_pk_fma_f32 v[250:251], v[244:245], v[248:249], 1.0 op_sel_hi:[1,1,0] neg_lo:[1,0,0] neg_hi:[1,0,0]
	v_pk_fma_f32 v[54:55], v[246:247], v[254:255], 1.0 op_sel_hi:[1,1,0] neg_lo:[1,0,0] neg_hi:[1,0,0]
	v_pk_fma_f32 v[248:249], v[250:251], v[248:249], v[248:249]
	v_pk_fma_f32 v[254:255], v[54:55], v[254:255], v[254:255]
	v_pk_fma_f32 v[250:251], v[244:245], v[248:249], 1.0 op_sel_hi:[1,1,0] neg_lo:[1,0,0] neg_hi:[1,0,0]
	v_pk_fma_f32 v[54:55], v[246:247], v[254:255], 1.0 op_sel_hi:[1,1,0] neg_lo:[1,0,0] neg_hi:[1,0,0]
	v_pk_fma_f32 v[252:253], v[250:251], v[248:249], v[248:249]
	v_pk_fma_f32 v[56:57], v[54:55], v[254:255], v[254:255]
	v_pk_fma_f32 v[250:251], v[244:245], v[252:253], 1.0 op_sel_hi:[1,1,0] neg_lo:[1,0,0] neg_hi:[1,0,0]
	v_pk_fma_f32 v[54:55], v[246:247], v[56:57], 1.0 op_sel_hi:[1,1,0] neg_lo:[1,0,0] neg_hi:[1,0,0]
	v_pk_fma_f32 v[252:253], v[250:251], v[248:249], v[252:253]
	v_pk_fma_f32 v[56:57], v[54:55], v[254:255], v[56:57]
	v_div_fixup_f32 v244, v252, v244, 1.0
	v_div_fixup_f32 v245, v253, v245, 1.0
	v_div_fixup_f32 v246, v56, v246, 1.0
	v_div_fixup_f32 v247, v57, v247, 1.0
	v_lshlrev_b32_e32 v66, 16, v58
	v_and_b32_e32 v67, 0xffff0000, v58
	v_lshlrev_b32_e32 v68, 16, v60
	v_and_b32_e32 v69, 0xffff0000, v60
	v_lshlrev_b32_e32 v60, 16, v61
	v_and_b32_e32 v61, 0xffff0000, v61
	v_lshlrev_b32_e32 v58, 16, v59
	v_and_b32_e32 v59, 0xffff0000, v59
	v_pk_fma_f32 v[44:45], v[44:45], v[240:241], v[66:67]
	v_pk_fma_f32 v[54:55], v[42:43], v[246:247], v[60:61]
	v_pk_fma_f32 v[42:43], v[40:41], v[242:243], v[68:69]
	v_add_lshl_u32 v56, v146, v50, 1
	v_pk_fma_f32 v[46:47], v[46:47], v[244:245], v[58:59]
	v_cvt_pk_bf16_f32 v40, v44, v45
	s_nop 0
	v_cvt_pk_bf16_f32 v41, v46, v47
	v_cvt_pk_bf16_f32 v42, v42, v43
	v_cvt_pk_bf16_f32 v43, v54, v55
	buffer_store_dwordx4 v[40:43], v56, s[20:23], 0 offen sc1
	s_nop 0
	s_waitcnt vmcnt(7)
; __device__ __forceinline__ float sigmoidf_(float x) { return 1.0f / (1.0f + __expf(-x)); }
; __device__ __forceinline__ u32x4 pack8(const f32x4 v0, const f32x4 v1) { u32x4 w; w.x = pk2(v0[0], v0[1]); w.y = pk2(v0[2], v0[3]); w.z = pk2(v1[0], v1[1]); w.w = pk2(v1[2], v1[3]); return w; }
; __device__ __forceinline__ void unpack8(const u32x4 w, f32x4& v0, f32x4& v1) { v0 = (f32x4){bflo(w.x), bfhi(w.x), bflo(w.y), bfhi(w.y)}; v1 = (f32x4){bflo(w.z), bfhi(w.z), bflo(w.w), bfhi(w.w)}; }
;     __device__ __forceinline__ void operator()(const f32x4 (&acc)[2][2][4][2], const Unit& u, int wr, int wc, int fr, int fq) const {
;     ...
;                 const int row = row0 + ai * 128 + m * 16;
;                 const bf16_t* rowp = z + (size_t)row * DIN + col0;
; #pragma unroll
;                 for (int bj = 0; bj < 2; ++bj) {
;                     const u32x4 gw = *(const u32x4*)(rowp + O_GA + bj * 128);
;                     f32x4 g0, g1; unpack8(gw, g0, g1);
;                     f32x4 v0, v1;
; #pragma unroll
;                     for (int j = 0; j < 4; ++j) { v0[j] = sigmoidf_(g0[j]) * acc[ai][bj][m][0][j]; v1[j] = sigmoidf_(g1[j]) * acc[ai][bj][m][1][j]; }
;                     const u32x4 mw = *(const u32x4*)(rowp + bj * 128); f32x4 m0, m1; unpack8(mw, m0, m1); v0 += m0; v1 += m1;
;                     __builtin_amdgcn_raw_buffer_store_b128(pack8(v0, v1), rsrc, (unsigned)(((size_t)row * DIN + col0 + bj * 128) * 2), 0, 16  ); }
	v_mov_b32_e32 v40, v232
	v_mov_b32_e32 v41, v233
	v_mov_b32_e32 v42, v234
	v_mov_b32_e32 v43, v235
	v_mov_b32_e32 v44, v236
	v_mov_b32_e32 v45, v237
	v_mov_b32_e32 v46, v238
	v_mov_b32_e32 v47, v239
	v_add_u32_e32 v202, 0x177200, v201
	global_load_dwordx4 v[232:235], v202, s[36:37]
	v_add_u32_e32 v202, 0x176000, v201
	global_load_dwordx4 v[236:239], v202, s[36:37]
	s_mov_b32 s100, 0xbfb8aa3b
	v_lshlrev_b32_e32 v240, 16, v42
	v_and_b32_e32 v241, 0xffff0000, v42
	v_lshlrev_b32_e32 v242, 16, v40
	v_and_b32_e32 v243, 0xffff0000, v40
	v_lshlrev_b32_e32 v244, 16, v41
	v_and_b32_e32 v245, 0xffff0000, v41
	v_lshlrev_b32_e32 v246, 16, v43
	v_and_b32_e32 v247, 0xffff0000, v43
	v_pk_mul_f32 v[240:241], v[240:241], s[100:101] op_sel_hi:[1,0]
	v_pk_mul_f32 v[242:243], v[242:243], s[100:101] op_sel_hi:[1,0]
	v_pk_mul_f32 v[244:245], v[244:245], s[100:101] op_sel_hi:[1,0]
	v_pk_mul_f32 v[246:247], v[246:247], s[100:101] op_sel_hi:[1,0]
	v_exp_f32_e32 v240, v240
	v_exp_f32_e32 v241, v241
	v_exp_f32_e32 v242, v242
	v_exp_f32_e32 v243, v243
	v_exp_f32_e32 v244, v244
	v_exp_f32_e32 v245, v245
	v_exp_f32_e32 v246, v246
	v_exp_f32_e32 v247, v247
	s_nop 0
	v_pk_add_f32 v[240:241], v[240:241], 1.0 op_sel_hi:[1,0]
	v_pk_add_f32 v[242:243], v[242:243], 1.0 op_sel_hi:[1,0]
	v_pk_add_f32 v[244:245], v[244:245], 1.0 op_sel_hi:[1,0]
	v_pk_add_f32 v[246:247], v[246:247], 1.0 op_sel_hi:[1,0]
	v_rcp_f32_e32 v248, v240
	v_rcp_f32_e32 v249, v241
	v_rcp_f32_e32 v254, v242
	v_rcp_f32_e32 v255, v243
	v_pk_fma_f32 v[250:251], v[240:241], v[248:249], 1.0 op_sel_hi:[1,1,0] neg_lo:[1,0,0] neg_hi:[1,0,0]
	v_pk_fma_f32 v[40:41], v[242:243], v[254:255], 1.0 op_sel_hi:[1,1,0] neg_lo:[1,0,0] neg_hi:[1,0,0]
	v_pk_fma_f32 v[248:249], v[250:251], v[248:249], v[248:249]
	v_pk_fma_f32 v[254:255], v[40:41], v[254:255], v[254:255]
	v_pk_fma_f32 v[250:251], v[240:241], v[248:249], 1.0 op_sel_hi:[1,1,0] neg_lo:[1,0,0] neg_hi:[1,0,0]
	v_pk_fma_f32 v[40:41], v[242:243], v[254:255], 1.0 op_sel_hi:[1,1,0] neg_lo:[1,0,0] neg_hi:[1,0,0]
	v_pk_fma_f32 v[252:253], v[250:251], v[248:249], v[248:249]
	v_pk_fma_f32 v[42:43], v[40:41], v[254:255], v[254:255]
	v_pk_fma_f32 v[250:251], v[240:241], v[252:253], 1.0 op_sel_hi:[1,1,0] neg_lo:[1,0,0] neg_hi:[1,0,0]
	v_pk_fma_f32 v[40:41], v[242:243], v[42:43], 1.0 op_sel_hi:[1,1,0] neg_lo:[1,0,0] neg_hi:[1,0,0]
	v_pk_fma_f32 v[252:253], v[250:251], v[248:249], v[252:253]
	v_pk_fma_f32 v[42:43], v[40:41], v[254:255], v[42:43]
	v_div_fixup_f32 v240, v252, v240, 1.0
	v_div_fixup_f32 v241, v253, v241, 1.0
	v_div_fixup_f32 v242, v42, v242, 1.0
	v_div_fixup_f32 v243, v43, v243, 1.0
	v_rcp_f32_e32 v248, v244
	v_rcp_f32_e32 v249, v245
	v_rcp_f32_e32 v254, v246
	v_rcp_f32_e32 v255, v247
	v_pk_fma_f32 v[250:251], v[244:245], v[248:249], 1.0 op_sel_hi:[1,1,0] neg_lo:[1,0,0] neg_hi:[1,0,0]
	v_pk_fma_f32 v[40:41], v[246:247], v[254:255], 1.0 op_sel_hi:[1,1,0] neg_lo:[1,0,0] neg_hi:[1,0,0]
	v_pk_fma_f32 v[248:249], v[250:251], v[248:249], v[248:249]
	v_pk_fma_f32 v[254:255], v[40:41], v[254:255], v[254:255]
	v_pk_fma_f32 v[250:251], v[244:245], v[248:249], 1.0 op_sel_hi:[1,1,0] neg_lo:[1,0,0] neg_hi:[1,0,0]
	v_pk_fma_f32 v[40:41], v[246:247], v[254:255], 1.0 op_sel_hi:[1,1,0] neg_lo:[1,0,0] neg_hi:[1,0,0]
	v_pk_fma_f32 v[252:253], v[250:251], v[248:249], v[248:249]
	v_pk_fma_f32 v[42:43], v[40:41], v[254:255], v[254:255]
	v_pk_fma_f32 v[250:251], v[244:245], v[252:253], 1.0 op_sel_hi:[1,1,0] neg_lo:[1,0,0] neg_hi:[1,0,0]
	v_pk_fma_f32 v[40:41], v[246:247], v[42:43], 1.0 op_sel_hi:[1,1,0] neg_lo:[1,0,0] neg_hi:[1,0,0]
	v_pk_fma_f32 v[252:253], v[250:251], v[248:249], v[252:253]
	v_pk_fma_f32 v[42:43], v[40:41], v[254:255], v[42:43]
	v_div_fixup_f32 v244, v252, v244, 1.0
	v_div_fixup_f32 v245, v253, v245, 1.0
	v_div_fixup_f32 v246, v42, v246, 1.0
	v_div_fixup_f32 v247, v43, v247, 1.0
	v_lshlrev_b32_e32 v52, 16, v44
	v_and_b32_e32 v53, 0xffff0000, v44
	v_lshlrev_b32_e32 v54, 16, v46
	v_and_b32_e32 v55, 0xffff0000, v46
	v_lshlrev_b32_e32 v46, 16, v47
	v_and_b32_e32 v47, 0xffff0000, v47
	v_lshlrev_b32_e32 v44, 16, v45
	v_and_b32_e32 v45, 0xffff0000, v45
	v_pk_fma_f32 v[36:37], v[36:37], v[242:243], v[52:53]
	v_pk_fma_f32 v[40:41], v[34:35], v[246:247], v[46:47]
	v_pk_fma_f32 v[34:35], v[32:33], v[240:241], v[54:55]
	v_cvt_pk_bf16_f32 v32, v36, v37
	v_pk_fma_f32 v[38:39], v[38:39], v[244:245], v[44:45]
	s_nop 0
	v_cvt_pk_bf16_f32 v33, v38, v39
	v_cvt_pk_bf16_f32 v34, v34, v35
	v_cvt_pk_bf16_f32 v35, v40, v41
	buffer_store_dwordx4 v[32:35], v56, s[20:23], 0 offen offset:256 sc1
	s_nop 1
	v_add_u32_e32 v32, 0xa0, v162
	v_mad_i64_i32 v[34:35], s[6:7], v32, s73, 0
	v_lshl_add_u64 v[32:33], v[34:35], 1, s[36:37]
	v_lshl_add_u64 v[32:33], v[32:33], 0, v[148:149]
	v_add_co_u32_e32 v36, vcc, s74, v32
	s_nop 1
	v_addc_co_u32_e32 v37, vcc, 0, v33, vcc
	s_waitcnt vmcnt(7)
; __device__ __forceinline__ float sigmoidf_(float x) { return 1.0f / (1.0f + __expf(-x)); }
; __device__ __forceinline__ u32x4 pack8(const f32x4 v0, const f32x4 v1) { u32x4 w; w.x = pk2(v0[0], v0[1]); w.y = pk2(v0[2], v0[3]); w.z = pk2(v1[0], v1[1]); w.w = pk2(v1[2], v1[3]); return w; }
; __device__ __forceinline__ void unpack8(const u32x4 w, f32x4& v0, f32x4& v1) { v0 = (f32x4){bflo(w.x), bfhi(w.x), bflo(w.y), bfhi(w.y)}; v1 = (f32x4){bflo(w.z), bfhi(w.z), bflo(w.w), bfhi(w.w)}; }
;     __device__ __forceinline__ void operator()(const f32x4 (&acc)[2][2][4][2], const Unit& u, int wr, int wc, int fr, int fq) const {
;     ...
;                 for (int bj = 0; bj < 2; ++bj) {
;                     const u32x4 gw = *(const u32x4*)(rowp + O_GA + bj * 128);
;                     f32x4 g0, g1; unpack8(gw, g0, g1);
;                     f32x4 v0, v1;
; #pragma unroll
;                     for (int j = 0; j < 4; ++j) { v0[j] = sigmoidf_(g0[j]) * acc[ai][bj][m][0][j]; v1[j] = sigmoidf_(g1[j]) * acc[ai][bj][m][1][j]; }
;                     const u32x4 mw = *(const u32x4*)(rowp + bj * 128); f32x4 m0, m1; unpack8(mw, m0, m1); v0 += m0; v1 += m1;
;                     __builtin_amdgcn_raw_buffer_store_b128(pack8(v0, v1), rsrc, (unsigned)(((size_t)row * DIN + col0 + bj * 128) * 2), 0, 16  ); }
	v_mov_b32_e32 v38, v204
	v_mov_b32_e32 v39, v205
	v_mov_b32_e32 v40, v206
	v_mov_b32_e32 v41, v207
	v_mov_b32_e32 v42, v208
	v_mov_b32_e32 v43, v209
	v_mov_b32_e32 v44, v210
	v_mov_b32_e32 v45, v211
	v_add_u32_e32 v202, 0x177300, v201
	global_load_dwordx4 v[204:207], v202, s[36:37]
	v_add_u32_e32 v202, 0x176100, v201
	global_load_dwordx4 v[208:211], v202, s[36:37]
	s_mov_b32 s100, 0xbfb8aa3b
	v_lshlrev_b32_e32 v240, 16, v38
	v_and_b32_e32 v241, 0xffff0000, v38
	v_lshlrev_b32_e32 v242, 16, v40
	v_and_b32_e32 v243, 0xffff0000, v40
	v_lshlrev_b32_e32 v244, 16, v39
	v_and_b32_e32 v245, 0xffff0000, v39
	v_lshlrev_b32_e32 v246, 16, v41
	v_and_b32_e32 v247, 0xffff0000, v41
	v_pk_mul_f32 v[240:241], v[240:241], s[100:101] op_sel_hi:[1,0]
	v_pk_mul_f32 v[242:243], v[242:243], s[100:101] op_sel_hi:[1,0]
	v_pk_mul_f32 v[244:245], v[244:245], s[100:101] op_sel_hi:[1,0]
	v_pk_mul_f32 v[246:247], v[246:247], s[100:101] op_sel_hi:[1,0]
	v_exp_f32_e32 v240, v240
	v_exp_f32_e32 v241, v241
	v_exp_f32_e32 v242, v242
	v_exp_f32_e32 v243, v243
	v_exp_f32_e32 v244, v244
	v_exp_f32_e32 v245, v245
	v_exp_f32_e32 v246, v246
	v_exp_f32_e32 v247, v247
	s_nop 0
	v_pk_add_f32 v[240:241], v[240:241], 1.0 op_sel_hi:[1,0]
	v_pk_add_f32 v[242:243], v[242:243], 1.0 op_sel_hi:[1,0]
	v_pk_add_f32 v[244:245], v[244:245], 1.0 op_sel_hi:[1,0]
	v_pk_add_f32 v[246:247], v[246:247], 1.0 op_sel_hi:[1,0]
	v_rcp_f32_e32 v248, v240
	v_rcp_f32_e32 v249, v241
	v_rcp_f32_e32 v254, v242
	v_rcp_f32_e32 v255, v243
	v_pk_fma_f32 v[250:251], v[240:241], v[248:249], 1.0 op_sel_hi:[1,1,0] neg_lo:[1,0,0] neg_hi:[1,0,0]
	v_pk_fma_f32 v[38:39], v[242:243], v[254:255], 1.0 op_sel_hi:[1,1,0] neg_lo:[1,0,0] neg_hi:[1,0,0]
	v_pk_fma_f32 v[248:249], v[250:251], v[248:249], v[248:249]
	v_pk_fma_f32 v[254:255], v[38:39], v[254:255], v[254:255]
	v_pk_fma_f32 v[250:251], v[240:241], v[248:249], 1.0 op_sel_hi:[1,1,0] neg_lo:[1,0,0] neg_hi:[1,0,0]
	v_pk_fma_f32 v[38:39], v[242:243], v[254:255], 1.0 op_sel_hi:[1,1,0] neg_lo:[1,0,0] neg_hi:[1,0,0]
	v_pk_fma_f32 v[252:253], v[250:251], v[248:249], v[248:249]
	v_pk_fma_f32 v[40:41], v[38:39], v[254:255], v[254:255]
	v_pk_fma_f32 v[250:251], v[240:241], v[252:253], 1.0 op_sel_hi:[1,1,0] neg_lo:[1,0,0] neg_hi:[1,0,0]
	v_pk_fma_f32 v[38:39], v[242:243], v[40:41], 1.0 op_sel_hi:[1,1,0] neg_lo:[1,0,0] neg_hi:[1,0,0]
	v_pk_fma_f32 v[252:253], v[250:251], v[248:249], v[252:253]
	v_pk_fma_f32 v[40:41], v[38:39], v[254:255], v[40:41]
	v_div_fixup_f32 v240, v252, v240, 1.0
	v_div_fixup_f32 v241, v253, v241, 1.0
	v_div_fixup_f32 v242, v40, v242, 1.0
	v_div_fixup_f32 v243, v41, v243, 1.0
	v_rcp_f32_e32 v248, v244
	v_rcp_f32_e32 v249, v245
	v_rcp_f32_e32 v254, v246
	v_rcp_f32_e32 v255, v247
	v_pk_fma_f32 v[250:251], v[244:245], v[248:249], 1.0 op_sel_hi:[1,1,0] neg_lo:[1,0,0] neg_hi:[1,0,0]
	v_pk_fma_f32 v[38:39], v[246:247], v[254:255], 1.0 op_sel_hi:[1,1,0] neg_lo:[1,0,0] neg_hi:[1,0,0]
	v_pk_fma_f32 v[248:249], v[250:251], v[248:249], v[248:249]
	v_pk_fma_f32 v[254:255], v[38:39], v[254:255], v[254:255]
	v_pk_fma_f32 v[250:251], v[244:245], v[248:249], 1.0 op_sel_hi:[1,1,0] neg_lo:[1,0,0] neg_hi:[1,0,0]
	v_pk_fma_f32 v[38:39], v[246:247], v[254:255], 1.0 op_sel_hi:[1,1,0] neg_lo:[1,0,0] neg_hi:[1,0,0]
	v_pk_fma_f32 v[252:253], v[250:251], v[248:249], v[248:249]
	v_pk_fma_f32 v[40:41], v[38:39], v[254:255], v[254:255]
	v_pk_fma_f32 v[250:251], v[244:245], v[252:253], 1.0 op_sel_hi:[1,1,0] neg_lo:[1,0,0] neg_hi:[1,0,0]
	v_pk_fma_f32 v[38:39], v[246:247], v[40:41], 1.0 op_sel_hi:[1,1,0] neg_lo:[1,0,0] neg_hi:[1,0,0]
	v_pk_fma_f32 v[252:253], v[250:251], v[248:249], v[252:253]
	v_pk_fma_f32 v[40:41], v[38:39], v[254:255], v[40:41]
	v_div_fixup_f32 v244, v252, v244, 1.0
	v_div_fixup_f32 v245, v253, v245, 1.0
	v_div_fixup_f32 v246, v40, v246, 1.0
	v_div_fixup_f32 v247, v41, v247, 1.0
	v_lshlrev_b32_e32 v50, 16, v42
	v_and_b32_e32 v51, 0xffff0000, v42
	v_lshlrev_b32_e32 v52, 16, v44
	v_and_b32_e32 v53, 0xffff0000, v44
	v_lshlrev_b32_e32 v44, 16, v45
	v_and_b32_e32 v45, 0xffff0000, v45
	v_lshlrev_b32_e32 v42, 16, v43
	v_and_b32_e32 v43, 0xffff0000, v43
	v_pk_fma_f32 v[28:29], v[28:29], v[240:241], v[50:51]
	v_pk_fma_f32 v[38:39], v[26:27], v[246:247], v[44:45]
	v_pk_fma_f32 v[26:27], v[24:25], v[242:243], v[52:53]
	v_add_lshl_u32 v40, v146, v34, 1
	v_pk_fma_f32 v[30:31], v[30:31], v[244:245], v[42:43]
	v_cvt_pk_bf16_f32 v24, v28, v29
	s_nop 0
	v_cvt_pk_bf16_f32 v25, v30, v31
	v_cvt_pk_bf16_f32 v26, v26, v27
	v_cvt_pk_bf16_f32 v27, v38, v39
	buffer_store_dwordx4 v[24:27], v40, s[20:23], 0 offen sc1
	s_nop 0
	s_waitcnt vmcnt(7)
; __device__ __forceinline__ float sigmoidf_(float x) { return 1.0f / (1.0f + __expf(-x)); }
; __device__ __forceinline__ u32x4 pack8(const f32x4 v0, const f32x4 v1) { u32x4 w; w.x = pk2(v0[0], v0[1]); w.y = pk2(v0[2], v0[3]); w.z = pk2(v1[0], v1[1]); w.w = pk2(v1[2], v1[3]); return w; }
; __device__ __forceinline__ void unpack8(const u32x4 w, f32x4& v0, f32x4& v1) { v0 = (f32x4){bflo(w.x), bfhi(w.x), bflo(w.y), bfhi(w.y)}; v1 = (f32x4){bflo(w.z), bfhi(w.z), bflo(w.w), bfhi(w.w)}; }
;     __device__ __forceinline__ void operator()(const f32x4 (&acc)[2][2][4][2], const Unit& u, int wr, int wc, int fr, int fq) const {
;     ...
;                 const int row = row0 + ai * 128 + m * 16;
;                 const bf16_t* rowp = z + (size_t)row * DIN + col0;
; #pragma unroll
;                 for (int bj = 0; bj < 2; ++bj) {
;                     const u32x4 gw = *(const u32x4*)(rowp + O_GA + bj * 128);
;                     f32x4 g0, g1; unpack8(gw, g0, g1);
;                     f32x4 v0, v1;
; #pragma unroll
;                     for (int j = 0; j < 4; ++j) { v0[j] = sigmoidf_(g0[j]) * acc[ai][bj][m][0][j]; v1[j] = sigmoidf_(g1[j]) * acc[ai][bj][m][1][j]; }
;                     const u32x4 mw = *(const u32x4*)(rowp + bj * 128); f32x4 m0, m1; unpack8(mw, m0, m1); v0 += m0; v1 += m1;
;                     __builtin_amdgcn_raw_buffer_store_b128(pack8(v0, v1), rsrc, (unsigned)(((size_t)row * DIN + col0 + bj * 128) * 2), 0, 16  ); }
	v_mov_b32_e32 v24, v212
	v_mov_b32_e32 v25, v213
	v_mov_b32_e32 v26, v214
	v_mov_b32_e32 v27, v215
	v_mov_b32_e32 v28, v216
	v_mov_b32_e32 v29, v217
	v_mov_b32_e32 v30, v218
	v_mov_b32_e32 v31, v219
	s_mov_b32 s100, 0xbfb8aa3b
	v_lshlrev_b32_e32 v240, 16, v26
	v_and_b32_e32 v241, 0xffff0000, v26
	v_lshlrev_b32_e32 v242, 16, v24
	v_and_b32_e32 v243, 0xffff0000, v24
	v_lshlrev_b32_e32 v244, 16, v25
	v_and_b32_e32 v245, 0xffff0000, v25
	v_lshlrev_b32_e32 v246, 16, v27
	v_and_b32_e32 v247, 0xffff0000, v27
	v_pk_mul_f32 v[240:241], v[240:241], s[100:101] op_sel_hi:[1,0]
	v_pk_mul_f32 v[242:243], v[242:243], s[100:101] op_sel_hi:[1,0]
	v_pk_mul_f32 v[244:245], v[244:245], s[100:101] op_sel_hi:[1,0]
	v_pk_mul_f32 v[246:247], v[246:247], s[100:101] op_sel_hi:[1,0]
	v_exp_f32_e32 v240, v240
	v_exp_f32_e32 v241, v241
	v_exp_f32_e32 v242, v242
	v_exp_f32_e32 v243, v243
	v_exp_f32_e32 v244, v244
	v_exp_f32_e32 v245, v245
	v_exp_f32_e32 v246, v246
	v_exp_f32_e32 v247, v247
	s_nop 0
	v_pk_add_f32 v[240:241], v[240:241], 1.0 op_sel_hi:[1,0]
	v_pk_add_f32 v[242:243], v[242:243], 1.0 op_sel_hi:[1,0]
	v_pk_add_f32 v[244:245], v[244:245], 1.0 op_sel_hi:[1,0]
	v_pk_add_f32 v[246:247], v[246:247], 1.0 op_sel_hi:[1,0]
	v_rcp_f32_e32 v248, v240
	v_rcp_f32_e32 v249, v241
	v_rcp_f32_e32 v254, v242
	v_rcp_f32_e32 v255, v243
	v_pk_fma_f32 v[250:251], v[240:241], v[248:249], 1.0 op_sel_hi:[1,1,0] neg_lo:[1,0,0] neg_hi:[1,0,0]
	v_pk_fma_f32 v[24:25], v[242:243], v[254:255], 1.0 op_sel_hi:[1,1,0] neg_lo:[1,0,0] neg_hi:[1,0,0]
	v_pk_fma_f32 v[248:249], v[250:251], v[248:249], v[248:249]
	v_pk_fma_f32 v[254:255], v[24:25], v[254:255], v[254:255]
	v_pk_fma_f32 v[250:251], v[240:241], v[248:249], 1.0 op_sel_hi:[1,1,0] neg_lo:[1,0,0] neg_hi:[1,0,0]
	v_pk_fma_f32 v[24:25], v[242:243], v[254:255], 1.0 op_sel_hi:[1,1,0] neg_lo:[1,0,0] neg_hi:[1,0,0]
	v_pk_fma_f32 v[252:253], v[250:251], v[248:249], v[248:249]
	v_pk_fma_f32 v[26:27], v[24:25], v[254:255], v[254:255]
	v_pk_fma_f32 v[250:251], v[240:241], v[252:253], 1.0 op_sel_hi:[1,1,0] neg_lo:[1,0,0] neg_hi:[1,0,0]
	v_pk_fma_f32 v[24:25], v[242:243], v[26:27], 1.0 op_sel_hi:[1,1,0] neg_lo:[1,0,0] neg_hi:[1,0,0]
	v_pk_fma_f32 v[252:253], v[250:251], v[248:249], v[252:253]
	v_pk_fma_f32 v[26:27], v[24:25], v[254:255], v[26:27]
	v_div_fixup_f32 v240, v252, v240, 1.0
	v_div_fixup_f32 v241, v253, v241, 1.0
	v_div_fixup_f32 v242, v26, v242, 1.0
	v_div_fixup_f32 v243, v27, v243, 1.0
	v_rcp_f32_e32 v248, v244
	v_rcp_f32_e32 v249, v245
	v_rcp_f32_e32 v254, v246
	v_rcp_f32_e32 v255, v247
	v_pk_fma_f32 v[250:251], v[244:245], v[248:249], 1.0 op_sel_hi:[1,1,0] neg_lo:[1,0,0] neg_hi:[1,0,0]
	v_pk_fma_f32 v[24:25], v[246:247], v[254:255], 1.0 op_sel_hi:[1,1,0] neg_lo:[1,0,0] neg_hi:[1,0,0]
	v_pk_fma_f32 v[248:249], v[250:251], v[248:249], v[248:249]
	v_pk_fma_f32 v[254:255], v[24:25], v[254:255], v[254:255]
	v_pk_fma_f32 v[250:251], v[244:245], v[248:249], 1.0 op_sel_hi:[1,1,0] neg_lo:[1,0,0] neg_hi:[1,0,0]
	v_pk_fma_f32 v[24:25], v[246:247], v[254:255], 1.0 op_sel_hi:[1,1,0] neg_lo:[1,0,0] neg_hi:[1,0,0]
	v_pk_fma_f32 v[252:253], v[250:251], v[248:249], v[248:249]
	v_pk_fma_f32 v[26:27], v[24:25], v[254:255], v[254:255]
	v_pk_fma_f32 v[250:251], v[244:245], v[252:253], 1.0 op_sel_hi:[1,1,0] neg_lo:[1,0,0] neg_hi:[1,0,0]
	v_pk_fma_f32 v[24:25], v[246:247], v[26:27], 1.0 op_sel_hi:[1,1,0] neg_lo:[1,0,0] neg_hi:[1,0,0]
	v_pk_fma_f32 v[252:253], v[250:251], v[248:249], v[252:253]
	v_pk_fma_f32 v[26:27], v[24:25], v[254:255], v[26:27]
	v_div_fixup_f32 v244, v252, v244, 1.0
	v_div_fixup_f32 v245, v253, v245, 1.0
	v_div_fixup_f32 v246, v26, v246, 1.0
	v_div_fixup_f32 v247, v27, v247, 1.0
	v_lshlrev_b32_e32 v36, 16, v28
	v_and_b32_e32 v37, 0xffff0000, v28
	v_lshlrev_b32_e32 v38, 16, v30
	v_and_b32_e32 v39, 0xffff0000, v30
	v_lshlrev_b32_e32 v30, 16, v31
	v_and_b32_e32 v31, 0xffff0000, v31
	v_lshlrev_b32_e32 v28, 16, v29
	v_and_b32_e32 v29, 0xffff0000, v29
	v_pk_fma_f32 v[20:21], v[20:21], v[242:243], v[36:37]
	v_pk_fma_f32 v[24:25], v[18:19], v[246:247], v[30:31]
	v_pk_fma_f32 v[18:19], v[16:17], v[240:241], v[38:39]
	v_cvt_pk_bf16_f32 v16, v20, v21
	v_pk_fma_f32 v[22:23], v[22:23], v[244:245], v[28:29]
	s_nop 0
	v_cvt_pk_bf16_f32 v17, v22, v23
	v_cvt_pk_bf16_f32 v18, v18, v19
	v_cvt_pk_bf16_f32 v19, v24, v25
	buffer_store_dwordx4 v[16:19], v40, s[20:23], 0 offen offset:256 sc1
	s_nop 1
	v_add_u32_e32 v16, 0xb0, v162
	v_mad_i64_i32 v[18:19], s[6:7], v16, s73, 0
	v_lshl_add_u64 v[16:17], v[18:19], 1, s[36:37]
	v_lshl_add_u64 v[16:17], v[16:17], 0, v[148:149]
	v_add_co_u32_e32 v20, vcc, s74, v16
	s_nop 1
	v_addc_co_u32_e32 v21, vcc, 0, v17, vcc
	s_waitcnt vmcnt(5)
; __device__ __forceinline__ float sigmoidf_(float x) { return 1.0f / (1.0f + __expf(-x)); }
; __device__ __forceinline__ u32x4 pack8(const f32x4 v0, const f32x4 v1) { u32x4 w; w.x = pk2(v0[0], v0[1]); w.y = pk2(v0[2], v0[3]); w.z = pk2(v1[0], v1[1]); w.w = pk2(v1[2], v1[3]); return w; }
; __device__ __forceinline__ void unpack8(const u32x4 w, f32x4& v0, f32x4& v1) { v0 = (f32x4){bflo(w.x), bfhi(w.x), bflo(w.y), bfhi(w.y)}; v1 = (f32x4){bflo(w.z), bfhi(w.z), bflo(w.w), bfhi(w.w)}; }
;     __device__ __forceinline__ void operator()(const f32x4 (&acc)[2][2][4][2], const Unit& u, int wr, int wc, int fr, int fq) const {
;     ...
;                 for (int bj = 0; bj < 2; ++bj) {
;                     const u32x4 gw = *(const u32x4*)(rowp + O_GA + bj * 128);
;                     f32x4 g0, g1; unpack8(gw, g0, g1);
;                     f32x4 v0, v1;
; #pragma unroll
;                     for (int j = 0; j < 4; ++j) { v0[j] = sigmoidf_(g0[j]) * acc[ai][bj][m][0][j]; v1[j] = sigmoidf_(g1[j]) * acc[ai][bj][m][1][j]; }
;                     const u32x4 mw = *(const u32x4*)(rowp + bj * 128); f32x4 m0, m1; unpack8(mw, m0, m1); v0 += m0; v1 += m1;
;                     __builtin_amdgcn_raw_buffer_store_b128(pack8(v0, v1), rsrc, (unsigned)(((size_t)row * DIN + col0 + bj * 128) * 2), 0, 16  ); }
	v_mov_b32_e32 v22, v232
	v_mov_b32_e32 v23, v233
	v_mov_b32_e32 v24, v234
	v_mov_b32_e32 v25, v235
	v_mov_b32_e32 v26, v236
	v_mov_b32_e32 v27, v237
	v_mov_b32_e32 v28, v238
	v_mov_b32_e32 v29, v239
	s_mov_b32 s100, 0xbfb8aa3b
	v_lshlrev_b32_e32 v240, 16, v22
	v_and_b32_e32 v241, 0xffff0000, v22
	v_lshlrev_b32_e32 v242, 16, v24
	v_and_b32_e32 v243, 0xffff0000, v24
	v_lshlrev_b32_e32 v244, 16, v23
	v_and_b32_e32 v245, 0xffff0000, v23
	v_lshlrev_b32_e32 v246, 16, v25
	v_and_b32_e32 v247, 0xffff0000, v25
	v_pk_mul_f32 v[240:241], v[240:241], s[100:101] op_sel_hi:[1,0]
	v_pk_mul_f32 v[242:243], v[242:243], s[100:101] op_sel_hi:[1,0]
	v_pk_mul_f32 v[244:245], v[244:245], s[100:101] op_sel_hi:[1,0]
	v_pk_mul_f32 v[246:247], v[246:247], s[100:101] op_sel_hi:[1,0]
	v_exp_f32_e32 v240, v240
	v_exp_f32_e32 v241, v241
	v_exp_f32_e32 v242, v242
	v_exp_f32_e32 v243, v243
	v_exp_f32_e32 v244, v244
	v_exp_f32_e32 v245, v245
	v_exp_f32_e32 v246, v246
	v_exp_f32_e32 v247, v247
	s_nop 0
	v_pk_add_f32 v[240:241], v[240:241], 1.0 op_sel_hi:[1,0]
	v_pk_add_f32 v[242:243], v[242:243], 1.0 op_sel_hi:[1,0]
	v_pk_add_f32 v[244:245], v[244:245], 1.0 op_sel_hi:[1,0]
	v_pk_add_f32 v[246:247], v[246:247], 1.0 op_sel_hi:[1,0]
	v_rcp_f32_e32 v248, v240
	v_rcp_f32_e32 v249, v241
	v_rcp_f32_e32 v254, v242
	v_rcp_f32_e32 v255, v243
	v_pk_fma_f32 v[250:251], v[240:241], v[248:249], 1.0 op_sel_hi:[1,1,0] neg_lo:[1,0,0] neg_hi:[1,0,0]
	v_pk_fma_f32 v[22:23], v[242:243], v[254:255], 1.0 op_sel_hi:[1,1,0] neg_lo:[1,0,0] neg_hi:[1,0,0]
	v_pk_fma_f32 v[248:249], v[250:251], v[248:249], v[248:249]
	v_pk_fma_f32 v[254:255], v[22:23], v[254:255], v[254:255]
	v_pk_fma_f32 v[250:251], v[240:241], v[248:249], 1.0 op_sel_hi:[1,1,0] neg_lo:[1,0,0] neg_hi:[1,0,0]
	v_pk_fma_f32 v[22:23], v[242:243], v[254:255], 1.0 op_sel_hi:[1,1,0] neg_lo:[1,0,0] neg_hi:[1,0,0]
	v_pk_fma_f32 v[252:253], v[250:251], v[248:249], v[248:249]
	v_pk_fma_f32 v[24:25], v[22:23], v[254:255], v[254:255]
	v_pk_fma_f32 v[250:251], v[240:241], v[252:253], 1.0 op_sel_hi:[1,1,0] neg_lo:[1,0,0] neg_hi:[1,0,0]
	v_pk_fma_f32 v[22:23], v[242:243], v[24:25], 1.0 op_sel_hi:[1,1,0] neg_lo:[1,0,0] neg_hi:[1,0,0]
	v_pk_fma_f32 v[252:253], v[250:251], v[248:249], v[252:253]
	v_pk_fma_f32 v[24:25], v[22:23], v[254:255], v[24:25]
	v_div_fixup_f32 v240, v252, v240, 1.0
	v_div_fixup_f32 v241, v253, v241, 1.0
	v_div_fixup_f32 v242, v24, v242, 1.0
	v_div_fixup_f32 v243, v25, v243, 1.0
	v_rcp_f32_e32 v248, v244
	v_rcp_f32_e32 v249, v245
	v_rcp_f32_e32 v254, v246
	v_rcp_f32_e32 v255, v247
	v_pk_fma_f32 v[250:251], v[244:245], v[248:249], 1.0 op_sel_hi:[1,1,0] neg_lo:[1,0,0] neg_hi:[1,0,0]
	v_pk_fma_f32 v[22:23], v[246:247], v[254:255], 1.0 op_sel_hi:[1,1,0] neg_lo:[1,0,0] neg_hi:[1,0,0]
	v_pk_fma_f32 v[248:249], v[250:251], v[248:249], v[248:249]
	v_pk_fma_f32 v[254:255], v[22:23], v[254:255], v[254:255]
	v_pk_fma_f32 v[250:251], v[244:245], v[248:249], 1.0 op_sel_hi:[1,1,0] neg_lo:[1,0,0] neg_hi:[1,0,0]
	v_pk_fma_f32 v[22:23], v[246:247], v[254:255], 1.0 op_sel_hi:[1,1,0] neg_lo:[1,0,0] neg_hi:[1,0,0]
	v_pk_fma_f32 v[252:253], v[250:251], v[248:249], v[248:249]
	v_pk_fma_f32 v[24:25], v[22:23], v[254:255], v[254:255]
	v_pk_fma_f32 v[250:251], v[244:245], v[252:253], 1.0 op_sel_hi:[1,1,0] neg_lo:[1,0,0] neg_hi:[1,0,0]
	v_pk_fma_f32 v[22:23], v[246:247], v[24:25], 1.0 op_sel_hi:[1,1,0] neg_lo:[1,0,0] neg_hi:[1,0,0]
	v_pk_fma_f32 v[252:253], v[250:251], v[248:249], v[252:253]
	v_pk_fma_f32 v[24:25], v[22:23], v[254:255], v[24:25]
	v_div_fixup_f32 v244, v252, v244, 1.0
	v_div_fixup_f32 v245, v253, v245, 1.0
	v_div_fixup_f32 v246, v24, v246, 1.0
	v_div_fixup_f32 v247, v25, v247, 1.0
	v_lshlrev_b32_e32 v34, 16, v26
	v_and_b32_e32 v35, 0xffff0000, v26
	v_lshlrev_b32_e32 v36, 16, v28
	v_and_b32_e32 v37, 0xffff0000, v28
	v_lshlrev_b32_e32 v28, 16, v29
	v_and_b32_e32 v29, 0xffff0000, v29
	v_lshlrev_b32_e32 v26, 16, v27
	v_and_b32_e32 v27, 0xffff0000, v27
	v_pk_fma_f32 v[12:13], v[12:13], v[240:241], v[34:35]
	v_pk_fma_f32 v[22:23], v[10:11], v[246:247], v[28:29]
	v_pk_fma_f32 v[10:11], v[8:9], v[242:243], v[36:37]
	v_add_lshl_u32 v24, v146, v18, 1
	v_pk_fma_f32 v[14:15], v[14:15], v[244:245], v[26:27]
	v_cvt_pk_bf16_f32 v8, v12, v13
	s_nop 0
	v_cvt_pk_bf16_f32 v9, v14, v15
	v_cvt_pk_bf16_f32 v10, v10, v11
	v_cvt_pk_bf16_f32 v11, v22, v23
	buffer_store_dwordx4 v[8:11], v24, s[20:23], 0 offen sc1
	s_nop 0
	s_waitcnt vmcnt(3)
; __device__ __forceinline__ float sigmoidf_(float x) { return 1.0f / (1.0f + __expf(-x)); }
; __device__ __forceinline__ u32x4 pack8(const f32x4 v0, const f32x4 v1) { u32x4 w; w.x = pk2(v0[0], v0[1]); w.y = pk2(v0[2], v0[3]); w.z = pk2(v1[0], v1[1]); w.w = pk2(v1[2], v1[3]); return w; }
; __device__ __forceinline__ void unpack8(const u32x4 w, f32x4& v0, f32x4& v1) { v0 = (f32x4){bflo(w.x), bfhi(w.x), bflo(w.y), bfhi(w.y)}; v1 = (f32x4){bflo(w.z), bfhi(w.z), bflo(w.w), bfhi(w.w)}; }
;     __device__ __forceinline__ void operator()(const f32x4 (&acc)[2][2][4][2], const Unit& u, int wr, int wc, int fr, int fq) const {
;     ...
;                 for (int bj = 0; bj < 2; ++bj) {
;                     const u32x4 gw = *(const u32x4*)(rowp + O_GA + bj * 128);
;                     f32x4 g0, g1; unpack8(gw, g0, g1);
;                     f32x4 v0, v1;
; #pragma unroll
;                     for (int j = 0; j < 4; ++j) { v0[j] = sigmoidf_(g0[j]) * acc[ai][bj][m][0][j]; v1[j] = sigmoidf_(g1[j]) * acc[ai][bj][m][1][j]; }
;                     const u32x4 mw = *(const u32x4*)(rowp + bj * 128); f32x4 m0, m1; unpack8(mw, m0, m1); v0 += m0; v1 += m1;
;                     __builtin_amdgcn_raw_buffer_store_b128(pack8(v0, v1), rsrc, (unsigned)(((size_t)row * DIN + col0 + bj * 128) * 2), 0, 16  ); }
;             }
;         asm volatile("s_waitcnt vmcnt(0)" ::: "memory");
;         if (fr == 0 && fq == 0) (void)__hip_atomic_fetch_add(ready + 64 * (pm_off + u.pm), 1u, __ATOMIC_RELAXED, __HIP_MEMORY_SCOPE_AGENT);
;     }
	v_mov_b32_e32 v8, v204
	v_mov_b32_e32 v9, v205
	v_mov_b32_e32 v10, v206
	v_mov_b32_e32 v11, v207
	v_mov_b32_e32 v12, v208
	v_mov_b32_e32 v13, v209
	v_mov_b32_e32 v14, v210
	v_mov_b32_e32 v15, v211
	s_mov_b32 s100, 0xbfb8aa3b
	v_lshlrev_b32_e32 v240, 16, v10
	v_and_b32_e32 v241, 0xffff0000, v10
	v_lshlrev_b32_e32 v242, 16, v8
	v_and_b32_e32 v243, 0xffff0000, v8
	v_lshlrev_b32_e32 v244, 16, v9
	v_and_b32_e32 v245, 0xffff0000, v9
	v_lshlrev_b32_e32 v246, 16, v11
	v_and_b32_e32 v247, 0xffff0000, v11
	v_pk_mul_f32 v[240:241], v[240:241], s[100:101] op_sel_hi:[1,0]
	v_pk_mul_f32 v[242:243], v[242:243], s[100:101] op_sel_hi:[1,0]
	v_pk_mul_f32 v[244:245], v[244:245], s[100:101] op_sel_hi:[1,0]
	v_pk_mul_f32 v[246:247], v[246:247], s[100:101] op_sel_hi:[1,0]
	v_exp_f32_e32 v240, v240
	v_exp_f32_e32 v241, v241
	v_exp_f32_e32 v242, v242
	v_exp_f32_e32 v243, v243
	v_exp_f32_e32 v244, v244
	v_exp_f32_e32 v245, v245
	v_exp_f32_e32 v246, v246
	v_exp_f32_e32 v247, v247
	s_nop 0
	v_pk_add_f32 v[240:241], v[240:241], 1.0 op_sel_hi:[1,0]
	v_pk_add_f32 v[242:243], v[242:243], 1.0 op_sel_hi:[1,0]
	v_pk_add_f32 v[244:245], v[244:245], 1.0 op_sel_hi:[1,0]
	v_pk_add_f32 v[246:247], v[246:247], 1.0 op_sel_hi:[1,0]
	v_rcp_f32_e32 v248, v240
	v_rcp_f32_e32 v249, v241
	v_rcp_f32_e32 v254, v242
	v_rcp_f32_e32 v255, v243
	v_pk_fma_f32 v[250:251], v[240:241], v[248:249], 1.0 op_sel_hi:[1,1,0] neg_lo:[1,0,0] neg_hi:[1,0,0]
	v_pk_fma_f32 v[8:9], v[242:243], v[254:255], 1.0 op_sel_hi:[1,1,0] neg_lo:[1,0,0] neg_hi:[1,0,0]
	v_pk_fma_f32 v[248:249], v[250:251], v[248:249], v[248:249]
	v_pk_fma_f32 v[254:255], v[8:9], v[254:255], v[254:255]
	v_pk_fma_f32 v[250:251], v[240:241], v[248:249], 1.0 op_sel_hi:[1,1,0] neg_lo:[1,0,0] neg_hi:[1,0,0]
	v_pk_fma_f32 v[8:9], v[242:243], v[254:255], 1.0 op_sel_hi:[1,1,0] neg_lo:[1,0,0] neg_hi:[1,0,0]
	v_pk_fma_f32 v[252:253], v[250:251], v[248:249], v[248:249]
	v_pk_fma_f32 v[10:11], v[8:9], v[254:255], v[254:255]
	v_pk_fma_f32 v[250:251], v[240:241], v[252:253], 1.0 op_sel_hi:[1,1,0] neg_lo:[1,0,0] neg_hi:[1,0,0]
	v_pk_fma_f32 v[8:9], v[242:243], v[10:11], 1.0 op_sel_hi:[1,1,0] neg_lo:[1,0,0] neg_hi:[1,0,0]
	v_pk_fma_f32 v[252:253], v[250:251], v[248:249], v[252:253]
	v_pk_fma_f32 v[10:11], v[8:9], v[254:255], v[10:11]
	v_div_fixup_f32 v240, v252, v240, 1.0
	v_div_fixup_f32 v241, v253, v241, 1.0
	v_div_fixup_f32 v242, v10, v242, 1.0
	v_div_fixup_f32 v243, v11, v243, 1.0
	v_rcp_f32_e32 v248, v244
	v_rcp_f32_e32 v249, v245
	v_rcp_f32_e32 v254, v246
	v_rcp_f32_e32 v255, v247
	v_pk_fma_f32 v[250:251], v[244:245], v[248:249], 1.0 op_sel_hi:[1,1,0] neg_lo:[1,0,0] neg_hi:[1,0,0]
	v_pk_fma_f32 v[8:9], v[246:247], v[254:255], 1.0 op_sel_hi:[1,1,0] neg_lo:[1,0,0] neg_hi:[1,0,0]
	v_pk_fma_f32 v[248:249], v[250:251], v[248:249], v[248:249]
	v_pk_fma_f32 v[254:255], v[8:9], v[254:255], v[254:255]
	v_pk_fma_f32 v[250:251], v[244:245], v[248:249], 1.0 op_sel_hi:[1,1,0] neg_lo:[1,0,0] neg_hi:[1,0,0]
	v_pk_fma_f32 v[8:9], v[246:247], v[254:255], 1.0 op_sel_hi:[1,1,0] neg_lo:[1,0,0] neg_hi:[1,0,0]
	v_pk_fma_f32 v[252:253], v[250:251], v[248:249], v[248:249]
	v_pk_fma_f32 v[10:11], v[8:9], v[254:255], v[254:255]
	v_pk_fma_f32 v[250:251], v[244:245], v[252:253], 1.0 op_sel_hi:[1,1,0] neg_lo:[1,0,0] neg_hi:[1,0,0]
	v_pk_fma_f32 v[8:9], v[246:247], v[10:11], 1.0 op_sel_hi:[1,1,0] neg_lo:[1,0,0] neg_hi:[1,0,0]
	v_pk_fma_f32 v[252:253], v[250:251], v[248:249], v[252:253]
	v_pk_fma_f32 v[10:11], v[8:9], v[254:255], v[10:11]
	v_div_fixup_f32 v244, v252, v244, 1.0
	v_div_fixup_f32 v245, v253, v245, 1.0
	v_div_fixup_f32 v246, v10, v246, 1.0
	v_div_fixup_f32 v247, v11, v247, 1.0
	v_lshlrev_b32_e32 v20, 16, v12
	v_and_b32_e32 v21, 0xffff0000, v12
	v_lshlrev_b32_e32 v22, 16, v14
	v_and_b32_e32 v23, 0xffff0000, v14
	v_lshlrev_b32_e32 v14, 16, v15
	v_and_b32_e32 v15, 0xffff0000, v15
	v_lshlrev_b32_e32 v12, 16, v13
	v_and_b32_e32 v13, 0xffff0000, v13
	v_pk_fma_f32 v[4:5], v[4:5], v[242:243], v[20:21]
	v_pk_fma_f32 v[8:9], v[2:3], v[246:247], v[14:15]
	v_pk_fma_f32 v[2:3], v[0:1], v[240:241], v[22:23]
	v_pk_fma_f32 v[6:7], v[6:7], v[244:245], v[12:13]
	v_cvt_pk_bf16_f32 v0, v4, v5
	s_nop 0
	v_cvt_pk_bf16_f32 v1, v6, v7
	v_cvt_pk_bf16_f32 v2, v2, v3
	v_cvt_pk_bf16_f32 v3, v8, v9
	buffer_store_dwordx4 v[0:3], v24, s[20:23], 0 offen offset:256 sc1
	s_waitcnt vmcnt(0)
	s_and_saveexec_b64 s[12:13], s[8:9]
	s_cbranch_execz .LBB0_1833
	s_mov_b64 s[14:15], exec
	v_mbcnt_lo_u32_b32 v0, s14, 0
	v_mbcnt_hi_u32_b32 v0, s15, v0
	v_cmp_eq_u32_e32 vcc, 0, v0
	s_and_b64 s[6:7], exec, vcc
	s_mov_b64 exec, s[6:7]
	s_cbranch_execz .LBB0_1833
	s_lshl_b32 s6, s75, 6
	s_ashr_i32 s7, s6, 31
	s_lshl_b64 s[6:7], s[6:7], 2
	s_add_u32 s6, s28, s6
	s_addc_u32 s7, s29, s7
	s_bcnt1_i32_b64 s14, s[14:15]
	v_mov_b32_e32 v0, s14
	global_atomic_add v131, v0, s[6:7]
	s_branch .LBB0_1833

; #define PG8_STAGE(bufoff, gbase, voff) do { _Pragma("unroll") for (int _i = 0; _i < 2; ++_i) \
;         __builtin_amdgcn_global_load_lds((const unsigned*)((const char*)(gbase) + (voff)[_i]), (LAS unsigned*)(lds + (bufoff) + ldsw + _i * 8192), 16, 0, 0); } while (0)
; #define PG8_LDA(dst, b, h) do { _Pragma("unroll") for (int m = 0; m < 4; ++m) _Pragma("unroll") for (int k = 0; k < 2; ++k) dst[m][k] = *(const LAS bf16x8*)(lds + PG8_SA(b, h) + aoff + m * 2048 + k * 1024); } while (0)
; #define PG8_LDB(dst, b, h) do { _Pragma("unroll") for (int n = 0; n < 2; ++n) _Pragma("unroll") for (int k = 0; k < 2; ++k) dst[n][k] = *(const LAS bf16x8*)(lds + PG8_SB(b, h) + boff + n * 2048 + k * 1024); } while (0)
; #define PG8_MMA(ai, bj, At, Bt) do { __builtin_amdgcn_s_setprio(1); _Pragma("unroll") for (int m = 0; m < 4; ++m) _Pragma("unroll") for (int n = 0; n < 2; ++n) _Pragma("unroll") for (int k = 0; k < 2; ++k) \
;         acc[ai][bj][m][n] = __builtin_amdgcn_mfma_f32_16x16x32_bf16(Bt[n][k], At[m][k], acc[ai][bj][m][n], 0, 0, 0); __builtin_amdgcn_s_setprio(0); } while (0)
; #define PG8_WAIT_L(n) asm volatile("s_waitcnt lgkmcnt(" #n ")" ::: "memory")
; #define PG8_BAR __builtin_amdgcn_s_barrier()
; #define PG8_SCHED __builtin_amdgcn_sched_barrier(0)
;     ...
;             PG8_LDB(B0, 0, 0); PG8_SCHED; PG8_LDA(At, 0, 0); PG8_STAGE(PG8_SA(1, 1), a1 + hA, voffA);
;             PG8_WAIT_L(8); PG8_BAR; PG8_WAIT_L(0); PG8_MMA(0, 0, At, B0); PG8_BAR; PG8_SCHED;
;             PG8_LDB(B1, 0, 1); PG8_STAGE(PG8_SB(0, 0), b2, voffB);
;             PG8_BAR; PG8_WAIT_L(0); PG8_MMA(0, 1, At, B1); PG8_BAR;
;             PG8_LDA(At, 0, 1); PG8_STAGE(PG8_SA(0, 0), a2, voffA);
;             PG8_BAR; PG8_WAIT_L(0); PG8_MMA(1, 0, At, B0); PG8_BAR; PG8_SCHED;
.LBB0_1864:
	ds_read_b128 v[140:143], v155
	ds_read_b128 v[146:149], v155 offset:1024
	ds_read_b128 v[158:161], v155 offset:2048
	ds_read_b128 v[162:165], v155 offset:3072
	s_add_u32 s12, s10, 0xfffe0080
	s_addc_u32 s13, s11, -1
	s_cmp_eq_u32 s45, 4
	s_cselect_b32 s15, s7, s13
	s_cselect_b32 s14, s16, s12
	s_cselect_b32 s13, s17, s44
	s_cselect_b32 s12, s33, s37
	v_lshl_add_u64 v[150:151], s[10:11], 0, v[138:139]
	s_add_i32 m0, s62, 0xc000
	ds_read_b128 v[170:173], v156
	ds_read_b128 v[174:177], v156 offset:1024
	ds_read_b128 v[178:181], v156 offset:2048
	ds_read_b128 v[182:185], v156 offset:3072
	ds_read_b128 v[186:189], v156 offset:4096
	ds_read_b128 v[190:193], v156 offset:5120
	ds_read_b128 v[194:197], v156 offset:6144
	ds_read_b128 v[198:201], v156 offset:7168
	global_load_lds_dwordx4 v[150:151], off
	v_lshl_add_u64 v[150:151], s[10:11], 0, v[136:137]
	s_add_i32 m0, s62, 0xe000
	s_nop 0
	global_load_lds_dwordx4 v[150:151], off
	s_waitcnt lgkmcnt(8)
	s_barrier
	s_waitcnt lgkmcnt(0)
	s_setprio 1
	s_waitcnt lgkmcnt(0)
	v_mfma_f32_16x16x32_bf16 v[124:127], v[140:143], v[170:173], v[124:127]
	v_mfma_f32_16x16x32_bf16 v[120:123], v[158:161], v[170:173], v[120:123]
	v_mfma_f32_16x16x32_bf16 v[108:111], v[140:143], v[178:181], v[108:111]
	v_mfma_f32_16x16x32_bf16 v[104:107], v[158:161], v[178:181], v[104:107]
	v_mfma_f32_16x16x32_bf16 v[92:95], v[140:143], v[186:189], v[92:95]
	v_mfma_f32_16x16x32_bf16 v[88:91], v[158:161], v[186:189], v[88:91]
	v_mfma_f32_16x16x32_bf16 v[76:79], v[140:143], v[194:197], v[76:79]
	v_mfma_f32_16x16x32_bf16 v[72:75], v[158:161], v[194:197], v[72:75]
	v_mfma_f32_16x16x32_bf16 v[124:127], v[146:149], v[174:177], v[124:127]
	v_mfma_f32_16x16x32_bf16 v[120:123], v[162:165], v[174:177], v[120:123]
	v_mfma_f32_16x16x32_bf16 v[108:111], v[146:149], v[182:185], v[108:111]
	v_mfma_f32_16x16x32_bf16 v[104:107], v[162:165], v[182:185], v[104:107]
	v_mfma_f32_16x16x32_bf16 v[92:95], v[146:149], v[190:193], v[92:95]
	v_mfma_f32_16x16x32_bf16 v[88:91], v[162:165], v[190:193], v[88:91]
	v_mfma_f32_16x16x32_bf16 v[76:79], v[146:149], v[198:201], v[76:79]
	v_mfma_f32_16x16x32_bf16 v[72:75], v[162:165], v[198:201], v[72:75]
	s_setprio 0
	s_barrier
	s_add_i32 s53, s71, s61
	v_lshl_add_u64 v[150:151], s[12:13], 0, v[130:131]
	s_mov_b32 m0, s53
	ds_read_b128 v[202:205], v157
	ds_read_b128 v[206:209], v157 offset:1024
	ds_read_b128 v[210:213], v157 offset:2048
	ds_read_b128 v[214:217], v157 offset:3072
	global_load_lds_dwordx4 v[150:151], off
	v_lshl_add_u64 v[218:219], s[12:13], 0, v[134:135]
	s_add_i32 m0, s53, 0x2000
	s_nop 0
	global_load_lds_dwordx4 v[218:219], off
	s_barrier
	s_waitcnt lgkmcnt(0)
	s_setprio 1
	s_waitcnt lgkmcnt(0)
	v_mfma_f32_16x16x32_bf16 v[116:119], v[202:205], v[170:173], v[116:119]
	v_mfma_f32_16x16x32_bf16 v[112:115], v[210:213], v[170:173], v[112:115]
	v_mfma_f32_16x16x32_bf16 v[100:103], v[202:205], v[178:181], v[100:103]
	v_mfma_f32_16x16x32_bf16 v[96:99], v[210:213], v[178:181], v[96:99]
	v_mfma_f32_16x16x32_bf16 v[84:87], v[202:205], v[186:189], v[84:87]
	v_mfma_f32_16x16x32_bf16 v[80:83], v[210:213], v[186:189], v[80:83]
	v_mfma_f32_16x16x32_bf16 v[68:71], v[202:205], v[194:197], v[68:71]
	v_mfma_f32_16x16x32_bf16 v[64:67], v[210:213], v[194:197], v[64:67]
	v_mfma_f32_16x16x32_bf16 v[116:119], v[206:209], v[174:177], v[116:119]
	v_mfma_f32_16x16x32_bf16 v[112:115], v[214:217], v[174:177], v[112:115]
	v_mfma_f32_16x16x32_bf16 v[100:103], v[206:209], v[182:185], v[100:103]
	v_mfma_f32_16x16x32_bf16 v[96:99], v[214:217], v[182:185], v[96:99]
	v_mfma_f32_16x16x32_bf16 v[84:87], v[206:209], v[190:193], v[84:87]
	v_mfma_f32_16x16x32_bf16 v[80:83], v[214:217], v[190:193], v[80:83]
	v_mfma_f32_16x16x32_bf16 v[68:71], v[206:209], v[198:201], v[68:71]
	v_mfma_f32_16x16x32_bf16 v[64:67], v[214:217], v[198:201], v[64:67]
	s_setprio 0
	s_mov_b32 m0, s62
	v_lshl_add_u64 v[220:221], s[14:15], 0, v[128:129]
	s_barrier
	ds_read_b128 v[170:173], v156 offset:16384
	ds_read_b128 v[174:177], v156 offset:17408
	ds_read_b128 v[178:181], v156 offset:18432
	ds_read_b128 v[182:185], v156 offset:19456
	ds_read_b128 v[186:189], v156 offset:20480
	ds_read_b128 v[190:193], v156 offset:21504
	ds_read_b128 v[194:197], v156 offset:22528
	ds_read_b128 v[198:201], v156 offset:23552
	global_load_lds_dwordx4 v[220:221], off
	v_lshl_add_u64 v[222:223], s[14:15], 0, v[132:133]
	s_mov_b32 m0, s63
	s_nop 0
	global_load_lds_dwordx4 v[222:223], off
	s_barrier
	s_waitcnt lgkmcnt(0)
	s_setprio 1
	s_waitcnt lgkmcnt(0)
	v_mfma_f32_16x16x32_bf16 v[60:63], v[140:143], v[170:173], v[60:63]
	v_mfma_f32_16x16x32_bf16 v[56:59], v[158:161], v[170:173], v[56:59]
	v_mfma_f32_16x16x32_bf16 v[44:47], v[140:143], v[178:181], v[44:47]
	v_mfma_f32_16x16x32_bf16 v[40:43], v[158:161], v[178:181], v[40:43]
	v_mfma_f32_16x16x32_bf16 v[28:31], v[140:143], v[186:189], v[28:31]
	v_mfma_f32_16x16x32_bf16 v[24:27], v[158:161], v[186:189], v[24:27]
	v_mfma_f32_16x16x32_bf16 v[12:15], v[140:143], v[194:197], v[12:15]
	v_mfma_f32_16x16x32_bf16 v[8:11], v[158:161], v[194:197], v[8:11]
	v_mfma_f32_16x16x32_bf16 v[60:63], v[146:149], v[174:177], v[60:63]
	v_mfma_f32_16x16x32_bf16 v[56:59], v[162:165], v[174:177], v[56:59]
	v_mfma_f32_16x16x32_bf16 v[44:47], v[146:149], v[182:185], v[44:47]
	v_mfma_f32_16x16x32_bf16 v[40:43], v[162:165], v[182:185], v[40:43]
	v_mfma_f32_16x16x32_bf16 v[28:31], v[146:149], v[190:193], v[28:31]
	v_mfma_f32_16x16x32_bf16 v[24:27], v[162:165], v[190:193], v[24:27]
	v_mfma_f32_16x16x32_bf16 v[12:15], v[146:149], v[198:201], v[12:15]
	v_mfma_f32_16x16x32_bf16 v[8:11], v[162:165], v[198:201], v[8:11]
	s_setprio 0
	s_barrier
; #define PG8_STAGE(bufoff, gbase, voff) do { _Pragma("unroll") for (int _i = 0; _i < 2; ++_i) \
;         __builtin_amdgcn_global_load_lds((const unsigned*)((const char*)(gbase) + (voff)[_i]), (LAS unsigned*)(lds + (bufoff) + ldsw + _i * 8192), 16, 0, 0); } while (0)
; #define PG8_LDA(dst, b, h) do { _Pragma("unroll") for (int m = 0; m < 4; ++m) _Pragma("unroll") for (int k = 0; k < 2; ++k) dst[m][k] = *(const LAS bf16x8*)(lds + PG8_SA(b, h) + aoff + m * 2048 + k * 1024); } while (0)
; #define PG8_LDB(dst, b, h) do { _Pragma("unroll") for (int n = 0; n < 2; ++n) _Pragma("unroll") for (int k = 0; k < 2; ++k) dst[n][k] = *(const LAS bf16x8*)(lds + PG8_SB(b, h) + boff + n * 2048 + k * 1024); } while (0)
; #define PG8_MMA(ai, bj, At, Bt) do { __builtin_amdgcn_s_setprio(1); _Pragma("unroll") for (int m = 0; m < 4; ++m) _Pragma("unroll") for (int n = 0; n < 2; ++n) _Pragma("unroll") for (int k = 0; k < 2; ++k) \
;         acc[ai][bj][m][n] = __builtin_amdgcn_mfma_f32_16x16x32_bf16(Bt[n][k], At[m][k], acc[ai][bj][m][n], 0, 0, 0); __builtin_amdgcn_s_setprio(0); } while (0)
; #define PG8_WAIT_V(n) asm volatile("s_waitcnt vmcnt(" #n ")" ::: "memory")
; #define PG8_WAIT_L(n) asm volatile("s_waitcnt lgkmcnt(" #n ")" ::: "memory")
; #define PG8_BAR __builtin_amdgcn_s_barrier()
; #define PG8_SCHED __builtin_amdgcn_sched_barrier(0)
;     ...
;             PG8_STAGE(PG8_SB(0, 1), b2 + hB, voffB);
;             PG8_WAIT_V(6); PG8_BAR; PG8_MMA(1, 1, At, B1); PG8_BAR;
;             PG8_LDB(B0, 1, 0); PG8_SCHED; PG8_LDA(At, 1, 0); PG8_STAGE(PG8_SA(0, 1), a2 + hA, voffA);
;             PG8_WAIT_L(8); PG8_BAR; PG8_WAIT_L(0); PG8_MMA(0, 0, At, B0); PG8_BAR; PG8_SCHED;
;             PG8_LDB(B1, 1, 1); PG8_STAGE(PG8_SB(1, 0), b3, voffB);
;             PG8_BAR; PG8_WAIT_L(0); PG8_MMA(0, 1, At, B1); PG8_BAR;
;             PG8_LDA(At, 1, 1); PG8_STAGE(PG8_SA(1, 0), a3, voffA);
	s_add_u32 s76, s12, 0x20000
	s_addc_u32 s77, s13, 0
	s_add_i32 s53, s72, s61
	v_lshl_add_u64 v[140:141], s[76:77], 0, v[130:131]
	s_mov_b32 m0, s53
	s_nop 0
	global_load_lds_dwordx4 v[140:141], off
	v_lshl_add_u64 v[140:141], s[76:77], 0, v[134:135]
	s_add_i32 m0, s53, 0x2000
	s_nop 0
	global_load_lds_dwordx4 v[140:141], off
	s_waitcnt vmcnt(6)
	s_barrier
	s_setprio 1
	v_mfma_f32_16x16x32_bf16 v[52:55], v[202:205], v[170:173], v[52:55]
	v_mfma_f32_16x16x32_bf16 v[48:51], v[210:213], v[170:173], v[48:51]
	v_mfma_f32_16x16x32_bf16 v[36:39], v[202:205], v[178:181], v[36:39]
	v_mfma_f32_16x16x32_bf16 v[32:35], v[210:213], v[178:181], v[32:35]
	v_mfma_f32_16x16x32_bf16 v[20:23], v[202:205], v[186:189], v[20:23]
	v_mfma_f32_16x16x32_bf16 v[16:19], v[210:213], v[186:189], v[16:19]
	v_mfma_f32_16x16x32_bf16 v[4:7], v[202:205], v[194:197], v[4:7]
	v_mfma_f32_16x16x32_bf16 v[0:3], v[210:213], v[194:197], v[0:3]
	v_mfma_f32_16x16x32_bf16 v[52:55], v[206:209], v[174:177], v[52:55]
	v_mfma_f32_16x16x32_bf16 v[48:51], v[214:217], v[174:177], v[48:51]
	v_mfma_f32_16x16x32_bf16 v[36:39], v[206:209], v[182:185], v[36:39]
	v_mfma_f32_16x16x32_bf16 v[32:35], v[214:217], v[182:185], v[32:35]
	v_mfma_f32_16x16x32_bf16 v[20:23], v[206:209], v[190:193], v[20:23]
	v_mfma_f32_16x16x32_bf16 v[16:19], v[214:217], v[190:193], v[16:19]
	v_mfma_f32_16x16x32_bf16 v[4:7], v[206:209], v[198:201], v[4:7]
	v_mfma_f32_16x16x32_bf16 v[0:3], v[214:217], v[198:201], v[0:3]
	s_setprio 0
	s_add_i32 s53, 0, 0x18000
	v_add_u32_e32 v162, s53, v153
	s_barrier
	ds_read_b128 v[140:143], v162
	ds_read_b128 v[146:149], v162 offset:1024
	ds_read_b128 v[158:161], v162 offset:2048
	ds_read_b128 v[162:165], v162 offset:3072
	s_add_u32 s14, s14, 0x20000
	s_addc_u32 s15, s15, 0
	s_mov_b32 m0, s64
	v_lshl_add_u64 v[202:203], s[14:15], 0, v[128:129]
	ds_read_b128 v[170:173], v156 offset:32768
	ds_read_b128 v[174:177], v156 offset:33792
	ds_read_b128 v[178:181], v156 offset:34816
	ds_read_b128 v[182:185], v156 offset:35840
	ds_read_b128 v[186:189], v156 offset:36864
	ds_read_b128 v[190:193], v156 offset:37888
	ds_read_b128 v[194:197], v156 offset:38912
	ds_read_b128 v[198:201], v156 offset:39936
	global_load_lds_dwordx4 v[202:203], off
	v_lshl_add_u64 v[202:203], s[14:15], 0, v[132:133]
	s_mov_b32 m0, s65
	s_nop 0
	global_load_lds_dwordx4 v[202:203], off
	s_waitcnt lgkmcnt(8)
	s_barrier
	s_waitcnt lgkmcnt(0)
	s_setprio 1
	s_waitcnt lgkmcnt(0)
	v_mfma_f32_16x16x32_bf16 v[124:127], v[140:143], v[170:173], v[124:127]
	v_mfma_f32_16x16x32_bf16 v[120:123], v[158:161], v[170:173], v[120:123]
	v_mfma_f32_16x16x32_bf16 v[108:111], v[140:143], v[178:181], v[108:111]
	v_mfma_f32_16x16x32_bf16 v[104:107], v[158:161], v[178:181], v[104:107]
	v_mfma_f32_16x16x32_bf16 v[92:95], v[140:143], v[186:189], v[92:95]
	v_mfma_f32_16x16x32_bf16 v[88:91], v[158:161], v[186:189], v[88:91]
	v_mfma_f32_16x16x32_bf16 v[76:79], v[140:143], v[194:197], v[76:79]
	v_mfma_f32_16x16x32_bf16 v[72:75], v[158:161], v[194:197], v[72:75]
	v_mfma_f32_16x16x32_bf16 v[124:127], v[146:149], v[174:177], v[124:127]
	v_mfma_f32_16x16x32_bf16 v[120:123], v[162:165], v[174:177], v[120:123]
	v_mfma_f32_16x16x32_bf16 v[108:111], v[146:149], v[182:185], v[108:111]
	v_mfma_f32_16x16x32_bf16 v[104:107], v[162:165], v[182:185], v[104:107]
	v_mfma_f32_16x16x32_bf16 v[92:95], v[146:149], v[190:193], v[92:95]
	v_mfma_f32_16x16x32_bf16 v[88:91], v[162:165], v[190:193], v[88:91]
	v_mfma_f32_16x16x32_bf16 v[76:79], v[146:149], v[198:201], v[76:79]
	v_mfma_f32_16x16x32_bf16 v[72:75], v[162:165], v[198:201], v[72:75]
	s_setprio 0
	s_barrier
	s_add_i32 s14, 0, 0x1c000
	s_add_i32 s15, s53, s61
	v_add_u32_e32 v169, s14, v153
	v_lshl_add_u64 v[150:151], v[150:151], 0, s[38:39]
	s_mov_b32 m0, s15
	ds_read_b128 v[202:205], v169
	ds_read_b128 v[206:209], v169 offset:1024
	ds_read_b128 v[210:213], v169 offset:2048
	ds_read_b128 v[214:217], v169 offset:3072
	global_load_lds_dwordx4 v[150:151], off
	v_lshl_add_u64 v[150:151], v[218:219], 0, s[38:39]
	s_add_i32 m0, s15, 0x2000
	s_nop 0
	global_load_lds_dwordx4 v[150:151], off
	s_barrier
	s_waitcnt lgkmcnt(0)
	s_setprio 1
	s_waitcnt lgkmcnt(0)
	v_mfma_f32_16x16x32_bf16 v[116:119], v[202:205], v[170:173], v[116:119]
	v_mfma_f32_16x16x32_bf16 v[112:115], v[210:213], v[170:173], v[112:115]
	v_mfma_f32_16x16x32_bf16 v[100:103], v[202:205], v[178:181], v[100:103]
	v_mfma_f32_16x16x32_bf16 v[96:99], v[210:213], v[178:181], v[96:99]
	v_mfma_f32_16x16x32_bf16 v[84:87], v[202:205], v[186:189], v[84:87]
	v_mfma_f32_16x16x32_bf16 v[80:83], v[210:213], v[186:189], v[80:83]
	v_mfma_f32_16x16x32_bf16 v[68:71], v[202:205], v[194:197], v[68:71]
	v_mfma_f32_16x16x32_bf16 v[64:67], v[210:213], v[194:197], v[64:67]
	v_mfma_f32_16x16x32_bf16 v[116:119], v[206:209], v[174:177], v[116:119]
	v_mfma_f32_16x16x32_bf16 v[112:115], v[214:217], v[174:177], v[112:115]
	v_mfma_f32_16x16x32_bf16 v[100:103], v[206:209], v[182:185], v[100:103]
	v_mfma_f32_16x16x32_bf16 v[96:99], v[214:217], v[182:185], v[96:99]
	v_mfma_f32_16x16x32_bf16 v[84:87], v[206:209], v[190:193], v[84:87]
	v_mfma_f32_16x16x32_bf16 v[80:83], v[214:217], v[190:193], v[80:83]
	v_mfma_f32_16x16x32_bf16 v[68:71], v[206:209], v[198:201], v[68:71]
	v_mfma_f32_16x16x32_bf16 v[64:67], v[214:217], v[198:201], v[64:67]
	s_setprio 0
	s_mov_b32 m0, s67
	v_lshl_add_u64 v[150:151], v[220:221], 0, s[38:39]
	s_barrier
	ds_read_b128 v[170:173], v156 offset:49152
	ds_read_b128 v[174:177], v156 offset:50176
	ds_read_b128 v[178:181], v156 offset:51200
	ds_read_b128 v[182:185], v156 offset:52224
	ds_read_b128 v[186:189], v156 offset:53248
	ds_read_b128 v[190:193], v156 offset:54272
	ds_read_b128 v[194:197], v156 offset:55296
	ds_read_b128 v[198:201], v156 offset:56320
	global_load_lds_dwordx4 v[150:151], off
	v_lshl_add_u64 v[150:151], v[222:223], 0, s[38:39]
	s_mov_b32 m0, s68
	s_nop 0
	global_load_lds_dwordx4 v[150:151], off
	s_barrier
; __device__ __forceinline__ float sigmoidf_(float x) { return 1.0f / (1.0f + __expf(-x)); }
; #define PG8_STAGE(bufoff, gbase, voff) do { _Pragma("unroll") for (int _i = 0; _i < 2; ++_i) \
;         __builtin_amdgcn_global_load_lds((const unsigned*)((const char*)(gbase) + (voff)[_i]), (LAS unsigned*)(lds + (bufoff) + ldsw + _i * 8192), 16, 0, 0); } while (0)
; #define PG8_MMA(ai, bj, At, Bt) do { __builtin_amdgcn_s_setprio(1); _Pragma("unroll") for (int m = 0; m < 4; ++m) _Pragma("unroll") for (int n = 0; n < 2; ++n) _Pragma("unroll") for (int k = 0; k < 2; ++k) \
;         acc[ai][bj][m][n] = __builtin_amdgcn_mfma_f32_16x16x32_bf16(Bt[n][k], At[m][k], acc[ai][bj][m][n], 0, 0, 0); __builtin_amdgcn_s_setprio(0); } while (0)
; #define PG8_WAIT_V(n) asm volatile("s_waitcnt vmcnt(" #n ")" ::: "memory")
; #define PG8_WAIT_L(n) asm volatile("s_waitcnt lgkmcnt(" #n ")" ::: "memory")
; #define PG8_BAR __builtin_amdgcn_s_barrier()
; #define PG8_SCHED __builtin_amdgcn_sched_barrier(0)
; __device__ __forceinline__ void unpack8(const u32x4 w, f32x4& v0, f32x4& v1) { v0 = (f32x4){bflo(w.x), bfhi(w.x), bflo(w.y), bfhi(w.y)}; v1 = (f32x4){bflo(w.z), bfhi(w.z), bflo(w.w), bfhi(w.w)}; }
;     ...
;             PG8_BAR; PG8_WAIT_L(0); PG8_MMA(1, 0, At, B0); PG8_BAR; PG8_SCHED;
;             PG8_STAGE(PG8_SB(1, 1), b3 + hB, voffB);
;             PG8_WAIT_V(6); PG8_BAR; PG8_MMA(1, 1, At, B1); PG8_BAR;
;         }
;     __device__ __forceinline__ void operator()(const f32x4 (&acc)[2][2][4][2], const Unit& u, int wr, int wc, int fr, int fq) const {
;     ...
;                 const int row = row0 + ai * 128 + m * 16;
;                 const bf16_t* rowp = z + (size_t)row * DIN + col0;
; #pragma unroll
;                 for (int bj = 0; bj < 2; ++bj) {
;                     const u32x4 gw = *(const u32x4*)(rowp + O_GA + bj * 128);
;                     f32x4 g0, g1; unpack8(gw, g0, g1);
;                     f32x4 v0, v1;
; #pragma unroll
;                     for (int j = 0; j < 4; ++j) { v0[j] = sigmoidf_(g0[j]) * acc[ai][bj][m][0][j]; v1[j] = sigmoidf_(g1[j]) * acc[ai][bj][m][1][j]; }
	s_waitcnt lgkmcnt(0)
	s_setprio 1
	s_waitcnt lgkmcnt(0)
	v_mfma_f32_16x16x32_bf16 v[60:63], v[140:143], v[170:173], v[60:63]
	v_mfma_f32_16x16x32_bf16 v[56:59], v[158:161], v[170:173], v[56:59]
	v_mfma_f32_16x16x32_bf16 v[44:47], v[140:143], v[178:181], v[44:47]
	v_mfma_f32_16x16x32_bf16 v[40:43], v[158:161], v[178:181], v[40:43]
	v_mfma_f32_16x16x32_bf16 v[28:31], v[140:143], v[186:189], v[28:31]
	v_mfma_f32_16x16x32_bf16 v[24:27], v[158:161], v[186:189], v[24:27]
	v_mfma_f32_16x16x32_bf16 v[12:15], v[140:143], v[194:197], v[12:15]
	v_mfma_f32_16x16x32_bf16 v[8:11], v[158:161], v[194:197], v[8:11]
	v_mfma_f32_16x16x32_bf16 v[60:63], v[146:149], v[174:177], v[60:63]
	v_mfma_f32_16x16x32_bf16 v[56:59], v[162:165], v[174:177], v[56:59]
	v_mfma_f32_16x16x32_bf16 v[44:47], v[146:149], v[182:185], v[44:47]
	v_mfma_f32_16x16x32_bf16 v[40:43], v[162:165], v[182:185], v[40:43]
	v_mfma_f32_16x16x32_bf16 v[28:31], v[146:149], v[190:193], v[28:31]
	v_mfma_f32_16x16x32_bf16 v[24:27], v[162:165], v[190:193], v[24:27]
	v_mfma_f32_16x16x32_bf16 v[12:15], v[146:149], v[198:201], v[12:15]
	v_mfma_f32_16x16x32_bf16 v[8:11], v[162:165], v[198:201], v[8:11]
	s_setprio 0
	s_barrier
	s_add_u32 s12, s12, 0x20080
	s_addc_u32 s13, s13, 0
	s_add_i32 s14, s14, s61
	v_lshl_add_u64 v[140:141], s[12:13], 0, v[130:131]
	s_mov_b32 m0, s14
	s_nop 0
	global_load_lds_dwordx4 v[140:141], off
	v_lshl_add_u64 v[140:141], s[12:13], 0, v[134:135]
	s_add_i32 m0, s14, 0x2000
	s_nop 0
	global_load_lds_dwordx4 v[140:141], off
	s_waitcnt vmcnt(6)
	s_barrier
	s_setprio 1
	v_mfma_f32_16x16x32_bf16 v[52:55], v[202:205], v[170:173], v[52:55]
	v_mfma_f32_16x16x32_bf16 v[48:51], v[210:213], v[170:173], v[48:51]
	v_mfma_f32_16x16x32_bf16 v[36:39], v[202:205], v[178:181], v[36:39]
	v_mfma_f32_16x16x32_bf16 v[32:35], v[210:213], v[178:181], v[32:35]
	v_mfma_f32_16x16x32_bf16 v[20:23], v[202:205], v[186:189], v[20:23]
	v_mfma_f32_16x16x32_bf16 v[16:19], v[210:213], v[186:189], v[16:19]
	v_mfma_f32_16x16x32_bf16 v[4:7], v[202:205], v[194:197], v[4:7]
	v_mfma_f32_16x16x32_bf16 v[0:3], v[210:213], v[194:197], v[0:3]
	v_mfma_f32_16x16x32_bf16 v[52:55], v[206:209], v[174:177], v[52:55]
	v_mfma_f32_16x16x32_bf16 v[48:51], v[214:217], v[174:177], v[48:51]
	v_mfma_f32_16x16x32_bf16 v[36:39], v[206:209], v[182:185], v[36:39]
	v_mfma_f32_16x16x32_bf16 v[32:35], v[214:217], v[182:185], v[32:35]
	v_mfma_f32_16x16x32_bf16 v[20:23], v[206:209], v[190:193], v[20:23]
	v_mfma_f32_16x16x32_bf16 v[16:19], v[214:217], v[190:193], v[16:19]
	v_mfma_f32_16x16x32_bf16 v[4:7], v[206:209], v[198:201], v[4:7]
	v_mfma_f32_16x16x32_bf16 v[0:3], v[214:217], v[198:201], v[0:3]
	s_setprio 0
	s_add_i32 s45, s45, 2
	s_add_u32 s37, s37, 0x100
	s_addc_u32 s44, s44, 0
	s_add_u32 s10, s10, 0x100
	s_addc_u32 s11, s11, 0
	s_cmp_gt_u32 s45, 5
	s_barrier
	s_cbranch_scc0 .LBB0_1864
	v_lshl_add_u32 v158, s75, 8, v152
	v_lshl_or_b32 v140, s6, 8, v154
	v_add_u32_e32 v142, 0x4000, v158
	v_ashrrev_i32_e32 v141, 31, v140
	v_mad_i64_i32 v[150:151], s[6:7], v142, s73, 0
	v_lshl_add_u64 v[146:147], v[150:151], 1, s[34:35]
	v_lshlrev_b64 v[142:143], 1, v[140:141]
	v_lshl_add_u64 v[146:147], v[146:147], 0, v[142:143]
	v_add_co_u32_e32 v148, vcc, 0x1000, v146
	s_nop 1
	v_addc_co_u32_e32 v149, vcc, 0, v147, vcc
	v_subrev_u32_e32 v197, s34, v146
	v_add_u32_e32 v198, 0x1200, v197
	global_load_dwordx4 v[200:203], v198, s[34:35]
	v_add_u32_e32 v198, 0x0, v197
	global_load_dwordx4 v[204:207], v198, s[34:35]
	v_add_u32_e32 v198, 0x1300, v197
	global_load_dwordx4 v[208:211], v198, s[34:35]
	v_add_u32_e32 v198, 0x100, v197
	global_load_dwordx4 v[212:215], v198, s[34:35]
	v_add_u32_e32 v198, 0x23200, v197
	global_load_dwordx4 v[232:235], v198, s[34:35]
	v_add_u32_e32 v198, 0x22000, v197
	global_load_dwordx4 v[236:239], v198, s[34:35]
	s_waitcnt vmcnt(4)
	v_mov_b32_e32 v160, v200
	v_mov_b32_e32 v161, v201
	v_mov_b32_e32 v162, v202
	v_mov_b32_e32 v163, v203
	v_mov_b32_e32 v170, v204
	v_mov_b32_e32 v171, v205
	v_mov_b32_e32 v172, v206
	v_mov_b32_e32 v173, v207
	v_add_u32_e32 v198, 0x23300, v197
	global_load_dwordx4 v[200:203], v198, s[34:35]
	v_add_u32_e32 v198, 0x22100, v197
	global_load_dwordx4 v[204:207], v198, s[34:35]
	s_mov_b32 s100, 0xbfb8aa3b
	v_lshlrev_b32_e32 v240, 16, v160
	v_and_b32_e32 v241, 0xffff0000, v160
	v_lshlrev_b32_e32 v242, 16, v162
	v_and_b32_e32 v243, 0xffff0000, v162
	v_lshlrev_b32_e32 v244, 16, v161
	v_and_b32_e32 v245, 0xffff0000, v161
	v_lshlrev_b32_e32 v246, 16, v163
	v_and_b32_e32 v247, 0xffff0000, v163
	v_pk_mul_f32 v[240:241], v[240:241], s[100:101] op_sel_hi:[1,0]
	v_pk_mul_f32 v[242:243], v[242:243], s[100:101] op_sel_hi:[1,0]
	v_pk_mul_f32 v[244:245], v[244:245], s[100:101] op_sel_hi:[1,0]
	v_pk_mul_f32 v[246:247], v[246:247], s[100:101] op_sel_hi:[1,0]
	v_exp_f32_e32 v240, v240
	v_exp_f32_e32 v241, v241
	v_exp_f32_e32 v242, v242
	v_exp_f32_e32 v243, v243
	v_exp_f32_e32 v244, v244
	v_exp_f32_e32 v245, v245
	v_exp_f32_e32 v246, v246
	v_exp_f32_e32 v247, v247
	s_nop 0
	v_pk_add_f32 v[240:241], v[240:241], 1.0 op_sel_hi:[1,0]
	v_pk_add_f32 v[242:243], v[242:243], 1.0 op_sel_hi:[1,0]
	v_pk_add_f32 v[244:245], v[244:245], 1.0 op_sel_hi:[1,0]
	v_pk_add_f32 v[246:247], v[246:247], 1.0 op_sel_hi:[1,0]
	v_rcp_f32_e32 v248, v240
	v_rcp_f32_e32 v249, v241
	v_rcp_f32_e32 v254, v242
	v_rcp_f32_e32 v255, v243
	v_pk_fma_f32 v[250:251], v[240:241], v[248:249], 1.0 op_sel_hi:[1,1,0] neg_lo:[1,0,0] neg_hi:[1,0,0]
	v_pk_fma_f32 v[160:161], v[242:243], v[254:255], 1.0 op_sel_hi:[1,1,0] neg_lo:[1,0,0] neg_hi:[1,0,0]
	v_pk_fma_f32 v[248:249], v[250:251], v[248:249], v[248:249]
	v_pk_fma_f32 v[254:255], v[160:161], v[254:255], v[254:255]
; __device__ __forceinline__ float sigmoidf_(float x) { return 1.0f / (1.0f + __expf(-x)); }
; __device__ __forceinline__ u32x4 pack8(const f32x4 v0, const f32x4 v1) { u32x4 w; w.x = pk2(v0[0], v0[1]); w.y = pk2(v0[2], v0[3]); w.z = pk2(v1[0], v1[1]); w.w = pk2(v1[2], v1[3]); return w; }
; __device__ __forceinline__ void unpack8(const u32x4 w, f32x4& v0, f32x4& v1) { v0 = (f32x4){bflo(w.x), bfhi(w.x), bflo(w.y), bfhi(w.y)}; v1 = (f32x4){bflo(w.z), bfhi(w.z), bflo(w.w), bfhi(w.w)}; }
;     __device__ __forceinline__ void operator()(const f32x4 (&acc)[2][2][4][2], const Unit& u, int wr, int wc, int fr, int fq) const {
;     ...
;                 const int row = row0 + ai * 128 + m * 16;
;                 const bf16_t* rowp = z + (size_t)row * DIN + col0;
; #pragma unroll
;                 for (int bj = 0; bj < 2; ++bj) {
;                     const u32x4 gw = *(const u32x4*)(rowp + O_GA + bj * 128);
;                     f32x4 g0, g1; unpack8(gw, g0, g1);
;                     f32x4 v0, v1;
; #pragma unroll
;                     for (int j = 0; j < 4; ++j) { v0[j] = sigmoidf_(g0[j]) * acc[ai][bj][m][0][j]; v1[j] = sigmoidf_(g1[j]) * acc[ai][bj][m][1][j]; }
;                     const u32x4 mw = *(const u32x4*)(rowp + bj * 128); f32x4 m0, m1; unpack8(mw, m0, m1); v0 += m0; v1 += m1;
;                     __builtin_amdgcn_raw_buffer_store_b128(pack8(v0, v1), rsrc, (unsigned)(((size_t)row * DIN + col0 + bj * 128) * 2), 0, 16  ); }
	v_pk_fma_f32 v[250:251], v[240:241], v[248:249], 1.0 op_sel_hi:[1,1,0] neg_lo:[1,0,0] neg_hi:[1,0,0]
	v_pk_fma_f32 v[160:161], v[242:243], v[254:255], 1.0 op_sel_hi:[1,1,0] neg_lo:[1,0,0] neg_hi:[1,0,0]
	v_pk_fma_f32 v[252:253], v[250:251], v[248:249], v[248:249]
	v_pk_fma_f32 v[162:163], v[160:161], v[254:255], v[254:255]
	v_pk_fma_f32 v[250:251], v[240:241], v[252:253], 1.0 op_sel_hi:[1,1,0] neg_lo:[1,0,0] neg_hi:[1,0,0]
	v_pk_fma_f32 v[160:161], v[242:243], v[162:163], 1.0 op_sel_hi:[1,1,0] neg_lo:[1,0,0] neg_hi:[1,0,0]
	v_pk_fma_f32 v[252:253], v[250:251], v[248:249], v[252:253]
	v_pk_fma_f32 v[162:163], v[160:161], v[254:255], v[162:163]
	v_div_fixup_f32 v240, v252, v240, 1.0
	v_div_fixup_f32 v241, v253, v241, 1.0
	v_div_fixup_f32 v242, v162, v242, 1.0
	v_div_fixup_f32 v243, v163, v243, 1.0
	v_rcp_f32_e32 v248, v244
	v_rcp_f32_e32 v249, v245
	v_rcp_f32_e32 v254, v246
	v_rcp_f32_e32 v255, v247
	v_pk_fma_f32 v[250:251], v[244:245], v[248:249], 1.0 op_sel_hi:[1,1,0] neg_lo:[1,0,0] neg_hi:[1,0,0]
	v_pk_fma_f32 v[160:161], v[246:247], v[254:255], 1.0 op_sel_hi:[1,1,0] neg_lo:[1,0,0] neg_hi:[1,0,0]
	v_pk_fma_f32 v[248:249], v[250:251], v[248:249], v[248:249]
	v_pk_fma_f32 v[254:255], v[160:161], v[254:255], v[254:255]
	v_pk_fma_f32 v[250:251], v[244:245], v[248:249], 1.0 op_sel_hi:[1,1,0] neg_lo:[1,0,0] neg_hi:[1,0,0]
	v_pk_fma_f32 v[160:161], v[246:247], v[254:255], 1.0 op_sel_hi:[1,1,0] neg_lo:[1,0,0] neg_hi:[1,0,0]
	v_pk_fma_f32 v[252:253], v[250:251], v[248:249], v[248:249]
	v_pk_fma_f32 v[162:163], v[160:161], v[254:255], v[254:255]
	v_pk_fma_f32 v[250:251], v[244:245], v[252:253], 1.0 op_sel_hi:[1,1,0] neg_lo:[1,0,0] neg_hi:[1,0,0]
	v_pk_fma_f32 v[160:161], v[246:247], v[162:163], 1.0 op_sel_hi:[1,1,0] neg_lo:[1,0,0] neg_hi:[1,0,0]
	v_pk_fma_f32 v[252:253], v[250:251], v[248:249], v[252:253]
	v_pk_fma_f32 v[162:163], v[160:161], v[254:255], v[162:163]
	v_div_fixup_f32 v244, v252, v244, 1.0
	v_div_fixup_f32 v245, v253, v245, 1.0
	v_div_fixup_f32 v246, v162, v246, 1.0
	v_div_fixup_f32 v247, v163, v247, 1.0
	s_mov_b64 vcc, s[10:11]
	s_mov_b64 vcc, s[12:13]
	s_mov_b64 vcc, s[14:15]
	s_mov_b64 vcc, s[16:17]
	v_and_b32_e32 v177, 0xffff0000, v170
	v_lshlrev_b32_e32 v178, 16, v172
	v_lshlrev_b32_e32 v176, 16, v170
	v_and_b32_e32 v179, 0xffff0000, v172
	v_lshlrev_b32_e32 v172, 16, v173
	v_and_b32_e32 v173, 0xffff0000, v173
	v_lshlrev_b32_e32 v170, 16, v171
	v_and_b32_e32 v171, 0xffff0000, v171
	v_pk_fma_f32 v[124:125], v[124:125], v[240:241], v[176:177]
	v_pk_fma_f32 v[160:161], v[122:123], v[246:247], v[172:173]
	v_pk_fma_f32 v[122:123], v[120:121], v[242:243], v[178:179]
	v_add_lshl_u32 v141, v140, v150, 1
	v_pk_fma_f32 v[126:127], v[126:127], v[244:245], v[170:171]
	v_cvt_pk_bf16_f32 v120, v124, v125
	s_nop 0
	v_cvt_pk_bf16_f32 v121, v126, v127
	v_cvt_pk_bf16_f32 v122, v122, v123
	v_cvt_pk_bf16_f32 v123, v160, v161
	buffer_store_dwordx4 v[120:123], v141, s[20:23], 0 offen sc1
	s_nop 0
	s_waitcnt vmcnt(5)
	v_mov_b32_e32 v120, v208
	v_mov_b32_e32 v121, v209
	v_mov_b32_e32 v122, v210
	v_mov_b32_e32 v123, v211
	v_mov_b32_e32 v124, v212
	v_mov_b32_e32 v125, v213
	v_mov_b32_e32 v126, v214
	v_mov_b32_e32 v127, v215
	v_add_u32_e32 v198, 0x45200, v197
	global_load_dwordx4 v[208:211], v198, s[34:35]
	v_add_u32_e32 v198, 0x44000, v197
	global_load_dwordx4 v[212:215], v198, s[34:35]
	s_mov_b32 s100, 0xbfb8aa3b
	v_lshlrev_b32_e32 v240, 16, v120
	v_and_b32_e32 v241, 0xffff0000, v120
	v_lshlrev_b32_e32 v242, 16, v122
	v_and_b32_e32 v243, 0xffff0000, v122
	v_lshlrev_b32_e32 v244, 16, v121
	v_and_b32_e32 v245, 0xffff0000, v121
	v_lshlrev_b32_e32 v246, 16, v123
	v_and_b32_e32 v247, 0xffff0000, v123
	v_pk_mul_f32 v[240:241], v[240:241], s[100:101] op_sel_hi:[1,0]
	v_pk_mul_f32 v[242:243], v[242:243], s[100:101] op_sel_hi:[1,0]
	v_pk_mul_f32 v[244:245], v[244:245], s[100:101] op_sel_hi:[1,0]
	v_pk_mul_f32 v[246:247], v[246:247], s[100:101] op_sel_hi:[1,0]
	v_exp_f32_e32 v240, v240
	v_exp_f32_e32 v241, v241
	v_exp_f32_e32 v242, v242
	v_exp_f32_e32 v243, v243
	v_exp_f32_e32 v244, v244
	v_exp_f32_e32 v245, v245
	v_exp_f32_e32 v246, v246
	v_exp_f32_e32 v247, v247
	s_nop 0
	v_pk_add_f32 v[240:241], v[240:241], 1.0 op_sel_hi:[1,0]
	v_pk_add_f32 v[242:243], v[242:243], 1.0 op_sel_hi:[1,0]
	v_pk_add_f32 v[244:245], v[244:245], 1.0 op_sel_hi:[1,0]
	v_pk_add_f32 v[246:247], v[246:247], 1.0 op_sel_hi:[1,0]
	v_rcp_f32_e32 v248, v240
	v_rcp_f32_e32 v249, v241
	v_rcp_f32_e32 v254, v242
	v_rcp_f32_e32 v255, v243
	v_pk_fma_f32 v[250:251], v[240:241], v[248:249], 1.0 op_sel_hi:[1,1,0] neg_lo:[1,0,0] neg_hi:[1,0,0]
	v_pk_fma_f32 v[120:121], v[242:243], v[254:255], 1.0 op_sel_hi:[1,1,0] neg_lo:[1,0,0] neg_hi:[1,0,0]
	v_pk_fma_f32 v[248:249], v[250:251], v[248:249], v[248:249]
	v_pk_fma_f32 v[254:255], v[120:121], v[254:255], v[254:255]
	v_pk_fma_f32 v[250:251], v[240:241], v[248:249], 1.0 op_sel_hi:[1,1,0] neg_lo:[1,0,0] neg_hi:[1,0,0]
	v_pk_fma_f32 v[120:121], v[242:243], v[254:255], 1.0 op_sel_hi:[1,1,0] neg_lo:[1,0,0] neg_hi:[1,0,0]
	v_pk_fma_f32 v[252:253], v[250:251], v[248:249], v[248:249]
	v_pk_fma_f32 v[122:123], v[120:121], v[254:255], v[254:255]
	v_pk_fma_f32 v[250:251], v[240:241], v[252:253], 1.0 op_sel_hi:[1,1,0] neg_lo:[1,0,0] neg_hi:[1,0,0]
	v_pk_fma_f32 v[120:121], v[242:243], v[122:123], 1.0 op_sel_hi:[1,1,0] neg_lo:[1,0,0] neg_hi:[1,0,0]
	v_pk_fma_f32 v[252:253], v[250:251], v[248:249], v[252:253]
	v_pk_fma_f32 v[122:123], v[120:121], v[254:255], v[122:123]
	v_div_fixup_f32 v240, v252, v240, 1.0
	v_div_fixup_f32 v241, v253, v241, 1.0
	v_div_fixup_f32 v242, v122, v242, 1.0
	v_div_fixup_f32 v243, v123, v243, 1.0
	v_rcp_f32_e32 v248, v244
	v_rcp_f32_e32 v249, v245
; __device__ __forceinline__ float sigmoidf_(float x) { return 1.0f / (1.0f + __expf(-x)); }
; __device__ __forceinline__ u32x4 pack8(const f32x4 v0, const f32x4 v1) { u32x4 w; w.x = pk2(v0[0], v0[1]); w.y = pk2(v0[2], v0[3]); w.z = pk2(v1[0], v1[1]); w.w = pk2(v1[2], v1[3]); return w; }
; __device__ __forceinline__ void unpack8(const u32x4 w, f32x4& v0, f32x4& v1) { v0 = (f32x4){bflo(w.x), bfhi(w.x), bflo(w.y), bfhi(w.y)}; v1 = (f32x4){bflo(w.z), bfhi(w.z), bflo(w.w), bfhi(w.w)}; }
;     __device__ __forceinline__ void operator()(const f32x4 (&acc)[2][2][4][2], const Unit& u, int wr, int wc, int fr, int fq) const {
;     ...
;                 const int row = row0 + ai * 128 + m * 16;
;                 const bf16_t* rowp = z + (size_t)row * DIN + col0;
; #pragma unroll
;                 for (int bj = 0; bj < 2; ++bj) {
;                     const u32x4 gw = *(const u32x4*)(rowp + O_GA + bj * 128);
;                     f32x4 g0, g1; unpack8(gw, g0, g1);
;                     f32x4 v0, v1;
; #pragma unroll
;                     for (int j = 0; j < 4; ++j) { v0[j] = sigmoidf_(g0[j]) * acc[ai][bj][m][0][j]; v1[j] = sigmoidf_(g1[j]) * acc[ai][bj][m][1][j]; }
;                     const u32x4 mw = *(const u32x4*)(rowp + bj * 128); f32x4 m0, m1; unpack8(mw, m0, m1); v0 += m0; v1 += m1;
;                     __builtin_amdgcn_raw_buffer_store_b128(pack8(v0, v1), rsrc, (unsigned)(((size_t)row * DIN + col0 + bj * 128) * 2), 0, 16  ); }
	v_rcp_f32_e32 v254, v246
	v_rcp_f32_e32 v255, v247
	v_pk_fma_f32 v[250:251], v[244:245], v[248:249], 1.0 op_sel_hi:[1,1,0] neg_lo:[1,0,0] neg_hi:[1,0,0]
	v_pk_fma_f32 v[120:121], v[246:247], v[254:255], 1.0 op_sel_hi:[1,1,0] neg_lo:[1,0,0] neg_hi:[1,0,0]
	v_pk_fma_f32 v[248:249], v[250:251], v[248:249], v[248:249]
	v_pk_fma_f32 v[254:255], v[120:121], v[254:255], v[254:255]
	v_pk_fma_f32 v[250:251], v[244:245], v[248:249], 1.0 op_sel_hi:[1,1,0] neg_lo:[1,0,0] neg_hi:[1,0,0]
	v_pk_fma_f32 v[120:121], v[246:247], v[254:255], 1.0 op_sel_hi:[1,1,0] neg_lo:[1,0,0] neg_hi:[1,0,0]
	v_pk_fma_f32 v[252:253], v[250:251], v[248:249], v[248:249]
	v_pk_fma_f32 v[122:123], v[120:121], v[254:255], v[254:255]
	v_pk_fma_f32 v[250:251], v[244:245], v[252:253], 1.0 op_sel_hi:[1,1,0] neg_lo:[1,0,0] neg_hi:[1,0,0]
	v_pk_fma_f32 v[120:121], v[246:247], v[122:123], 1.0 op_sel_hi:[1,1,0] neg_lo:[1,0,0] neg_hi:[1,0,0]
	v_pk_fma_f32 v[252:253], v[250:251], v[248:249], v[252:253]
	v_pk_fma_f32 v[122:123], v[120:121], v[254:255], v[122:123]
	v_div_fixup_f32 v244, v252, v244, 1.0
	v_div_fixup_f32 v245, v253, v245, 1.0
	v_div_fixup_f32 v246, v122, v246, 1.0
	v_div_fixup_f32 v247, v123, v247, 1.0
	v_lshlrev_b32_e32 v150, 16, v124
	v_and_b32_e32 v151, 0xffff0000, v124
	v_lshlrev_b32_e32 v160, 16, v126
	v_and_b32_e32 v161, 0xffff0000, v126
	v_lshlrev_b32_e32 v126, 16, v127
	v_and_b32_e32 v127, 0xffff0000, v127
	v_lshlrev_b32_e32 v124, 16, v125
	v_and_b32_e32 v125, 0xffff0000, v125
	v_pk_fma_f32 v[116:117], v[116:117], v[240:241], v[150:151]
	v_pk_fma_f32 v[120:121], v[114:115], v[246:247], v[126:127]
	v_pk_fma_f32 v[114:115], v[112:113], v[242:243], v[160:161]
	v_cvt_pk_bf16_f32 v112, v116, v117
	v_pk_fma_f32 v[118:119], v[118:119], v[244:245], v[124:125]
	s_nop 0
	v_cvt_pk_bf16_f32 v113, v118, v119
	v_cvt_pk_bf16_f32 v114, v114, v115
	v_cvt_pk_bf16_f32 v115, v120, v121
	buffer_store_dwordx4 v[112:115], v141, s[20:23], 0 offen offset:256 sc1
	s_nop 1
	v_add_u32_e32 v112, 0x4010, v158
	v_mad_i64_i32 v[114:115], s[6:7], v112, s73, 0
	v_lshl_add_u64 v[112:113], v[114:115], 1, s[34:35]
	v_lshl_add_u64 v[112:113], v[112:113], 0, v[142:143]
	v_add_co_u32_e32 v116, vcc, s74, v112
	s_nop 1
	v_addc_co_u32_e32 v117, vcc, 0, v113, vcc
	s_waitcnt vmcnt(6)
	v_mov_b32_e32 v118, v232
	v_mov_b32_e32 v119, v233
	v_mov_b32_e32 v120, v234
	v_mov_b32_e32 v121, v235
	v_mov_b32_e32 v122, v236
	v_mov_b32_e32 v123, v237
	v_mov_b32_e32 v124, v238
	v_mov_b32_e32 v125, v239
	v_add_u32_e32 v198, 0x45300, v197
	global_load_dwordx4 v[232:235], v198, s[34:35]
	v_add_u32_e32 v198, 0x44100, v197
	global_load_dwordx4 v[236:239], v198, s[34:35]
	s_mov_b32 s100, 0xbfb8aa3b
	v_lshlrev_b32_e32 v240, 16, v118
	v_and_b32_e32 v241, 0xffff0000, v118
	v_lshlrev_b32_e32 v242, 16, v120
	v_and_b32_e32 v243, 0xffff0000, v120
	v_lshlrev_b32_e32 v244, 16, v119
	v_and_b32_e32 v245, 0xffff0000, v119
	v_lshlrev_b32_e32 v246, 16, v121
	v_and_b32_e32 v247, 0xffff0000, v121
	v_pk_mul_f32 v[240:241], v[240:241], s[100:101] op_sel_hi:[1,0]
	v_pk_mul_f32 v[242:243], v[242:243], s[100:101] op_sel_hi:[1,0]
	v_pk_mul_f32 v[244:245], v[244:245], s[100:101] op_sel_hi:[1,0]
	v_pk_mul_f32 v[246:247], v[246:247], s[100:101] op_sel_hi:[1,0]
	v_exp_f32_e32 v240, v240
	v_exp_f32_e32 v241, v241
	v_exp_f32_e32 v242, v242
	v_exp_f32_e32 v243, v243
	v_exp_f32_e32 v244, v244
	v_exp_f32_e32 v245, v245
	v_exp_f32_e32 v246, v246
	v_exp_f32_e32 v247, v247
	s_nop 0
	v_pk_add_f32 v[240:241], v[240:241], 1.0 op_sel_hi:[1,0]
	v_pk_add_f32 v[242:243], v[242:243], 1.0 op_sel_hi:[1,0]
	v_pk_add_f32 v[244:245], v[244:245], 1.0 op_sel_hi:[1,0]
	v_pk_add_f32 v[246:247], v[246:247], 1.0 op_sel_hi:[1,0]
	v_rcp_f32_e32 v248, v240
	v_rcp_f32_e32 v249, v241
	v_rcp_f32_e32 v254, v242
	v_rcp_f32_e32 v255, v243
	v_pk_fma_f32 v[250:251], v[240:241], v[248:249], 1.0 op_sel_hi:[1,1,0] neg_lo:[1,0,0] neg_hi:[1,0,0]
	v_pk_fma_f32 v[118:119], v[242:243], v[254:255], 1.0 op_sel_hi:[1,1,0] neg_lo:[1,0,0] neg_hi:[1,0,0]
	v_pk_fma_f32 v[248:249], v[250:251], v[248:249], v[248:249]
	v_pk_fma_f32 v[254:255], v[118:119], v[254:255], v[254:255]
	v_pk_fma_f32 v[250:251], v[240:241], v[248:249], 1.0 op_sel_hi:[1,1,0] neg_lo:[1,0,0] neg_hi:[1,0,0]
	v_pk_fma_f32 v[118:119], v[242:243], v[254:255], 1.0 op_sel_hi:[1,1,0] neg_lo:[1,0,0] neg_hi:[1,0,0]
	v_pk_fma_f32 v[252:253], v[250:251], v[248:249], v[248:249]
	v_pk_fma_f32 v[120:121], v[118:119], v[254:255], v[254:255]
	v_pk_fma_f32 v[250:251], v[240:241], v[252:253], 1.0 op_sel_hi:[1,1,0] neg_lo:[1,0,0] neg_hi:[1,0,0]
	v_pk_fma_f32 v[118:119], v[242:243], v[120:121], 1.0 op_sel_hi:[1,1,0] neg_lo:[1,0,0] neg_hi:[1,0,0]
	v_pk_fma_f32 v[252:253], v[250:251], v[248:249], v[252:253]
	v_pk_fma_f32 v[120:121], v[118:119], v[254:255], v[120:121]
	v_div_fixup_f32 v240, v252, v240, 1.0
	v_div_fixup_f32 v241, v253, v241, 1.0
	v_div_fixup_f32 v242, v120, v242, 1.0
	v_div_fixup_f32 v243, v121, v243, 1.0
	v_rcp_f32_e32 v248, v244
	v_rcp_f32_e32 v249, v245
	v_rcp_f32_e32 v254, v246
	v_rcp_f32_e32 v255, v247
	v_pk_fma_f32 v[250:251], v[244:245], v[248:249], 1.0 op_sel_hi:[1,1,0] neg_lo:[1,0,0] neg_hi:[1,0,0]
	v_pk_fma_f32 v[118:119], v[246:247], v[254:255], 1.0 op_sel_hi:[1,1,0] neg_lo:[1,0,0] neg_hi:[1,0,0]
	v_pk_fma_f32 v[248:249], v[250:251], v[248:249], v[248:249]
	v_pk_fma_f32 v[254:255], v[118:119], v[254:255], v[254:255]
	v_pk_fma_f32 v[250:251], v[244:245], v[248:249], 1.0 op_sel_hi:[1,1,0] neg_lo:[1,0,0] neg_hi:[1,0,0]
	v_pk_fma_f32 v[118:119], v[246:247], v[254:255], 1.0 op_sel_hi:[1,1,0] neg_lo:[1,0,0] neg_hi:[1,0,0]
	v_pk_fma_f32 v[252:253], v[250:251], v[248:249], v[248:249]
	v_pk_fma_f32 v[120:121], v[118:119], v[254:255], v[254:255]
	v_pk_fma_f32 v[250:251], v[244:245], v[252:253], 1.0 op_sel_hi:[1,1,0] neg_lo:[1,0,0] neg_hi:[1,0,0]
	v_pk_fma_f32 v[118:119], v[246:247], v[120:121], 1.0 op_sel_hi:[1,1,0] neg_lo:[1,0,0] neg_hi:[1,0,0]
	v_pk_fma_f32 v[252:253], v[250:251], v[248:249], v[252:253]
	v_pk_fma_f32 v[120:121], v[118:119], v[254:255], v[120:121]
	v_div_fixup_f32 v244, v252, v244, 1.0
	v_div_fixup_f32 v245, v253, v245, 1.0
	v_div_fixup_f32 v246, v120, v246, 1.0
	v_div_fixup_f32 v247, v121, v247, 1.0
	v_and_b32_e32 v151, 0xffff0000, v124
	v_lshlrev_b32_e32 v148, 16, v122
	v_and_b32_e32 v149, 0xffff0000, v122
	v_lshlrev_b32_e32 v150, 16, v124
	v_lshlrev_b32_e32 v124, 16, v125
	v_and_b32_e32 v125, 0xffff0000, v125
	v_lshlrev_b32_e32 v122, 16, v123
	v_and_b32_e32 v123, 0xffff0000, v123
	v_pk_fma_f32 v[108:109], v[108:109], v[240:241], v[148:149]
	v_pk_fma_f32 v[118:119], v[106:107], v[246:247], v[124:125]
	v_pk_fma_f32 v[106:107], v[104:105], v[242:243], v[150:151]
	v_add_lshl_u32 v120, v140, v114, 1
	v_pk_fma_f32 v[110:111], v[110:111], v[244:245], v[122:123]
	v_cvt_pk_bf16_f32 v104, v108, v109
	s_nop 0
	v_cvt_pk_bf16_f32 v105, v110, v111
	v_cvt_pk_bf16_f32 v106, v106, v107
	v_cvt_pk_bf16_f32 v107, v118, v119
	buffer_store_dwordx4 v[104:107], v120, s[20:23], 0 offen sc1
	s_nop 0
	s_waitcnt vmcnt(7)
; __device__ __forceinline__ float sigmoidf_(float x) { return 1.0f / (1.0f + __expf(-x)); }
; __device__ __forceinline__ u32x4 pack8(const f32x4 v0, const f32x4 v1) { u32x4 w; w.x = pk2(v0[0], v0[1]); w.y = pk2(v0[2], v0[3]); w.z = pk2(v1[0], v1[1]); w.w = pk2(v1[2], v1[3]); return w; }
; __device__ __forceinline__ void unpack8(const u32x4 w, f32x4& v0, f32x4& v1) { v0 = (f32x4){bflo(w.x), bfhi(w.x), bflo(w.y), bfhi(w.y)}; v1 = (f32x4){bflo(w.z), bfhi(w.z), bflo(w.w), bfhi(w.w)}; }
;     __device__ __forceinline__ void operator()(const f32x4 (&acc)[2][2][4][2], const Unit& u, int wr, int wc, int fr, int fq) const {
;     ...
;                 const int row = row0 + ai * 128 + m * 16;
;                 const bf16_t* rowp = z + (size_t)row * DIN + col0;
; #pragma unroll
;                 for (int bj = 0; bj < 2; ++bj) {
;                     const u32x4 gw = *(const u32x4*)(rowp + O_GA + bj * 128);
;                     f32x4 g0, g1; unpack8(gw, g0, g1);
;                     f32x4 v0, v1;
; #pragma unroll
;                     for (int j = 0; j < 4; ++j) { v0[j] = sigmoidf_(g0[j]) * acc[ai][bj][m][0][j]; v1[j] = sigmoidf_(g1[j]) * acc[ai][bj][m][1][j]; }
;                     const u32x4 mw = *(const u32x4*)(rowp + bj * 128); f32x4 m0, m1; unpack8(mw, m0, m1); v0 += m0; v1 += m1;
;                     __builtin_amdgcn_raw_buffer_store_b128(pack8(v0, v1), rsrc, (unsigned)(((size_t)row * DIN + col0 + bj * 128) * 2), 0, 16  ); }
	v_mov_b32_e32 v104, v200
	v_mov_b32_e32 v105, v201
	v_mov_b32_e32 v106, v202
	v_mov_b32_e32 v107, v203
	v_mov_b32_e32 v108, v204
	v_mov_b32_e32 v109, v205
	v_mov_b32_e32 v110, v206
	v_mov_b32_e32 v111, v207
	v_add_u32_e32 v198, 0x67200, v197
	global_load_dwordx4 v[200:203], v198, s[34:35]
	v_add_u32_e32 v198, 0x66000, v197
	global_load_dwordx4 v[204:207], v198, s[34:35]
	s_mov_b32 s100, 0xbfb8aa3b
	v_lshlrev_b32_e32 v240, 16, v106
	v_and_b32_e32 v241, 0xffff0000, v106
	v_lshlrev_b32_e32 v242, 16, v104
	v_and_b32_e32 v243, 0xffff0000, v104
	v_lshlrev_b32_e32 v244, 16, v105
	v_and_b32_e32 v245, 0xffff0000, v105
	v_lshlrev_b32_e32 v246, 16, v107
	v_and_b32_e32 v247, 0xffff0000, v107
	v_pk_mul_f32 v[240:241], v[240:241], s[100:101] op_sel_hi:[1,0]
	v_pk_mul_f32 v[242:243], v[242:243], s[100:101] op_sel_hi:[1,0]
	v_pk_mul_f32 v[244:245], v[244:245], s[100:101] op_sel_hi:[1,0]
	v_pk_mul_f32 v[246:247], v[246:247], s[100:101] op_sel_hi:[1,0]
	v_exp_f32_e32 v240, v240
	v_exp_f32_e32 v241, v241
	v_exp_f32_e32 v242, v242
	v_exp_f32_e32 v243, v243
	v_exp_f32_e32 v244, v244
	v_exp_f32_e32 v245, v245
	v_exp_f32_e32 v246, v246
	v_exp_f32_e32 v247, v247
	s_nop 0
	v_pk_add_f32 v[240:241], v[240:241], 1.0 op_sel_hi:[1,0]
	v_pk_add_f32 v[242:243], v[242:243], 1.0 op_sel_hi:[1,0]
	v_pk_add_f32 v[244:245], v[244:245], 1.0 op_sel_hi:[1,0]
	v_pk_add_f32 v[246:247], v[246:247], 1.0 op_sel_hi:[1,0]
	v_rcp_f32_e32 v248, v240
	v_rcp_f32_e32 v249, v241
	v_rcp_f32_e32 v254, v242
	v_rcp_f32_e32 v255, v243
	v_pk_fma_f32 v[250:251], v[240:241], v[248:249], 1.0 op_sel_hi:[1,1,0] neg_lo:[1,0,0] neg_hi:[1,0,0]
	v_pk_fma_f32 v[104:105], v[242:243], v[254:255], 1.0 op_sel_hi:[1,1,0] neg_lo:[1,0,0] neg_hi:[1,0,0]
	v_pk_fma_f32 v[248:249], v[250:251], v[248:249], v[248:249]
	v_pk_fma_f32 v[254:255], v[104:105], v[254:255], v[254:255]
	v_pk_fma_f32 v[250:251], v[240:241], v[248:249], 1.0 op_sel_hi:[1,1,0] neg_lo:[1,0,0] neg_hi:[1,0,0]
	v_pk_fma_f32 v[104:105], v[242:243], v[254:255], 1.0 op_sel_hi:[1,1,0] neg_lo:[1,0,0] neg_hi:[1,0,0]
	v_pk_fma_f32 v[252:253], v[250:251], v[248:249], v[248:249]
	v_pk_fma_f32 v[106:107], v[104:105], v[254:255], v[254:255]
	v_pk_fma_f32 v[250:251], v[240:241], v[252:253], 1.0 op_sel_hi:[1,1,0] neg_lo:[1,0,0] neg_hi:[1,0,0]
	v_pk_fma_f32 v[104:105], v[242:243], v[106:107], 1.0 op_sel_hi:[1,1,0] neg_lo:[1,0,0] neg_hi:[1,0,0]
	v_pk_fma_f32 v[252:253], v[250:251], v[248:249], v[252:253]
	v_pk_fma_f32 v[106:107], v[104:105], v[254:255], v[106:107]
	v_div_fixup_f32 v240, v252, v240, 1.0
	v_div_fixup_f32 v241, v253, v241, 1.0
	v_div_fixup_f32 v242, v106, v242, 1.0
	v_div_fixup_f32 v243, v107, v243, 1.0
	v_rcp_f32_e32 v248, v244
	v_rcp_f32_e32 v249, v245
	v_rcp_f32_e32 v254, v246
	v_rcp_f32_e32 v255, v247
	v_pk_fma_f32 v[250:251], v[244:245], v[248:249], 1.0 op_sel_hi:[1,1,0] neg_lo:[1,0,0] neg_hi:[1,0,0]
	v_pk_fma_f32 v[104:105], v[246:247], v[254:255], 1.0 op_sel_hi:[1,1,0] neg_lo:[1,0,0] neg_hi:[1,0,0]
	v_pk_fma_f32 v[248:249], v[250:251], v[248:249], v[248:249]
	v_pk_fma_f32 v[254:255], v[104:105], v[254:255], v[254:255]
	v_pk_fma_f32 v[250:251], v[244:245], v[248:249], 1.0 op_sel_hi:[1,1,0] neg_lo:[1,0,0] neg_hi:[1,0,0]
	v_pk_fma_f32 v[104:105], v[246:247], v[254:255], 1.0 op_sel_hi:[1,1,0] neg_lo:[1,0,0] neg_hi:[1,0,0]
	v_pk_fma_f32 v[252:253], v[250:251], v[248:249], v[248:249]
	v_pk_fma_f32 v[106:107], v[104:105], v[254:255], v[254:255]
	v_pk_fma_f32 v[250:251], v[244:245], v[252:253], 1.0 op_sel_hi:[1,1,0] neg_lo:[1,0,0] neg_hi:[1,0,0]
	v_pk_fma_f32 v[104:105], v[246:247], v[106:107], 1.0 op_sel_hi:[1,1,0] neg_lo:[1,0,0] neg_hi:[1,0,0]
	v_pk_fma_f32 v[252:253], v[250:251], v[248:249], v[252:253]
	v_pk_fma_f32 v[106:107], v[104:105], v[254:255], v[106:107]
	v_div_fixup_f32 v244, v252, v244, 1.0
	v_div_fixup_f32 v245, v253, v245, 1.0
	v_div_fixup_f32 v246, v106, v246, 1.0
	v_div_fixup_f32 v247, v107, v247, 1.0
	v_lshlrev_b32_e32 v116, 16, v108
	v_and_b32_e32 v117, 0xffff0000, v108
	v_lshlrev_b32_e32 v118, 16, v110
	v_and_b32_e32 v119, 0xffff0000, v110
	v_lshlrev_b32_e32 v110, 16, v111
	v_and_b32_e32 v111, 0xffff0000, v111
	v_lshlrev_b32_e32 v108, 16, v109
	v_and_b32_e32 v109, 0xffff0000, v109
	v_pk_fma_f32 v[100:101], v[100:101], v[242:243], v[116:117]
	v_pk_fma_f32 v[104:105], v[98:99], v[246:247], v[110:111]
	v_pk_fma_f32 v[98:99], v[96:97], v[240:241], v[118:119]
	v_cvt_pk_bf16_f32 v96, v100, v101
	v_pk_fma_f32 v[102:103], v[102:103], v[244:245], v[108:109]
	s_nop 0
	v_cvt_pk_bf16_f32 v97, v102, v103
	v_cvt_pk_bf16_f32 v98, v98, v99
	v_cvt_pk_bf16_f32 v99, v104, v105
	buffer_store_dwordx4 v[96:99], v120, s[20:23], 0 offen offset:256 sc1
	s_nop 1
	v_add_u32_e32 v96, 0x4020, v158
	v_mad_i64_i32 v[98:99], s[6:7], v96, s73, 0
	v_lshl_add_u64 v[96:97], v[98:99], 1, s[34:35]
	v_lshl_add_u64 v[96:97], v[96:97], 0, v[142:143]
	v_add_co_u32_e32 v100, vcc, s74, v96
	s_nop 1
	v_addc_co_u32_e32 v101, vcc, 0, v97, vcc
	s_waitcnt vmcnt(7)
; __device__ __forceinline__ float sigmoidf_(float x) { return 1.0f / (1.0f + __expf(-x)); }
; __device__ __forceinline__ u32x4 pack8(const f32x4 v0, const f32x4 v1) { u32x4 w; w.x = pk2(v0[0], v0[1]); w.y = pk2(v0[2], v0[3]); w.z = pk2(v1[0], v1[1]); w.w = pk2(v1[2], v1[3]); return w; }
; __device__ __forceinline__ void unpack8(const u32x4 w, f32x4& v0, f32x4& v1) { v0 = (f32x4){bflo(w.x), bfhi(w.x), bflo(w.y), bfhi(w.y)}; v1 = (f32x4){bflo(w.z), bfhi(w.z), bflo(w.w), bfhi(w.w)}; }
;     __device__ __forceinline__ void operator()(const f32x4 (&acc)[2][2][4][2], const Unit& u, int wr, int wc, int fr, int fq) const {
;     ...
;                 for (int bj = 0; bj < 2; ++bj) {
;                     const u32x4 gw = *(const u32x4*)(rowp + O_GA + bj * 128);
;                     f32x4 g0, g1; unpack8(gw, g0, g1);
;                     f32x4 v0, v1;
; #pragma unroll
;                     for (int j = 0; j < 4; ++j) { v0[j] = sigmoidf_(g0[j]) * acc[ai][bj][m][0][j]; v1[j] = sigmoidf_(g1[j]) * acc[ai][bj][m][1][j]; }
;                     const u32x4 mw = *(const u32x4*)(rowp + bj * 128); f32x4 m0, m1; unpack8(mw, m0, m1); v0 += m0; v1 += m1;
;                     __builtin_amdgcn_raw_buffer_store_b128(pack8(v0, v1), rsrc, (unsigned)(((size_t)row * DIN + col0 + bj * 128) * 2), 0, 16  ); }
	v_mov_b32_e32 v102, v208
	v_mov_b32_e32 v103, v209
	v_mov_b32_e32 v104, v210
	v_mov_b32_e32 v105, v211
	v_mov_b32_e32 v106, v212
	v_mov_b32_e32 v107, v213
	v_mov_b32_e32 v108, v214
	v_mov_b32_e32 v109, v215
	v_add_u32_e32 v198, 0x67300, v197
	global_load_dwordx4 v[208:211], v198, s[34:35]
	v_add_u32_e32 v198, 0x66100, v197
	global_load_dwordx4 v[212:215], v198, s[34:35]
	s_mov_b32 s100, 0xbfb8aa3b
	v_lshlrev_b32_e32 v240, 16, v102
	v_and_b32_e32 v241, 0xffff0000, v102
	v_lshlrev_b32_e32 v242, 16, v104
	v_and_b32_e32 v243, 0xffff0000, v104
	v_lshlrev_b32_e32 v244, 16, v103
	v_and_b32_e32 v245, 0xffff0000, v103
	v_lshlrev_b32_e32 v246, 16, v105
	v_and_b32_e32 v247, 0xffff0000, v105
	v_pk_mul_f32 v[240:241], v[240:241], s[100:101] op_sel_hi:[1,0]
	v_pk_mul_f32 v[242:243], v[242:243], s[100:101] op_sel_hi:[1,0]
	v_pk_mul_f32 v[244:245], v[244:245], s[100:101] op_sel_hi:[1,0]
	v_pk_mul_f32 v[246:247], v[246:247], s[100:101] op_sel_hi:[1,0]
	v_exp_f32_e32 v240, v240
	v_exp_f32_e32 v241, v241
	v_exp_f32_e32 v242, v242
	v_exp_f32_e32 v243, v243
	v_exp_f32_e32 v244, v244
	v_exp_f32_e32 v245, v245
	v_exp_f32_e32 v246, v246
	v_exp_f32_e32 v247, v247
	s_nop 0
	v_pk_add_f32 v[240:241], v[240:241], 1.0 op_sel_hi:[1,0]
	v_pk_add_f32 v[242:243], v[242:243], 1.0 op_sel_hi:[1,0]
	v_pk_add_f32 v[244:245], v[244:245], 1.0 op_sel_hi:[1,0]
	v_pk_add_f32 v[246:247], v[246:247], 1.0 op_sel_hi:[1,0]
	v_rcp_f32_e32 v248, v240
	v_rcp_f32_e32 v249, v241
	v_rcp_f32_e32 v254, v242
	v_rcp_f32_e32 v255, v243
	v_pk_fma_f32 v[250:251], v[240:241], v[248:249], 1.0 op_sel_hi:[1,1,0] neg_lo:[1,0,0] neg_hi:[1,0,0]
	v_pk_fma_f32 v[102:103], v[242:243], v[254:255], 1.0 op_sel_hi:[1,1,0] neg_lo:[1,0,0] neg_hi:[1,0,0]
	v_pk_fma_f32 v[248:249], v[250:251], v[248:249], v[248:249]
	v_pk_fma_f32 v[254:255], v[102:103], v[254:255], v[254:255]
	v_pk_fma_f32 v[250:251], v[240:241], v[248:249], 1.0 op_sel_hi:[1,1,0] neg_lo:[1,0,0] neg_hi:[1,0,0]
	v_pk_fma_f32 v[102:103], v[242:243], v[254:255], 1.0 op_sel_hi:[1,1,0] neg_lo:[1,0,0] neg_hi:[1,0,0]
	v_pk_fma_f32 v[252:253], v[250:251], v[248:249], v[248:249]
	v_pk_fma_f32 v[104:105], v[102:103], v[254:255], v[254:255]
	v_pk_fma_f32 v[250:251], v[240:241], v[252:253], 1.0 op_sel_hi:[1,1,0] neg_lo:[1,0,0] neg_hi:[1,0,0]
	v_pk_fma_f32 v[102:103], v[242:243], v[104:105], 1.0 op_sel_hi:[1,1,0] neg_lo:[1,0,0] neg_hi:[1,0,0]
	v_pk_fma_f32 v[252:253], v[250:251], v[248:249], v[252:253]
	v_pk_fma_f32 v[104:105], v[102:103], v[254:255], v[104:105]
	v_div_fixup_f32 v240, v252, v240, 1.0
	v_div_fixup_f32 v241, v253, v241, 1.0
	v_div_fixup_f32 v242, v104, v242, 1.0
	v_div_fixup_f32 v243, v105, v243, 1.0
	v_rcp_f32_e32 v248, v244
	v_rcp_f32_e32 v249, v245
	v_rcp_f32_e32 v254, v246
	v_rcp_f32_e32 v255, v247
	v_pk_fma_f32 v[250:251], v[244:245], v[248:249], 1.0 op_sel_hi:[1,1,0] neg_lo:[1,0,0] neg_hi:[1,0,0]
	v_pk_fma_f32 v[102:103], v[246:247], v[254:255], 1.0 op_sel_hi:[1,1,0] neg_lo:[1,0,0] neg_hi:[1,0,0]
	v_pk_fma_f32 v[248:249], v[250:251], v[248:249], v[248:249]
	v_pk_fma_f32 v[254:255], v[102:103], v[254:255], v[254:255]
	v_pk_fma_f32 v[250:251], v[244:245], v[248:249], 1.0 op_sel_hi:[1,1,0] neg_lo:[1,0,0] neg_hi:[1,0,0]
	v_pk_fma_f32 v[102:103], v[246:247], v[254:255], 1.0 op_sel_hi:[1,1,0] neg_lo:[1,0,0] neg_hi:[1,0,0]
	v_pk_fma_f32 v[252:253], v[250:251], v[248:249], v[248:249]
	v_pk_fma_f32 v[104:105], v[102:103], v[254:255], v[254:255]
	v_pk_fma_f32 v[250:251], v[244:245], v[252:253], 1.0 op_sel_hi:[1,1,0] neg_lo:[1,0,0] neg_hi:[1,0,0]
	v_pk_fma_f32 v[102:103], v[246:247], v[104:105], 1.0 op_sel_hi:[1,1,0] neg_lo:[1,0,0] neg_hi:[1,0,0]
	v_pk_fma_f32 v[252:253], v[250:251], v[248:249], v[252:253]
	v_pk_fma_f32 v[104:105], v[102:103], v[254:255], v[104:105]
	v_div_fixup_f32 v244, v252, v244, 1.0
	v_div_fixup_f32 v245, v253, v245, 1.0
	v_div_fixup_f32 v246, v104, v246, 1.0
	v_div_fixup_f32 v247, v105, v247, 1.0
	v_lshlrev_b32_e32 v114, 16, v106
	v_and_b32_e32 v115, 0xffff0000, v106
	v_lshlrev_b32_e32 v116, 16, v108
	v_and_b32_e32 v117, 0xffff0000, v108
	v_lshlrev_b32_e32 v108, 16, v109
	v_and_b32_e32 v109, 0xffff0000, v109
	v_lshlrev_b32_e32 v106, 16, v107
	v_and_b32_e32 v107, 0xffff0000, v107
	v_pk_fma_f32 v[92:93], v[92:93], v[240:241], v[114:115]
	v_pk_fma_f32 v[102:103], v[90:91], v[246:247], v[108:109]
	v_pk_fma_f32 v[90:91], v[88:89], v[242:243], v[116:117]
	v_add_lshl_u32 v104, v140, v98, 1
	v_pk_fma_f32 v[94:95], v[94:95], v[244:245], v[106:107]
	v_cvt_pk_bf16_f32 v88, v92, v93
	s_nop 0
	v_cvt_pk_bf16_f32 v89, v94, v95
	v_cvt_pk_bf16_f32 v90, v90, v91
	v_cvt_pk_bf16_f32 v91, v102, v103
	buffer_store_dwordx4 v[88:91], v104, s[20:23], 0 offen sc1
	s_nop 0
	s_waitcnt vmcnt(7)
; __device__ __forceinline__ float sigmoidf_(float x) { return 1.0f / (1.0f + __expf(-x)); }
; __device__ __forceinline__ u32x4 pack8(const f32x4 v0, const f32x4 v1) { u32x4 w; w.x = pk2(v0[0], v0[1]); w.y = pk2(v0[2], v0[3]); w.z = pk2(v1[0], v1[1]); w.w = pk2(v1[2], v1[3]); return w; }
; __device__ __forceinline__ void unpack8(const u32x4 w, f32x4& v0, f32x4& v1) { v0 = (f32x4){bflo(w.x), bfhi(w.x), bflo(w.y), bfhi(w.y)}; v1 = (f32x4){bflo(w.z), bfhi(w.z), bflo(w.w), bfhi(w.w)}; }
;     __device__ __forceinline__ void operator()(const f32x4 (&acc)[2][2][4][2], const Unit& u, int wr, int wc, int fr, int fq) const {
;     ...
;                 const int row = row0 + ai * 128 + m * 16;
;                 const bf16_t* rowp = z + (size_t)row * DIN + col0;
; #pragma unroll
;                 for (int bj = 0; bj < 2; ++bj) {
;                     const u32x4 gw = *(const u32x4*)(rowp + O_GA + bj * 128);
;                     f32x4 g0, g1; unpack8(gw, g0, g1);
;                     f32x4 v0, v1;
; #pragma unroll
;                     for (int j = 0; j < 4; ++j) { v0[j] = sigmoidf_(g0[j]) * acc[ai][bj][m][0][j]; v1[j] = sigmoidf_(g1[j]) * acc[ai][bj][m][1][j]; }
;                     const u32x4 mw = *(const u32x4*)(rowp + bj * 128); f32x4 m0, m1; unpack8(mw, m0, m1); v0 += m0; v1 += m1;
;                     __builtin_amdgcn_raw_buffer_store_b128(pack8(v0, v1), rsrc, (unsigned)(((size_t)row * DIN + col0 + bj * 128) * 2), 0, 16  ); }
	v_mov_b32_e32 v88, v232
	v_mov_b32_e32 v89, v233
	v_mov_b32_e32 v90, v234
	v_mov_b32_e32 v91, v235
	v_mov_b32_e32 v92, v236
	v_mov_b32_e32 v93, v237
	v_mov_b32_e32 v94, v238
	v_mov_b32_e32 v95, v239
	v_add_u32_e32 v198, 0x111200, v197
	global_load_dwordx4 v[232:235], v198, s[34:35]
	v_add_u32_e32 v198, 0x110000, v197
	global_load_dwordx4 v[236:239], v198, s[34:35]
	s_mov_b32 s100, 0xbfb8aa3b
	v_lshlrev_b32_e32 v240, 16, v90
	v_and_b32_e32 v241, 0xffff0000, v90
	v_lshlrev_b32_e32 v242, 16, v88
	v_and_b32_e32 v243, 0xffff0000, v88
	v_lshlrev_b32_e32 v244, 16, v89
	v_and_b32_e32 v245, 0xffff0000, v89
	v_lshlrev_b32_e32 v246, 16, v91
	v_and_b32_e32 v247, 0xffff0000, v91
	v_pk_mul_f32 v[240:241], v[240:241], s[100:101] op_sel_hi:[1,0]
	v_pk_mul_f32 v[242:243], v[242:243], s[100:101] op_sel_hi:[1,0]
	v_pk_mul_f32 v[244:245], v[244:245], s[100:101] op_sel_hi:[1,0]
	v_pk_mul_f32 v[246:247], v[246:247], s[100:101] op_sel_hi:[1,0]
	v_exp_f32_e32 v240, v240
	v_exp_f32_e32 v241, v241
	v_exp_f32_e32 v242, v242
	v_exp_f32_e32 v243, v243
	v_exp_f32_e32 v244, v244
	v_exp_f32_e32 v245, v245
	v_exp_f32_e32 v246, v246
	v_exp_f32_e32 v247, v247
	s_nop 0
	v_pk_add_f32 v[240:241], v[240:241], 1.0 op_sel_hi:[1,0]
	v_pk_add_f32 v[242:243], v[242:243], 1.0 op_sel_hi:[1,0]
	v_pk_add_f32 v[244:245], v[244:245], 1.0 op_sel_hi:[1,0]
	v_pk_add_f32 v[246:247], v[246:247], 1.0 op_sel_hi:[1,0]
	v_rcp_f32_e32 v248, v240
	v_rcp_f32_e32 v249, v241
	v_rcp_f32_e32 v254, v242
	v_rcp_f32_e32 v255, v243
	v_pk_fma_f32 v[250:251], v[240:241], v[248:249], 1.0 op_sel_hi:[1,1,0] neg_lo:[1,0,0] neg_hi:[1,0,0]
	v_pk_fma_f32 v[88:89], v[242:243], v[254:255], 1.0 op_sel_hi:[1,1,0] neg_lo:[1,0,0] neg_hi:[1,0,0]
	v_pk_fma_f32 v[248:249], v[250:251], v[248:249], v[248:249]
	v_pk_fma_f32 v[254:255], v[88:89], v[254:255], v[254:255]
	v_pk_fma_f32 v[250:251], v[240:241], v[248:249], 1.0 op_sel_hi:[1,1,0] neg_lo:[1,0,0] neg_hi:[1,0,0]
	v_pk_fma_f32 v[88:89], v[242:243], v[254:255], 1.0 op_sel_hi:[1,1,0] neg_lo:[1,0,0] neg_hi:[1,0,0]
	v_pk_fma_f32 v[252:253], v[250:251], v[248:249], v[248:249]
	v_pk_fma_f32 v[90:91], v[88:89], v[254:255], v[254:255]
	v_pk_fma_f32 v[250:251], v[240:241], v[252:253], 1.0 op_sel_hi:[1,1,0] neg_lo:[1,0,0] neg_hi:[1,0,0]
	v_pk_fma_f32 v[88:89], v[242:243], v[90:91], 1.0 op_sel_hi:[1,1,0] neg_lo:[1,0,0] neg_hi:[1,0,0]
	v_pk_fma_f32 v[252:253], v[250:251], v[248:249], v[252:253]
	v_pk_fma_f32 v[90:91], v[88:89], v[254:255], v[90:91]
	v_div_fixup_f32 v240, v252, v240, 1.0
	v_div_fixup_f32 v241, v253, v241, 1.0
	v_div_fixup_f32 v242, v90, v242, 1.0
	v_div_fixup_f32 v243, v91, v243, 1.0
	v_rcp_f32_e32 v248, v244
	v_rcp_f32_e32 v249, v245
	v_rcp_f32_e32 v254, v246
	v_rcp_f32_e32 v255, v247
	v_pk_fma_f32 v[250:251], v[244:245], v[248:249], 1.0 op_sel_hi:[1,1,0] neg_lo:[1,0,0] neg_hi:[1,0,0]
	v_pk_fma_f32 v[88:89], v[246:247], v[254:255], 1.0 op_sel_hi:[1,1,0] neg_lo:[1,0,0] neg_hi:[1,0,0]
	v_pk_fma_f32 v[248:249], v[250:251], v[248:249], v[248:249]
	v_pk_fma_f32 v[254:255], v[88:89], v[254:255], v[254:255]
	v_pk_fma_f32 v[250:251], v[244:245], v[248:249], 1.0 op_sel_hi:[1,1,0] neg_lo:[1,0,0] neg_hi:[1,0,0]
	v_pk_fma_f32 v[88:89], v[246:247], v[254:255], 1.0 op_sel_hi:[1,1,0] neg_lo:[1,0,0] neg_hi:[1,0,0]
	v_pk_fma_f32 v[252:253], v[250:251], v[248:249], v[248:249]
	v_pk_fma_f32 v[90:91], v[88:89], v[254:255], v[254:255]
	v_pk_fma_f32 v[250:251], v[244:245], v[252:253], 1.0 op_sel_hi:[1,1,0] neg_lo:[1,0,0] neg_hi:[1,0,0]
	v_pk_fma_f32 v[88:89], v[246:247], v[90:91], 1.0 op_sel_hi:[1,1,0] neg_lo:[1,0,0] neg_hi:[1,0,0]
	v_pk_fma_f32 v[252:253], v[250:251], v[248:249], v[252:253]
	v_pk_fma_f32 v[90:91], v[88:89], v[254:255], v[90:91]
	v_div_fixup_f32 v244, v252, v244, 1.0
	v_div_fixup_f32 v245, v253, v245, 1.0
	v_div_fixup_f32 v246, v90, v246, 1.0
	v_div_fixup_f32 v247, v91, v247, 1.0
	v_lshlrev_b32_e32 v100, 16, v92
	v_and_b32_e32 v101, 0xffff0000, v92
	v_lshlrev_b32_e32 v102, 16, v94
	v_and_b32_e32 v103, 0xffff0000, v94
	v_lshlrev_b32_e32 v94, 16, v95
	v_and_b32_e32 v95, 0xffff0000, v95
	v_lshlrev_b32_e32 v92, 16, v93
	v_and_b32_e32 v93, 0xffff0000, v93
	v_pk_fma_f32 v[84:85], v[84:85], v[242:243], v[100:101]
	v_pk_fma_f32 v[88:89], v[82:83], v[246:247], v[94:95]
	v_pk_fma_f32 v[82:83], v[80:81], v[240:241], v[102:103]
	v_cvt_pk_bf16_f32 v80, v84, v85
	v_pk_fma_f32 v[86:87], v[86:87], v[244:245], v[92:93]
	s_nop 0
	v_cvt_pk_bf16_f32 v81, v86, v87
	v_cvt_pk_bf16_f32 v82, v82, v83
	v_cvt_pk_bf16_f32 v83, v88, v89
	buffer_store_dwordx4 v[80:83], v104, s[20:23], 0 offen offset:256 sc1
	s_nop 1
	v_add_u32_e32 v80, 0x4030, v158
	v_mad_i64_i32 v[82:83], s[6:7], v80, s73, 0
	v_lshl_add_u64 v[80:81], v[82:83], 1, s[34:35]
	v_lshl_add_u64 v[80:81], v[80:81], 0, v[142:143]
	v_add_co_u32_e32 v84, vcc, s74, v80
	s_nop 1
	v_addc_co_u32_e32 v85, vcc, 0, v81, vcc
	s_waitcnt vmcnt(7)
; __device__ __forceinline__ float sigmoidf_(float x) { return 1.0f / (1.0f + __expf(-x)); }
; __device__ __forceinline__ u32x4 pack8(const f32x4 v0, const f32x4 v1) { u32x4 w; w.x = pk2(v0[0], v0[1]); w.y = pk2(v0[2], v0[3]); w.z = pk2(v1[0], v1[1]); w.w = pk2(v1[2], v1[3]); return w; }
; __device__ __forceinline__ void unpack8(const u32x4 w, f32x4& v0, f32x4& v1) { v0 = (f32x4){bflo(w.x), bfhi(w.x), bflo(w.y), bfhi(w.y)}; v1 = (f32x4){bflo(w.z), bfhi(w.z), bflo(w.w), bfhi(w.w)}; }
;     __device__ __forceinline__ void operator()(const f32x4 (&acc)[2][2][4][2], const Unit& u, int wr, int wc, int fr, int fq) const {
;     ...
;                 for (int bj = 0; bj < 2; ++bj) {
;                     const u32x4 gw = *(const u32x4*)(rowp + O_GA + bj * 128);
;                     f32x4 g0, g1; unpack8(gw, g0, g1);
;                     f32x4 v0, v1;
; #pragma unroll
;                     for (int j = 0; j < 4; ++j) { v0[j] = sigmoidf_(g0[j]) * acc[ai][bj][m][0][j]; v1[j] = sigmoidf_(g1[j]) * acc[ai][bj][m][1][j]; }
;                     const u32x4 mw = *(const u32x4*)(rowp + bj * 128); f32x4 m0, m1; unpack8(mw, m0, m1); v0 += m0; v1 += m1;
;                     __builtin_amdgcn_raw_buffer_store_b128(pack8(v0, v1), rsrc, (unsigned)(((size_t)row * DIN + col0 + bj * 128) * 2), 0, 16  ); }
	v_mov_b32_e32 v86, v200
	v_mov_b32_e32 v87, v201
	v_mov_b32_e32 v88, v202
	v_mov_b32_e32 v89, v203
	v_mov_b32_e32 v90, v204
	v_mov_b32_e32 v91, v205
	v_mov_b32_e32 v92, v206
	v_mov_b32_e32 v93, v207
	v_add_u32_e32 v198, 0x111300, v197
	global_load_dwordx4 v[200:203], v198, s[34:35]
	v_add_u32_e32 v198, 0x110100, v197
	global_load_dwordx4 v[204:207], v198, s[34:35]
	s_mov_b32 s100, 0xbfb8aa3b
	v_lshlrev_b32_e32 v240, 16, v86
	v_and_b32_e32 v241, 0xffff0000, v86
	v_lshlrev_b32_e32 v242, 16, v88
	v_and_b32_e32 v243, 0xffff0000, v88
	v_lshlrev_b32_e32 v244, 16, v87
	v_and_b32_e32 v245, 0xffff0000, v87
	v_lshlrev_b32_e32 v246, 16, v89
	v_and_b32_e32 v247, 0xffff0000, v89
	v_pk_mul_f32 v[240:241], v[240:241], s[100:101] op_sel_hi:[1,0]
	v_pk_mul_f32 v[242:243], v[242:243], s[100:101] op_sel_hi:[1,0]
	v_pk_mul_f32 v[244:245], v[244:245], s[100:101] op_sel_hi:[1,0]
	v_pk_mul_f32 v[246:247], v[246:247], s[100:101] op_sel_hi:[1,0]
	v_exp_f32_e32 v240, v240
	v_exp_f32_e32 v241, v241
	v_exp_f32_e32 v242, v242
	v_exp_f32_e32 v243, v243
	v_exp_f32_e32 v244, v244
	v_exp_f32_e32 v245, v245
	v_exp_f32_e32 v246, v246
	v_exp_f32_e32 v247, v247
	s_nop 0
	v_pk_add_f32 v[240:241], v[240:241], 1.0 op_sel_hi:[1,0]
	v_pk_add_f32 v[242:243], v[242:243], 1.0 op_sel_hi:[1,0]
	v_pk_add_f32 v[244:245], v[244:245], 1.0 op_sel_hi:[1,0]
	v_pk_add_f32 v[246:247], v[246:247], 1.0 op_sel_hi:[1,0]
	v_rcp_f32_e32 v248, v240
	v_rcp_f32_e32 v249, v241
	v_rcp_f32_e32 v254, v242
	v_rcp_f32_e32 v255, v243
	v_pk_fma_f32 v[250:251], v[240:241], v[248:249], 1.0 op_sel_hi:[1,1,0] neg_lo:[1,0,0] neg_hi:[1,0,0]
	v_pk_fma_f32 v[86:87], v[242:243], v[254:255], 1.0 op_sel_hi:[1,1,0] neg_lo:[1,0,0] neg_hi:[1,0,0]
	v_pk_fma_f32 v[248:249], v[250:251], v[248:249], v[248:249]
	v_pk_fma_f32 v[254:255], v[86:87], v[254:255], v[254:255]
	v_pk_fma_f32 v[250:251], v[240:241], v[248:249], 1.0 op_sel_hi:[1,1,0] neg_lo:[1,0,0] neg_hi:[1,0,0]
	v_pk_fma_f32 v[86:87], v[242:243], v[254:255], 1.0 op_sel_hi:[1,1,0] neg_lo:[1,0,0] neg_hi:[1,0,0]
	v_pk_fma_f32 v[252:253], v[250:251], v[248:249], v[248:249]
	v_pk_fma_f32 v[88:89], v[86:87], v[254:255], v[254:255]
	v_pk_fma_f32 v[250:251], v[240:241], v[252:253], 1.0 op_sel_hi:[1,1,0] neg_lo:[1,0,0] neg_hi:[1,0,0]
	v_pk_fma_f32 v[86:87], v[242:243], v[88:89], 1.0 op_sel_hi:[1,1,0] neg_lo:[1,0,0] neg_hi:[1,0,0]
	v_pk_fma_f32 v[252:253], v[250:251], v[248:249], v[252:253]
	v_pk_fma_f32 v[88:89], v[86:87], v[254:255], v[88:89]
	v_div_fixup_f32 v240, v252, v240, 1.0
	v_div_fixup_f32 v241, v253, v241, 1.0
	v_div_fixup_f32 v242, v88, v242, 1.0
	v_div_fixup_f32 v243, v89, v243, 1.0
	v_rcp_f32_e32 v248, v244
	v_rcp_f32_e32 v249, v245
	v_rcp_f32_e32 v254, v246
	v_rcp_f32_e32 v255, v247
	v_pk_fma_f32 v[250:251], v[244:245], v[248:249], 1.0 op_sel_hi:[1,1,0] neg_lo:[1,0,0] neg_hi:[1,0,0]
	v_pk_fma_f32 v[86:87], v[246:247], v[254:255], 1.0 op_sel_hi:[1,1,0] neg_lo:[1,0,0] neg_hi:[1,0,0]
	v_pk_fma_f32 v[248:249], v[250:251], v[248:249], v[248:249]
	v_pk_fma_f32 v[254:255], v[86:87], v[254:255], v[254:255]
	v_pk_fma_f32 v[250:251], v[244:245], v[248:249], 1.0 op_sel_hi:[1,1,0] neg_lo:[1,0,0] neg_hi:[1,0,0]
	v_pk_fma_f32 v[86:87], v[246:247], v[254:255], 1.0 op_sel_hi:[1,1,0] neg_lo:[1,0,0] neg_hi:[1,0,0]
	v_pk_fma_f32 v[252:253], v[250:251], v[248:249], v[248:249]
	v_pk_fma_f32 v[88:89], v[86:87], v[254:255], v[254:255]
	v_pk_fma_f32 v[250:251], v[244:245], v[252:253], 1.0 op_sel_hi:[1,1,0] neg_lo:[1,0,0] neg_hi:[1,0,0]
	v_pk_fma_f32 v[86:87], v[246:247], v[88:89], 1.0 op_sel_hi:[1,1,0] neg_lo:[1,0,0] neg_hi:[1,0,0]
	v_pk_fma_f32 v[252:253], v[250:251], v[248:249], v[252:253]
	v_pk_fma_f32 v[88:89], v[86:87], v[254:255], v[88:89]
	v_div_fixup_f32 v244, v252, v244, 1.0
	v_div_fixup_f32 v245, v253, v245, 1.0
	v_div_fixup_f32 v246, v88, v246, 1.0
	v_div_fixup_f32 v247, v89, v247, 1.0
	v_lshlrev_b32_e32 v98, 16, v90
	v_and_b32_e32 v99, 0xffff0000, v90
	v_lshlrev_b32_e32 v100, 16, v92
	v_and_b32_e32 v101, 0xffff0000, v92
	v_lshlrev_b32_e32 v92, 16, v93
	v_and_b32_e32 v93, 0xffff0000, v93
	v_lshlrev_b32_e32 v90, 16, v91
	v_and_b32_e32 v91, 0xffff0000, v91
	v_pk_fma_f32 v[76:77], v[76:77], v[240:241], v[98:99]
	v_pk_fma_f32 v[86:87], v[74:75], v[246:247], v[92:93]
	v_pk_fma_f32 v[74:75], v[72:73], v[242:243], v[100:101]
	v_add_lshl_u32 v88, v140, v82, 1
	v_pk_fma_f32 v[78:79], v[78:79], v[244:245], v[90:91]
	v_cvt_pk_bf16_f32 v72, v76, v77
	s_nop 0
	v_cvt_pk_bf16_f32 v73, v78, v79
	v_cvt_pk_bf16_f32 v74, v74, v75
	v_cvt_pk_bf16_f32 v75, v86, v87
	buffer_store_dwordx4 v[72:75], v88, s[20:23], 0 offen sc1
	s_nop 0
	s_waitcnt vmcnt(7)
; __device__ __forceinline__ float sigmoidf_(float x) { return 1.0f / (1.0f + __expf(-x)); }
; __device__ __forceinline__ u32x4 pack8(const f32x4 v0, const f32x4 v1) { u32x4 w; w.x = pk2(v0[0], v0[1]); w.y = pk2(v0[2], v0[3]); w.z = pk2(v1[0], v1[1]); w.w = pk2(v1[2], v1[3]); return w; }
; __device__ __forceinline__ void unpack8(const u32x4 w, f32x4& v0, f32x4& v1) { v0 = (f32x4){bflo(w.x), bfhi(w.x), bflo(w.y), bfhi(w.y)}; v1 = (f32x4){bflo(w.z), bfhi(w.z), bflo(w.w), bfhi(w.w)}; }
;     __device__ __forceinline__ void operator()(const f32x4 (&acc)[2][2][4][2], const Unit& u, int wr, int wc, int fr, int fq) const {
;     ...
;                 const int row = row0 + ai * 128 + m * 16;
;                 const bf16_t* rowp = z + (size_t)row * DIN + col0;
; #pragma unroll
;                 for (int bj = 0; bj < 2; ++bj) {
;                     const u32x4 gw = *(const u32x4*)(rowp + O_GA + bj * 128);
;                     f32x4 g0, g1; unpack8(gw, g0, g1);
;                     f32x4 v0, v1;
; #pragma unroll
;                     for (int j = 0; j < 4; ++j) { v0[j] = sigmoidf_(g0[j]) * acc[ai][bj][m][0][j]; v1[j] = sigmoidf_(g1[j]) * acc[ai][bj][m][1][j]; }
;                     const u32x4 mw = *(const u32x4*)(rowp + bj * 128); f32x4 m0, m1; unpack8(mw, m0, m1); v0 += m0; v1 += m1;
;                     __builtin_amdgcn_raw_buffer_store_b128(pack8(v0, v1), rsrc, (unsigned)(((size_t)row * DIN + col0 + bj * 128) * 2), 0, 16  ); }
	v_mov_b32_e32 v72, v208
	v_mov_b32_e32 v73, v209
	v_mov_b32_e32 v74, v210
	v_mov_b32_e32 v75, v211
	v_mov_b32_e32 v76, v212
	v_mov_b32_e32 v77, v213
	v_mov_b32_e32 v78, v214
	v_mov_b32_e32 v79, v215
	v_add_u32_e32 v198, 0x133200, v197
	global_load_dwordx4 v[208:211], v198, s[34:35]
	v_add_u32_e32 v198, 0x132000, v197
	global_load_dwordx4 v[212:215], v198, s[34:35]
	s_mov_b32 s100, 0xbfb8aa3b
	v_lshlrev_b32_e32 v240, 16, v74
	v_and_b32_e32 v241, 0xffff0000, v74
	v_lshlrev_b32_e32 v242, 16, v72
	v_and_b32_e32 v243, 0xffff0000, v72
	v_lshlrev_b32_e32 v244, 16, v73
	v_and_b32_e32 v245, 0xffff0000, v73
	v_lshlrev_b32_e32 v246, 16, v75
	v_and_b32_e32 v247, 0xffff0000, v75
	v_pk_mul_f32 v[240:241], v[240:241], s[100:101] op_sel_hi:[1,0]
	v_pk_mul_f32 v[242:243], v[242:243], s[100:101] op_sel_hi:[1,0]
	v_pk_mul_f32 v[244:245], v[244:245], s[100:101] op_sel_hi:[1,0]
	v_pk_mul_f32 v[246:247], v[246:247], s[100:101] op_sel_hi:[1,0]
	v_exp_f32_e32 v240, v240
	v_exp_f32_e32 v241, v241
	v_exp_f32_e32 v242, v242
	v_exp_f32_e32 v243, v243
	v_exp_f32_e32 v244, v244
	v_exp_f32_e32 v245, v245
	v_exp_f32_e32 v246, v246
	v_exp_f32_e32 v247, v247
	s_nop 0
	v_pk_add_f32 v[240:241], v[240:241], 1.0 op_sel_hi:[1,0]
	v_pk_add_f32 v[242:243], v[242:243], 1.0 op_sel_hi:[1,0]
	v_pk_add_f32 v[244:245], v[244:245], 1.0 op_sel_hi:[1,0]
	v_pk_add_f32 v[246:247], v[246:247], 1.0 op_sel_hi:[1,0]
	v_rcp_f32_e32 v248, v240
	v_rcp_f32_e32 v249, v241
	v_rcp_f32_e32 v254, v242
	v_rcp_f32_e32 v255, v243
	v_pk_fma_f32 v[250:251], v[240:241], v[248:249], 1.0 op_sel_hi:[1,1,0] neg_lo:[1,0,0] neg_hi:[1,0,0]
	v_pk_fma_f32 v[72:73], v[242:243], v[254:255], 1.0 op_sel_hi:[1,1,0] neg_lo:[1,0,0] neg_hi:[1,0,0]
	v_pk_fma_f32 v[248:249], v[250:251], v[248:249], v[248:249]
	v_pk_fma_f32 v[254:255], v[72:73], v[254:255], v[254:255]
	v_pk_fma_f32 v[250:251], v[240:241], v[248:249], 1.0 op_sel_hi:[1,1,0] neg_lo:[1,0,0] neg_hi:[1,0,0]
	v_pk_fma_f32 v[72:73], v[242:243], v[254:255], 1.0 op_sel_hi:[1,1,0] neg_lo:[1,0,0] neg_hi:[1,0,0]
	v_pk_fma_f32 v[252:253], v[250:251], v[248:249], v[248:249]
	v_pk_fma_f32 v[74:75], v[72:73], v[254:255], v[254:255]
	v_pk_fma_f32 v[250:251], v[240:241], v[252:253], 1.0 op_sel_hi:[1,1,0] neg_lo:[1,0,0] neg_hi:[1,0,0]
	v_pk_fma_f32 v[72:73], v[242:243], v[74:75], 1.0 op_sel_hi:[1,1,0] neg_lo:[1,0,0] neg_hi:[1,0,0]
	v_pk_fma_f32 v[252:253], v[250:251], v[248:249], v[252:253]
	v_pk_fma_f32 v[74:75], v[72:73], v[254:255], v[74:75]
	v_div_fixup_f32 v240, v252, v240, 1.0
	v_div_fixup_f32 v241, v253, v241, 1.0
	v_div_fixup_f32 v242, v74, v242, 1.0
	v_div_fixup_f32 v243, v75, v243, 1.0
	v_rcp_f32_e32 v248, v244
	v_rcp_f32_e32 v249, v245
	v_rcp_f32_e32 v254, v246
	v_rcp_f32_e32 v255, v247
	v_pk_fma_f32 v[250:251], v[244:245], v[248:249], 1.0 op_sel_hi:[1,1,0] neg_lo:[1,0,0] neg_hi:[1,0,0]
	v_pk_fma_f32 v[72:73], v[246:247], v[254:255], 1.0 op_sel_hi:[1,1,0] neg_lo:[1,0,0] neg_hi:[1,0,0]
	v_pk_fma_f32 v[248:249], v[250:251], v[248:249], v[248:249]
	v_pk_fma_f32 v[254:255], v[72:73], v[254:255], v[254:255]
	v_pk_fma_f32 v[250:251], v[244:245], v[248:249], 1.0 op_sel_hi:[1,1,0] neg_lo:[1,0,0] neg_hi:[1,0,0]
	v_pk_fma_f32 v[72:73], v[246:247], v[254:255], 1.0 op_sel_hi:[1,1,0] neg_lo:[1,0,0] neg_hi:[1,0,0]
	v_pk_fma_f32 v[252:253], v[250:251], v[248:249], v[248:249]
	v_pk_fma_f32 v[74:75], v[72:73], v[254:255], v[254:255]
	v_pk_fma_f32 v[250:251], v[244:245], v[252:253], 1.0 op_sel_hi:[1,1,0] neg_lo:[1,0,0] neg_hi:[1,0,0]
	v_pk_fma_f32 v[72:73], v[246:247], v[74:75], 1.0 op_sel_hi:[1,1,0] neg_lo:[1,0,0] neg_hi:[1,0,0]
	v_pk_fma_f32 v[252:253], v[250:251], v[248:249], v[252:253]
	v_pk_fma_f32 v[74:75], v[72:73], v[254:255], v[74:75]
	v_div_fixup_f32 v244, v252, v244, 1.0
	v_div_fixup_f32 v245, v253, v245, 1.0
	v_div_fixup_f32 v246, v74, v246, 1.0
	v_div_fixup_f32 v247, v75, v247, 1.0
	v_lshlrev_b32_e32 v84, 16, v76
	v_and_b32_e32 v85, 0xffff0000, v76
	v_lshlrev_b32_e32 v86, 16, v78
	v_and_b32_e32 v87, 0xffff0000, v78
	v_lshlrev_b32_e32 v78, 16, v79
	v_and_b32_e32 v79, 0xffff0000, v79
	v_lshlrev_b32_e32 v76, 16, v77
	v_and_b32_e32 v77, 0xffff0000, v77
	v_pk_fma_f32 v[68:69], v[68:69], v[242:243], v[84:85]
	v_pk_fma_f32 v[72:73], v[66:67], v[246:247], v[78:79]
	v_pk_fma_f32 v[66:67], v[64:65], v[240:241], v[86:87]
	v_cvt_pk_bf16_f32 v64, v68, v69
	v_pk_fma_f32 v[70:71], v[70:71], v[244:245], v[76:77]
	s_nop 0
	v_cvt_pk_bf16_f32 v65, v70, v71
	v_cvt_pk_bf16_f32 v66, v66, v67
	v_cvt_pk_bf16_f32 v67, v72, v73
	buffer_store_dwordx4 v[64:67], v88, s[20:23], 0 offen offset:256 sc1
	s_nop 1
	v_add_u32_e32 v64, 0x4080, v158
	v_mad_i64_i32 v[66:67], s[6:7], v64, s73, 0
	v_lshl_add_u64 v[64:65], v[66:67], 1, s[34:35]
	v_lshl_add_u64 v[64:65], v[64:65], 0, v[142:143]
	v_add_co_u32_e32 v68, vcc, s74, v64
	s_nop 1
	v_addc_co_u32_e32 v69, vcc, 0, v65, vcc
	s_waitcnt vmcnt(7)
; __device__ __forceinline__ float sigmoidf_(float x) { return 1.0f / (1.0f + __expf(-x)); }
; __device__ __forceinline__ u32x4 pack8(const f32x4 v0, const f32x4 v1) { u32x4 w; w.x = pk2(v0[0], v0[1]); w.y = pk2(v0[2], v0[3]); w.z = pk2(v1[0], v1[1]); w.w = pk2(v1[2], v1[3]); return w; }
; __device__ __forceinline__ void unpack8(const u32x4 w, f32x4& v0, f32x4& v1) { v0 = (f32x4){bflo(w.x), bfhi(w.x), bflo(w.y), bfhi(w.y)}; v1 = (f32x4){bflo(w.z), bfhi(w.z), bflo(w.w), bfhi(w.w)}; }
;     __device__ __forceinline__ void operator()(const f32x4 (&acc)[2][2][4][2], const Unit& u, int wr, int wc, int fr, int fq) const {
;     ...
;                 for (int bj = 0; bj < 2; ++bj) {
;                     const u32x4 gw = *(const u32x4*)(rowp + O_GA + bj * 128);
;                     f32x4 g0, g1; unpack8(gw, g0, g1);
;                     f32x4 v0, v1;
; #pragma unroll
;                     for (int j = 0; j < 4; ++j) { v0[j] = sigmoidf_(g0[j]) * acc[ai][bj][m][0][j]; v1[j] = sigmoidf_(g1[j]) * acc[ai][bj][m][1][j]; }
;                     const u32x4 mw = *(const u32x4*)(rowp + bj * 128); f32x4 m0, m1; unpack8(mw, m0, m1); v0 += m0; v1 += m1;
;                     __builtin_amdgcn_raw_buffer_store_b128(pack8(v0, v1), rsrc, (unsigned)(((size_t)row * DIN + col0 + bj * 128) * 2), 0, 16  ); }
	v_mov_b32_e32 v70, v232
	v_mov_b32_e32 v71, v233
	v_mov_b32_e32 v72, v234
	v_mov_b32_e32 v73, v235
	v_mov_b32_e32 v74, v236
	v_mov_b32_e32 v75, v237
	v_mov_b32_e32 v76, v238
	v_mov_b32_e32 v77, v239
	v_add_u32_e32 v198, 0x133300, v197
	global_load_dwordx4 v[232:235], v198, s[34:35]
	v_add_u32_e32 v198, 0x132100, v197
	global_load_dwordx4 v[236:239], v198, s[34:35]
	s_mov_b32 s100, 0xbfb8aa3b
	v_lshlrev_b32_e32 v240, 16, v70
	v_and_b32_e32 v241, 0xffff0000, v70
	v_lshlrev_b32_e32 v242, 16, v72
	v_and_b32_e32 v243, 0xffff0000, v72
	v_lshlrev_b32_e32 v244, 16, v71
	v_and_b32_e32 v245, 0xffff0000, v71
	v_lshlrev_b32_e32 v246, 16, v73
	v_and_b32_e32 v247, 0xffff0000, v73
	v_pk_mul_f32 v[240:241], v[240:241], s[100:101] op_sel_hi:[1,0]
	v_pk_mul_f32 v[242:243], v[242:243], s[100:101] op_sel_hi:[1,0]
	v_pk_mul_f32 v[244:245], v[244:245], s[100:101] op_sel_hi:[1,0]
	v_pk_mul_f32 v[246:247], v[246:247], s[100:101] op_sel_hi:[1,0]
	v_exp_f32_e32 v240, v240
	v_exp_f32_e32 v241, v241
	v_exp_f32_e32 v242, v242
	v_exp_f32_e32 v243, v243
	v_exp_f32_e32 v244, v244
	v_exp_f32_e32 v245, v245
	v_exp_f32_e32 v246, v246
	v_exp_f32_e32 v247, v247
	s_nop 0
	v_pk_add_f32 v[240:241], v[240:241], 1.0 op_sel_hi:[1,0]
	v_pk_add_f32 v[242:243], v[242:243], 1.0 op_sel_hi:[1,0]
	v_pk_add_f32 v[244:245], v[244:245], 1.0 op_sel_hi:[1,0]
	v_pk_add_f32 v[246:247], v[246:247], 1.0 op_sel_hi:[1,0]
	v_rcp_f32_e32 v248, v240
	v_rcp_f32_e32 v249, v241
	v_rcp_f32_e32 v254, v242
	v_rcp_f32_e32 v255, v243
	v_pk_fma_f32 v[250:251], v[240:241], v[248:249], 1.0 op_sel_hi:[1,1,0] neg_lo:[1,0,0] neg_hi:[1,0,0]
	v_pk_fma_f32 v[70:71], v[242:243], v[254:255], 1.0 op_sel_hi:[1,1,0] neg_lo:[1,0,0] neg_hi:[1,0,0]
	v_pk_fma_f32 v[248:249], v[250:251], v[248:249], v[248:249]
	v_pk_fma_f32 v[254:255], v[70:71], v[254:255], v[254:255]
	v_pk_fma_f32 v[250:251], v[240:241], v[248:249], 1.0 op_sel_hi:[1,1,0] neg_lo:[1,0,0] neg_hi:[1,0,0]
	v_pk_fma_f32 v[70:71], v[242:243], v[254:255], 1.0 op_sel_hi:[1,1,0] neg_lo:[1,0,0] neg_hi:[1,0,0]
	v_pk_fma_f32 v[252:253], v[250:251], v[248:249], v[248:249]
	v_pk_fma_f32 v[72:73], v[70:71], v[254:255], v[254:255]
	v_pk_fma_f32 v[250:251], v[240:241], v[252:253], 1.0 op_sel_hi:[1,1,0] neg_lo:[1,0,0] neg_hi:[1,0,0]
	v_pk_fma_f32 v[70:71], v[242:243], v[72:73], 1.0 op_sel_hi:[1,1,0] neg_lo:[1,0,0] neg_hi:[1,0,0]
	v_pk_fma_f32 v[252:253], v[250:251], v[248:249], v[252:253]
	v_pk_fma_f32 v[72:73], v[70:71], v[254:255], v[72:73]
	v_div_fixup_f32 v240, v252, v240, 1.0
	v_div_fixup_f32 v241, v253, v241, 1.0
	v_div_fixup_f32 v242, v72, v242, 1.0
	v_div_fixup_f32 v243, v73, v243, 1.0
	v_rcp_f32_e32 v248, v244
	v_rcp_f32_e32 v249, v245
	v_rcp_f32_e32 v254, v246
	v_rcp_f32_e32 v255, v247
	v_pk_fma_f32 v[250:251], v[244:245], v[248:249], 1.0 op_sel_hi:[1,1,0] neg_lo:[1,0,0] neg_hi:[1,0,0]
	v_pk_fma_f32 v[70:71], v[246:247], v[254:255], 1.0 op_sel_hi:[1,1,0] neg_lo:[1,0,0] neg_hi:[1,0,0]
	v_pk_fma_f32 v[248:249], v[250:251], v[248:249], v[248:249]
	v_pk_fma_f32 v[254:255], v[70:71], v[254:255], v[254:255]
	v_pk_fma_f32 v[250:251], v[244:245], v[248:249], 1.0 op_sel_hi:[1,1,0] neg_lo:[1,0,0] neg_hi:[1,0,0]
	v_pk_fma_f32 v[70:71], v[246:247], v[254:255], 1.0 op_sel_hi:[1,1,0] neg_lo:[1,0,0] neg_hi:[1,0,0]
	v_pk_fma_f32 v[252:253], v[250:251], v[248:249], v[248:249]
	v_pk_fma_f32 v[72:73], v[70:71], v[254:255], v[254:255]
	v_pk_fma_f32 v[250:251], v[244:245], v[252:253], 1.0 op_sel_hi:[1,1,0] neg_lo:[1,0,0] neg_hi:[1,0,0]
	v_pk_fma_f32 v[70:71], v[246:247], v[72:73], 1.0 op_sel_hi:[1,1,0] neg_lo:[1,0,0] neg_hi:[1,0,0]
	v_pk_fma_f32 v[252:253], v[250:251], v[248:249], v[252:253]
	v_pk_fma_f32 v[72:73], v[70:71], v[254:255], v[72:73]
	v_div_fixup_f32 v244, v252, v244, 1.0
	v_div_fixup_f32 v245, v253, v245, 1.0
	v_div_fixup_f32 v246, v72, v246, 1.0
	v_div_fixup_f32 v247, v73, v247, 1.0
	v_lshlrev_b32_e32 v82, 16, v74
	v_and_b32_e32 v83, 0xffff0000, v74
	v_lshlrev_b32_e32 v84, 16, v76
	v_and_b32_e32 v85, 0xffff0000, v76
	v_lshlrev_b32_e32 v76, 16, v77
	v_and_b32_e32 v77, 0xffff0000, v77
	v_lshlrev_b32_e32 v74, 16, v75
	v_and_b32_e32 v75, 0xffff0000, v75
	v_pk_fma_f32 v[60:61], v[60:61], v[240:241], v[82:83]
	v_pk_fma_f32 v[70:71], v[58:59], v[246:247], v[76:77]
	v_pk_fma_f32 v[58:59], v[56:57], v[242:243], v[84:85]
	v_add_lshl_u32 v72, v140, v66, 1
	v_pk_fma_f32 v[62:63], v[62:63], v[244:245], v[74:75]
	v_cvt_pk_bf16_f32 v56, v60, v61
	s_nop 0
	v_cvt_pk_bf16_f32 v57, v62, v63
	v_cvt_pk_bf16_f32 v58, v58, v59
	v_cvt_pk_bf16_f32 v59, v70, v71
	buffer_store_dwordx4 v[56:59], v72, s[20:23], 0 offen sc1
	s_nop 0
	s_waitcnt vmcnt(7)
; __device__ __forceinline__ float sigmoidf_(float x) { return 1.0f / (1.0f + __expf(-x)); }
; __device__ __forceinline__ u32x4 pack8(const f32x4 v0, const f32x4 v1) { u32x4 w; w.x = pk2(v0[0], v0[1]); w.y = pk2(v0[2], v0[3]); w.z = pk2(v1[0], v1[1]); w.w = pk2(v1[2], v1[3]); return w; }
; __device__ __forceinline__ void unpack8(const u32x4 w, f32x4& v0, f32x4& v1) { v0 = (f32x4){bflo(w.x), bfhi(w.x), bflo(w.y), bfhi(w.y)}; v1 = (f32x4){bflo(w.z), bfhi(w.z), bflo(w.w), bfhi(w.w)}; }
;     __device__ __forceinline__ void operator()(const f32x4 (&acc)[2][2][4][2], const Unit& u, int wr, int wc, int fr, int fq) const {
;     ...
;                 const int row = row0 + ai * 128 + m * 16;
;                 const bf16_t* rowp = z + (size_t)row * DIN + col0;
; #pragma unroll
;                 for (int bj = 0; bj < 2; ++bj) {
;                     const u32x4 gw = *(const u32x4*)(rowp + O_GA + bj * 128);
;                     f32x4 g0, g1; unpack8(gw, g0, g1);
;                     f32x4 v0, v1;
; #pragma unroll
;                     for (int j = 0; j < 4; ++j) { v0[j] = sigmoidf_(g0[j]) * acc[ai][bj][m][0][j]; v1[j] = sigmoidf_(g1[j]) * acc[ai][bj][m][1][j]; }
;                     const u32x4 mw = *(const u32x4*)(rowp + bj * 128); f32x4 m0, m1; unpack8(mw, m0, m1); v0 += m0; v1 += m1;
;                     __builtin_amdgcn_raw_buffer_store_b128(pack8(v0, v1), rsrc, (unsigned)(((size_t)row * DIN + col0 + bj * 128) * 2), 0, 16  ); }
	v_mov_b32_e32 v56, v200
	v_mov_b32_e32 v57, v201
	v_mov_b32_e32 v58, v202
	v_mov_b32_e32 v59, v203
	v_mov_b32_e32 v60, v204
	v_mov_b32_e32 v61, v205
	v_mov_b32_e32 v62, v206
	v_mov_b32_e32 v63, v207
	v_add_u32_e32 v198, 0x155200, v197
	global_load_dwordx4 v[200:203], v198, s[34:35]
	v_add_u32_e32 v198, 0x154000, v197
	global_load_dwordx4 v[204:207], v198, s[34:35]
	s_mov_b32 s100, 0xbfb8aa3b
	v_lshlrev_b32_e32 v240, 16, v58
	v_and_b32_e32 v241, 0xffff0000, v58
	v_lshlrev_b32_e32 v242, 16, v56
	v_and_b32_e32 v243, 0xffff0000, v56
	v_lshlrev_b32_e32 v244, 16, v57
	v_and_b32_e32 v245, 0xffff0000, v57
	v_lshlrev_b32_e32 v246, 16, v59
	v_and_b32_e32 v247, 0xffff0000, v59
	v_pk_mul_f32 v[240:241], v[240:241], s[100:101] op_sel_hi:[1,0]
	v_pk_mul_f32 v[242:243], v[242:243], s[100:101] op_sel_hi:[1,0]
	v_pk_mul_f32 v[244:245], v[244:245], s[100:101] op_sel_hi:[1,0]
	v_pk_mul_f32 v[246:247], v[246:247], s[100:101] op_sel_hi:[1,0]
	v_exp_f32_e32 v240, v240
	v_exp_f32_e32 v241, v241
	v_exp_f32_e32 v242, v242
	v_exp_f32_e32 v243, v243
	v_exp_f32_e32 v244, v244
	v_exp_f32_e32 v245, v245
	v_exp_f32_e32 v246, v246
	v_exp_f32_e32 v247, v247
	s_nop 0
	v_pk_add_f32 v[240:241], v[240:241], 1.0 op_sel_hi:[1,0]
	v_pk_add_f32 v[242:243], v[242:243], 1.0 op_sel_hi:[1,0]
	v_pk_add_f32 v[244:245], v[244:245], 1.0 op_sel_hi:[1,0]
	v_pk_add_f32 v[246:247], v[246:247], 1.0 op_sel_hi:[1,0]
	v_rcp_f32_e32 v248, v240
	v_rcp_f32_e32 v249, v241
	v_rcp_f32_e32 v254, v242
	v_rcp_f32_e32 v255, v243
	v_pk_fma_f32 v[250:251], v[240:241], v[248:249], 1.0 op_sel_hi:[1,1,0] neg_lo:[1,0,0] neg_hi:[1,0,0]
	v_pk_fma_f32 v[56:57], v[242:243], v[254:255], 1.0 op_sel_hi:[1,1,0] neg_lo:[1,0,0] neg_hi:[1,0,0]
	v_pk_fma_f32 v[248:249], v[250:251], v[248:249], v[248:249]
	v_pk_fma_f32 v[254:255], v[56:57], v[254:255], v[254:255]
	v_pk_fma_f32 v[250:251], v[240:241], v[248:249], 1.0 op_sel_hi:[1,1,0] neg_lo:[1,0,0] neg_hi:[1,0,0]
	v_pk_fma_f32 v[56:57], v[242:243], v[254:255], 1.0 op_sel_hi:[1,1,0] neg_lo:[1,0,0] neg_hi:[1,0,0]
	v_pk_fma_f32 v[252:253], v[250:251], v[248:249], v[248:249]
	v_pk_fma_f32 v[58:59], v[56:57], v[254:255], v[254:255]
	v_pk_fma_f32 v[250:251], v[240:241], v[252:253], 1.0 op_sel_hi:[1,1,0] neg_lo:[1,0,0] neg_hi:[1,0,0]
	v_pk_fma_f32 v[56:57], v[242:243], v[58:59], 1.0 op_sel_hi:[1,1,0] neg_lo:[1,0,0] neg_hi:[1,0,0]
	v_pk_fma_f32 v[252:253], v[250:251], v[248:249], v[252:253]
	v_pk_fma_f32 v[58:59], v[56:57], v[254:255], v[58:59]
	v_div_fixup_f32 v240, v252, v240, 1.0
	v_div_fixup_f32 v241, v253, v241, 1.0
	v_div_fixup_f32 v242, v58, v242, 1.0
	v_div_fixup_f32 v243, v59, v243, 1.0
	v_rcp_f32_e32 v248, v244
	v_rcp_f32_e32 v249, v245
	v_rcp_f32_e32 v254, v246
	v_rcp_f32_e32 v255, v247
	v_pk_fma_f32 v[250:251], v[244:245], v[248:249], 1.0 op_sel_hi:[1,1,0] neg_lo:[1,0,0] neg_hi:[1,0,0]
	v_pk_fma_f32 v[56:57], v[246:247], v[254:255], 1.0 op_sel_hi:[1,1,0] neg_lo:[1,0,0] neg_hi:[1,0,0]
	v_pk_fma_f32 v[248:249], v[250:251], v[248:249], v[248:249]
	v_pk_fma_f32 v[254:255], v[56:57], v[254:255], v[254:255]
	v_pk_fma_f32 v[250:251], v[244:245], v[248:249], 1.0 op_sel_hi:[1,1,0] neg_lo:[1,0,0] neg_hi:[1,0,0]
	v_pk_fma_f32 v[56:57], v[246:247], v[254:255], 1.0 op_sel_hi:[1,1,0] neg_lo:[1,0,0] neg_hi:[1,0,0]
	v_pk_fma_f32 v[252:253], v[250:251], v[248:249], v[248:249]
	v_pk_fma_f32 v[58:59], v[56:57], v[254:255], v[254:255]
	v_pk_fma_f32 v[250:251], v[244:245], v[252:253], 1.0 op_sel_hi:[1,1,0] neg_lo:[1,0,0] neg_hi:[1,0,0]
	v_pk_fma_f32 v[56:57], v[246:247], v[58:59], 1.0 op_sel_hi:[1,1,0] neg_lo:[1,0,0] neg_hi:[1,0,0]
	v_pk_fma_f32 v[252:253], v[250:251], v[248:249], v[252:253]
	v_pk_fma_f32 v[58:59], v[56:57], v[254:255], v[58:59]
	v_div_fixup_f32 v244, v252, v244, 1.0
	v_div_fixup_f32 v245, v253, v245, 1.0
	v_div_fixup_f32 v246, v58, v246, 1.0
	v_div_fixup_f32 v247, v59, v247, 1.0
	v_lshlrev_b32_e32 v68, 16, v60
	v_and_b32_e32 v69, 0xffff0000, v60
	v_lshlrev_b32_e32 v70, 16, v62
	v_and_b32_e32 v71, 0xffff0000, v62
	v_lshlrev_b32_e32 v62, 16, v63
	v_and_b32_e32 v63, 0xffff0000, v63
	v_lshlrev_b32_e32 v60, 16, v61
	v_and_b32_e32 v61, 0xffff0000, v61
	v_pk_fma_f32 v[52:53], v[52:53], v[242:243], v[68:69]
	v_pk_fma_f32 v[56:57], v[50:51], v[246:247], v[62:63]
	v_pk_fma_f32 v[50:51], v[48:49], v[240:241], v[70:71]
	v_cvt_pk_bf16_f32 v48, v52, v53
	v_pk_fma_f32 v[54:55], v[54:55], v[244:245], v[60:61]
	s_nop 0
	v_cvt_pk_bf16_f32 v49, v54, v55
	v_cvt_pk_bf16_f32 v50, v50, v51
	v_cvt_pk_bf16_f32 v51, v56, v57
	buffer_store_dwordx4 v[48:51], v72, s[20:23], 0 offen offset:256 sc1
	s_nop 1
	v_add_u32_e32 v48, 0x4090, v158
	v_mad_i64_i32 v[50:51], s[6:7], v48, s73, 0
	v_lshl_add_u64 v[48:49], v[50:51], 1, s[34:35]
	v_lshl_add_u64 v[48:49], v[48:49], 0, v[142:143]
	v_add_co_u32_e32 v52, vcc, s74, v48
	s_nop 1
	v_addc_co_u32_e32 v53, vcc, 0, v49, vcc
	s_waitcnt vmcnt(7)
; __device__ __forceinline__ float sigmoidf_(float x) { return 1.0f / (1.0f + __expf(-x)); }
; __device__ __forceinline__ u32x4 pack8(const f32x4 v0, const f32x4 v1) { u32x4 w; w.x = pk2(v0[0], v0[1]); w.y = pk2(v0[2], v0[3]); w.z = pk2(v1[0], v1[1]); w.w = pk2(v1[2], v1[3]); return w; }
; __device__ __forceinline__ void unpack8(const u32x4 w, f32x4& v0, f32x4& v1) { v0 = (f32x4){bflo(w.x), bfhi(w.x), bflo(w.y), bfhi(w.y)}; v1 = (f32x4){bflo(w.z), bfhi(w.z), bflo(w.w), bfhi(w.w)}; }
;     __device__ __forceinline__ void operator()(const f32x4 (&acc)[2][2][4][2], const Unit& u, int wr, int wc, int fr, int fq) const {
;     ...
;                 for (int bj = 0; bj < 2; ++bj) {
;                     const u32x4 gw = *(const u32x4*)(rowp + O_GA + bj * 128);
;                     f32x4 g0, g1; unpack8(gw, g0, g1);
;                     f32x4 v0, v1;
; #pragma unroll
;                     for (int j = 0; j < 4; ++j) { v0[j] = sigmoidf_(g0[j]) * acc[ai][bj][m][0][j]; v1[j] = sigmoidf_(g1[j]) * acc[ai][bj][m][1][j]; }
;                     const u32x4 mw = *(const u32x4*)(rowp + bj * 128); f32x4 m0, m1; unpack8(mw, m0, m1); v0 += m0; v1 += m1;
;                     __builtin_amdgcn_raw_buffer_store_b128(pack8(v0, v1), rsrc, (unsigned)(((size_t)row * DIN + col0 + bj * 128) * 2), 0, 16  ); }
	v_mov_b32_e32 v54, v208
	v_mov_b32_e32 v55, v209
	v_mov_b32_e32 v56, v210
	v_mov_b32_e32 v57, v211
	v_mov_b32_e32 v58, v212
	v_mov_b32_e32 v59, v213
	v_mov_b32_e32 v60, v214
	v_mov_b32_e32 v61, v215
	v_add_u32_e32 v198, 0x155300, v197
	global_load_dwordx4 v[208:211], v198, s[34:35]
	v_add_u32_e32 v198, 0x154100, v197
	global_load_dwordx4 v[212:215], v198, s[34:35]
	s_mov_b32 s100, 0xbfb8aa3b
	v_lshlrev_b32_e32 v240, 16, v54
	v_and_b32_e32 v241, 0xffff0000, v54
	v_lshlrev_b32_e32 v242, 16, v56
	v_and_b32_e32 v243, 0xffff0000, v56
	v_lshlrev_b32_e32 v244, 16, v55
	v_and_b32_e32 v245, 0xffff0000, v55
	v_lshlrev_b32_e32 v246, 16, v57
	v_and_b32_e32 v247, 0xffff0000, v57
	v_pk_mul_f32 v[240:241], v[240:241], s[100:101] op_sel_hi:[1,0]
	v_pk_mul_f32 v[242:243], v[242:243], s[100:101] op_sel_hi:[1,0]
	v_pk_mul_f32 v[244:245], v[244:245], s[100:101] op_sel_hi:[1,0]
	v_pk_mul_f32 v[246:247], v[246:247], s[100:101] op_sel_hi:[1,0]
	v_exp_f32_e32 v240, v240
	v_exp_f32_e32 v241, v241
	v_exp_f32_e32 v242, v242
	v_exp_f32_e32 v243, v243
	v_exp_f32_e32 v244, v244
	v_exp_f32_e32 v245, v245
	v_exp_f32_e32 v246, v246
	v_exp_f32_e32 v247, v247
	s_nop 0
	v_pk_add_f32 v[240:241], v[240:241], 1.0 op_sel_hi:[1,0]
	v_pk_add_f32 v[242:243], v[242:243], 1.0 op_sel_hi:[1,0]
	v_pk_add_f32 v[244:245], v[244:245], 1.0 op_sel_hi:[1,0]
	v_pk_add_f32 v[246:247], v[246:247], 1.0 op_sel_hi:[1,0]
	v_rcp_f32_e32 v248, v240
	v_rcp_f32_e32 v249, v241
	v_rcp_f32_e32 v254, v242
	v_rcp_f32_e32 v255, v243
	v_pk_fma_f32 v[250:251], v[240:241], v[248:249], 1.0 op_sel_hi:[1,1,0] neg_lo:[1,0,0] neg_hi:[1,0,0]
	v_pk_fma_f32 v[54:55], v[242:243], v[254:255], 1.0 op_sel_hi:[1,1,0] neg_lo:[1,0,0] neg_hi:[1,0,0]
	v_pk_fma_f32 v[248:249], v[250:251], v[248:249], v[248:249]
	v_pk_fma_f32 v[254:255], v[54:55], v[254:255], v[254:255]
	v_pk_fma_f32 v[250:251], v[240:241], v[248:249], 1.0 op_sel_hi:[1,1,0] neg_lo:[1,0,0] neg_hi:[1,0,0]
	v_pk_fma_f32 v[54:55], v[242:243], v[254:255], 1.0 op_sel_hi:[1,1,0] neg_lo:[1,0,0] neg_hi:[1,0,0]
	v_pk_fma_f32 v[252:253], v[250:251], v[248:249], v[248:249]
	v_pk_fma_f32 v[56:57], v[54:55], v[254:255], v[254:255]
	v_pk_fma_f32 v[250:251], v[240:241], v[252:253], 1.0 op_sel_hi:[1,1,0] neg_lo:[1,0,0] neg_hi:[1,0,0]
	v_pk_fma_f32 v[54:55], v[242:243], v[56:57], 1.0 op_sel_hi:[1,1,0] neg_lo:[1,0,0] neg_hi:[1,0,0]
	v_pk_fma_f32 v[252:253], v[250:251], v[248:249], v[252:253]
	v_pk_fma_f32 v[56:57], v[54:55], v[254:255], v[56:57]
	v_div_fixup_f32 v240, v252, v240, 1.0
	v_div_fixup_f32 v241, v253, v241, 1.0
	v_div_fixup_f32 v242, v56, v242, 1.0
	v_div_fixup_f32 v243, v57, v243, 1.0
	v_rcp_f32_e32 v248, v244
	v_rcp_f32_e32 v249, v245
	v_rcp_f32_e32 v254, v246
	v_rcp_f32_e32 v255, v247
	v_pk_fma_f32 v[250:251], v[244:245], v[248:249], 1.0 op_sel_hi:[1,1,0] neg_lo:[1,0,0] neg_hi:[1,0,0]
	v_pk_fma_f32 v[54:55], v[246:247], v[254:255], 1.0 op_sel_hi:[1,1,0] neg_lo:[1,0,0] neg_hi:[1,0,0]
	v_pk_fma_f32 v[248:249], v[250:251], v[248:249], v[248:249]
	v_pk_fma_f32 v[254:255], v[54:55], v[254:255], v[254:255]
	v_pk_fma_f32 v[250:251], v[244:245], v[248:249], 1.0 op_sel_hi:[1,1,0] neg_lo:[1,0,0] neg_hi:[1,0,0]
	v_pk_fma_f32 v[54:55], v[246:247], v[254:255], 1.0 op_sel_hi:[1,1,0] neg_lo:[1,0,0] neg_hi:[1,0,0]
	v_pk_fma_f32 v[252:253], v[250:251], v[248:249], v[248:249]
	v_pk_fma_f32 v[56:57], v[54:55], v[254:255], v[254:255]
	v_pk_fma_f32 v[250:251], v[244:245], v[252:253], 1.0 op_sel_hi:[1,1,0] neg_lo:[1,0,0] neg_hi:[1,0,0]
	v_pk_fma_f32 v[54:55], v[246:247], v[56:57], 1.0 op_sel_hi:[1,1,0] neg_lo:[1,0,0] neg_hi:[1,0,0]
	v_pk_fma_f32 v[252:253], v[250:251], v[248:249], v[252:253]
	v_pk_fma_f32 v[56:57], v[54:55], v[254:255], v[56:57]
	v_div_fixup_f32 v244, v252, v244, 1.0
	v_div_fixup_f32 v245, v253, v245, 1.0
	v_div_fixup_f32 v246, v56, v246, 1.0
	v_div_fixup_f32 v247, v57, v247, 1.0
	v_lshlrev_b32_e32 v66, 16, v58
	v_and_b32_e32 v67, 0xffff0000, v58
	v_lshlrev_b32_e32 v68, 16, v60
	v_and_b32_e32 v69, 0xffff0000, v60
	v_lshlrev_b32_e32 v60, 16, v61
	v_and_b32_e32 v61, 0xffff0000, v61
	v_lshlrev_b32_e32 v58, 16, v59
	v_and_b32_e32 v59, 0xffff0000, v59
	v_pk_fma_f32 v[44:45], v[44:45], v[240:241], v[66:67]
	v_pk_fma_f32 v[54:55], v[42:43], v[246:247], v[60:61]
	v_pk_fma_f32 v[42:43], v[40:41], v[242:243], v[68:69]
	v_add_lshl_u32 v56, v140, v50, 1
	v_pk_fma_f32 v[46:47], v[46:47], v[244:245], v[58:59]
	v_cvt_pk_bf16_f32 v40, v44, v45
	s_nop 0
	v_cvt_pk_bf16_f32 v41, v46, v47
	v_cvt_pk_bf16_f32 v42, v42, v43
	v_cvt_pk_bf16_f32 v43, v54, v55
	buffer_store_dwordx4 v[40:43], v56, s[20:23], 0 offen sc1
	s_nop 0
	s_waitcnt vmcnt(7)
; __device__ __forceinline__ float sigmoidf_(float x) { return 1.0f / (1.0f + __expf(-x)); }
; __device__ __forceinline__ u32x4 pack8(const f32x4 v0, const f32x4 v1) { u32x4 w; w.x = pk2(v0[0], v0[1]); w.y = pk2(v0[2], v0[3]); w.z = pk2(v1[0], v1[1]); w.w = pk2(v1[2], v1[3]); return w; }
; __device__ __forceinline__ void unpack8(const u32x4 w, f32x4& v0, f32x4& v1) { v0 = (f32x4){bflo(w.x), bfhi(w.x), bflo(w.y), bfhi(w.y)}; v1 = (f32x4){bflo(w.z), bfhi(w.z), bflo(w.w), bfhi(w.w)}; }
;     __device__ __forceinline__ void operator()(const f32x4 (&acc)[2][2][4][2], const Unit& u, int wr, int wc, int fr, int fq) const {
;     ...
;                 const int row = row0 + ai * 128 + m * 16;
;                 const bf16_t* rowp = z + (size_t)row * DIN + col0;
; #pragma unroll
;                 for (int bj = 0; bj < 2; ++bj) {
;                     const u32x4 gw = *(const u32x4*)(rowp + O_GA + bj * 128);
;                     f32x4 g0, g1; unpack8(gw, g0, g1);
;                     f32x4 v0, v1;
; #pragma unroll
;                     for (int j = 0; j < 4; ++j) { v0[j] = sigmoidf_(g0[j]) * acc[ai][bj][m][0][j]; v1[j] = sigmoidf_(g1[j]) * acc[ai][bj][m][1][j]; }
;                     const u32x4 mw = *(const u32x4*)(rowp + bj * 128); f32x4 m0, m1; unpack8(mw, m0, m1); v0 += m0; v1 += m1;
;                     __builtin_amdgcn_raw_buffer_store_b128(pack8(v0, v1), rsrc, (unsigned)(((size_t)row * DIN + col0 + bj * 128) * 2), 0, 16  ); }
	v_mov_b32_e32 v40, v232
	v_mov_b32_e32 v41, v233
	v_mov_b32_e32 v42, v234
	v_mov_b32_e32 v43, v235
	v_mov_b32_e32 v44, v236
	v_mov_b32_e32 v45, v237
	v_mov_b32_e32 v46, v238
	v_mov_b32_e32 v47, v239
	v_add_u32_e32 v198, 0x177200, v197
	global_load_dwordx4 v[232:235], v198, s[34:35]
	v_add_u32_e32 v198, 0x176000, v197
	global_load_dwordx4 v[236:239], v198, s[34:35]
	s_mov_b32 s100, 0xbfb8aa3b
	v_lshlrev_b32_e32 v240, 16, v42
	v_and_b32_e32 v241, 0xffff0000, v42
	v_lshlrev_b32_e32 v242, 16, v40
	v_and_b32_e32 v243, 0xffff0000, v40
	v_lshlrev_b32_e32 v244, 16, v41
	v_and_b32_e32 v245, 0xffff0000, v41
	v_lshlrev_b32_e32 v246, 16, v43
	v_and_b32_e32 v247, 0xffff0000, v43
	v_pk_mul_f32 v[240:241], v[240:241], s[100:101] op_sel_hi:[1,0]
	v_pk_mul_f32 v[242:243], v[242:243], s[100:101] op_sel_hi:[1,0]
	v_pk_mul_f32 v[244:245], v[244:245], s[100:101] op_sel_hi:[1,0]
	v_pk_mul_f32 v[246:247], v[246:247], s[100:101] op_sel_hi:[1,0]
	v_exp_f32_e32 v240, v240
	v_exp_f32_e32 v241, v241
	v_exp_f32_e32 v242, v242
	v_exp_f32_e32 v243, v243
	v_exp_f32_e32 v244, v244
	v_exp_f32_e32 v245, v245
	v_exp_f32_e32 v246, v246
	v_exp_f32_e32 v247, v247
	s_nop 0
	v_pk_add_f32 v[240:241], v[240:241], 1.0 op_sel_hi:[1,0]
	v_pk_add_f32 v[242:243], v[242:243], 1.0 op_sel_hi:[1,0]
	v_pk_add_f32 v[244:245], v[244:245], 1.0 op_sel_hi:[1,0]
	v_pk_add_f32 v[246:247], v[246:247], 1.0 op_sel_hi:[1,0]
	v_rcp_f32_e32 v248, v240
	v_rcp_f32_e32 v249, v241
	v_rcp_f32_e32 v254, v242
	v_rcp_f32_e32 v255, v243
	v_pk_fma_f32 v[250:251], v[240:241], v[248:249], 1.0 op_sel_hi:[1,1,0] neg_lo:[1,0,0] neg_hi:[1,0,0]
	v_pk_fma_f32 v[40:41], v[242:243], v[254:255], 1.0 op_sel_hi:[1,1,0] neg_lo:[1,0,0] neg_hi:[1,0,0]
	v_pk_fma_f32 v[248:249], v[250:251], v[248:249], v[248:249]
	v_pk_fma_f32 v[254:255], v[40:41], v[254:255], v[254:255]
	v_pk_fma_f32 v[250:251], v[240:241], v[248:249], 1.0 op_sel_hi:[1,1,0] neg_lo:[1,0,0] neg_hi:[1,0,0]
	v_pk_fma_f32 v[40:41], v[242:243], v[254:255], 1.0 op_sel_hi:[1,1,0] neg_lo:[1,0,0] neg_hi:[1,0,0]
	v_pk_fma_f32 v[252:253], v[250:251], v[248:249], v[248:249]
	v_pk_fma_f32 v[42:43], v[40:41], v[254:255], v[254:255]
	v_pk_fma_f32 v[250:251], v[240:241], v[252:253], 1.0 op_sel_hi:[1,1,0] neg_lo:[1,0,0] neg_hi:[1,0,0]
	v_pk_fma_f32 v[40:41], v[242:243], v[42:43], 1.0 op_sel_hi:[1,1,0] neg_lo:[1,0,0] neg_hi:[1,0,0]
	v_pk_fma_f32 v[252:253], v[250:251], v[248:249], v[252:253]
	v_pk_fma_f32 v[42:43], v[40:41], v[254:255], v[42:43]
	v_div_fixup_f32 v240, v252, v240, 1.0
	v_div_fixup_f32 v241, v253, v241, 1.0
	v_div_fixup_f32 v242, v42, v242, 1.0
	v_div_fixup_f32 v243, v43, v243, 1.0
	v_rcp_f32_e32 v248, v244
	v_rcp_f32_e32 v249, v245
	v_rcp_f32_e32 v254, v246
	v_rcp_f32_e32 v255, v247
	v_pk_fma_f32 v[250:251], v[244:245], v[248:249], 1.0 op_sel_hi:[1,1,0] neg_lo:[1,0,0] neg_hi:[1,0,0]
	v_pk_fma_f32 v[40:41], v[246:247], v[254:255], 1.0 op_sel_hi:[1,1,0] neg_lo:[1,0,0] neg_hi:[1,0,0]
	v_pk_fma_f32 v[248:249], v[250:251], v[248:249], v[248:249]
	v_pk_fma_f32 v[254:255], v[40:41], v[254:255], v[254:255]
	v_pk_fma_f32 v[250:251], v[244:245], v[248:249], 1.0 op_sel_hi:[1,1,0] neg_lo:[1,0,0] neg_hi:[1,0,0]
	v_pk_fma_f32 v[40:41], v[246:247], v[254:255], 1.0 op_sel_hi:[1,1,0] neg_lo:[1,0,0] neg_hi:[1,0,0]
	v_pk_fma_f32 v[252:253], v[250:251], v[248:249], v[248:249]
	v_pk_fma_f32 v[42:43], v[40:41], v[254:255], v[254:255]
	v_pk_fma_f32 v[250:251], v[244:245], v[252:253], 1.0 op_sel_hi:[1,1,0] neg_lo:[1,0,0] neg_hi:[1,0,0]
	v_pk_fma_f32 v[40:41], v[246:247], v[42:43], 1.0 op_sel_hi:[1,1,0] neg_lo:[1,0,0] neg_hi:[1,0,0]
	v_pk_fma_f32 v[252:253], v[250:251], v[248:249], v[252:253]
	v_pk_fma_f32 v[42:43], v[40:41], v[254:255], v[42:43]
	v_div_fixup_f32 v244, v252, v244, 1.0
	v_div_fixup_f32 v245, v253, v245, 1.0
	v_div_fixup_f32 v246, v42, v246, 1.0
	v_div_fixup_f32 v247, v43, v247, 1.0
	v_lshlrev_b32_e32 v52, 16, v44
	v_and_b32_e32 v53, 0xffff0000, v44
	v_lshlrev_b32_e32 v54, 16, v46
	v_and_b32_e32 v55, 0xffff0000, v46
	v_lshlrev_b32_e32 v46, 16, v47
	v_and_b32_e32 v47, 0xffff0000, v47
	v_lshlrev_b32_e32 v44, 16, v45
	v_and_b32_e32 v45, 0xffff0000, v45
	v_pk_fma_f32 v[36:37], v[36:37], v[242:243], v[52:53]
	v_pk_fma_f32 v[40:41], v[34:35], v[246:247], v[46:47]
	v_pk_fma_f32 v[34:35], v[32:33], v[240:241], v[54:55]
	v_cvt_pk_bf16_f32 v32, v36, v37
	v_pk_fma_f32 v[38:39], v[38:39], v[244:245], v[44:45]
	s_nop 0
	v_cvt_pk_bf16_f32 v33, v38, v39
	v_cvt_pk_bf16_f32 v34, v34, v35
	v_cvt_pk_bf16_f32 v35, v40, v41
	buffer_store_dwordx4 v[32:35], v56, s[20:23], 0 offen offset:256 sc1
	s_nop 1
	v_add_u32_e32 v32, 0x40a0, v158
	v_mad_i64_i32 v[34:35], s[6:7], v32, s73, 0
	v_lshl_add_u64 v[32:33], v[34:35], 1, s[34:35]
	v_lshl_add_u64 v[32:33], v[32:33], 0, v[142:143]
	v_add_co_u32_e32 v36, vcc, s74, v32
	s_nop 1
	v_addc_co_u32_e32 v37, vcc, 0, v33, vcc
	s_waitcnt vmcnt(7)
; __device__ __forceinline__ float sigmoidf_(float x) { return 1.0f / (1.0f + __expf(-x)); }
; __device__ __forceinline__ u32x4 pack8(const f32x4 v0, const f32x4 v1) { u32x4 w; w.x = pk2(v0[0], v0[1]); w.y = pk2(v0[2], v0[3]); w.z = pk2(v1[0], v1[1]); w.w = pk2(v1[2], v1[3]); return w; }
; __device__ __forceinline__ void unpack8(const u32x4 w, f32x4& v0, f32x4& v1) { v0 = (f32x4){bflo(w.x), bfhi(w.x), bflo(w.y), bfhi(w.y)}; v1 = (f32x4){bflo(w.z), bfhi(w.z), bflo(w.w), bfhi(w.w)}; }
;     __device__ __forceinline__ void operator()(const f32x4 (&acc)[2][2][4][2], const Unit& u, int wr, int wc, int fr, int fq) const {
;     ...
;                 for (int bj = 0; bj < 2; ++bj) {
;                     const u32x4 gw = *(const u32x4*)(rowp + O_GA + bj * 128);
;                     f32x4 g0, g1; unpack8(gw, g0, g1);
;                     f32x4 v0, v1;
; #pragma unroll
;                     for (int j = 0; j < 4; ++j) { v0[j] = sigmoidf_(g0[j]) * acc[ai][bj][m][0][j]; v1[j] = sigmoidf_(g1[j]) * acc[ai][bj][m][1][j]; }
;                     const u32x4 mw = *(const u32x4*)(rowp + bj * 128); f32x4 m0, m1; unpack8(mw, m0, m1); v0 += m0; v1 += m1;
;                     __builtin_amdgcn_raw_buffer_store_b128(pack8(v0, v1), rsrc, (unsigned)(((size_t)row * DIN + col0 + bj * 128) * 2), 0, 16  ); }
	v_mov_b32_e32 v38, v200
	v_mov_b32_e32 v39, v201
	v_mov_b32_e32 v40, v202
	v_mov_b32_e32 v41, v203
	v_mov_b32_e32 v42, v204
	v_mov_b32_e32 v43, v205
	v_mov_b32_e32 v44, v206
	v_mov_b32_e32 v45, v207
	v_add_u32_e32 v198, 0x177300, v197
	global_load_dwordx4 v[200:203], v198, s[34:35]
	v_add_u32_e32 v198, 0x176100, v197
	global_load_dwordx4 v[204:207], v198, s[34:35]
	s_mov_b32 s100, 0xbfb8aa3b
	v_lshlrev_b32_e32 v240, 16, v38
	v_and_b32_e32 v241, 0xffff0000, v38
	v_lshlrev_b32_e32 v242, 16, v40
	v_and_b32_e32 v243, 0xffff0000, v40
	v_lshlrev_b32_e32 v244, 16, v39
	v_and_b32_e32 v245, 0xffff0000, v39
	v_lshlrev_b32_e32 v246, 16, v41
	v_and_b32_e32 v247, 0xffff0000, v41
	v_pk_mul_f32 v[240:241], v[240:241], s[100:101] op_sel_hi:[1,0]
	v_pk_mul_f32 v[242:243], v[242:243], s[100:101] op_sel_hi:[1,0]
	v_pk_mul_f32 v[244:245], v[244:245], s[100:101] op_sel_hi:[1,0]
	v_pk_mul_f32 v[246:247], v[246:247], s[100:101] op_sel_hi:[1,0]
	v_exp_f32_e32 v240, v240
	v_exp_f32_e32 v241, v241
	v_exp_f32_e32 v242, v242
	v_exp_f32_e32 v243, v243
	v_exp_f32_e32 v244, v244
	v_exp_f32_e32 v245, v245
	v_exp_f32_e32 v246, v246
	v_exp_f32_e32 v247, v247
	s_nop 0
	v_pk_add_f32 v[240:241], v[240:241], 1.0 op_sel_hi:[1,0]
	v_pk_add_f32 v[242:243], v[242:243], 1.0 op_sel_hi:[1,0]
	v_pk_add_f32 v[244:245], v[244:245], 1.0 op_sel_hi:[1,0]
	v_pk_add_f32 v[246:247], v[246:247], 1.0 op_sel_hi:[1,0]
	v_rcp_f32_e32 v248, v240
	v_rcp_f32_e32 v249, v241
	v_rcp_f32_e32 v254, v242
	v_rcp_f32_e32 v255, v243
	v_pk_fma_f32 v[250:251], v[240:241], v[248:249], 1.0 op_sel_hi:[1,1,0] neg_lo:[1,0,0] neg_hi:[1,0,0]
	v_pk_fma_f32 v[38:39], v[242:243], v[254:255], 1.0 op_sel_hi:[1,1,0] neg_lo:[1,0,0] neg_hi:[1,0,0]
	v_pk_fma_f32 v[248:249], v[250:251], v[248:249], v[248:249]
	v_pk_fma_f32 v[254:255], v[38:39], v[254:255], v[254:255]
	v_pk_fma_f32 v[250:251], v[240:241], v[248:249], 1.0 op_sel_hi:[1,1,0] neg_lo:[1,0,0] neg_hi:[1,0,0]
	v_pk_fma_f32 v[38:39], v[242:243], v[254:255], 1.0 op_sel_hi:[1,1,0] neg_lo:[1,0,0] neg_hi:[1,0,0]
	v_pk_fma_f32 v[252:253], v[250:251], v[248:249], v[248:249]
	v_pk_fma_f32 v[40:41], v[38:39], v[254:255], v[254:255]
	v_pk_fma_f32 v[250:251], v[240:241], v[252:253], 1.0 op_sel_hi:[1,1,0] neg_lo:[1,0,0] neg_hi:[1,0,0]
	v_pk_fma_f32 v[38:39], v[242:243], v[40:41], 1.0 op_sel_hi:[1,1,0] neg_lo:[1,0,0] neg_hi:[1,0,0]
	v_pk_fma_f32 v[252:253], v[250:251], v[248:249], v[252:253]
	v_pk_fma_f32 v[40:41], v[38:39], v[254:255], v[40:41]
	v_div_fixup_f32 v240, v252, v240, 1.0
	v_div_fixup_f32 v241, v253, v241, 1.0
	v_div_fixup_f32 v242, v40, v242, 1.0
	v_div_fixup_f32 v243, v41, v243, 1.0
	v_rcp_f32_e32 v248, v244
	v_rcp_f32_e32 v249, v245
	v_rcp_f32_e32 v254, v246
	v_rcp_f32_e32 v255, v247
	v_pk_fma_f32 v[250:251], v[244:245], v[248:249], 1.0 op_sel_hi:[1,1,0] neg_lo:[1,0,0] neg_hi:[1,0,0]
	v_pk_fma_f32 v[38:39], v[246:247], v[254:255], 1.0 op_sel_hi:[1,1,0] neg_lo:[1,0,0] neg_hi:[1,0,0]
	v_pk_fma_f32 v[248:249], v[250:251], v[248:249], v[248:249]
	v_pk_fma_f32 v[254:255], v[38:39], v[254:255], v[254:255]
	v_pk_fma_f32 v[250:251], v[244:245], v[248:249], 1.0 op_sel_hi:[1,1,0] neg_lo:[1,0,0] neg_hi:[1,0,0]
	v_pk_fma_f32 v[38:39], v[246:247], v[254:255], 1.0 op_sel_hi:[1,1,0] neg_lo:[1,0,0] neg_hi:[1,0,0]
	v_pk_fma_f32 v[252:253], v[250:251], v[248:249], v[248:249]
	v_pk_fma_f32 v[40:41], v[38:39], v[254:255], v[254:255]
	v_pk_fma_f32 v[250:251], v[244:245], v[252:253], 1.0 op_sel_hi:[1,1,0] neg_lo:[1,0,0] neg_hi:[1,0,0]
	v_pk_fma_f32 v[38:39], v[246:247], v[40:41], 1.0 op_sel_hi:[1,1,0] neg_lo:[1,0,0] neg_hi:[1,0,0]
	v_pk_fma_f32 v[252:253], v[250:251], v[248:249], v[252:253]
	v_pk_fma_f32 v[40:41], v[38:39], v[254:255], v[40:41]
	v_div_fixup_f32 v244, v252, v244, 1.0
	v_div_fixup_f32 v245, v253, v245, 1.0
	v_div_fixup_f32 v246, v40, v246, 1.0
	v_div_fixup_f32 v247, v41, v247, 1.0
	v_lshlrev_b32_e32 v50, 16, v42
	v_and_b32_e32 v51, 0xffff0000, v42
	v_lshlrev_b32_e32 v52, 16, v44
	v_and_b32_e32 v53, 0xffff0000, v44
	v_lshlrev_b32_e32 v44, 16, v45
	v_and_b32_e32 v45, 0xffff0000, v45
	v_lshlrev_b32_e32 v42, 16, v43
	v_and_b32_e32 v43, 0xffff0000, v43
	v_pk_fma_f32 v[28:29], v[28:29], v[240:241], v[50:51]
	v_pk_fma_f32 v[38:39], v[26:27], v[246:247], v[44:45]
	v_pk_fma_f32 v[26:27], v[24:25], v[242:243], v[52:53]
	v_add_lshl_u32 v40, v140, v34, 1
	v_pk_fma_f32 v[30:31], v[30:31], v[244:245], v[42:43]
	v_cvt_pk_bf16_f32 v24, v28, v29
	s_nop 0
	v_cvt_pk_bf16_f32 v25, v30, v31
	v_cvt_pk_bf16_f32 v26, v26, v27
	v_cvt_pk_bf16_f32 v27, v38, v39
	buffer_store_dwordx4 v[24:27], v40, s[20:23], 0 offen sc1
	s_nop 0
	s_waitcnt vmcnt(7)
; __device__ __forceinline__ float sigmoidf_(float x) { return 1.0f / (1.0f + __expf(-x)); }
; __device__ __forceinline__ u32x4 pack8(const f32x4 v0, const f32x4 v1) { u32x4 w; w.x = pk2(v0[0], v0[1]); w.y = pk2(v0[2], v0[3]); w.z = pk2(v1[0], v1[1]); w.w = pk2(v1[2], v1[3]); return w; }
; __device__ __forceinline__ void unpack8(const u32x4 w, f32x4& v0, f32x4& v1) { v0 = (f32x4){bflo(w.x), bfhi(w.x), bflo(w.y), bfhi(w.y)}; v1 = (f32x4){bflo(w.z), bfhi(w.z), bflo(w.w), bfhi(w.w)}; }
;     __device__ __forceinline__ void operator()(const f32x4 (&acc)[2][2][4][2], const Unit& u, int wr, int wc, int fr, int fq) const {
;     ...
;                 for (int bj = 0; bj < 2; ++bj) {
;                     const u32x4 gw = *(const u32x4*)(rowp + O_GA + bj * 128);
;                     f32x4 g0, g1; unpack8(gw, g0, g1);
;                     f32x4 v0, v1;
; #pragma unroll
;                     for (int j = 0; j < 4; ++j) { v0[j] = sigmoidf_(g0[j]) * acc[ai][bj][m][0][j]; v1[j] = sigmoidf_(g1[j]) * acc[ai][bj][m][1][j]; }
;                     const u32x4 mw = *(const u32x4*)(rowp + bj * 128); f32x4 m0, m1; unpack8(mw, m0, m1); v0 += m0; v1 += m1;
;                     __builtin_amdgcn_raw_buffer_store_b128(pack8(v0, v1), rsrc, (unsigned)(((size_t)row * DIN + col0 + bj * 128) * 2), 0, 16  ); }
	v_mov_b32_e32 v24, v208
	v_mov_b32_e32 v25, v209
	v_mov_b32_e32 v26, v210
	v_mov_b32_e32 v27, v211
	v_mov_b32_e32 v28, v212
	v_mov_b32_e32 v29, v213
	v_mov_b32_e32 v30, v214
	v_mov_b32_e32 v31, v215
	s_mov_b32 s100, 0xbfb8aa3b
	v_lshlrev_b32_e32 v240, 16, v26
	v_and_b32_e32 v241, 0xffff0000, v26
	v_lshlrev_b32_e32 v242, 16, v24
	v_and_b32_e32 v243, 0xffff0000, v24
	v_lshlrev_b32_e32 v244, 16, v25
	v_and_b32_e32 v245, 0xffff0000, v25
	v_lshlrev_b32_e32 v246, 16, v27
	v_and_b32_e32 v247, 0xffff0000, v27
	v_pk_mul_f32 v[240:241], v[240:241], s[100:101] op_sel_hi:[1,0]
	v_pk_mul_f32 v[242:243], v[242:243], s[100:101] op_sel_hi:[1,0]
	v_pk_mul_f32 v[244:245], v[244:245], s[100:101] op_sel_hi:[1,0]
	v_pk_mul_f32 v[246:247], v[246:247], s[100:101] op_sel_hi:[1,0]
	v_exp_f32_e32 v240, v240
	v_exp_f32_e32 v241, v241
	v_exp_f32_e32 v242, v242
	v_exp_f32_e32 v243, v243
	v_exp_f32_e32 v244, v244
	v_exp_f32_e32 v245, v245
	v_exp_f32_e32 v246, v246
	v_exp_f32_e32 v247, v247
	s_nop 0
	v_pk_add_f32 v[240:241], v[240:241], 1.0 op_sel_hi:[1,0]
	v_pk_add_f32 v[242:243], v[242:243], 1.0 op_sel_hi:[1,0]
	v_pk_add_f32 v[244:245], v[244:245], 1.0 op_sel_hi:[1,0]
	v_pk_add_f32 v[246:247], v[246:247], 1.0 op_sel_hi:[1,0]
	v_rcp_f32_e32 v248, v240
	v_rcp_f32_e32 v249, v241
	v_rcp_f32_e32 v254, v242
	v_rcp_f32_e32 v255, v243
	v_pk_fma_f32 v[250:251], v[240:241], v[248:249], 1.0 op_sel_hi:[1,1,0] neg_lo:[1,0,0] neg_hi:[1,0,0]
	v_pk_fma_f32 v[24:25], v[242:243], v[254:255], 1.0 op_sel_hi:[1,1,0] neg_lo:[1,0,0] neg_hi:[1,0,0]
	v_pk_fma_f32 v[248:249], v[250:251], v[248:249], v[248:249]
	v_pk_fma_f32 v[254:255], v[24:25], v[254:255], v[254:255]
	v_pk_fma_f32 v[250:251], v[240:241], v[248:249], 1.0 op_sel_hi:[1,1,0] neg_lo:[1,0,0] neg_hi:[1,0,0]
	v_pk_fma_f32 v[24:25], v[242:243], v[254:255], 1.0 op_sel_hi:[1,1,0] neg_lo:[1,0,0] neg_hi:[1,0,0]
	v_pk_fma_f32 v[252:253], v[250:251], v[248:249], v[248:249]
	v_pk_fma_f32 v[26:27], v[24:25], v[254:255], v[254:255]
	v_pk_fma_f32 v[250:251], v[240:241], v[252:253], 1.0 op_sel_hi:[1,1,0] neg_lo:[1,0,0] neg_hi:[1,0,0]
	v_pk_fma_f32 v[24:25], v[242:243], v[26:27], 1.0 op_sel_hi:[1,1,0] neg_lo:[1,0,0] neg_hi:[1,0,0]
	v_pk_fma_f32 v[252:253], v[250:251], v[248:249], v[252:253]
	v_pk_fma_f32 v[26:27], v[24:25], v[254:255], v[26:27]
	v_div_fixup_f32 v240, v252, v240, 1.0
	v_div_fixup_f32 v241, v253, v241, 1.0
	v_div_fixup_f32 v242, v26, v242, 1.0
	v_div_fixup_f32 v243, v27, v243, 1.0
	v_rcp_f32_e32 v248, v244
	v_rcp_f32_e32 v249, v245
	v_rcp_f32_e32 v254, v246
	v_rcp_f32_e32 v255, v247
	v_pk_fma_f32 v[250:251], v[244:245], v[248:249], 1.0 op_sel_hi:[1,1,0] neg_lo:[1,0,0] neg_hi:[1,0,0]
	v_pk_fma_f32 v[24:25], v[246:247], v[254:255], 1.0 op_sel_hi:[1,1,0] neg_lo:[1,0,0] neg_hi:[1,0,0]
	v_pk_fma_f32 v[248:249], v[250:251], v[248:249], v[248:249]
	v_pk_fma_f32 v[254:255], v[24:25], v[254:255], v[254:255]
	v_pk_fma_f32 v[250:251], v[244:245], v[248:249], 1.0 op_sel_hi:[1,1,0] neg_lo:[1,0,0] neg_hi:[1,0,0]
	v_pk_fma_f32 v[24:25], v[246:247], v[254:255], 1.0 op_sel_hi:[1,1,0] neg_lo:[1,0,0] neg_hi:[1,0,0]
	v_pk_fma_f32 v[252:253], v[250:251], v[248:249], v[248:249]
	v_pk_fma_f32 v[26:27], v[24:25], v[254:255], v[254:255]
	v_pk_fma_f32 v[250:251], v[244:245], v[252:253], 1.0 op_sel_hi:[1,1,0] neg_lo:[1,0,0] neg_hi:[1,0,0]
	v_pk_fma_f32 v[24:25], v[246:247], v[26:27], 1.0 op_sel_hi:[1,1,0] neg_lo:[1,0,0] neg_hi:[1,0,0]
	v_pk_fma_f32 v[252:253], v[250:251], v[248:249], v[252:253]
	v_pk_fma_f32 v[26:27], v[24:25], v[254:255], v[26:27]
	v_div_fixup_f32 v244, v252, v244, 1.0
	v_div_fixup_f32 v245, v253, v245, 1.0
	v_div_fixup_f32 v246, v26, v246, 1.0
	v_div_fixup_f32 v247, v27, v247, 1.0
	v_lshlrev_b32_e32 v36, 16, v28
	v_and_b32_e32 v37, 0xffff0000, v28
	v_lshlrev_b32_e32 v38, 16, v30
	v_and_b32_e32 v39, 0xffff0000, v30
	v_lshlrev_b32_e32 v30, 16, v31
	v_and_b32_e32 v31, 0xffff0000, v31
	v_lshlrev_b32_e32 v28, 16, v29
	v_and_b32_e32 v29, 0xffff0000, v29
	v_pk_fma_f32 v[20:21], v[20:21], v[242:243], v[36:37]
	v_pk_fma_f32 v[24:25], v[18:19], v[246:247], v[30:31]
	v_pk_fma_f32 v[18:19], v[16:17], v[240:241], v[38:39]
	v_cvt_pk_bf16_f32 v16, v20, v21
	v_pk_fma_f32 v[22:23], v[22:23], v[244:245], v[28:29]
	s_nop 0
	v_cvt_pk_bf16_f32 v17, v22, v23
	v_cvt_pk_bf16_f32 v18, v18, v19
	v_cvt_pk_bf16_f32 v19, v24, v25
	buffer_store_dwordx4 v[16:19], v40, s[20:23], 0 offen offset:256 sc1
	s_nop 1
	v_add_u32_e32 v16, 0x40b0, v158
	v_mad_i64_i32 v[18:19], s[6:7], v16, s73, 0
	v_lshl_add_u64 v[16:17], v[18:19], 1, s[34:35]
	v_lshl_add_u64 v[16:17], v[16:17], 0, v[142:143]
	v_add_co_u32_e32 v20, vcc, s74, v16
	s_nop 1
	v_addc_co_u32_e32 v21, vcc, 0, v17, vcc
	s_waitcnt vmcnt(5)
; __device__ __forceinline__ float sigmoidf_(float x) { return 1.0f / (1.0f + __expf(-x)); }
; __device__ __forceinline__ u32x4 pack8(const f32x4 v0, const f32x4 v1) { u32x4 w; w.x = pk2(v0[0], v0[1]); w.y = pk2(v0[2], v0[3]); w.z = pk2(v1[0], v1[1]); w.w = pk2(v1[2], v1[3]); return w; }
; __device__ __forceinline__ void unpack8(const u32x4 w, f32x4& v0, f32x4& v1) { v0 = (f32x4){bflo(w.x), bfhi(w.x), bflo(w.y), bfhi(w.y)}; v1 = (f32x4){bflo(w.z), bfhi(w.z), bflo(w.w), bfhi(w.w)}; }
;     __device__ __forceinline__ void operator()(const f32x4 (&acc)[2][2][4][2], const Unit& u, int wr, int wc, int fr, int fq) const {
;     ...
;                 for (int bj = 0; bj < 2; ++bj) {
;                     const u32x4 gw = *(const u32x4*)(rowp + O_GA + bj * 128);
;                     f32x4 g0, g1; unpack8(gw, g0, g1);
;                     f32x4 v0, v1;
; #pragma unroll
;                     for (int j = 0; j < 4; ++j) { v0[j] = sigmoidf_(g0[j]) * acc[ai][bj][m][0][j]; v1[j] = sigmoidf_(g1[j]) * acc[ai][bj][m][1][j]; }
;                     const u32x4 mw = *(const u32x4*)(rowp + bj * 128); f32x4 m0, m1; unpack8(mw, m0, m1); v0 += m0; v1 += m1;
;                     __builtin_amdgcn_raw_buffer_store_b128(pack8(v0, v1), rsrc, (unsigned)(((size_t)row * DIN + col0 + bj * 128) * 2), 0, 16  ); }
	v_mov_b32_e32 v22, v232
	v_mov_b32_e32 v23, v233
	v_mov_b32_e32 v24, v234
	v_mov_b32_e32 v25, v235
	v_mov_b32_e32 v26, v236
	v_mov_b32_e32 v27, v237
	v_mov_b32_e32 v28, v238
	v_mov_b32_e32 v29, v239
	s_mov_b32 s100, 0xbfb8aa3b
	v_lshlrev_b32_e32 v240, 16, v22
	v_and_b32_e32 v241, 0xffff0000, v22
	v_lshlrev_b32_e32 v242, 16, v24
	v_and_b32_e32 v243, 0xffff0000, v24
	v_lshlrev_b32_e32 v244, 16, v23
	v_and_b32_e32 v245, 0xffff0000, v23
	v_lshlrev_b32_e32 v246, 16, v25
	v_and_b32_e32 v247, 0xffff0000, v25
	v_pk_mul_f32 v[240:241], v[240:241], s[100:101] op_sel_hi:[1,0]
	v_pk_mul_f32 v[242:243], v[242:243], s[100:101] op_sel_hi:[1,0]
	v_pk_mul_f32 v[244:245], v[244:245], s[100:101] op_sel_hi:[1,0]
	v_pk_mul_f32 v[246:247], v[246:247], s[100:101] op_sel_hi:[1,0]
	v_exp_f32_e32 v240, v240
	v_exp_f32_e32 v241, v241
	v_exp_f32_e32 v242, v242
	v_exp_f32_e32 v243, v243
	v_exp_f32_e32 v244, v244
	v_exp_f32_e32 v245, v245
	v_exp_f32_e32 v246, v246
	v_exp_f32_e32 v247, v247
	s_nop 0
	v_pk_add_f32 v[240:241], v[240:241], 1.0 op_sel_hi:[1,0]
	v_pk_add_f32 v[242:243], v[242:243], 1.0 op_sel_hi:[1,0]
	v_pk_add_f32 v[244:245], v[244:245], 1.0 op_sel_hi:[1,0]
	v_pk_add_f32 v[246:247], v[246:247], 1.0 op_sel_hi:[1,0]
	v_rcp_f32_e32 v248, v240
	v_rcp_f32_e32 v249, v241
	v_rcp_f32_e32 v254, v242
	v_rcp_f32_e32 v255, v243
	v_pk_fma_f32 v[250:251], v[240:241], v[248:249], 1.0 op_sel_hi:[1,1,0] neg_lo:[1,0,0] neg_hi:[1,0,0]
	v_pk_fma_f32 v[22:23], v[242:243], v[254:255], 1.0 op_sel_hi:[1,1,0] neg_lo:[1,0,0] neg_hi:[1,0,0]
	v_pk_fma_f32 v[248:249], v[250:251], v[248:249], v[248:249]
	v_pk_fma_f32 v[254:255], v[22:23], v[254:255], v[254:255]
	v_pk_fma_f32 v[250:251], v[240:241], v[248:249], 1.0 op_sel_hi:[1,1,0] neg_lo:[1,0,0] neg_hi:[1,0,0]
	v_pk_fma_f32 v[22:23], v[242:243], v[254:255], 1.0 op_sel_hi:[1,1,0] neg_lo:[1,0,0] neg_hi:[1,0,0]
	v_pk_fma_f32 v[252:253], v[250:251], v[248:249], v[248:249]
	v_pk_fma_f32 v[24:25], v[22:23], v[254:255], v[254:255]
	v_pk_fma_f32 v[250:251], v[240:241], v[252:253], 1.0 op_sel_hi:[1,1,0] neg_lo:[1,0,0] neg_hi:[1,0,0]
	v_pk_fma_f32 v[22:23], v[242:243], v[24:25], 1.0 op_sel_hi:[1,1,0] neg_lo:[1,0,0] neg_hi:[1,0,0]
	v_pk_fma_f32 v[252:253], v[250:251], v[248:249], v[252:253]
	v_pk_fma_f32 v[24:25], v[22:23], v[254:255], v[24:25]
	v_div_fixup_f32 v240, v252, v240, 1.0
	v_div_fixup_f32 v241, v253, v241, 1.0
	v_div_fixup_f32 v242, v24, v242, 1.0
	v_div_fixup_f32 v243, v25, v243, 1.0
	v_rcp_f32_e32 v248, v244
	v_rcp_f32_e32 v249, v245
	v_rcp_f32_e32 v254, v246
	v_rcp_f32_e32 v255, v247
	v_pk_fma_f32 v[250:251], v[244:245], v[248:249], 1.0 op_sel_hi:[1,1,0] neg_lo:[1,0,0] neg_hi:[1,0,0]
	v_pk_fma_f32 v[22:23], v[246:247], v[254:255], 1.0 op_sel_hi:[1,1,0] neg_lo:[1,0,0] neg_hi:[1,0,0]
	v_pk_fma_f32 v[248:249], v[250:251], v[248:249], v[248:249]
	v_pk_fma_f32 v[254:255], v[22:23], v[254:255], v[254:255]
	v_pk_fma_f32 v[250:251], v[244:245], v[248:249], 1.0 op_sel_hi:[1,1,0] neg_lo:[1,0,0] neg_hi:[1,0,0]
	v_pk_fma_f32 v[22:23], v[246:247], v[254:255], 1.0 op_sel_hi:[1,1,0] neg_lo:[1,0,0] neg_hi:[1,0,0]
	v_pk_fma_f32 v[252:253], v[250:251], v[248:249], v[248:249]
	v_pk_fma_f32 v[24:25], v[22:23], v[254:255], v[254:255]
	v_pk_fma_f32 v[250:251], v[244:245], v[252:253], 1.0 op_sel_hi:[1,1,0] neg_lo:[1,0,0] neg_hi:[1,0,0]
	v_pk_fma_f32 v[22:23], v[246:247], v[24:25], 1.0 op_sel_hi:[1,1,0] neg_lo:[1,0,0] neg_hi:[1,0,0]
	v_pk_fma_f32 v[252:253], v[250:251], v[248:249], v[252:253]
	v_pk_fma_f32 v[24:25], v[22:23], v[254:255], v[24:25]
	v_div_fixup_f32 v244, v252, v244, 1.0
	v_div_fixup_f32 v245, v253, v245, 1.0
	v_div_fixup_f32 v246, v24, v246, 1.0
	v_div_fixup_f32 v247, v25, v247, 1.0
	v_lshlrev_b32_e32 v34, 16, v26
	v_and_b32_e32 v35, 0xffff0000, v26
	v_lshlrev_b32_e32 v36, 16, v28
	v_and_b32_e32 v37, 0xffff0000, v28
	v_lshlrev_b32_e32 v28, 16, v29
	v_and_b32_e32 v29, 0xffff0000, v29
	v_lshlrev_b32_e32 v26, 16, v27
	v_and_b32_e32 v27, 0xffff0000, v27
	v_pk_fma_f32 v[12:13], v[12:13], v[240:241], v[34:35]
	v_pk_fma_f32 v[22:23], v[10:11], v[246:247], v[28:29]
	v_pk_fma_f32 v[10:11], v[8:9], v[242:243], v[36:37]
	v_add_lshl_u32 v24, v140, v18, 1
	v_pk_fma_f32 v[14:15], v[14:15], v[244:245], v[26:27]
	v_cvt_pk_bf16_f32 v8, v12, v13
	s_nop 0
	v_cvt_pk_bf16_f32 v9, v14, v15
	v_cvt_pk_bf16_f32 v10, v10, v11
	v_cvt_pk_bf16_f32 v11, v22, v23
	buffer_store_dwordx4 v[8:11], v24, s[20:23], 0 offen sc1
	s_nop 0
	s_waitcnt vmcnt(3)
; __device__ __forceinline__ float sigmoidf_(float x) { return 1.0f / (1.0f + __expf(-x)); }
; __device__ __forceinline__ u32x4 pack8(const f32x4 v0, const f32x4 v1) { u32x4 w; w.x = pk2(v0[0], v0[1]); w.y = pk2(v0[2], v0[3]); w.z = pk2(v1[0], v1[1]); w.w = pk2(v1[2], v1[3]); return w; }
; __device__ __forceinline__ void unpack8(const u32x4 w, f32x4& v0, f32x4& v1) { v0 = (f32x4){bflo(w.x), bfhi(w.x), bflo(w.y), bfhi(w.y)}; v1 = (f32x4){bflo(w.z), bfhi(w.z), bflo(w.w), bfhi(w.w)}; }
;     __device__ __forceinline__ void operator()(const f32x4 (&acc)[2][2][4][2], const Unit& u, int wr, int wc, int fr, int fq) const {
;     ...
;                 for (int bj = 0; bj < 2; ++bj) {
;                     const u32x4 gw = *(const u32x4*)(rowp + O_GA + bj * 128);
;                     f32x4 g0, g1; unpack8(gw, g0, g1);
;                     f32x4 v0, v1;
; #pragma unroll
;                     for (int j = 0; j < 4; ++j) { v0[j] = sigmoidf_(g0[j]) * acc[ai][bj][m][0][j]; v1[j] = sigmoidf_(g1[j]) * acc[ai][bj][m][1][j]; }
;                     const u32x4 mw = *(const u32x4*)(rowp + bj * 128); f32x4 m0, m1; unpack8(mw, m0, m1); v0 += m0; v1 += m1;
;                     __builtin_amdgcn_raw_buffer_store_b128(pack8(v0, v1), rsrc, (unsigned)(((size_t)row * DIN + col0 + bj * 128) * 2), 0, 16  ); }
;             }
;         asm volatile("s_waitcnt vmcnt(0)" ::: "memory");
;         if (fr == 0 && fq == 0) (void)__hip_atomic_fetch_add(ready + 64 * (pm_off + u.pm), 1u, __ATOMIC_RELAXED, __HIP_MEMORY_SCOPE_AGENT);
	v_mov_b32_e32 v8, v200
	v_mov_b32_e32 v9, v201
	v_mov_b32_e32 v10, v202
	v_mov_b32_e32 v11, v203
	v_mov_b32_e32 v12, v204
	v_mov_b32_e32 v13, v205
	v_mov_b32_e32 v14, v206
	v_mov_b32_e32 v15, v207
	s_mov_b32 s100, 0xbfb8aa3b
	v_lshlrev_b32_e32 v240, 16, v10
	v_and_b32_e32 v241, 0xffff0000, v10
	v_lshlrev_b32_e32 v242, 16, v8
	v_and_b32_e32 v243, 0xffff0000, v8
	v_lshlrev_b32_e32 v244, 16, v9
	v_and_b32_e32 v245, 0xffff0000, v9
	v_lshlrev_b32_e32 v246, 16, v11
	v_and_b32_e32 v247, 0xffff0000, v11
	v_pk_mul_f32 v[240:241], v[240:241], s[100:101] op_sel_hi:[1,0]
	v_pk_mul_f32 v[242:243], v[242:243], s[100:101] op_sel_hi:[1,0]
	v_pk_mul_f32 v[244:245], v[244:245], s[100:101] op_sel_hi:[1,0]
	v_pk_mul_f32 v[246:247], v[246:247], s[100:101] op_sel_hi:[1,0]
	v_exp_f32_e32 v240, v240
	v_exp_f32_e32 v241, v241
	v_exp_f32_e32 v242, v242
	v_exp_f32_e32 v243, v243
	v_exp_f32_e32 v244, v244
	v_exp_f32_e32 v245, v245
	v_exp_f32_e32 v246, v246
	v_exp_f32_e32 v247, v247
	s_nop 0
	v_pk_add_f32 v[240:241], v[240:241], 1.0 op_sel_hi:[1,0]
	v_pk_add_f32 v[242:243], v[242:243], 1.0 op_sel_hi:[1,0]
	v_pk_add_f32 v[244:245], v[244:245], 1.0 op_sel_hi:[1,0]
	v_pk_add_f32 v[246:247], v[246:247], 1.0 op_sel_hi:[1,0]
	v_rcp_f32_e32 v248, v240
	v_rcp_f32_e32 v249, v241
	v_rcp_f32_e32 v254, v242
	v_rcp_f32_e32 v255, v243
	v_pk_fma_f32 v[250:251], v[240:241], v[248:249], 1.0 op_sel_hi:[1,1,0] neg_lo:[1,0,0] neg_hi:[1,0,0]
	v_pk_fma_f32 v[8:9], v[242:243], v[254:255], 1.0 op_sel_hi:[1,1,0] neg_lo:[1,0,0] neg_hi:[1,0,0]
	v_pk_fma_f32 v[248:249], v[250:251], v[248:249], v[248:249]
	v_pk_fma_f32 v[254:255], v[8:9], v[254:255], v[254:255]
	v_pk_fma_f32 v[250:251], v[240:241], v[248:249], 1.0 op_sel_hi:[1,1,0] neg_lo:[1,0,0] neg_hi:[1,0,0]
	v_pk_fma_f32 v[8:9], v[242:243], v[254:255], 1.0 op_sel_hi:[1,1,0] neg_lo:[1,0,0] neg_hi:[1,0,0]
	v_pk_fma_f32 v[252:253], v[250:251], v[248:249], v[248:249]
	v_pk_fma_f32 v[10:11], v[8:9], v[254:255], v[254:255]
	v_pk_fma_f32 v[250:251], v[240:241], v[252:253], 1.0 op_sel_hi:[1,1,0] neg_lo:[1,0,0] neg_hi:[1,0,0]
	v_pk_fma_f32 v[8:9], v[242:243], v[10:11], 1.0 op_sel_hi:[1,1,0] neg_lo:[1,0,0] neg_hi:[1,0,0]
	v_pk_fma_f32 v[252:253], v[250:251], v[248:249], v[252:253]
	v_pk_fma_f32 v[10:11], v[8:9], v[254:255], v[10:11]
	v_div_fixup_f32 v240, v252, v240, 1.0
	v_div_fixup_f32 v241, v253, v241, 1.0
	v_div_fixup_f32 v242, v10, v242, 1.0
	v_div_fixup_f32 v243, v11, v243, 1.0
	v_rcp_f32_e32 v248, v244
	v_rcp_f32_e32 v249, v245
	v_rcp_f32_e32 v254, v246
	v_rcp_f32_e32 v255, v247
	v_pk_fma_f32 v[250:251], v[244:245], v[248:249], 1.0 op_sel_hi:[1,1,0] neg_lo:[1,0,0] neg_hi:[1,0,0]
	v_pk_fma_f32 v[8:9], v[246:247], v[254:255], 1.0 op_sel_hi:[1,1,0] neg_lo:[1,0,0] neg_hi:[1,0,0]
	v_pk_fma_f32 v[248:249], v[250:251], v[248:249], v[248:249]
	v_pk_fma_f32 v[254:255], v[8:9], v[254:255], v[254:255]
	v_pk_fma_f32 v[250:251], v[244:245], v[248:249], 1.0 op_sel_hi:[1,1,0] neg_lo:[1,0,0] neg_hi:[1,0,0]
	v_pk_fma_f32 v[8:9], v[246:247], v[254:255], 1.0 op_sel_hi:[1,1,0] neg_lo:[1,0,0] neg_hi:[1,0,0]
	v_pk_fma_f32 v[252:253], v[250:251], v[248:249], v[248:249]
	v_pk_fma_f32 v[10:11], v[8:9], v[254:255], v[254:255]
	v_pk_fma_f32 v[250:251], v[244:245], v[252:253], 1.0 op_sel_hi:[1,1,0] neg_lo:[1,0,0] neg_hi:[1,0,0]
	v_pk_fma_f32 v[8:9], v[246:247], v[10:11], 1.0 op_sel_hi:[1,1,0] neg_lo:[1,0,0] neg_hi:[1,0,0]
	v_pk_fma_f32 v[252:253], v[250:251], v[248:249], v[252:253]
	v_pk_fma_f32 v[10:11], v[8:9], v[254:255], v[10:11]
	v_div_fixup_f32 v244, v252, v244, 1.0
	v_div_fixup_f32 v245, v253, v245, 1.0
	v_div_fixup_f32 v246, v10, v246, 1.0
	v_div_fixup_f32 v247, v11, v247, 1.0
	v_lshlrev_b32_e32 v20, 16, v12
	v_and_b32_e32 v21, 0xffff0000, v12
	v_lshlrev_b32_e32 v22, 16, v14
	v_and_b32_e32 v23, 0xffff0000, v14
	v_lshlrev_b32_e32 v14, 16, v15
	v_and_b32_e32 v15, 0xffff0000, v15
	v_lshlrev_b32_e32 v12, 16, v13
	v_and_b32_e32 v13, 0xffff0000, v13
	v_pk_fma_f32 v[4:5], v[4:5], v[242:243], v[20:21]
	v_pk_fma_f32 v[8:9], v[2:3], v[246:247], v[14:15]
	v_pk_fma_f32 v[2:3], v[0:1], v[240:241], v[22:23]
	v_pk_fma_f32 v[6:7], v[6:7], v[244:245], v[12:13]
	v_cvt_pk_bf16_f32 v0, v4, v5
	s_nop 0
	v_cvt_pk_bf16_f32 v1, v6, v7
	v_cvt_pk_bf16_f32 v2, v2, v3
	v_cvt_pk_bf16_f32 v3, v8, v9
	buffer_store_dwordx4 v[0:3], v24, s[20:23], 0 offen offset:256 sc1
	s_waitcnt vmcnt(0)
	s_and_saveexec_b64 s[10:11], s[8:9]
	s_cbranch_execz .LBB0_1856
	s_mov_b64 s[12:13], exec
	v_mbcnt_lo_u32_b32 v0, s12, 0
	v_mbcnt_hi_u32_b32 v0, s13, v0
	v_cmp_eq_u32_e32 vcc, 0, v0
	s_and_b64 s[6:7], exec, vcc
	s_mov_b64 exec, s[6:7]
	s_cbranch_execz .LBB0_1856
	s_lshl_b32 s6, s75, 6
	s_addk_i32 s6, 0x1000
	s_ashr_i32 s7, s6, 31
	s_lshl_b64 s[6:7], s[6:7], 2
	s_add_u32 s6, s28, s6
	s_addc_u32 s7, s29, s7
	s_bcnt1_i32_b64 s12, s[12:13]
	v_mov_b32_e32 v0, s12
	global_atomic_add v131, v0, s[6:7]
	s_branch .LBB0_1856
